# GEMM K-loops: one more s_setprio 0/1 flip in the middle of every 16-MFMA run (flip every 8 MFMAs instead of every 16)
# speedup vs baseline: 1.0021x; 1.0021x over previous
; #define PG8_STAGE(bufoff, gbase, voff) do { _Pragma("unroll") for (int _i = 0; _i < 2; ++_i) \
;         __builtin_amdgcn_global_load_lds((const unsigned*)((const char*)(gbase) + (voff)[_i]), (PG8_LAS unsigned*)(lds + (bufoff) + ldsw + _i * 8192), 16, 0, 0); } while (0)
; #define PG8_LDA(dst, b, h) do { _Pragma("unroll") for (int m = 0; m < 4; ++m) _Pragma("unroll") for (int k = 0; k < 2; ++k) dst[m][k] = *(const PG8_LAS bf16x8*)(lds + PG8_SA(b, h) + aoff + m * 2048 + k * 1024); } while (0)
; #define PG8_LDB(dst, b, h) do { _Pragma("unroll") for (int n = 0; n < 2; ++n) _Pragma("unroll") for (int k = 0; k < 2; ++k) dst[n][k] = *(const PG8_LAS bf16x8*)(lds + PG8_SB(b, h) + boff + n * 2048 + k * 1024); } while (0)
; #define PG8_MMA(ai, bj, At, Bt) do { __builtin_amdgcn_s_setprio(1); _Pragma("unroll") for (int m = 0; m < 4; ++m) _Pragma("unroll") for (int n = 0; n < 2; ++n) _Pragma("unroll") for (int k = 0; k < 2; ++k) \
;         acc[ai][bj][m][n] = __builtin_amdgcn_mfma_f32_16x16x32_bf16(Bt[n][k], At[m][k], acc[ai][bj][m][n], 0, 0, 0); __builtin_amdgcn_s_setprio(0); } while (0)
; #define PG8_WAIT_V(n) asm volatile("s_waitcnt vmcnt(" #n ")" ::: "memory")
; #define PG8_WAIT_L(n) asm volatile("s_waitcnt lgkmcnt(" #n ")" ::: "memory")
; #define PG8_BAR __builtin_amdgcn_s_barrier()
; #define PG8_SCHED __builtin_amdgcn_sched_barrier(0)
; template <class Epi, class Sched, bool ALIGN_EPI = true, bool SP2 = true>
; __device__ __forceinline__ void gemm_phase(PG8_LAS unsigned char* lds, const Gemm g, const Sched& S, const Epi& E) {
;     ...
;             PG8_LDB(B0, 0, 0); PG8_LDB(B1, 0, 1); PG8_SCHED; PG8_LDA(At, 0, 0); PG8_STAGE(PG8_SA(1, 1), a1 + hstepA, voffA);
;             PG8_WAIT_V(8); PG8_WAIT_L(0); PG8_BAR; PG8_MMA(0, 0, At, B0); PG8_MMA(0, 1, At, B1); PG8_BAR; PG8_SCHED;
;             PG8_LDA(At, 0, 1); PG8_STAGE(PG8_SB(0, 0), b2, voffB); PG8_STAGE(PG8_SB(0, 1), b2 + hstepB, voffB); PG8_STAGE(PG8_SA(0, 0), a2, voffA);
;             PG8_WAIT_V(8); PG8_WAIT_L(0); PG8_BAR; PG8_MMA(1, 0, At, B0); PG8_MMA(1, 1, At, B1); PG8_BAR; PG8_SCHED;
.LBB0_132:
	ds_read_b128 v[150:153], v147
	ds_read_b128 v[154:157], v147 offset:1024
	ds_read_b128 v[158:161], v147 offset:2048
	ds_read_b128 v[162:165], v147 offset:3072
	ds_read_b128 v[166:169], v148
	ds_read_b128 v[170:173], v148 offset:1024
	ds_read_b128 v[174:177], v148 offset:2048
	ds_read_b128 v[178:181], v148 offset:3072
	s_add_u32 s24, s22, 0xfffc0080
	s_addc_u32 s25, s23, -1
	s_cmp_eq_u32 s58, 12
	s_cselect_b32 s27, s17, s25
	s_cselect_b32 s26, s50, s24
	s_cselect_b32 s25, s15, s57
	s_cselect_b32 s24, s51, s56
	v_lshl_add_u64 v[214:215], s[22:23], 0, v[138:139]
	s_add_i32 m0, s13, 0xc000
	ds_read_b128 v[182:185], v149
	ds_read_b128 v[186:189], v149 offset:1024
	ds_read_b128 v[190:193], v149 offset:2048
	ds_read_b128 v[194:197], v149 offset:3072
	ds_read_b128 v[198:201], v149 offset:4096
	ds_read_b128 v[202:205], v149 offset:5120
	ds_read_b128 v[206:209], v149 offset:6144
	ds_read_b128 v[210:213], v149 offset:7168
	global_load_lds_dwordx4 v[214:215], off
	v_lshl_add_u64 v[214:215], s[22:23], 0, v[136:137]
	s_add_i32 m0, s13, 0xe000
	s_nop 0
	global_load_lds_dwordx4 v[214:215], off
	s_waitcnt vmcnt(8)
	s_waitcnt lgkmcnt(0)
	s_barrier
	s_setprio 1
	s_waitcnt lgkmcnt(0)
	v_mfma_f32_16x16x32_bf16 v[124:127], v[150:153], v[182:185], v[124:127]
	v_mfma_f32_16x16x32_bf16 v[120:123], v[158:161], v[182:185], v[120:123]
	v_mfma_f32_16x16x32_bf16 v[116:119], v[150:153], v[190:193], v[116:119]
	v_mfma_f32_16x16x32_bf16 v[112:115], v[158:161], v[190:193], v[112:115]
	v_mfma_f32_16x16x32_bf16 v[100:103], v[150:153], v[198:201], v[100:103]
	v_mfma_f32_16x16x32_bf16 v[96:99], v[158:161], v[198:201], v[96:99]
	v_mfma_f32_16x16x32_bf16 v[84:87], v[150:153], v[206:209], v[84:87]
	v_mfma_f32_16x16x32_bf16 v[80:83], v[158:161], v[206:209], v[80:83]
	s_setprio 0
	s_setprio 1
	v_mfma_f32_16x16x32_bf16 v[124:127], v[154:157], v[186:189], v[124:127]
	v_mfma_f32_16x16x32_bf16 v[120:123], v[162:165], v[186:189], v[120:123]
	v_mfma_f32_16x16x32_bf16 v[116:119], v[154:157], v[194:197], v[116:119]
	v_mfma_f32_16x16x32_bf16 v[112:115], v[162:165], v[194:197], v[112:115]
	v_mfma_f32_16x16x32_bf16 v[100:103], v[154:157], v[202:205], v[100:103]
	v_mfma_f32_16x16x32_bf16 v[96:99], v[162:165], v[202:205], v[96:99]
	v_mfma_f32_16x16x32_bf16 v[84:87], v[154:157], v[210:213], v[84:87]
	v_mfma_f32_16x16x32_bf16 v[80:83], v[162:165], v[210:213], v[80:83]
	s_setprio 0
	s_setprio 1
	v_mfma_f32_16x16x32_bf16 v[108:111], v[166:169], v[182:185], v[108:111]
	v_mfma_f32_16x16x32_bf16 v[104:107], v[174:177], v[182:185], v[104:107]
	v_mfma_f32_16x16x32_bf16 v[92:95], v[166:169], v[190:193], v[92:95]
	v_mfma_f32_16x16x32_bf16 v[88:91], v[174:177], v[190:193], v[88:91]
	v_mfma_f32_16x16x32_bf16 v[76:79], v[166:169], v[198:201], v[76:79]
	v_mfma_f32_16x16x32_bf16 v[72:75], v[174:177], v[198:201], v[72:75]
	v_mfma_f32_16x16x32_bf16 v[68:71], v[166:169], v[206:209], v[68:71]
	v_mfma_f32_16x16x32_bf16 v[64:67], v[174:177], v[206:209], v[64:67]
	s_setprio 0
	s_setprio 1
	v_mfma_f32_16x16x32_bf16 v[108:111], v[170:173], v[186:189], v[108:111]
	v_mfma_f32_16x16x32_bf16 v[104:107], v[178:181], v[186:189], v[104:107]
	v_mfma_f32_16x16x32_bf16 v[92:95], v[170:173], v[194:197], v[92:95]
	v_mfma_f32_16x16x32_bf16 v[88:91], v[178:181], v[194:197], v[88:91]
	v_mfma_f32_16x16x32_bf16 v[76:79], v[170:173], v[202:205], v[76:79]
	v_mfma_f32_16x16x32_bf16 v[72:75], v[178:181], v[202:205], v[72:75]
	v_mfma_f32_16x16x32_bf16 v[68:71], v[170:173], v[210:213], v[68:71]
	v_mfma_f32_16x16x32_bf16 v[64:67], v[178:181], v[210:213], v[64:67]
	s_setprio 0
	s_barrier
	s_add_i32 s52, s46, s31
	v_lshl_add_u64 v[214:215], s[24:25], 0, v[132:133]
	s_mov_b32 m0, s52
	ds_read_b128 v[182:185], v149 offset:16384
	ds_read_b128 v[186:189], v149 offset:17408
	ds_read_b128 v[190:193], v149 offset:18432
	ds_read_b128 v[194:197], v149 offset:19456
	ds_read_b128 v[198:201], v149 offset:20480
	ds_read_b128 v[202:205], v149 offset:21504
	ds_read_b128 v[206:209], v149 offset:22528
	ds_read_b128 v[210:213], v149 offset:23552
	global_load_lds_dwordx4 v[214:215], off
	s_add_i32 m0, s52, 0x2000
	s_add_u32 s60, s24, 0x40000
	v_lshl_add_u64 v[216:217], s[24:25], 0, v[128:129]
	s_addc_u32 s61, s25, 0
	s_add_i32 s52, s47, s31
	global_load_lds_dwordx4 v[216:217], off
	v_lshl_add_u64 v[218:219], s[60:61], 0, v[132:133]
	s_mov_b32 m0, s52
	v_lshl_add_u64 v[220:221], s[26:27], 0, v[130:131]
	global_load_lds_dwordx4 v[218:219], off
	v_lshl_add_u64 v[218:219], s[60:61], 0, v[128:129]
	s_add_i32 m0, s52, 0x2000
	s_nop 0
	global_load_lds_dwordx4 v[218:219], off
	v_lshl_add_u64 v[218:219], s[26:27], 0, v[134:135]
	s_mov_b32 m0, s13
	s_nop 0
	global_load_lds_dwordx4 v[218:219], off
	s_mov_b32 m0, s36
	s_nop 0
	global_load_lds_dwordx4 v[220:221], off
	s_waitcnt vmcnt(8)
	s_waitcnt lgkmcnt(0)
	s_barrier
; #define PG8_STAGE(bufoff, gbase, voff) do { _Pragma("unroll") for (int _i = 0; _i < 2; ++_i) \
;         __builtin_amdgcn_global_load_lds((const unsigned*)((const char*)(gbase) + (voff)[_i]), (PG8_LAS unsigned*)(lds + (bufoff) + ldsw + _i * 8192), 16, 0, 0); } while (0)
; #define PG8_LDA(dst, b, h) do { _Pragma("unroll") for (int m = 0; m < 4; ++m) _Pragma("unroll") for (int k = 0; k < 2; ++k) dst[m][k] = *(const PG8_LAS bf16x8*)(lds + PG8_SA(b, h) + aoff + m * 2048 + k * 1024); } while (0)
; #define PG8_LDB(dst, b, h) do { _Pragma("unroll") for (int n = 0; n < 2; ++n) _Pragma("unroll") for (int k = 0; k < 2; ++k) dst[n][k] = *(const PG8_LAS bf16x8*)(lds + PG8_SB(b, h) + boff + n * 2048 + k * 1024); } while (0)
; #define PG8_MMA(ai, bj, At, Bt) do { __builtin_amdgcn_s_setprio(1); _Pragma("unroll") for (int m = 0; m < 4; ++m) _Pragma("unroll") for (int n = 0; n < 2; ++n) _Pragma("unroll") for (int k = 0; k < 2; ++k) \
;         acc[ai][bj][m][n] = __builtin_amdgcn_mfma_f32_16x16x32_bf16(Bt[n][k], At[m][k], acc[ai][bj][m][n], 0, 0, 0); __builtin_amdgcn_s_setprio(0); } while (0)
; #define PG8_WAIT_V(n) asm volatile("s_waitcnt vmcnt(" #n ")" ::: "memory")
; #define PG8_WAIT_L(n) asm volatile("s_waitcnt lgkmcnt(" #n ")" ::: "memory")
; #define PG8_BAR __builtin_amdgcn_s_barrier()
; #define PG8_SCHED __builtin_amdgcn_sched_barrier(0)
; template <class Epi, class Sched, bool ALIGN_EPI = true, bool SP2 = true>
; __device__ __forceinline__ void gemm_phase(PG8_LAS unsigned char* lds, const Gemm g, const Sched& S, const Epi& E) {
;     ...
;             PG8_WAIT_V(8); PG8_WAIT_L(0); PG8_BAR; PG8_MMA(1, 0, At, B0); PG8_MMA(1, 1, At, B1); PG8_BAR; PG8_SCHED;
;             PG8_LDB(B0, 1, 0); PG8_LDB(B1, 1, 1); PG8_SCHED; PG8_LDA(At, 1, 0); PG8_STAGE(PG8_SA(0, 1), a2 + hstepA, voffA);
;             PG8_WAIT_V(8); PG8_WAIT_L(0); PG8_BAR; PG8_MMA(0, 0, At, B0); PG8_MMA(0, 1, At, B1); PG8_BAR; PG8_SCHED;
	s_setprio 1
	s_waitcnt lgkmcnt(0)
	v_mfma_f32_16x16x32_bf16 v[60:63], v[150:153], v[182:185], v[60:63]
	v_mfma_f32_16x16x32_bf16 v[56:59], v[158:161], v[182:185], v[56:59]
	v_mfma_f32_16x16x32_bf16 v[52:55], v[150:153], v[190:193], v[52:55]
	v_mfma_f32_16x16x32_bf16 v[48:51], v[158:161], v[190:193], v[48:51]
	v_mfma_f32_16x16x32_bf16 v[36:39], v[150:153], v[198:201], v[36:39]
	v_mfma_f32_16x16x32_bf16 v[32:35], v[158:161], v[198:201], v[32:35]
	v_mfma_f32_16x16x32_bf16 v[20:23], v[150:153], v[206:209], v[20:23]
	v_mfma_f32_16x16x32_bf16 v[16:19], v[158:161], v[206:209], v[16:19]
	s_setprio 0
	s_setprio 1
	v_mfma_f32_16x16x32_bf16 v[60:63], v[154:157], v[186:189], v[60:63]
	v_mfma_f32_16x16x32_bf16 v[56:59], v[162:165], v[186:189], v[56:59]
	v_mfma_f32_16x16x32_bf16 v[52:55], v[154:157], v[194:197], v[52:55]
	v_mfma_f32_16x16x32_bf16 v[48:51], v[162:165], v[194:197], v[48:51]
	v_mfma_f32_16x16x32_bf16 v[36:39], v[154:157], v[202:205], v[36:39]
	v_mfma_f32_16x16x32_bf16 v[32:35], v[162:165], v[202:205], v[32:35]
	v_mfma_f32_16x16x32_bf16 v[20:23], v[154:157], v[210:213], v[20:23]
	v_mfma_f32_16x16x32_bf16 v[16:19], v[162:165], v[210:213], v[16:19]
	s_setprio 0
	s_setprio 1
	v_mfma_f32_16x16x32_bf16 v[44:47], v[166:169], v[182:185], v[44:47]
	v_mfma_f32_16x16x32_bf16 v[40:43], v[174:177], v[182:185], v[40:43]
	v_mfma_f32_16x16x32_bf16 v[28:31], v[166:169], v[190:193], v[28:31]
	v_mfma_f32_16x16x32_bf16 v[24:27], v[174:177], v[190:193], v[24:27]
	v_mfma_f32_16x16x32_bf16 v[12:15], v[166:169], v[198:201], v[12:15]
	v_mfma_f32_16x16x32_bf16 v[8:11], v[174:177], v[198:201], v[8:11]
	v_mfma_f32_16x16x32_bf16 v[4:7], v[166:169], v[206:209], v[4:7]
	v_mfma_f32_16x16x32_bf16 v[0:3], v[174:177], v[206:209], v[0:3]
	s_setprio 0
	s_setprio 1
	v_mfma_f32_16x16x32_bf16 v[44:47], v[170:173], v[186:189], v[44:47]
	v_mfma_f32_16x16x32_bf16 v[40:43], v[178:181], v[186:189], v[40:43]
	v_mfma_f32_16x16x32_bf16 v[28:31], v[170:173], v[194:197], v[28:31]
	v_mfma_f32_16x16x32_bf16 v[24:27], v[178:181], v[194:197], v[24:27]
	v_mfma_f32_16x16x32_bf16 v[12:15], v[170:173], v[202:205], v[12:15]
	v_mfma_f32_16x16x32_bf16 v[8:11], v[178:181], v[202:205], v[8:11]
	v_mfma_f32_16x16x32_bf16 v[4:7], v[170:173], v[210:213], v[4:7]
	v_mfma_f32_16x16x32_bf16 v[0:3], v[178:181], v[210:213], v[0:3]
	s_setprio 0
	s_barrier
	s_add_i32 s52, 0, 0x18000
	s_add_i32 s53, 0, 0x1c000
	v_add_u32_e32 v162, s52, v145
	v_add_u32_e32 v178, s53, v145
	ds_read_b128 v[150:153], v162
	ds_read_b128 v[154:157], v162 offset:1024
	ds_read_b128 v[158:161], v162 offset:2048
	ds_read_b128 v[162:165], v162 offset:3072
	ds_read_b128 v[166:169], v178
	ds_read_b128 v[170:173], v178 offset:1024
	ds_read_b128 v[174:177], v178 offset:2048
	ds_read_b128 v[178:181], v178 offset:3072
	s_add_u32 s26, s26, 0x40000
	s_addc_u32 s27, s27, 0
	s_mov_b32 m0, s37
	v_lshl_add_u64 v[222:223], s[26:27], 0, v[134:135]
	ds_read_b128 v[182:185], v149 offset:32768
	ds_read_b128 v[186:189], v149 offset:33792
	ds_read_b128 v[190:193], v149 offset:34816
	ds_read_b128 v[194:197], v149 offset:35840
	ds_read_b128 v[198:201], v149 offset:36864
	ds_read_b128 v[202:205], v149 offset:37888
	ds_read_b128 v[206:209], v149 offset:38912
	ds_read_b128 v[210:213], v149 offset:39936
	global_load_lds_dwordx4 v[222:223], off
	v_lshl_add_u64 v[222:223], s[26:27], 0, v[130:131]
	s_mov_b32 m0, s38
	s_nop 0
	global_load_lds_dwordx4 v[222:223], off
	s_waitcnt vmcnt(8)
	s_waitcnt lgkmcnt(0)
	s_barrier
	s_setprio 1
	s_waitcnt lgkmcnt(0)
	v_mfma_f32_16x16x32_bf16 v[124:127], v[150:153], v[182:185], v[124:127]
	v_mfma_f32_16x16x32_bf16 v[120:123], v[158:161], v[182:185], v[120:123]
	v_mfma_f32_16x16x32_bf16 v[116:119], v[150:153], v[190:193], v[116:119]
	v_mfma_f32_16x16x32_bf16 v[112:115], v[158:161], v[190:193], v[112:115]
	v_mfma_f32_16x16x32_bf16 v[100:103], v[150:153], v[198:201], v[100:103]
	v_mfma_f32_16x16x32_bf16 v[96:99], v[158:161], v[198:201], v[96:99]
	v_mfma_f32_16x16x32_bf16 v[84:87], v[150:153], v[206:209], v[84:87]
	v_mfma_f32_16x16x32_bf16 v[80:83], v[158:161], v[206:209], v[80:83]
	s_setprio 0
	s_setprio 1
	v_mfma_f32_16x16x32_bf16 v[124:127], v[154:157], v[186:189], v[124:127]
	v_mfma_f32_16x16x32_bf16 v[120:123], v[162:165], v[186:189], v[120:123]
	v_mfma_f32_16x16x32_bf16 v[116:119], v[154:157], v[194:197], v[116:119]
	v_mfma_f32_16x16x32_bf16 v[112:115], v[162:165], v[194:197], v[112:115]
	v_mfma_f32_16x16x32_bf16 v[100:103], v[154:157], v[202:205], v[100:103]
	v_mfma_f32_16x16x32_bf16 v[96:99], v[162:165], v[202:205], v[96:99]
	v_mfma_f32_16x16x32_bf16 v[84:87], v[154:157], v[210:213], v[84:87]
	v_mfma_f32_16x16x32_bf16 v[80:83], v[162:165], v[210:213], v[80:83]
	s_setprio 0
	s_setprio 1
	v_mfma_f32_16x16x32_bf16 v[108:111], v[166:169], v[182:185], v[108:111]
	v_mfma_f32_16x16x32_bf16 v[104:107], v[174:177], v[182:185], v[104:107]
	v_mfma_f32_16x16x32_bf16 v[92:95], v[166:169], v[190:193], v[92:95]
	v_mfma_f32_16x16x32_bf16 v[88:91], v[174:177], v[190:193], v[88:91]
	v_mfma_f32_16x16x32_bf16 v[76:79], v[166:169], v[198:201], v[76:79]
	v_mfma_f32_16x16x32_bf16 v[72:75], v[174:177], v[198:201], v[72:75]
	v_mfma_f32_16x16x32_bf16 v[68:71], v[166:169], v[206:209], v[68:71]
	v_mfma_f32_16x16x32_bf16 v[64:67], v[174:177], v[206:209], v[64:67]
	s_setprio 0
	s_setprio 1
	v_mfma_f32_16x16x32_bf16 v[108:111], v[170:173], v[186:189], v[108:111]
	v_mfma_f32_16x16x32_bf16 v[104:107], v[178:181], v[186:189], v[104:107]
	v_mfma_f32_16x16x32_bf16 v[92:95], v[170:173], v[194:197], v[92:95]
	v_mfma_f32_16x16x32_bf16 v[88:91], v[178:181], v[194:197], v[88:91]
	v_mfma_f32_16x16x32_bf16 v[76:79], v[170:173], v[202:205], v[76:79]
	v_mfma_f32_16x16x32_bf16 v[72:75], v[178:181], v[202:205], v[72:75]
	v_mfma_f32_16x16x32_bf16 v[68:71], v[170:173], v[210:213], v[68:71]
	v_mfma_f32_16x16x32_bf16 v[64:67], v[178:181], v[210:213], v[64:67]
	s_setprio 0
	s_barrier
; #define PG8_STAGE(bufoff, gbase, voff) do { _Pragma("unroll") for (int _i = 0; _i < 2; ++_i) \
;         __builtin_amdgcn_global_load_lds((const unsigned*)((const char*)(gbase) + (voff)[_i]), (PG8_LAS unsigned*)(lds + (bufoff) + ldsw + _i * 8192), 16, 0, 0); } while (0)
; #define PG8_LDA(dst, b, h) do { _Pragma("unroll") for (int m = 0; m < 4; ++m) _Pragma("unroll") for (int k = 0; k < 2; ++k) dst[m][k] = *(const PG8_LAS bf16x8*)(lds + PG8_SA(b, h) + aoff + m * 2048 + k * 1024); } while (0)
; #define PG8_MMA(ai, bj, At, Bt) do { __builtin_amdgcn_s_setprio(1); _Pragma("unroll") for (int m = 0; m < 4; ++m) _Pragma("unroll") for (int n = 0; n < 2; ++n) _Pragma("unroll") for (int k = 0; k < 2; ++k) \
;         acc[ai][bj][m][n] = __builtin_amdgcn_mfma_f32_16x16x32_bf16(Bt[n][k], At[m][k], acc[ai][bj][m][n], 0, 0, 0); __builtin_amdgcn_s_setprio(0); } while (0)
; #define PG8_WAIT_V(n) asm volatile("s_waitcnt vmcnt(" #n ")" ::: "memory")
; #define PG8_WAIT_L(n) asm volatile("s_waitcnt lgkmcnt(" #n ")" ::: "memory")
; #define PG8_BAR __builtin_amdgcn_s_barrier()
; #define PG8_SCHED __builtin_amdgcn_sched_barrier(0)
; template <class Epi, class Sched, bool ALIGN_EPI = true, bool SP2 = true>
; __device__ __forceinline__ void gemm_phase(PG8_LAS unsigned char* lds, const Gemm g, const Sched& S, const Epi& E) {
;     ...
;             PG8_LDA(At, 1, 1); PG8_STAGE(PG8_SB(1, 0), b3, voffB); PG8_STAGE(PG8_SB(1, 1), b3 + hstepB, voffB); PG8_STAGE(PG8_SA(1, 0), a3, voffA);
;             PG8_WAIT_V(8); PG8_WAIT_L(0); PG8_BAR; PG8_MMA(1, 0, At, B0); PG8_MMA(1, 1, At, B1); PG8_BAR; PG8_SCHED;
;         }
	s_add_i32 s26, s52, s31
	v_lshl_add_u64 v[214:215], v[214:215], 0, s[8:9]
	s_mov_b32 m0, s26
	ds_read_b128 v[182:185], v149 offset:49152
	ds_read_b128 v[186:189], v149 offset:50176
	ds_read_b128 v[190:193], v149 offset:51200
	ds_read_b128 v[194:197], v149 offset:52224
	ds_read_b128 v[198:201], v149 offset:53248
	ds_read_b128 v[202:205], v149 offset:54272
	ds_read_b128 v[206:209], v149 offset:55296
	ds_read_b128 v[210:213], v149 offset:56320
	global_load_lds_dwordx4 v[214:215], off
	s_add_i32 m0, s26, 0x2000
	s_add_u32 s24, s24, 0x40080
	v_lshl_add_u64 v[214:215], v[216:217], 0, s[8:9]
	s_addc_u32 s25, s25, 0
	s_add_i32 s26, s53, s31
	global_load_lds_dwordx4 v[214:215], off
	v_lshl_add_u64 v[214:215], s[24:25], 0, v[132:133]
	s_mov_b32 m0, s26
	s_nop 0
	global_load_lds_dwordx4 v[214:215], off
	v_lshl_add_u64 v[214:215], s[24:25], 0, v[128:129]
	s_add_i32 m0, s26, 0x2000
	s_nop 0
	global_load_lds_dwordx4 v[214:215], off
	v_lshl_add_u64 v[214:215], v[218:219], 0, s[8:9]
	s_mov_b32 m0, s39
	s_nop 0
	global_load_lds_dwordx4 v[214:215], off
	v_lshl_add_u64 v[214:215], v[220:221], 0, s[8:9]
	s_mov_b32 m0, s40
	s_nop 0
	global_load_lds_dwordx4 v[214:215], off
	s_waitcnt vmcnt(8)
	s_waitcnt lgkmcnt(0)
	s_barrier
	s_setprio 1
	s_waitcnt lgkmcnt(0)
	v_mfma_f32_16x16x32_bf16 v[60:63], v[150:153], v[182:185], v[60:63]
	v_mfma_f32_16x16x32_bf16 v[56:59], v[158:161], v[182:185], v[56:59]
	v_mfma_f32_16x16x32_bf16 v[52:55], v[150:153], v[190:193], v[52:55]
	v_mfma_f32_16x16x32_bf16 v[48:51], v[158:161], v[190:193], v[48:51]
	v_mfma_f32_16x16x32_bf16 v[36:39], v[150:153], v[198:201], v[36:39]
	v_mfma_f32_16x16x32_bf16 v[32:35], v[158:161], v[198:201], v[32:35]
	v_mfma_f32_16x16x32_bf16 v[20:23], v[150:153], v[206:209], v[20:23]
	v_mfma_f32_16x16x32_bf16 v[16:19], v[158:161], v[206:209], v[16:19]
	s_setprio 0
	s_setprio 1
	v_mfma_f32_16x16x32_bf16 v[60:63], v[154:157], v[186:189], v[60:63]
	v_mfma_f32_16x16x32_bf16 v[56:59], v[162:165], v[186:189], v[56:59]
	v_mfma_f32_16x16x32_bf16 v[52:55], v[154:157], v[194:197], v[52:55]
	v_mfma_f32_16x16x32_bf16 v[48:51], v[162:165], v[194:197], v[48:51]
	v_mfma_f32_16x16x32_bf16 v[36:39], v[154:157], v[202:205], v[36:39]
	v_mfma_f32_16x16x32_bf16 v[32:35], v[162:165], v[202:205], v[32:35]
	v_mfma_f32_16x16x32_bf16 v[20:23], v[154:157], v[210:213], v[20:23]
	v_mfma_f32_16x16x32_bf16 v[16:19], v[162:165], v[210:213], v[16:19]
	s_setprio 0
	s_setprio 1
	v_mfma_f32_16x16x32_bf16 v[44:47], v[166:169], v[182:185], v[44:47]
	v_mfma_f32_16x16x32_bf16 v[40:43], v[174:177], v[182:185], v[40:43]
	v_mfma_f32_16x16x32_bf16 v[28:31], v[166:169], v[190:193], v[28:31]
	v_mfma_f32_16x16x32_bf16 v[24:27], v[174:177], v[190:193], v[24:27]
	v_mfma_f32_16x16x32_bf16 v[12:15], v[166:169], v[198:201], v[12:15]
	v_mfma_f32_16x16x32_bf16 v[8:11], v[174:177], v[198:201], v[8:11]
	v_mfma_f32_16x16x32_bf16 v[4:7], v[166:169], v[206:209], v[4:7]
	v_mfma_f32_16x16x32_bf16 v[0:3], v[174:177], v[206:209], v[0:3]
	s_setprio 0
	s_setprio 1
	v_mfma_f32_16x16x32_bf16 v[44:47], v[170:173], v[186:189], v[44:47]
	v_mfma_f32_16x16x32_bf16 v[40:43], v[178:181], v[186:189], v[40:43]
	v_mfma_f32_16x16x32_bf16 v[28:31], v[170:173], v[194:197], v[28:31]
	v_mfma_f32_16x16x32_bf16 v[24:27], v[178:181], v[194:197], v[24:27]
	v_mfma_f32_16x16x32_bf16 v[12:15], v[170:173], v[202:205], v[12:15]
	v_mfma_f32_16x16x32_bf16 v[8:11], v[178:181], v[202:205], v[8:11]
	v_mfma_f32_16x16x32_bf16 v[4:7], v[170:173], v[210:213], v[4:7]
	v_mfma_f32_16x16x32_bf16 v[0:3], v[178:181], v[210:213], v[0:3]
	s_setprio 0
	s_barrier
	s_add_i32 s58, s58, 2
	s_add_u32 s56, s56, 0x100
	s_addc_u32 s57, s57, 0
	s_add_u32 s22, s22, 0x100
	s_addc_u32 s23, s23, 0
	s_cmp_gt_u32 s58, 13
	s_cbranch_scc0 .LBB0_132
	s_and_b64 vcc, exec, s[10:11]
	s_cbranch_vccz .LBB0_135
	s_barrier

; #define PG8_STAGE(bufoff, gbase, voff) do { _Pragma("unroll") for (int _i = 0; _i < 2; ++_i) \
;         __builtin_amdgcn_global_load_lds((const unsigned*)((const char*)(gbase) + (voff)[_i]), (PG8_LAS unsigned*)(lds + (bufoff) + ldsw + _i * 8192), 16, 0, 0); } while (0)
; #define PG8_LDA(dst, b, h) do { _Pragma("unroll") for (int m = 0; m < 4; ++m) _Pragma("unroll") for (int k = 0; k < 2; ++k) dst[m][k] = *(const PG8_LAS bf16x8*)(lds + PG8_SA(b, h) + aoff + m * 2048 + k * 1024); } while (0)
; #define PG8_LDB(dst, b, h) do { _Pragma("unroll") for (int n = 0; n < 2; ++n) _Pragma("unroll") for (int k = 0; k < 2; ++k) dst[n][k] = *(const PG8_LAS bf16x8*)(lds + PG8_SB(b, h) + boff + n * 2048 + k * 1024); } while (0)
; #define PG8_MMA(ai, bj, At, Bt) do { __builtin_amdgcn_s_setprio(1); _Pragma("unroll") for (int m = 0; m < 4; ++m) _Pragma("unroll") for (int n = 0; n < 2; ++n) _Pragma("unroll") for (int k = 0; k < 2; ++k) \
;         acc[ai][bj][m][n] = __builtin_amdgcn_mfma_f32_16x16x32_bf16(Bt[n][k], At[m][k], acc[ai][bj][m][n], 0, 0, 0); __builtin_amdgcn_s_setprio(0); } while (0)
; #define PG8_WAIT_V(n) asm volatile("s_waitcnt vmcnt(" #n ")" ::: "memory")
; #define PG8_WAIT_L(n) asm volatile("s_waitcnt lgkmcnt(" #n ")" ::: "memory")
; #define PG8_BAR __builtin_amdgcn_s_barrier()
; #define PG8_SCHED __builtin_amdgcn_sched_barrier(0)
; template <class Epi, class Sched, bool ALIGN_EPI = true, bool SP2 = true>
; __device__ __forceinline__ void gemm_phase(PG8_LAS unsigned char* lds, const Gemm g, const Sched& S, const Epi& E) {
;     ...
;             PG8_LDB(B0, 0, 0); PG8_LDB(B1, 0, 1); PG8_SCHED; PG8_LDA(At, 0, 0); PG8_STAGE(PG8_SA(1, 1), a1 + hstepA, voffA);
;             PG8_WAIT_V(8); PG8_WAIT_L(0); PG8_BAR; PG8_MMA(0, 0, At, B0); PG8_MMA(0, 1, At, B1); PG8_BAR; PG8_SCHED;
;             PG8_LDA(At, 0, 1); PG8_STAGE(PG8_SB(0, 0), b2, voffB); PG8_STAGE(PG8_SB(0, 1), b2 + hstepB, voffB); PG8_STAGE(PG8_SA(0, 0), a2, voffA);
;             PG8_WAIT_V(8); PG8_WAIT_L(0); PG8_BAR; PG8_MMA(1, 0, At, B0); PG8_MMA(1, 1, At, B1); PG8_BAR; PG8_SCHED;
.LBB0_200:
	ds_read_b128 v[146:149], v143
	ds_read_b128 v[150:153], v143 offset:1024
	ds_read_b128 v[154:157], v143 offset:2048
	ds_read_b128 v[158:161], v143 offset:3072
	ds_read_b128 v[162:165], v144
	ds_read_b128 v[166:169], v144 offset:1024
	ds_read_b128 v[170:173], v144 offset:2048
	ds_read_b128 v[174:177], v144 offset:3072
	s_add_u32 s24, s22, 0xfffc0080
	s_addc_u32 s25, s23, -1
	s_cmp_eq_u32 s57, 12
	s_cselect_b32 s27, s17, s25
	s_cselect_b32 s26, s49, s24
	s_cselect_b32 s25, s15, s56
	s_cselect_b32 s24, s50, s51
	v_lshl_add_u64 v[210:211], s[22:23], 0, v[138:139]
	s_add_i32 m0, s35, 0xc000
	ds_read_b128 v[178:181], v145
	ds_read_b128 v[182:185], v145 offset:1024
	ds_read_b128 v[186:189], v145 offset:2048
	ds_read_b128 v[190:193], v145 offset:3072
	ds_read_b128 v[194:197], v145 offset:4096
	ds_read_b128 v[198:201], v145 offset:5120
	ds_read_b128 v[202:205], v145 offset:6144
	ds_read_b128 v[206:209], v145 offset:7168
	global_load_lds_dwordx4 v[210:211], off
	v_lshl_add_u64 v[210:211], s[22:23], 0, v[136:137]
	s_add_i32 m0, s35, 0xe000
	s_nop 0
	global_load_lds_dwordx4 v[210:211], off
	s_waitcnt vmcnt(8)
	s_waitcnt lgkmcnt(0)
	s_barrier
	s_setprio 1
	s_waitcnt lgkmcnt(0)
	v_mfma_f32_16x16x32_bf16 v[124:127], v[146:149], v[178:181], v[124:127]
	v_mfma_f32_16x16x32_bf16 v[120:123], v[154:157], v[178:181], v[120:123]
	v_mfma_f32_16x16x32_bf16 v[116:119], v[146:149], v[186:189], v[116:119]
	v_mfma_f32_16x16x32_bf16 v[112:115], v[154:157], v[186:189], v[112:115]
	v_mfma_f32_16x16x32_bf16 v[100:103], v[146:149], v[194:197], v[100:103]
	v_mfma_f32_16x16x32_bf16 v[96:99], v[154:157], v[194:197], v[96:99]
	v_mfma_f32_16x16x32_bf16 v[84:87], v[146:149], v[202:205], v[84:87]
	v_mfma_f32_16x16x32_bf16 v[80:83], v[154:157], v[202:205], v[80:83]
	s_setprio 0
	s_setprio 1
	v_mfma_f32_16x16x32_bf16 v[124:127], v[150:153], v[182:185], v[124:127]
	v_mfma_f32_16x16x32_bf16 v[120:123], v[158:161], v[182:185], v[120:123]
	v_mfma_f32_16x16x32_bf16 v[116:119], v[150:153], v[190:193], v[116:119]
	v_mfma_f32_16x16x32_bf16 v[112:115], v[158:161], v[190:193], v[112:115]
	v_mfma_f32_16x16x32_bf16 v[100:103], v[150:153], v[198:201], v[100:103]
	v_mfma_f32_16x16x32_bf16 v[96:99], v[158:161], v[198:201], v[96:99]
	v_mfma_f32_16x16x32_bf16 v[84:87], v[150:153], v[206:209], v[84:87]
	v_mfma_f32_16x16x32_bf16 v[80:83], v[158:161], v[206:209], v[80:83]
	s_setprio 0
	s_setprio 1
	v_mfma_f32_16x16x32_bf16 v[108:111], v[162:165], v[178:181], v[108:111]
	v_mfma_f32_16x16x32_bf16 v[104:107], v[170:173], v[178:181], v[104:107]
	v_mfma_f32_16x16x32_bf16 v[92:95], v[162:165], v[186:189], v[92:95]
	v_mfma_f32_16x16x32_bf16 v[88:91], v[170:173], v[186:189], v[88:91]
	v_mfma_f32_16x16x32_bf16 v[76:79], v[162:165], v[194:197], v[76:79]
	v_mfma_f32_16x16x32_bf16 v[72:75], v[170:173], v[194:197], v[72:75]
	v_mfma_f32_16x16x32_bf16 v[68:71], v[162:165], v[202:205], v[68:71]
	v_mfma_f32_16x16x32_bf16 v[64:67], v[170:173], v[202:205], v[64:67]
	s_setprio 0
	s_setprio 1
	v_mfma_f32_16x16x32_bf16 v[108:111], v[166:169], v[182:185], v[108:111]
	v_mfma_f32_16x16x32_bf16 v[104:107], v[174:177], v[182:185], v[104:107]
	v_mfma_f32_16x16x32_bf16 v[92:95], v[166:169], v[190:193], v[92:95]
	v_mfma_f32_16x16x32_bf16 v[88:91], v[174:177], v[190:193], v[88:91]
	v_mfma_f32_16x16x32_bf16 v[76:79], v[166:169], v[198:201], v[76:79]
	v_mfma_f32_16x16x32_bf16 v[72:75], v[174:177], v[198:201], v[72:75]
	v_mfma_f32_16x16x32_bf16 v[68:71], v[166:169], v[206:209], v[68:71]
	v_mfma_f32_16x16x32_bf16 v[64:67], v[174:177], v[206:209], v[64:67]
	s_setprio 0
	s_barrier
	s_add_i32 s52, s46, s34
	v_lshl_add_u64 v[210:211], s[24:25], 0, v[130:131]
	s_mov_b32 m0, s52
	ds_read_b128 v[178:181], v145 offset:16384
	ds_read_b128 v[182:185], v145 offset:17408
	ds_read_b128 v[186:189], v145 offset:18432
	ds_read_b128 v[190:193], v145 offset:19456
	ds_read_b128 v[194:197], v145 offset:20480
	ds_read_b128 v[198:201], v145 offset:21504
	ds_read_b128 v[202:205], v145 offset:22528
	ds_read_b128 v[206:209], v145 offset:23552
	global_load_lds_dwordx4 v[210:211], off
	s_add_i32 m0, s52, 0x2000
	s_add_u32 s58, s24, 0x40000
	v_lshl_add_u64 v[212:213], s[24:25], 0, v[134:135]
	s_addc_u32 s59, s25, 0
	s_add_i32 s52, s47, s34
	global_load_lds_dwordx4 v[212:213], off
	v_lshl_add_u64 v[214:215], s[58:59], 0, v[130:131]
	s_mov_b32 m0, s52
	v_lshl_add_u64 v[216:217], s[26:27], 0, v[132:133]
	global_load_lds_dwordx4 v[214:215], off
	v_lshl_add_u64 v[214:215], s[58:59], 0, v[134:135]
	s_add_i32 m0, s52, 0x2000
	s_nop 0
	global_load_lds_dwordx4 v[214:215], off
	v_lshl_add_u64 v[214:215], s[26:27], 0, v[128:129]
	s_mov_b32 m0, s35
	s_nop 0
	global_load_lds_dwordx4 v[214:215], off
	s_mov_b32 m0, s36
	s_nop 0
	global_load_lds_dwordx4 v[216:217], off
	s_waitcnt vmcnt(8)
	s_waitcnt lgkmcnt(0)
	s_barrier
; #define PG8_STAGE(bufoff, gbase, voff) do { _Pragma("unroll") for (int _i = 0; _i < 2; ++_i) \
;         __builtin_amdgcn_global_load_lds((const unsigned*)((const char*)(gbase) + (voff)[_i]), (PG8_LAS unsigned*)(lds + (bufoff) + ldsw + _i * 8192), 16, 0, 0); } while (0)
; #define PG8_LDA(dst, b, h) do { _Pragma("unroll") for (int m = 0; m < 4; ++m) _Pragma("unroll") for (int k = 0; k < 2; ++k) dst[m][k] = *(const PG8_LAS bf16x8*)(lds + PG8_SA(b, h) + aoff + m * 2048 + k * 1024); } while (0)
; #define PG8_LDB(dst, b, h) do { _Pragma("unroll") for (int n = 0; n < 2; ++n) _Pragma("unroll") for (int k = 0; k < 2; ++k) dst[n][k] = *(const PG8_LAS bf16x8*)(lds + PG8_SB(b, h) + boff + n * 2048 + k * 1024); } while (0)
; #define PG8_MMA(ai, bj, At, Bt) do { __builtin_amdgcn_s_setprio(1); _Pragma("unroll") for (int m = 0; m < 4; ++m) _Pragma("unroll") for (int n = 0; n < 2; ++n) _Pragma("unroll") for (int k = 0; k < 2; ++k) \
;         acc[ai][bj][m][n] = __builtin_amdgcn_mfma_f32_16x16x32_bf16(Bt[n][k], At[m][k], acc[ai][bj][m][n], 0, 0, 0); __builtin_amdgcn_s_setprio(0); } while (0)
; #define PG8_WAIT_V(n) asm volatile("s_waitcnt vmcnt(" #n ")" ::: "memory")
; #define PG8_WAIT_L(n) asm volatile("s_waitcnt lgkmcnt(" #n ")" ::: "memory")
; #define PG8_BAR __builtin_amdgcn_s_barrier()
; #define PG8_SCHED __builtin_amdgcn_sched_barrier(0)
; template <class Epi, class Sched, bool ALIGN_EPI = true, bool SP2 = true>
; __device__ __forceinline__ void gemm_phase(PG8_LAS unsigned char* lds, const Gemm g, const Sched& S, const Epi& E) {
;     ...
;             PG8_WAIT_V(8); PG8_WAIT_L(0); PG8_BAR; PG8_MMA(1, 0, At, B0); PG8_MMA(1, 1, At, B1); PG8_BAR; PG8_SCHED;
;             PG8_LDB(B0, 1, 0); PG8_LDB(B1, 1, 1); PG8_SCHED; PG8_LDA(At, 1, 0); PG8_STAGE(PG8_SA(0, 1), a2 + hstepA, voffA);
;             PG8_WAIT_V(8); PG8_WAIT_L(0); PG8_BAR; PG8_MMA(0, 0, At, B0); PG8_MMA(0, 1, At, B1); PG8_BAR; PG8_SCHED;
	s_setprio 1
	s_waitcnt lgkmcnt(0)
	v_mfma_f32_16x16x32_bf16 v[60:63], v[146:149], v[178:181], v[60:63]
	v_mfma_f32_16x16x32_bf16 v[56:59], v[154:157], v[178:181], v[56:59]
	v_mfma_f32_16x16x32_bf16 v[52:55], v[146:149], v[186:189], v[52:55]
	v_mfma_f32_16x16x32_bf16 v[48:51], v[154:157], v[186:189], v[48:51]
	v_mfma_f32_16x16x32_bf16 v[36:39], v[146:149], v[194:197], v[36:39]
	v_mfma_f32_16x16x32_bf16 v[32:35], v[154:157], v[194:197], v[32:35]
	v_mfma_f32_16x16x32_bf16 v[20:23], v[146:149], v[202:205], v[20:23]
	v_mfma_f32_16x16x32_bf16 v[16:19], v[154:157], v[202:205], v[16:19]
	s_setprio 0
	s_setprio 1
	v_mfma_f32_16x16x32_bf16 v[60:63], v[150:153], v[182:185], v[60:63]
	v_mfma_f32_16x16x32_bf16 v[56:59], v[158:161], v[182:185], v[56:59]
	v_mfma_f32_16x16x32_bf16 v[52:55], v[150:153], v[190:193], v[52:55]
	v_mfma_f32_16x16x32_bf16 v[48:51], v[158:161], v[190:193], v[48:51]
	v_mfma_f32_16x16x32_bf16 v[36:39], v[150:153], v[198:201], v[36:39]
	v_mfma_f32_16x16x32_bf16 v[32:35], v[158:161], v[198:201], v[32:35]
	v_mfma_f32_16x16x32_bf16 v[20:23], v[150:153], v[206:209], v[20:23]
	v_mfma_f32_16x16x32_bf16 v[16:19], v[158:161], v[206:209], v[16:19]
	s_setprio 0
	s_setprio 1
	v_mfma_f32_16x16x32_bf16 v[44:47], v[162:165], v[178:181], v[44:47]
	v_mfma_f32_16x16x32_bf16 v[40:43], v[170:173], v[178:181], v[40:43]
	v_mfma_f32_16x16x32_bf16 v[28:31], v[162:165], v[186:189], v[28:31]
	v_mfma_f32_16x16x32_bf16 v[24:27], v[170:173], v[186:189], v[24:27]
	v_mfma_f32_16x16x32_bf16 v[12:15], v[162:165], v[194:197], v[12:15]
	v_mfma_f32_16x16x32_bf16 v[8:11], v[170:173], v[194:197], v[8:11]
	v_mfma_f32_16x16x32_bf16 v[4:7], v[162:165], v[202:205], v[4:7]
	v_mfma_f32_16x16x32_bf16 v[0:3], v[170:173], v[202:205], v[0:3]
	s_setprio 0
	s_setprio 1
	v_mfma_f32_16x16x32_bf16 v[44:47], v[166:169], v[182:185], v[44:47]
	v_mfma_f32_16x16x32_bf16 v[40:43], v[174:177], v[182:185], v[40:43]
	v_mfma_f32_16x16x32_bf16 v[28:31], v[166:169], v[190:193], v[28:31]
	v_mfma_f32_16x16x32_bf16 v[24:27], v[174:177], v[190:193], v[24:27]
	v_mfma_f32_16x16x32_bf16 v[12:15], v[166:169], v[198:201], v[12:15]
	v_mfma_f32_16x16x32_bf16 v[8:11], v[174:177], v[198:201], v[8:11]
	v_mfma_f32_16x16x32_bf16 v[4:7], v[166:169], v[206:209], v[4:7]
	v_mfma_f32_16x16x32_bf16 v[0:3], v[174:177], v[206:209], v[0:3]
	s_setprio 0
	s_barrier
	s_add_i32 s52, 0, 0x18000
	s_add_i32 s53, 0, 0x1c000
	v_add_u32_e32 v158, s52, v141
	v_add_u32_e32 v174, s53, v141
	ds_read_b128 v[146:149], v158
	ds_read_b128 v[150:153], v158 offset:1024
	ds_read_b128 v[154:157], v158 offset:2048
	ds_read_b128 v[158:161], v158 offset:3072
	ds_read_b128 v[162:165], v174
	ds_read_b128 v[166:169], v174 offset:1024
	ds_read_b128 v[170:173], v174 offset:2048
	ds_read_b128 v[174:177], v174 offset:3072
	s_add_u32 s26, s26, 0x40000
	s_addc_u32 s27, s27, 0
	s_mov_b32 m0, s37
	v_lshl_add_u64 v[218:219], s[26:27], 0, v[128:129]
	ds_read_b128 v[178:181], v145 offset:32768
	ds_read_b128 v[182:185], v145 offset:33792
	ds_read_b128 v[186:189], v145 offset:34816
	ds_read_b128 v[190:193], v145 offset:35840
	ds_read_b128 v[194:197], v145 offset:36864
	ds_read_b128 v[198:201], v145 offset:37888
	ds_read_b128 v[202:205], v145 offset:38912
	ds_read_b128 v[206:209], v145 offset:39936
	global_load_lds_dwordx4 v[218:219], off
	v_lshl_add_u64 v[218:219], s[26:27], 0, v[132:133]
	s_mov_b32 m0, s38
	s_nop 0
	global_load_lds_dwordx4 v[218:219], off
	s_waitcnt vmcnt(8)
	s_waitcnt lgkmcnt(0)
	s_barrier
	s_setprio 1
	s_waitcnt lgkmcnt(0)
	v_mfma_f32_16x16x32_bf16 v[124:127], v[146:149], v[178:181], v[124:127]
	v_mfma_f32_16x16x32_bf16 v[120:123], v[154:157], v[178:181], v[120:123]
	v_mfma_f32_16x16x32_bf16 v[116:119], v[146:149], v[186:189], v[116:119]
	v_mfma_f32_16x16x32_bf16 v[112:115], v[154:157], v[186:189], v[112:115]
	v_mfma_f32_16x16x32_bf16 v[100:103], v[146:149], v[194:197], v[100:103]
	v_mfma_f32_16x16x32_bf16 v[96:99], v[154:157], v[194:197], v[96:99]
	v_mfma_f32_16x16x32_bf16 v[84:87], v[146:149], v[202:205], v[84:87]
	v_mfma_f32_16x16x32_bf16 v[80:83], v[154:157], v[202:205], v[80:83]
	s_setprio 0
	s_setprio 1
	v_mfma_f32_16x16x32_bf16 v[124:127], v[150:153], v[182:185], v[124:127]
	v_mfma_f32_16x16x32_bf16 v[120:123], v[158:161], v[182:185], v[120:123]
	v_mfma_f32_16x16x32_bf16 v[116:119], v[150:153], v[190:193], v[116:119]
	v_mfma_f32_16x16x32_bf16 v[112:115], v[158:161], v[190:193], v[112:115]
	v_mfma_f32_16x16x32_bf16 v[100:103], v[150:153], v[198:201], v[100:103]
	v_mfma_f32_16x16x32_bf16 v[96:99], v[158:161], v[198:201], v[96:99]
	v_mfma_f32_16x16x32_bf16 v[84:87], v[150:153], v[206:209], v[84:87]
	v_mfma_f32_16x16x32_bf16 v[80:83], v[158:161], v[206:209], v[80:83]
	s_setprio 0
	s_setprio 1
	v_mfma_f32_16x16x32_bf16 v[108:111], v[162:165], v[178:181], v[108:111]
	v_mfma_f32_16x16x32_bf16 v[104:107], v[170:173], v[178:181], v[104:107]
	v_mfma_f32_16x16x32_bf16 v[92:95], v[162:165], v[186:189], v[92:95]
	v_mfma_f32_16x16x32_bf16 v[88:91], v[170:173], v[186:189], v[88:91]
	v_mfma_f32_16x16x32_bf16 v[76:79], v[162:165], v[194:197], v[76:79]
	v_mfma_f32_16x16x32_bf16 v[72:75], v[170:173], v[194:197], v[72:75]
	v_mfma_f32_16x16x32_bf16 v[68:71], v[162:165], v[202:205], v[68:71]
	v_mfma_f32_16x16x32_bf16 v[64:67], v[170:173], v[202:205], v[64:67]
	s_setprio 0
	s_setprio 1
	v_mfma_f32_16x16x32_bf16 v[108:111], v[166:169], v[182:185], v[108:111]
	v_mfma_f32_16x16x32_bf16 v[104:107], v[174:177], v[182:185], v[104:107]
	v_mfma_f32_16x16x32_bf16 v[92:95], v[166:169], v[190:193], v[92:95]
	v_mfma_f32_16x16x32_bf16 v[88:91], v[174:177], v[190:193], v[88:91]
	v_mfma_f32_16x16x32_bf16 v[76:79], v[166:169], v[198:201], v[76:79]
	v_mfma_f32_16x16x32_bf16 v[72:75], v[174:177], v[198:201], v[72:75]
	v_mfma_f32_16x16x32_bf16 v[68:71], v[166:169], v[206:209], v[68:71]
	v_mfma_f32_16x16x32_bf16 v[64:67], v[174:177], v[206:209], v[64:67]
	s_setprio 0
	s_barrier
; #define PG8_STAGE(bufoff, gbase, voff) do { _Pragma("unroll") for (int _i = 0; _i < 2; ++_i) \
;         __builtin_amdgcn_global_load_lds((const unsigned*)((const char*)(gbase) + (voff)[_i]), (PG8_LAS unsigned*)(lds + (bufoff) + ldsw + _i * 8192), 16, 0, 0); } while (0)
; #define PG8_LDA(dst, b, h) do { _Pragma("unroll") for (int m = 0; m < 4; ++m) _Pragma("unroll") for (int k = 0; k < 2; ++k) dst[m][k] = *(const PG8_LAS bf16x8*)(lds + PG8_SA(b, h) + aoff + m * 2048 + k * 1024); } while (0)
; #define PG8_MMA(ai, bj, At, Bt) do { __builtin_amdgcn_s_setprio(1); _Pragma("unroll") for (int m = 0; m < 4; ++m) _Pragma("unroll") for (int n = 0; n < 2; ++n) _Pragma("unroll") for (int k = 0; k < 2; ++k) \
;         acc[ai][bj][m][n] = __builtin_amdgcn_mfma_f32_16x16x32_bf16(Bt[n][k], At[m][k], acc[ai][bj][m][n], 0, 0, 0); __builtin_amdgcn_s_setprio(0); } while (0)
; #define PG8_WAIT_V(n) asm volatile("s_waitcnt vmcnt(" #n ")" ::: "memory")
; #define PG8_WAIT_L(n) asm volatile("s_waitcnt lgkmcnt(" #n ")" ::: "memory")
; #define PG8_BAR __builtin_amdgcn_s_barrier()
; #define PG8_SCHED __builtin_amdgcn_sched_barrier(0)
; template <class Epi, class Sched, bool ALIGN_EPI = true, bool SP2 = true>
; __device__ __forceinline__ void gemm_phase(PG8_LAS unsigned char* lds, const Gemm g, const Sched& S, const Epi& E) {
;     ...
;             PG8_LDA(At, 1, 1); PG8_STAGE(PG8_SB(1, 0), b3, voffB); PG8_STAGE(PG8_SB(1, 1), b3 + hstepB, voffB); PG8_STAGE(PG8_SA(1, 0), a3, voffA);
;             PG8_WAIT_V(8); PG8_WAIT_L(0); PG8_BAR; PG8_MMA(1, 0, At, B0); PG8_MMA(1, 1, At, B1); PG8_BAR; PG8_SCHED;
;         }
	s_add_i32 s26, s52, s34
	v_lshl_add_u64 v[210:211], v[210:211], 0, s[6:7]
	s_mov_b32 m0, s26
	ds_read_b128 v[178:181], v145 offset:49152
	ds_read_b128 v[182:185], v145 offset:50176
	ds_read_b128 v[186:189], v145 offset:51200
	ds_read_b128 v[190:193], v145 offset:52224
	ds_read_b128 v[194:197], v145 offset:53248
	ds_read_b128 v[198:201], v145 offset:54272
	ds_read_b128 v[202:205], v145 offset:55296
	ds_read_b128 v[206:209], v145 offset:56320
	global_load_lds_dwordx4 v[210:211], off
	s_add_i32 m0, s26, 0x2000
	s_add_u32 s24, s24, 0x40080
	v_lshl_add_u64 v[210:211], v[212:213], 0, s[6:7]
	s_addc_u32 s25, s25, 0
	s_add_i32 s26, s53, s34
	global_load_lds_dwordx4 v[210:211], off
	v_lshl_add_u64 v[210:211], s[24:25], 0, v[130:131]
	s_mov_b32 m0, s26
	s_nop 0
	global_load_lds_dwordx4 v[210:211], off
	v_lshl_add_u64 v[210:211], s[24:25], 0, v[134:135]
	s_add_i32 m0, s26, 0x2000
	s_nop 0
	global_load_lds_dwordx4 v[210:211], off
	v_lshl_add_u64 v[210:211], v[214:215], 0, s[6:7]
	s_mov_b32 m0, s40
	s_nop 0
	global_load_lds_dwordx4 v[210:211], off
	v_lshl_add_u64 v[210:211], v[216:217], 0, s[6:7]
	s_mov_b32 m0, s41
	s_nop 0
	global_load_lds_dwordx4 v[210:211], off
	s_waitcnt vmcnt(8)
	s_waitcnt lgkmcnt(0)
	s_barrier
	s_setprio 1
	s_waitcnt lgkmcnt(0)
	v_mfma_f32_16x16x32_bf16 v[60:63], v[146:149], v[178:181], v[60:63]
	v_mfma_f32_16x16x32_bf16 v[56:59], v[154:157], v[178:181], v[56:59]
	v_mfma_f32_16x16x32_bf16 v[52:55], v[146:149], v[186:189], v[52:55]
	v_mfma_f32_16x16x32_bf16 v[48:51], v[154:157], v[186:189], v[48:51]
	v_mfma_f32_16x16x32_bf16 v[36:39], v[146:149], v[194:197], v[36:39]
	v_mfma_f32_16x16x32_bf16 v[32:35], v[154:157], v[194:197], v[32:35]
	v_mfma_f32_16x16x32_bf16 v[20:23], v[146:149], v[202:205], v[20:23]
	v_mfma_f32_16x16x32_bf16 v[16:19], v[154:157], v[202:205], v[16:19]
	s_setprio 0
	s_setprio 1
	v_mfma_f32_16x16x32_bf16 v[60:63], v[150:153], v[182:185], v[60:63]
	v_mfma_f32_16x16x32_bf16 v[56:59], v[158:161], v[182:185], v[56:59]
	v_mfma_f32_16x16x32_bf16 v[52:55], v[150:153], v[190:193], v[52:55]
	v_mfma_f32_16x16x32_bf16 v[48:51], v[158:161], v[190:193], v[48:51]
	v_mfma_f32_16x16x32_bf16 v[36:39], v[150:153], v[198:201], v[36:39]
	v_mfma_f32_16x16x32_bf16 v[32:35], v[158:161], v[198:201], v[32:35]
	v_mfma_f32_16x16x32_bf16 v[20:23], v[150:153], v[206:209], v[20:23]
	v_mfma_f32_16x16x32_bf16 v[16:19], v[158:161], v[206:209], v[16:19]
	s_setprio 0
	s_setprio 1
	v_mfma_f32_16x16x32_bf16 v[44:47], v[162:165], v[178:181], v[44:47]
	v_mfma_f32_16x16x32_bf16 v[40:43], v[170:173], v[178:181], v[40:43]
	v_mfma_f32_16x16x32_bf16 v[28:31], v[162:165], v[186:189], v[28:31]
	v_mfma_f32_16x16x32_bf16 v[24:27], v[170:173], v[186:189], v[24:27]
	v_mfma_f32_16x16x32_bf16 v[12:15], v[162:165], v[194:197], v[12:15]
	v_mfma_f32_16x16x32_bf16 v[8:11], v[170:173], v[194:197], v[8:11]
	v_mfma_f32_16x16x32_bf16 v[4:7], v[162:165], v[202:205], v[4:7]
	v_mfma_f32_16x16x32_bf16 v[0:3], v[170:173], v[202:205], v[0:3]
	s_setprio 0
	s_setprio 1
	v_mfma_f32_16x16x32_bf16 v[44:47], v[166:169], v[182:185], v[44:47]
	v_mfma_f32_16x16x32_bf16 v[40:43], v[174:177], v[182:185], v[40:43]
	v_mfma_f32_16x16x32_bf16 v[28:31], v[166:169], v[190:193], v[28:31]
	v_mfma_f32_16x16x32_bf16 v[24:27], v[174:177], v[190:193], v[24:27]
	v_mfma_f32_16x16x32_bf16 v[12:15], v[166:169], v[198:201], v[12:15]
	v_mfma_f32_16x16x32_bf16 v[8:11], v[174:177], v[198:201], v[8:11]
	v_mfma_f32_16x16x32_bf16 v[4:7], v[166:169], v[206:209], v[4:7]
	v_mfma_f32_16x16x32_bf16 v[0:3], v[174:177], v[206:209], v[0:3]
	s_setprio 0
	s_barrier
	s_add_i32 s57, s57, 2
	s_add_u32 s51, s51, 0x100
	s_addc_u32 s56, s56, 0
	s_add_u32 s22, s22, 0x100
	s_addc_u32 s23, s23, 0
	s_cmp_gt_u32 s57, 13
	s_cbranch_scc0 .LBB0_200
	s_and_b64 vcc, exec, s[8:9]
	s_cbranch_vccz .LBB0_203
	s_barrier

; #define PG8_STAGE(bufoff, gbase, voff) do { _Pragma("unroll") for (int _i = 0; _i < 2; ++_i) \
;         __builtin_amdgcn_global_load_lds((const unsigned*)((const char*)(gbase) + (voff)[_i]), (PG8_LAS unsigned*)(lds + (bufoff) + ldsw + _i * 8192), 16, 0, 0); } while (0)
; #define PG8_LDA(dst, b, h) do { _Pragma("unroll") for (int m = 0; m < 4; ++m) _Pragma("unroll") for (int k = 0; k < 2; ++k) dst[m][k] = *(const PG8_LAS bf16x8*)(lds + PG8_SA(b, h) + aoff + m * 2048 + k * 1024); } while (0)
; #define PG8_LDB(dst, b, h) do { _Pragma("unroll") for (int n = 0; n < 2; ++n) _Pragma("unroll") for (int k = 0; k < 2; ++k) dst[n][k] = *(const PG8_LAS bf16x8*)(lds + PG8_SB(b, h) + boff + n * 2048 + k * 1024); } while (0)
; #define PG8_MMA(ai, bj, At, Bt) do { __builtin_amdgcn_s_setprio(1); _Pragma("unroll") for (int m = 0; m < 4; ++m) _Pragma("unroll") for (int n = 0; n < 2; ++n) _Pragma("unroll") for (int k = 0; k < 2; ++k) \
;         acc[ai][bj][m][n] = __builtin_amdgcn_mfma_f32_16x16x32_bf16(Bt[n][k], At[m][k], acc[ai][bj][m][n], 0, 0, 0); __builtin_amdgcn_s_setprio(0); } while (0)
; #define PG8_WAIT_V(n) asm volatile("s_waitcnt vmcnt(" #n ")" ::: "memory")
; #define PG8_WAIT_L(n) asm volatile("s_waitcnt lgkmcnt(" #n ")" ::: "memory")
; #define PG8_BAR __builtin_amdgcn_s_barrier()
; #define PG8_SCHED __builtin_amdgcn_sched_barrier(0)
; template <class Epi, class Sched, bool ALIGN_EPI = true, bool SP2 = true>
; __device__ __forceinline__ void gemm_phase(PG8_LAS unsigned char* lds, const Gemm g, const Sched& S, const Epi& E) {
;     ...
;             PG8_LDB(B0, 0, 0); PG8_LDB(B1, 0, 1); PG8_SCHED; PG8_LDA(At, 0, 0); PG8_STAGE(PG8_SA(1, 1), a1 + hstepA, voffA);
;             PG8_WAIT_V(8); PG8_WAIT_L(0); PG8_BAR; PG8_MMA(0, 0, At, B0); PG8_MMA(0, 1, At, B1); PG8_BAR; PG8_SCHED;
;             PG8_LDA(At, 0, 1); PG8_STAGE(PG8_SB(0, 0), b2, voffB); PG8_STAGE(PG8_SB(0, 1), b2 + hstepB, voffB); PG8_STAGE(PG8_SA(0, 0), a2, voffA);
;             PG8_WAIT_V(8); PG8_WAIT_L(0); PG8_BAR; PG8_MMA(1, 0, At, B0); PG8_MMA(1, 1, At, B1); PG8_BAR; PG8_SCHED;
.LBB0_226:
	ds_read_b128 v[142:145], v155
	ds_read_b128 v[146:149], v155 offset:1024
	ds_read_b128 v[158:161], v155 offset:2048
	ds_read_b128 v[162:165], v155 offset:3072
	ds_read_b128 v[166:169], v156
	ds_read_b128 v[170:173], v156 offset:1024
	ds_read_b128 v[174:177], v156 offset:2048
	ds_read_b128 v[178:181], v156 offset:3072
	s_add_u32 s30, s28, 0xfffc0080
	s_addc_u32 s31, s29, -1
	s_cmp_eq_u32 s61, 12
	s_cselect_b32 s35, s3, s31
	s_cselect_b32 s34, s5, s30
	s_cselect_b32 s31, s21, s60
	s_cselect_b32 s30, s23, s59
	v_lshl_add_u64 v[150:151], s[28:29], 0, v[140:141]
	s_add_i32 m0, s40, 0xc000
	ds_read_b128 v[182:185], v157
	ds_read_b128 v[186:189], v157 offset:1024
	ds_read_b128 v[190:193], v157 offset:2048
	ds_read_b128 v[194:197], v157 offset:3072
	ds_read_b128 v[198:201], v157 offset:4096
	ds_read_b128 v[202:205], v157 offset:5120
	ds_read_b128 v[206:209], v157 offset:6144
	ds_read_b128 v[210:213], v157 offset:7168
	global_load_lds_dwordx4 v[150:151], off
	v_lshl_add_u64 v[150:151], s[28:29], 0, v[138:139]
	s_add_i32 m0, s40, 0xe000
	s_nop 0
	global_load_lds_dwordx4 v[150:151], off
	s_waitcnt vmcnt(8)
	s_waitcnt lgkmcnt(0)
	s_barrier
	s_setprio 1
	s_waitcnt lgkmcnt(0)
	v_mfma_f32_16x16x32_bf16 v[124:127], v[142:145], v[182:185], v[124:127]
	v_mfma_f32_16x16x32_bf16 v[120:123], v[158:161], v[182:185], v[120:123]
	v_mfma_f32_16x16x32_bf16 v[108:111], v[142:145], v[190:193], v[108:111]
	v_mfma_f32_16x16x32_bf16 v[104:107], v[158:161], v[190:193], v[104:107]
	v_mfma_f32_16x16x32_bf16 v[92:95], v[142:145], v[198:201], v[92:95]
	v_mfma_f32_16x16x32_bf16 v[88:91], v[158:161], v[198:201], v[88:91]
	v_mfma_f32_16x16x32_bf16 v[76:79], v[142:145], v[206:209], v[76:79]
	v_mfma_f32_16x16x32_bf16 v[72:75], v[158:161], v[206:209], v[72:75]
	s_setprio 0
	s_setprio 1
	v_mfma_f32_16x16x32_bf16 v[124:127], v[146:149], v[186:189], v[124:127]
	v_mfma_f32_16x16x32_bf16 v[120:123], v[162:165], v[186:189], v[120:123]
	v_mfma_f32_16x16x32_bf16 v[108:111], v[146:149], v[194:197], v[108:111]
	v_mfma_f32_16x16x32_bf16 v[104:107], v[162:165], v[194:197], v[104:107]
	v_mfma_f32_16x16x32_bf16 v[92:95], v[146:149], v[202:205], v[92:95]
	v_mfma_f32_16x16x32_bf16 v[88:91], v[162:165], v[202:205], v[88:91]
	v_mfma_f32_16x16x32_bf16 v[76:79], v[146:149], v[210:213], v[76:79]
	v_mfma_f32_16x16x32_bf16 v[72:75], v[162:165], v[210:213], v[72:75]
	s_setprio 0
	s_setprio 1
	v_mfma_f32_16x16x32_bf16 v[116:119], v[166:169], v[182:185], v[116:119]
	v_mfma_f32_16x16x32_bf16 v[112:115], v[174:177], v[182:185], v[112:115]
	v_mfma_f32_16x16x32_bf16 v[100:103], v[166:169], v[190:193], v[100:103]
	v_mfma_f32_16x16x32_bf16 v[96:99], v[174:177], v[190:193], v[96:99]
	v_mfma_f32_16x16x32_bf16 v[84:87], v[166:169], v[198:201], v[84:87]
	v_mfma_f32_16x16x32_bf16 v[80:83], v[174:177], v[198:201], v[80:83]
	v_mfma_f32_16x16x32_bf16 v[68:71], v[166:169], v[206:209], v[68:71]
	v_mfma_f32_16x16x32_bf16 v[64:67], v[174:177], v[206:209], v[64:67]
	s_setprio 0
	s_setprio 1
	v_mfma_f32_16x16x32_bf16 v[116:119], v[170:173], v[186:189], v[116:119]
	v_mfma_f32_16x16x32_bf16 v[112:115], v[178:181], v[186:189], v[112:115]
	v_mfma_f32_16x16x32_bf16 v[100:103], v[170:173], v[194:197], v[100:103]
	v_mfma_f32_16x16x32_bf16 v[96:99], v[178:181], v[194:197], v[96:99]
	v_mfma_f32_16x16x32_bf16 v[84:87], v[170:173], v[202:205], v[84:87]
	v_mfma_f32_16x16x32_bf16 v[80:83], v[178:181], v[202:205], v[80:83]
	v_mfma_f32_16x16x32_bf16 v[68:71], v[170:173], v[210:213], v[68:71]
	v_mfma_f32_16x16x32_bf16 v[64:67], v[178:181], v[210:213], v[64:67]
	s_setprio 0
	s_barrier
	s_add_i32 s52, s56, s39
	v_lshl_add_u64 v[150:151], s[30:31], 0, v[130:131]
	s_mov_b32 m0, s52
	ds_read_b128 v[182:185], v157 offset:16384
	ds_read_b128 v[186:189], v157 offset:17408
	ds_read_b128 v[190:193], v157 offset:18432
	ds_read_b128 v[194:197], v157 offset:19456
	ds_read_b128 v[198:201], v157 offset:20480
	ds_read_b128 v[202:205], v157 offset:21504
	ds_read_b128 v[206:209], v157 offset:22528
	ds_read_b128 v[210:213], v157 offset:23552
	global_load_lds_dwordx4 v[150:151], off
	s_add_i32 m0, s52, 0x2000
	s_add_u32 s62, s30, 0x40000
	v_lshl_add_u64 v[214:215], s[30:31], 0, v[134:135]
	s_addc_u32 s63, s31, 0
	s_add_i32 s52, s57, s39
	global_load_lds_dwordx4 v[214:215], off
	v_lshl_add_u64 v[216:217], s[62:63], 0, v[130:131]
	s_mov_b32 m0, s52
	v_lshl_add_u64 v[218:219], s[34:35], 0, v[132:133]
	global_load_lds_dwordx4 v[216:217], off
	v_lshl_add_u64 v[216:217], s[62:63], 0, v[134:135]
	s_add_i32 m0, s52, 0x2000
	s_nop 0
	global_load_lds_dwordx4 v[216:217], off
	v_lshl_add_u64 v[216:217], s[34:35], 0, v[128:129]
	s_mov_b32 m0, s40
	s_nop 0
	global_load_lds_dwordx4 v[216:217], off
	s_mov_b32 m0, s41
	s_nop 0
	global_load_lds_dwordx4 v[218:219], off
	s_waitcnt vmcnt(8)
	s_waitcnt lgkmcnt(0)
	s_barrier
; #define PG8_STAGE(bufoff, gbase, voff) do { _Pragma("unroll") for (int _i = 0; _i < 2; ++_i) \
;         __builtin_amdgcn_global_load_lds((const unsigned*)((const char*)(gbase) + (voff)[_i]), (PG8_LAS unsigned*)(lds + (bufoff) + ldsw + _i * 8192), 16, 0, 0); } while (0)
; #define PG8_LDA(dst, b, h) do { _Pragma("unroll") for (int m = 0; m < 4; ++m) _Pragma("unroll") for (int k = 0; k < 2; ++k) dst[m][k] = *(const PG8_LAS bf16x8*)(lds + PG8_SA(b, h) + aoff + m * 2048 + k * 1024); } while (0)
; #define PG8_LDB(dst, b, h) do { _Pragma("unroll") for (int n = 0; n < 2; ++n) _Pragma("unroll") for (int k = 0; k < 2; ++k) dst[n][k] = *(const PG8_LAS bf16x8*)(lds + PG8_SB(b, h) + boff + n * 2048 + k * 1024); } while (0)
; #define PG8_MMA(ai, bj, At, Bt) do { __builtin_amdgcn_s_setprio(1); _Pragma("unroll") for (int m = 0; m < 4; ++m) _Pragma("unroll") for (int n = 0; n < 2; ++n) _Pragma("unroll") for (int k = 0; k < 2; ++k) \
;         acc[ai][bj][m][n] = __builtin_amdgcn_mfma_f32_16x16x32_bf16(Bt[n][k], At[m][k], acc[ai][bj][m][n], 0, 0, 0); __builtin_amdgcn_s_setprio(0); } while (0)
; #define PG8_WAIT_V(n) asm volatile("s_waitcnt vmcnt(" #n ")" ::: "memory")
; #define PG8_WAIT_L(n) asm volatile("s_waitcnt lgkmcnt(" #n ")" ::: "memory")
; #define PG8_BAR __builtin_amdgcn_s_barrier()
; #define PG8_SCHED __builtin_amdgcn_sched_barrier(0)
; template <class Epi, class Sched, bool ALIGN_EPI = true, bool SP2 = true>
; __device__ __forceinline__ void gemm_phase(PG8_LAS unsigned char* lds, const Gemm g, const Sched& S, const Epi& E) {
;     ...
;             PG8_WAIT_V(8); PG8_WAIT_L(0); PG8_BAR; PG8_MMA(1, 0, At, B0); PG8_MMA(1, 1, At, B1); PG8_BAR; PG8_SCHED;
;             PG8_LDB(B0, 1, 0); PG8_LDB(B1, 1, 1); PG8_SCHED; PG8_LDA(At, 1, 0); PG8_STAGE(PG8_SA(0, 1), a2 + hstepA, voffA);
;             PG8_WAIT_V(8); PG8_WAIT_L(0); PG8_BAR; PG8_MMA(0, 0, At, B0); PG8_MMA(0, 1, At, B1); PG8_BAR; PG8_SCHED;
	s_setprio 1
	s_waitcnt lgkmcnt(0)
	v_mfma_f32_16x16x32_bf16 v[60:63], v[142:145], v[182:185], v[60:63]
	v_mfma_f32_16x16x32_bf16 v[56:59], v[158:161], v[182:185], v[56:59]
	v_mfma_f32_16x16x32_bf16 v[44:47], v[142:145], v[190:193], v[44:47]
	v_mfma_f32_16x16x32_bf16 v[40:43], v[158:161], v[190:193], v[40:43]
	v_mfma_f32_16x16x32_bf16 v[28:31], v[142:145], v[198:201], v[28:31]
	v_mfma_f32_16x16x32_bf16 v[24:27], v[158:161], v[198:201], v[24:27]
	v_mfma_f32_16x16x32_bf16 v[12:15], v[142:145], v[206:209], v[12:15]
	v_mfma_f32_16x16x32_bf16 v[8:11], v[158:161], v[206:209], v[8:11]
	s_setprio 0
	s_setprio 1
	v_mfma_f32_16x16x32_bf16 v[60:63], v[146:149], v[186:189], v[60:63]
	v_mfma_f32_16x16x32_bf16 v[56:59], v[162:165], v[186:189], v[56:59]
	v_mfma_f32_16x16x32_bf16 v[44:47], v[146:149], v[194:197], v[44:47]
	v_mfma_f32_16x16x32_bf16 v[40:43], v[162:165], v[194:197], v[40:43]
	v_mfma_f32_16x16x32_bf16 v[28:31], v[146:149], v[202:205], v[28:31]
	v_mfma_f32_16x16x32_bf16 v[24:27], v[162:165], v[202:205], v[24:27]
	v_mfma_f32_16x16x32_bf16 v[12:15], v[146:149], v[210:213], v[12:15]
	v_mfma_f32_16x16x32_bf16 v[8:11], v[162:165], v[210:213], v[8:11]
	s_setprio 0
	s_setprio 1
	v_mfma_f32_16x16x32_bf16 v[52:55], v[166:169], v[182:185], v[52:55]
	v_mfma_f32_16x16x32_bf16 v[48:51], v[174:177], v[182:185], v[48:51]
	v_mfma_f32_16x16x32_bf16 v[36:39], v[166:169], v[190:193], v[36:39]
	v_mfma_f32_16x16x32_bf16 v[32:35], v[174:177], v[190:193], v[32:35]
	v_mfma_f32_16x16x32_bf16 v[20:23], v[166:169], v[198:201], v[20:23]
	v_mfma_f32_16x16x32_bf16 v[16:19], v[174:177], v[198:201], v[16:19]
	v_mfma_f32_16x16x32_bf16 v[4:7], v[166:169], v[206:209], v[4:7]
	v_mfma_f32_16x16x32_bf16 v[0:3], v[174:177], v[206:209], v[0:3]
	s_setprio 0
	s_setprio 1
	v_mfma_f32_16x16x32_bf16 v[52:55], v[170:173], v[186:189], v[52:55]
	v_mfma_f32_16x16x32_bf16 v[48:51], v[178:181], v[186:189], v[48:51]
	v_mfma_f32_16x16x32_bf16 v[36:39], v[170:173], v[194:197], v[36:39]
	v_mfma_f32_16x16x32_bf16 v[32:35], v[178:181], v[194:197], v[32:35]
	v_mfma_f32_16x16x32_bf16 v[20:23], v[170:173], v[202:205], v[20:23]
	v_mfma_f32_16x16x32_bf16 v[16:19], v[178:181], v[202:205], v[16:19]
	v_mfma_f32_16x16x32_bf16 v[4:7], v[170:173], v[210:213], v[4:7]
	v_mfma_f32_16x16x32_bf16 v[0:3], v[178:181], v[210:213], v[0:3]
	s_setprio 0
	s_barrier
	s_add_i32 s52, 0, 0x18000
	v_add_u32_e32 v136, s52, v153
	s_add_i32 s53, 0, 0x1c000
	ds_read_b128 v[142:145], v136
	ds_read_b128 v[146:149], v136 offset:1024
	ds_read_b128 v[158:161], v136 offset:2048
	ds_read_b128 v[162:165], v136 offset:3072
	v_add_u32_e32 v136, s53, v153
	ds_read_b128 v[166:169], v136
	ds_read_b128 v[170:173], v136 offset:1024
	ds_read_b128 v[174:177], v136 offset:2048
	ds_read_b128 v[178:181], v136 offset:3072
	s_add_u32 s34, s34, 0x40000
	s_addc_u32 s35, s35, 0
	s_mov_b32 m0, s43
	v_lshl_add_u64 v[220:221], s[34:35], 0, v[128:129]
	ds_read_b128 v[182:185], v157 offset:32768
	ds_read_b128 v[186:189], v157 offset:33792
	ds_read_b128 v[190:193], v157 offset:34816
	ds_read_b128 v[194:197], v157 offset:35840
	ds_read_b128 v[198:201], v157 offset:36864
	ds_read_b128 v[202:205], v157 offset:37888
	ds_read_b128 v[206:209], v157 offset:38912
	ds_read_b128 v[210:213], v157 offset:39936
	global_load_lds_dwordx4 v[220:221], off
	v_lshl_add_u64 v[220:221], s[34:35], 0, v[132:133]
	s_mov_b32 m0, s45
	s_nop 0
	global_load_lds_dwordx4 v[220:221], off
	s_waitcnt vmcnt(8)
	s_waitcnt lgkmcnt(0)
	s_barrier
	s_setprio 1
	s_waitcnt lgkmcnt(0)
	v_mfma_f32_16x16x32_bf16 v[124:127], v[142:145], v[182:185], v[124:127]
	v_mfma_f32_16x16x32_bf16 v[120:123], v[158:161], v[182:185], v[120:123]
	v_mfma_f32_16x16x32_bf16 v[108:111], v[142:145], v[190:193], v[108:111]
	v_mfma_f32_16x16x32_bf16 v[104:107], v[158:161], v[190:193], v[104:107]
	v_mfma_f32_16x16x32_bf16 v[92:95], v[142:145], v[198:201], v[92:95]
	v_mfma_f32_16x16x32_bf16 v[88:91], v[158:161], v[198:201], v[88:91]
	v_mfma_f32_16x16x32_bf16 v[76:79], v[142:145], v[206:209], v[76:79]
	v_mfma_f32_16x16x32_bf16 v[72:75], v[158:161], v[206:209], v[72:75]
	s_setprio 0
	s_setprio 1
	v_mfma_f32_16x16x32_bf16 v[124:127], v[146:149], v[186:189], v[124:127]
	v_mfma_f32_16x16x32_bf16 v[120:123], v[162:165], v[186:189], v[120:123]
	v_mfma_f32_16x16x32_bf16 v[108:111], v[146:149], v[194:197], v[108:111]
	v_mfma_f32_16x16x32_bf16 v[104:107], v[162:165], v[194:197], v[104:107]
	v_mfma_f32_16x16x32_bf16 v[92:95], v[146:149], v[202:205], v[92:95]
	v_mfma_f32_16x16x32_bf16 v[88:91], v[162:165], v[202:205], v[88:91]
	v_mfma_f32_16x16x32_bf16 v[76:79], v[146:149], v[210:213], v[76:79]
	v_mfma_f32_16x16x32_bf16 v[72:75], v[162:165], v[210:213], v[72:75]
	s_setprio 0
	s_setprio 1
	v_mfma_f32_16x16x32_bf16 v[116:119], v[166:169], v[182:185], v[116:119]
	v_mfma_f32_16x16x32_bf16 v[112:115], v[174:177], v[182:185], v[112:115]
	v_mfma_f32_16x16x32_bf16 v[100:103], v[166:169], v[190:193], v[100:103]
	v_mfma_f32_16x16x32_bf16 v[96:99], v[174:177], v[190:193], v[96:99]
	v_mfma_f32_16x16x32_bf16 v[84:87], v[166:169], v[198:201], v[84:87]
	v_mfma_f32_16x16x32_bf16 v[80:83], v[174:177], v[198:201], v[80:83]
	v_mfma_f32_16x16x32_bf16 v[68:71], v[166:169], v[206:209], v[68:71]
	v_mfma_f32_16x16x32_bf16 v[64:67], v[174:177], v[206:209], v[64:67]
	s_setprio 0
	s_setprio 1
	v_mfma_f32_16x16x32_bf16 v[116:119], v[170:173], v[186:189], v[116:119]
	v_mfma_f32_16x16x32_bf16 v[112:115], v[178:181], v[186:189], v[112:115]
	v_mfma_f32_16x16x32_bf16 v[100:103], v[170:173], v[194:197], v[100:103]
	v_mfma_f32_16x16x32_bf16 v[96:99], v[178:181], v[194:197], v[96:99]
	v_mfma_f32_16x16x32_bf16 v[84:87], v[170:173], v[202:205], v[84:87]
	v_mfma_f32_16x16x32_bf16 v[80:83], v[178:181], v[202:205], v[80:83]
	v_mfma_f32_16x16x32_bf16 v[68:71], v[170:173], v[210:213], v[68:71]
	v_mfma_f32_16x16x32_bf16 v[64:67], v[178:181], v[210:213], v[64:67]
	s_setprio 0
	s_barrier
; #define PG8_STAGE(bufoff, gbase, voff) do { _Pragma("unroll") for (int _i = 0; _i < 2; ++_i) \
;         __builtin_amdgcn_global_load_lds((const unsigned*)((const char*)(gbase) + (voff)[_i]), (PG8_LAS unsigned*)(lds + (bufoff) + ldsw + _i * 8192), 16, 0, 0); } while (0)
; #define PG8_LDA(dst, b, h) do { _Pragma("unroll") for (int m = 0; m < 4; ++m) _Pragma("unroll") for (int k = 0; k < 2; ++k) dst[m][k] = *(const PG8_LAS bf16x8*)(lds + PG8_SA(b, h) + aoff + m * 2048 + k * 1024); } while (0)
; #define PG8_MMA(ai, bj, At, Bt) do { __builtin_amdgcn_s_setprio(1); _Pragma("unroll") for (int m = 0; m < 4; ++m) _Pragma("unroll") for (int n = 0; n < 2; ++n) _Pragma("unroll") for (int k = 0; k < 2; ++k) \
;         acc[ai][bj][m][n] = __builtin_amdgcn_mfma_f32_16x16x32_bf16(Bt[n][k], At[m][k], acc[ai][bj][m][n], 0, 0, 0); __builtin_amdgcn_s_setprio(0); } while (0)
; #define PG8_WAIT_V(n) asm volatile("s_waitcnt vmcnt(" #n ")" ::: "memory")
; #define PG8_WAIT_L(n) asm volatile("s_waitcnt lgkmcnt(" #n ")" ::: "memory")
; #define PG8_BAR __builtin_amdgcn_s_barrier()
; #define PG8_SCHED __builtin_amdgcn_sched_barrier(0)
; template <class Epi, class Sched, bool ALIGN_EPI = true, bool SP2 = true>
; __device__ __forceinline__ void gemm_phase(PG8_LAS unsigned char* lds, const Gemm g, const Sched& S, const Epi& E) {
;     ...
;             PG8_LDA(At, 1, 1); PG8_STAGE(PG8_SB(1, 0), b3, voffB); PG8_STAGE(PG8_SB(1, 1), b3 + hstepB, voffB); PG8_STAGE(PG8_SA(1, 0), a3, voffA);
;             PG8_WAIT_V(8); PG8_WAIT_L(0); PG8_BAR; PG8_MMA(1, 0, At, B0); PG8_MMA(1, 1, At, B1); PG8_BAR; PG8_SCHED;
;         }
	s_add_i32 s34, s52, s39
	v_lshl_add_u64 v[150:151], v[150:151], 0, s[12:13]
	s_mov_b32 m0, s34
	ds_read_b128 v[182:185], v157 offset:49152
	ds_read_b128 v[186:189], v157 offset:50176
	ds_read_b128 v[190:193], v157 offset:51200
	ds_read_b128 v[194:197], v157 offset:52224
	ds_read_b128 v[198:201], v157 offset:53248
	ds_read_b128 v[202:205], v157 offset:54272
	ds_read_b128 v[206:209], v157 offset:55296
	ds_read_b128 v[210:213], v157 offset:56320
	global_load_lds_dwordx4 v[150:151], off
	s_add_i32 m0, s34, 0x2000
	s_add_u32 s30, s30, 0x40080
	v_lshl_add_u64 v[150:151], v[214:215], 0, s[12:13]
	s_addc_u32 s31, s31, 0
	s_add_i32 s34, s53, s39
	global_load_lds_dwordx4 v[150:151], off
	v_lshl_add_u64 v[150:151], s[30:31], 0, v[130:131]
	s_mov_b32 m0, s34
	s_nop 0
	global_load_lds_dwordx4 v[150:151], off
	v_lshl_add_u64 v[150:151], s[30:31], 0, v[134:135]
	s_add_i32 m0, s34, 0x2000
	s_nop 0
	global_load_lds_dwordx4 v[150:151], off
	v_lshl_add_u64 v[150:151], v[216:217], 0, s[12:13]
	s_mov_b32 m0, s47
	s_nop 0
	global_load_lds_dwordx4 v[150:151], off
	v_lshl_add_u64 v[150:151], v[218:219], 0, s[12:13]
	s_mov_b32 m0, s48
	s_nop 0
	global_load_lds_dwordx4 v[150:151], off
	s_waitcnt vmcnt(8)
	s_waitcnt lgkmcnt(0)
	s_barrier
	s_setprio 1
	s_waitcnt lgkmcnt(0)
	v_mfma_f32_16x16x32_bf16 v[60:63], v[142:145], v[182:185], v[60:63]
	v_mfma_f32_16x16x32_bf16 v[56:59], v[158:161], v[182:185], v[56:59]
	v_mfma_f32_16x16x32_bf16 v[44:47], v[142:145], v[190:193], v[44:47]
	v_mfma_f32_16x16x32_bf16 v[40:43], v[158:161], v[190:193], v[40:43]
	v_mfma_f32_16x16x32_bf16 v[28:31], v[142:145], v[198:201], v[28:31]
	v_mfma_f32_16x16x32_bf16 v[24:27], v[158:161], v[198:201], v[24:27]
	v_mfma_f32_16x16x32_bf16 v[12:15], v[142:145], v[206:209], v[12:15]
	v_mfma_f32_16x16x32_bf16 v[8:11], v[158:161], v[206:209], v[8:11]
	s_setprio 0
	s_setprio 1
	v_mfma_f32_16x16x32_bf16 v[60:63], v[146:149], v[186:189], v[60:63]
	v_mfma_f32_16x16x32_bf16 v[56:59], v[162:165], v[186:189], v[56:59]
	v_mfma_f32_16x16x32_bf16 v[44:47], v[146:149], v[194:197], v[44:47]
	v_mfma_f32_16x16x32_bf16 v[40:43], v[162:165], v[194:197], v[40:43]
	v_mfma_f32_16x16x32_bf16 v[28:31], v[146:149], v[202:205], v[28:31]
	v_mfma_f32_16x16x32_bf16 v[24:27], v[162:165], v[202:205], v[24:27]
	v_mfma_f32_16x16x32_bf16 v[12:15], v[146:149], v[210:213], v[12:15]
	v_mfma_f32_16x16x32_bf16 v[8:11], v[162:165], v[210:213], v[8:11]
	s_setprio 0
	s_setprio 1
	v_mfma_f32_16x16x32_bf16 v[52:55], v[166:169], v[182:185], v[52:55]
	v_mfma_f32_16x16x32_bf16 v[48:51], v[174:177], v[182:185], v[48:51]
	v_mfma_f32_16x16x32_bf16 v[36:39], v[166:169], v[190:193], v[36:39]
	v_mfma_f32_16x16x32_bf16 v[32:35], v[174:177], v[190:193], v[32:35]
	v_mfma_f32_16x16x32_bf16 v[20:23], v[166:169], v[198:201], v[20:23]
	v_mfma_f32_16x16x32_bf16 v[16:19], v[174:177], v[198:201], v[16:19]
	v_mfma_f32_16x16x32_bf16 v[4:7], v[166:169], v[206:209], v[4:7]
	v_mfma_f32_16x16x32_bf16 v[0:3], v[174:177], v[206:209], v[0:3]
	s_setprio 0
	s_setprio 1
	v_mfma_f32_16x16x32_bf16 v[52:55], v[170:173], v[186:189], v[52:55]
	v_mfma_f32_16x16x32_bf16 v[48:51], v[178:181], v[186:189], v[48:51]
	v_mfma_f32_16x16x32_bf16 v[36:39], v[170:173], v[194:197], v[36:39]
	v_mfma_f32_16x16x32_bf16 v[32:35], v[178:181], v[194:197], v[32:35]
	v_mfma_f32_16x16x32_bf16 v[20:23], v[170:173], v[202:205], v[20:23]
	v_mfma_f32_16x16x32_bf16 v[16:19], v[178:181], v[202:205], v[16:19]
	v_mfma_f32_16x16x32_bf16 v[4:7], v[170:173], v[210:213], v[4:7]
	v_mfma_f32_16x16x32_bf16 v[0:3], v[178:181], v[210:213], v[0:3]
	s_setprio 0
	s_barrier
	s_add_i32 s61, s61, 2
	s_add_u32 s59, s59, 0x100
	s_addc_u32 s60, s60, 0
	s_add_u32 s28, s28, 0x100
	s_addc_u32 s29, s29, 0
	s_cmp_gt_u32 s61, 13
	s_cbranch_scc0 .LBB0_226
	s_and_b64 vcc, exec, s[14:15]
	s_cbranch_vccz .LBB0_229
	s_barrier

; #define PG8_STAGE(bufoff, gbase, voff) do { _Pragma("unroll") for (int _i = 0; _i < 2; ++_i) \
;         __builtin_amdgcn_global_load_lds((const unsigned*)((const char*)(gbase) + (voff)[_i]), (PG8_LAS unsigned*)(lds + (bufoff) + ldsw + _i * 8192), 16, 0, 0); } while (0)
; #define PG8_LDA(dst, b, h) do { _Pragma("unroll") for (int m = 0; m < 4; ++m) _Pragma("unroll") for (int k = 0; k < 2; ++k) dst[m][k] = *(const PG8_LAS bf16x8*)(lds + PG8_SA(b, h) + aoff + m * 2048 + k * 1024); } while (0)
; #define PG8_LDB(dst, b, h) do { _Pragma("unroll") for (int n = 0; n < 2; ++n) _Pragma("unroll") for (int k = 0; k < 2; ++k) dst[n][k] = *(const PG8_LAS bf16x8*)(lds + PG8_SB(b, h) + boff + n * 2048 + k * 1024); } while (0)
; #define PG8_MMA(ai, bj, At, Bt) do { __builtin_amdgcn_s_setprio(1); _Pragma("unroll") for (int m = 0; m < 4; ++m) _Pragma("unroll") for (int n = 0; n < 2; ++n) _Pragma("unroll") for (int k = 0; k < 2; ++k) \
;         acc[ai][bj][m][n] = __builtin_amdgcn_mfma_f32_16x16x32_bf16(Bt[n][k], At[m][k], acc[ai][bj][m][n], 0, 0, 0); __builtin_amdgcn_s_setprio(0); } while (0)
; #define PG8_WAIT_V(n) asm volatile("s_waitcnt vmcnt(" #n ")" ::: "memory")
; #define PG8_WAIT_L(n) asm volatile("s_waitcnt lgkmcnt(" #n ")" ::: "memory")
; #define PG8_BAR __builtin_amdgcn_s_barrier()
; #define PG8_SCHED __builtin_amdgcn_sched_barrier(0)
; template <class Epi, class Sched, bool ALIGN_EPI = true, bool SP2 = true>
; __device__ __forceinline__ void gemm_phase(PG8_LAS unsigned char* lds, const Gemm g, const Sched& S, const Epi& E) {
;     ...
;             PG8_LDB(B0, 0, 0); PG8_LDB(B1, 0, 1); PG8_SCHED; PG8_LDA(At, 0, 0); PG8_STAGE(PG8_SA(1, 1), a1 + hstepA, voffA);
;             PG8_WAIT_V(8); PG8_WAIT_L(0); PG8_BAR; PG8_MMA(0, 0, At, B0); PG8_MMA(0, 1, At, B1); PG8_BAR; PG8_SCHED;
;             PG8_LDA(At, 0, 1); PG8_STAGE(PG8_SB(0, 0), b2, voffB); PG8_STAGE(PG8_SB(0, 1), b2 + hstepB, voffB); PG8_STAGE(PG8_SA(0, 0), a2, voffA);
;             PG8_WAIT_V(8); PG8_WAIT_L(0); PG8_BAR; PG8_MMA(1, 0, At, B0); PG8_MMA(1, 1, At, B1); PG8_BAR; PG8_SCHED;
.LBB0_306:
	ds_read_b128 v[146:149], v143
	ds_read_b128 v[150:153], v143 offset:1024
	ds_read_b128 v[154:157], v143 offset:2048
	ds_read_b128 v[158:161], v143 offset:3072
	ds_read_b128 v[162:165], v144
	ds_read_b128 v[166:169], v144 offset:1024
	ds_read_b128 v[170:173], v144 offset:2048
	ds_read_b128 v[174:177], v144 offset:3072
	s_add_u32 s36, s34, 0xfffc0080
	s_addc_u32 s37, s35, -1
	s_cmp_eq_u32 s73, 12
	s_cselect_b32 s39, s25, s37
	s_cselect_b32 s38, s66, s36
	s_cselect_b32 s37, s23, s72
	s_cselect_b32 s36, s70, s71
	v_lshl_add_u64 v[210:211], s[34:35], 0, v[138:139]
	s_add_i32 m0, s48, 0xc000
	ds_read_b128 v[178:181], v145
	ds_read_b128 v[182:185], v145 offset:1024
	ds_read_b128 v[186:189], v145 offset:2048
	ds_read_b128 v[190:193], v145 offset:3072
	ds_read_b128 v[194:197], v145 offset:4096
	ds_read_b128 v[198:201], v145 offset:5120
	ds_read_b128 v[202:205], v145 offset:6144
	ds_read_b128 v[206:209], v145 offset:7168
	global_load_lds_dwordx4 v[210:211], off
	v_lshl_add_u64 v[210:211], s[34:35], 0, v[136:137]
	s_add_i32 m0, s48, 0xe000
	s_nop 0
	global_load_lds_dwordx4 v[210:211], off
	s_waitcnt vmcnt(8)
	s_waitcnt lgkmcnt(0)
	s_barrier
	s_setprio 1
	s_waitcnt lgkmcnt(0)
	v_mfma_f32_16x16x32_bf16 v[124:127], v[146:149], v[178:181], v[124:127]
	v_mfma_f32_16x16x32_bf16 v[120:123], v[154:157], v[178:181], v[120:123]
	v_mfma_f32_16x16x32_bf16 v[116:119], v[146:149], v[186:189], v[116:119]
	v_mfma_f32_16x16x32_bf16 v[112:115], v[154:157], v[186:189], v[112:115]
	v_mfma_f32_16x16x32_bf16 v[100:103], v[146:149], v[194:197], v[100:103]
	v_mfma_f32_16x16x32_bf16 v[96:99], v[154:157], v[194:197], v[96:99]
	v_mfma_f32_16x16x32_bf16 v[84:87], v[146:149], v[202:205], v[84:87]
	v_mfma_f32_16x16x32_bf16 v[80:83], v[154:157], v[202:205], v[80:83]
	s_setprio 0
	s_setprio 1
	v_mfma_f32_16x16x32_bf16 v[124:127], v[150:153], v[182:185], v[124:127]
	v_mfma_f32_16x16x32_bf16 v[120:123], v[158:161], v[182:185], v[120:123]
	v_mfma_f32_16x16x32_bf16 v[116:119], v[150:153], v[190:193], v[116:119]
	v_mfma_f32_16x16x32_bf16 v[112:115], v[158:161], v[190:193], v[112:115]
	v_mfma_f32_16x16x32_bf16 v[100:103], v[150:153], v[198:201], v[100:103]
	v_mfma_f32_16x16x32_bf16 v[96:99], v[158:161], v[198:201], v[96:99]
	v_mfma_f32_16x16x32_bf16 v[84:87], v[150:153], v[206:209], v[84:87]
	v_mfma_f32_16x16x32_bf16 v[80:83], v[158:161], v[206:209], v[80:83]
	s_setprio 0
	s_setprio 1
	v_mfma_f32_16x16x32_bf16 v[108:111], v[162:165], v[178:181], v[108:111]
	v_mfma_f32_16x16x32_bf16 v[104:107], v[170:173], v[178:181], v[104:107]
	v_mfma_f32_16x16x32_bf16 v[92:95], v[162:165], v[186:189], v[92:95]
	v_mfma_f32_16x16x32_bf16 v[88:91], v[170:173], v[186:189], v[88:91]
	v_mfma_f32_16x16x32_bf16 v[76:79], v[162:165], v[194:197], v[76:79]
	v_mfma_f32_16x16x32_bf16 v[72:75], v[170:173], v[194:197], v[72:75]
	v_mfma_f32_16x16x32_bf16 v[68:71], v[162:165], v[202:205], v[68:71]
	v_mfma_f32_16x16x32_bf16 v[64:67], v[170:173], v[202:205], v[64:67]
	s_setprio 0
	s_setprio 1
	v_mfma_f32_16x16x32_bf16 v[108:111], v[166:169], v[182:185], v[108:111]
	v_mfma_f32_16x16x32_bf16 v[104:107], v[174:177], v[182:185], v[104:107]
	v_mfma_f32_16x16x32_bf16 v[92:95], v[166:169], v[190:193], v[92:95]
	v_mfma_f32_16x16x32_bf16 v[88:91], v[174:177], v[190:193], v[88:91]
	v_mfma_f32_16x16x32_bf16 v[76:79], v[166:169], v[198:201], v[76:79]
	v_mfma_f32_16x16x32_bf16 v[72:75], v[174:177], v[198:201], v[72:75]
	v_mfma_f32_16x16x32_bf16 v[68:71], v[166:169], v[206:209], v[68:71]
	v_mfma_f32_16x16x32_bf16 v[64:67], v[174:177], v[206:209], v[64:67]
	s_setprio 0
	s_barrier
	s_add_i32 s52, s60, s46
	v_lshl_add_u64 v[210:211], s[36:37], 0, v[132:133]
	s_mov_b32 m0, s52
	ds_read_b128 v[178:181], v145 offset:16384
	ds_read_b128 v[182:185], v145 offset:17408
	ds_read_b128 v[186:189], v145 offset:18432
	ds_read_b128 v[190:193], v145 offset:19456
	ds_read_b128 v[194:197], v145 offset:20480
	ds_read_b128 v[198:201], v145 offset:21504
	ds_read_b128 v[202:205], v145 offset:22528
	ds_read_b128 v[206:209], v145 offset:23552
	global_load_lds_dwordx4 v[210:211], off
	s_add_i32 m0, s52, 0x2000
	s_add_u32 s74, s36, 0x40000
	v_lshl_add_u64 v[212:213], s[36:37], 0, v[128:129]
	s_addc_u32 s75, s37, 0
	s_add_i32 s52, s61, s46
	global_load_lds_dwordx4 v[212:213], off
	v_lshl_add_u64 v[214:215], s[74:75], 0, v[132:133]
	s_mov_b32 m0, s52
	v_lshl_add_u64 v[216:217], s[38:39], 0, v[130:131]
	global_load_lds_dwordx4 v[214:215], off
	v_lshl_add_u64 v[214:215], s[74:75], 0, v[128:129]
	s_add_i32 m0, s52, 0x2000
	s_nop 0
	global_load_lds_dwordx4 v[214:215], off
	v_lshl_add_u64 v[214:215], s[38:39], 0, v[134:135]
	s_mov_b32 m0, s48
	s_nop 0
	global_load_lds_dwordx4 v[214:215], off
	s_mov_b32 m0, s49
	s_nop 0
	global_load_lds_dwordx4 v[216:217], off
	s_waitcnt vmcnt(8)
	s_waitcnt lgkmcnt(0)
	s_barrier
; #define PG8_STAGE(bufoff, gbase, voff) do { _Pragma("unroll") for (int _i = 0; _i < 2; ++_i) \
;         __builtin_amdgcn_global_load_lds((const unsigned*)((const char*)(gbase) + (voff)[_i]), (PG8_LAS unsigned*)(lds + (bufoff) + ldsw + _i * 8192), 16, 0, 0); } while (0)
; #define PG8_LDA(dst, b, h) do { _Pragma("unroll") for (int m = 0; m < 4; ++m) _Pragma("unroll") for (int k = 0; k < 2; ++k) dst[m][k] = *(const PG8_LAS bf16x8*)(lds + PG8_SA(b, h) + aoff + m * 2048 + k * 1024); } while (0)
; #define PG8_LDB(dst, b, h) do { _Pragma("unroll") for (int n = 0; n < 2; ++n) _Pragma("unroll") for (int k = 0; k < 2; ++k) dst[n][k] = *(const PG8_LAS bf16x8*)(lds + PG8_SB(b, h) + boff + n * 2048 + k * 1024); } while (0)
; #define PG8_MMA(ai, bj, At, Bt) do { __builtin_amdgcn_s_setprio(1); _Pragma("unroll") for (int m = 0; m < 4; ++m) _Pragma("unroll") for (int n = 0; n < 2; ++n) _Pragma("unroll") for (int k = 0; k < 2; ++k) \
;         acc[ai][bj][m][n] = __builtin_amdgcn_mfma_f32_16x16x32_bf16(Bt[n][k], At[m][k], acc[ai][bj][m][n], 0, 0, 0); __builtin_amdgcn_s_setprio(0); } while (0)
; #define PG8_WAIT_V(n) asm volatile("s_waitcnt vmcnt(" #n ")" ::: "memory")
; #define PG8_WAIT_L(n) asm volatile("s_waitcnt lgkmcnt(" #n ")" ::: "memory")
; #define PG8_BAR __builtin_amdgcn_s_barrier()
; #define PG8_SCHED __builtin_amdgcn_sched_barrier(0)
; template <class Epi, class Sched, bool ALIGN_EPI = true, bool SP2 = true>
; __device__ __forceinline__ void gemm_phase(PG8_LAS unsigned char* lds, const Gemm g, const Sched& S, const Epi& E) {
;     ...
;             PG8_WAIT_V(8); PG8_WAIT_L(0); PG8_BAR; PG8_MMA(1, 0, At, B0); PG8_MMA(1, 1, At, B1); PG8_BAR; PG8_SCHED;
;             PG8_LDB(B0, 1, 0); PG8_LDB(B1, 1, 1); PG8_SCHED; PG8_LDA(At, 1, 0); PG8_STAGE(PG8_SA(0, 1), a2 + hstepA, voffA);
;             PG8_WAIT_V(8); PG8_WAIT_L(0); PG8_BAR; PG8_MMA(0, 0, At, B0); PG8_MMA(0, 1, At, B1); PG8_BAR; PG8_SCHED;
	s_setprio 1
	s_waitcnt lgkmcnt(0)
	v_mfma_f32_16x16x32_bf16 v[60:63], v[146:149], v[178:181], v[60:63]
	v_mfma_f32_16x16x32_bf16 v[56:59], v[154:157], v[178:181], v[56:59]
	v_mfma_f32_16x16x32_bf16 v[52:55], v[146:149], v[186:189], v[52:55]
	v_mfma_f32_16x16x32_bf16 v[48:51], v[154:157], v[186:189], v[48:51]
	v_mfma_f32_16x16x32_bf16 v[36:39], v[146:149], v[194:197], v[36:39]
	v_mfma_f32_16x16x32_bf16 v[32:35], v[154:157], v[194:197], v[32:35]
	v_mfma_f32_16x16x32_bf16 v[20:23], v[146:149], v[202:205], v[20:23]
	v_mfma_f32_16x16x32_bf16 v[16:19], v[154:157], v[202:205], v[16:19]
	s_setprio 0
	s_setprio 1
	v_mfma_f32_16x16x32_bf16 v[60:63], v[150:153], v[182:185], v[60:63]
	v_mfma_f32_16x16x32_bf16 v[56:59], v[158:161], v[182:185], v[56:59]
	v_mfma_f32_16x16x32_bf16 v[52:55], v[150:153], v[190:193], v[52:55]
	v_mfma_f32_16x16x32_bf16 v[48:51], v[158:161], v[190:193], v[48:51]
	v_mfma_f32_16x16x32_bf16 v[36:39], v[150:153], v[198:201], v[36:39]
	v_mfma_f32_16x16x32_bf16 v[32:35], v[158:161], v[198:201], v[32:35]
	v_mfma_f32_16x16x32_bf16 v[20:23], v[150:153], v[206:209], v[20:23]
	v_mfma_f32_16x16x32_bf16 v[16:19], v[158:161], v[206:209], v[16:19]
	s_setprio 0
	s_setprio 1
	v_mfma_f32_16x16x32_bf16 v[44:47], v[162:165], v[178:181], v[44:47]
	v_mfma_f32_16x16x32_bf16 v[40:43], v[170:173], v[178:181], v[40:43]
	v_mfma_f32_16x16x32_bf16 v[28:31], v[162:165], v[186:189], v[28:31]
	v_mfma_f32_16x16x32_bf16 v[24:27], v[170:173], v[186:189], v[24:27]
	v_mfma_f32_16x16x32_bf16 v[12:15], v[162:165], v[194:197], v[12:15]
	v_mfma_f32_16x16x32_bf16 v[8:11], v[170:173], v[194:197], v[8:11]
	v_mfma_f32_16x16x32_bf16 v[4:7], v[162:165], v[202:205], v[4:7]
	v_mfma_f32_16x16x32_bf16 v[0:3], v[170:173], v[202:205], v[0:3]
	s_setprio 0
	s_setprio 1
	v_mfma_f32_16x16x32_bf16 v[44:47], v[166:169], v[182:185], v[44:47]
	v_mfma_f32_16x16x32_bf16 v[40:43], v[174:177], v[182:185], v[40:43]
	v_mfma_f32_16x16x32_bf16 v[28:31], v[166:169], v[190:193], v[28:31]
	v_mfma_f32_16x16x32_bf16 v[24:27], v[174:177], v[190:193], v[24:27]
	v_mfma_f32_16x16x32_bf16 v[12:15], v[166:169], v[198:201], v[12:15]
	v_mfma_f32_16x16x32_bf16 v[8:11], v[174:177], v[198:201], v[8:11]
	v_mfma_f32_16x16x32_bf16 v[4:7], v[166:169], v[206:209], v[4:7]
	v_mfma_f32_16x16x32_bf16 v[0:3], v[174:177], v[206:209], v[0:3]
	s_setprio 0
	s_barrier
	s_add_i32 s52, 0, 0x18000
	s_add_i32 s53, 0, 0x1c000
	v_add_u32_e32 v158, s52, v141
	v_add_u32_e32 v174, s53, v141
	ds_read_b128 v[146:149], v158
	ds_read_b128 v[150:153], v158 offset:1024
	ds_read_b128 v[154:157], v158 offset:2048
	ds_read_b128 v[158:161], v158 offset:3072
	ds_read_b128 v[162:165], v174
	ds_read_b128 v[166:169], v174 offset:1024
	ds_read_b128 v[170:173], v174 offset:2048
	ds_read_b128 v[174:177], v174 offset:3072
	s_add_u32 s38, s38, 0x40000
	s_addc_u32 s39, s39, 0
	s_mov_b32 m0, s50
	v_lshl_add_u64 v[218:219], s[38:39], 0, v[134:135]
	ds_read_b128 v[178:181], v145 offset:32768
	ds_read_b128 v[182:185], v145 offset:33792
	ds_read_b128 v[186:189], v145 offset:34816
	ds_read_b128 v[190:193], v145 offset:35840
	ds_read_b128 v[194:197], v145 offset:36864
	ds_read_b128 v[198:201], v145 offset:37888
	ds_read_b128 v[202:205], v145 offset:38912
	ds_read_b128 v[206:209], v145 offset:39936
	global_load_lds_dwordx4 v[218:219], off
	v_lshl_add_u64 v[218:219], s[38:39], 0, v[130:131]
	s_mov_b32 m0, s51
	s_nop 0
	global_load_lds_dwordx4 v[218:219], off
	s_waitcnt vmcnt(8)
	s_waitcnt lgkmcnt(0)
	s_barrier
	s_setprio 1
	s_waitcnt lgkmcnt(0)
	v_mfma_f32_16x16x32_bf16 v[124:127], v[146:149], v[178:181], v[124:127]
	v_mfma_f32_16x16x32_bf16 v[120:123], v[154:157], v[178:181], v[120:123]
	v_mfma_f32_16x16x32_bf16 v[116:119], v[146:149], v[186:189], v[116:119]
	v_mfma_f32_16x16x32_bf16 v[112:115], v[154:157], v[186:189], v[112:115]
	v_mfma_f32_16x16x32_bf16 v[100:103], v[146:149], v[194:197], v[100:103]
	v_mfma_f32_16x16x32_bf16 v[96:99], v[154:157], v[194:197], v[96:99]
	v_mfma_f32_16x16x32_bf16 v[84:87], v[146:149], v[202:205], v[84:87]
	v_mfma_f32_16x16x32_bf16 v[80:83], v[154:157], v[202:205], v[80:83]
	s_setprio 0
	s_setprio 1
	v_mfma_f32_16x16x32_bf16 v[124:127], v[150:153], v[182:185], v[124:127]
	v_mfma_f32_16x16x32_bf16 v[120:123], v[158:161], v[182:185], v[120:123]
	v_mfma_f32_16x16x32_bf16 v[116:119], v[150:153], v[190:193], v[116:119]
	v_mfma_f32_16x16x32_bf16 v[112:115], v[158:161], v[190:193], v[112:115]
	v_mfma_f32_16x16x32_bf16 v[100:103], v[150:153], v[198:201], v[100:103]
	v_mfma_f32_16x16x32_bf16 v[96:99], v[158:161], v[198:201], v[96:99]
	v_mfma_f32_16x16x32_bf16 v[84:87], v[150:153], v[206:209], v[84:87]
	v_mfma_f32_16x16x32_bf16 v[80:83], v[158:161], v[206:209], v[80:83]
	s_setprio 0
	s_setprio 1
	v_mfma_f32_16x16x32_bf16 v[108:111], v[162:165], v[178:181], v[108:111]
	v_mfma_f32_16x16x32_bf16 v[104:107], v[170:173], v[178:181], v[104:107]
	v_mfma_f32_16x16x32_bf16 v[92:95], v[162:165], v[186:189], v[92:95]
	v_mfma_f32_16x16x32_bf16 v[88:91], v[170:173], v[186:189], v[88:91]
	v_mfma_f32_16x16x32_bf16 v[76:79], v[162:165], v[194:197], v[76:79]
	v_mfma_f32_16x16x32_bf16 v[72:75], v[170:173], v[194:197], v[72:75]
	v_mfma_f32_16x16x32_bf16 v[68:71], v[162:165], v[202:205], v[68:71]
	v_mfma_f32_16x16x32_bf16 v[64:67], v[170:173], v[202:205], v[64:67]
	s_setprio 0
	s_setprio 1
	v_mfma_f32_16x16x32_bf16 v[108:111], v[166:169], v[182:185], v[108:111]
	v_mfma_f32_16x16x32_bf16 v[104:107], v[174:177], v[182:185], v[104:107]
	v_mfma_f32_16x16x32_bf16 v[92:95], v[166:169], v[190:193], v[92:95]
	v_mfma_f32_16x16x32_bf16 v[88:91], v[174:177], v[190:193], v[88:91]
	v_mfma_f32_16x16x32_bf16 v[76:79], v[166:169], v[198:201], v[76:79]
	v_mfma_f32_16x16x32_bf16 v[72:75], v[174:177], v[198:201], v[72:75]
	v_mfma_f32_16x16x32_bf16 v[68:71], v[166:169], v[206:209], v[68:71]
	v_mfma_f32_16x16x32_bf16 v[64:67], v[174:177], v[206:209], v[64:67]
	s_setprio 0
	s_barrier
; #define PG8_STAGE(bufoff, gbase, voff) do { _Pragma("unroll") for (int _i = 0; _i < 2; ++_i) \
;         __builtin_amdgcn_global_load_lds((const unsigned*)((const char*)(gbase) + (voff)[_i]), (PG8_LAS unsigned*)(lds + (bufoff) + ldsw + _i * 8192), 16, 0, 0); } while (0)
; #define PG8_LDA(dst, b, h) do { _Pragma("unroll") for (int m = 0; m < 4; ++m) _Pragma("unroll") for (int k = 0; k < 2; ++k) dst[m][k] = *(const PG8_LAS bf16x8*)(lds + PG8_SA(b, h) + aoff + m * 2048 + k * 1024); } while (0)
; #define PG8_MMA(ai, bj, At, Bt) do { __builtin_amdgcn_s_setprio(1); _Pragma("unroll") for (int m = 0; m < 4; ++m) _Pragma("unroll") for (int n = 0; n < 2; ++n) _Pragma("unroll") for (int k = 0; k < 2; ++k) \
;         acc[ai][bj][m][n] = __builtin_amdgcn_mfma_f32_16x16x32_bf16(Bt[n][k], At[m][k], acc[ai][bj][m][n], 0, 0, 0); __builtin_amdgcn_s_setprio(0); } while (0)
; #define PG8_WAIT_V(n) asm volatile("s_waitcnt vmcnt(" #n ")" ::: "memory")
; #define PG8_WAIT_L(n) asm volatile("s_waitcnt lgkmcnt(" #n ")" ::: "memory")
; #define PG8_BAR __builtin_amdgcn_s_barrier()
; #define PG8_SCHED __builtin_amdgcn_sched_barrier(0)
; template <class Epi, class Sched, bool ALIGN_EPI = true, bool SP2 = true>
; __device__ __forceinline__ void gemm_phase(PG8_LAS unsigned char* lds, const Gemm g, const Sched& S, const Epi& E) {
;     ...
;             PG8_LDA(At, 1, 1); PG8_STAGE(PG8_SB(1, 0), b3, voffB); PG8_STAGE(PG8_SB(1, 1), b3 + hstepB, voffB); PG8_STAGE(PG8_SA(1, 0), a3, voffA);
;             PG8_WAIT_V(8); PG8_WAIT_L(0); PG8_BAR; PG8_MMA(1, 0, At, B0); PG8_MMA(1, 1, At, B1); PG8_BAR; PG8_SCHED;
;         }
;         if constexpr (ALIGN_EPI) { if (wr == 0) PG8_BAR; }
	s_add_i32 s38, s52, s46
	v_lshl_add_u64 v[210:211], v[210:211], 0, s[8:9]
	s_mov_b32 m0, s38
	ds_read_b128 v[178:181], v145 offset:49152
	ds_read_b128 v[182:185], v145 offset:50176
	ds_read_b128 v[186:189], v145 offset:51200
	ds_read_b128 v[190:193], v145 offset:52224
	ds_read_b128 v[194:197], v145 offset:53248
	ds_read_b128 v[198:201], v145 offset:54272
	ds_read_b128 v[202:205], v145 offset:55296
	ds_read_b128 v[206:209], v145 offset:56320
	global_load_lds_dwordx4 v[210:211], off
	s_add_i32 m0, s38, 0x2000
	s_add_u32 s36, s36, 0x40080
	v_lshl_add_u64 v[210:211], v[212:213], 0, s[8:9]
	s_addc_u32 s37, s37, 0
	s_add_i32 s38, s53, s46
	global_load_lds_dwordx4 v[210:211], off
	v_lshl_add_u64 v[210:211], s[36:37], 0, v[132:133]
	s_mov_b32 m0, s38
	s_nop 0
	global_load_lds_dwordx4 v[210:211], off
	v_lshl_add_u64 v[210:211], s[36:37], 0, v[128:129]
	s_add_i32 m0, s38, 0x2000
	s_nop 0
	global_load_lds_dwordx4 v[210:211], off
	v_lshl_add_u64 v[210:211], v[214:215], 0, s[8:9]
	s_mov_b32 m0, s56
	s_nop 0
	global_load_lds_dwordx4 v[210:211], off
	v_lshl_add_u64 v[210:211], v[216:217], 0, s[8:9]
	s_mov_b32 m0, s57
	s_nop 0
	global_load_lds_dwordx4 v[210:211], off
	s_waitcnt vmcnt(8)
	s_waitcnt lgkmcnt(0)
	s_barrier
	s_setprio 1
	s_waitcnt lgkmcnt(0)
	v_mfma_f32_16x16x32_bf16 v[60:63], v[146:149], v[178:181], v[60:63]
	v_mfma_f32_16x16x32_bf16 v[56:59], v[154:157], v[178:181], v[56:59]
	v_mfma_f32_16x16x32_bf16 v[52:55], v[146:149], v[186:189], v[52:55]
	v_mfma_f32_16x16x32_bf16 v[48:51], v[154:157], v[186:189], v[48:51]
	v_mfma_f32_16x16x32_bf16 v[36:39], v[146:149], v[194:197], v[36:39]
	v_mfma_f32_16x16x32_bf16 v[32:35], v[154:157], v[194:197], v[32:35]
	v_mfma_f32_16x16x32_bf16 v[20:23], v[146:149], v[202:205], v[20:23]
	v_mfma_f32_16x16x32_bf16 v[16:19], v[154:157], v[202:205], v[16:19]
	s_setprio 0
	s_setprio 1
	v_mfma_f32_16x16x32_bf16 v[60:63], v[150:153], v[182:185], v[60:63]
	v_mfma_f32_16x16x32_bf16 v[56:59], v[158:161], v[182:185], v[56:59]
	v_mfma_f32_16x16x32_bf16 v[52:55], v[150:153], v[190:193], v[52:55]
	v_mfma_f32_16x16x32_bf16 v[48:51], v[158:161], v[190:193], v[48:51]
	v_mfma_f32_16x16x32_bf16 v[36:39], v[150:153], v[198:201], v[36:39]
	v_mfma_f32_16x16x32_bf16 v[32:35], v[158:161], v[198:201], v[32:35]
	v_mfma_f32_16x16x32_bf16 v[20:23], v[150:153], v[206:209], v[20:23]
	v_mfma_f32_16x16x32_bf16 v[16:19], v[158:161], v[206:209], v[16:19]
	s_setprio 0
	s_setprio 1
	v_mfma_f32_16x16x32_bf16 v[44:47], v[162:165], v[178:181], v[44:47]
	v_mfma_f32_16x16x32_bf16 v[40:43], v[170:173], v[178:181], v[40:43]
	v_mfma_f32_16x16x32_bf16 v[28:31], v[162:165], v[186:189], v[28:31]
	v_mfma_f32_16x16x32_bf16 v[24:27], v[170:173], v[186:189], v[24:27]
	v_mfma_f32_16x16x32_bf16 v[12:15], v[162:165], v[194:197], v[12:15]
	v_mfma_f32_16x16x32_bf16 v[8:11], v[170:173], v[194:197], v[8:11]
	v_mfma_f32_16x16x32_bf16 v[4:7], v[162:165], v[202:205], v[4:7]
	v_mfma_f32_16x16x32_bf16 v[0:3], v[170:173], v[202:205], v[0:3]
	s_setprio 0
	s_setprio 1
	v_mfma_f32_16x16x32_bf16 v[44:47], v[166:169], v[182:185], v[44:47]
	v_mfma_f32_16x16x32_bf16 v[40:43], v[174:177], v[182:185], v[40:43]
	v_mfma_f32_16x16x32_bf16 v[28:31], v[166:169], v[190:193], v[28:31]
	v_mfma_f32_16x16x32_bf16 v[24:27], v[174:177], v[190:193], v[24:27]
	v_mfma_f32_16x16x32_bf16 v[12:15], v[166:169], v[198:201], v[12:15]
	v_mfma_f32_16x16x32_bf16 v[8:11], v[174:177], v[198:201], v[8:11]
	v_mfma_f32_16x16x32_bf16 v[4:7], v[166:169], v[206:209], v[4:7]
	v_mfma_f32_16x16x32_bf16 v[0:3], v[174:177], v[206:209], v[0:3]
	s_setprio 0
	s_barrier
	s_add_i32 s73, s73, 2
	s_add_u32 s71, s71, 0x100
	s_addc_u32 s72, s72, 0
	s_add_u32 s34, s34, 0x100
	s_addc_u32 s35, s35, 0
	s_cmp_gt_u32 s73, 13
	s_cbranch_scc0 .LBB0_306
	s_and_b64 vcc, exec, s[10:11]
	s_cbranch_vccz .LBB0_309
	s_barrier

; #define PG8_STAGE(bufoff, gbase, voff) do { _Pragma("unroll") for (int _i = 0; _i < 2; ++_i) \
;         __builtin_amdgcn_global_load_lds((const unsigned*)((const char*)(gbase) + (voff)[_i]), (PG8_LAS unsigned*)(lds + (bufoff) + ldsw + _i * 8192), 16, 0, 0); } while (0)
; #define PG8_LDA(dst, b, h) do { _Pragma("unroll") for (int m = 0; m < 4; ++m) _Pragma("unroll") for (int k = 0; k < 2; ++k) dst[m][k] = *(const PG8_LAS bf16x8*)(lds + PG8_SA(b, h) + aoff + m * 2048 + k * 1024); } while (0)
; #define PG8_LDB(dst, b, h) do { _Pragma("unroll") for (int n = 0; n < 2; ++n) _Pragma("unroll") for (int k = 0; k < 2; ++k) dst[n][k] = *(const PG8_LAS bf16x8*)(lds + PG8_SB(b, h) + boff + n * 2048 + k * 1024); } while (0)
; #define PG8_MMA(ai, bj, At, Bt) do { __builtin_amdgcn_s_setprio(1); _Pragma("unroll") for (int m = 0; m < 4; ++m) _Pragma("unroll") for (int n = 0; n < 2; ++n) _Pragma("unroll") for (int k = 0; k < 2; ++k) \
;         acc[ai][bj][m][n] = __builtin_amdgcn_mfma_f32_16x16x32_bf16(Bt[n][k], At[m][k], acc[ai][bj][m][n], 0, 0, 0); __builtin_amdgcn_s_setprio(0); } while (0)
; #define PG8_WAIT_V(n) asm volatile("s_waitcnt vmcnt(" #n ")" ::: "memory")
; #define PG8_BAR __builtin_amdgcn_s_barrier()
; template <class Epi, class Sched, bool ALIGN_EPI = true, bool SP2 = true>
; __device__ __forceinline__ void gemm_phase(PG8_LAS unsigned char* lds, const Gemm g, const Sched& S, const Epi& E) {
;     ...
;         const bool has_next = S.next(ui + 1, nxt);
;         const char* nA = has_next ? (const char*)g.A + (size_t)nxt.pm * tstepA : cA; const char* nB = has_next ? (const char*)g.Bt + (size_t)nxt.pn * tstepB : cB;
;         for (int t = 0; t < nt; t += 2) {
;             const bool last = (t == nt - 2);
;             const char* a1 = cA + (size_t)(t + 1) * kstep;
;             const char* a2 = last ? nA : cA + (size_t)(t + 2) * kstep; const char* b2 = last ? nB : cB + (size_t)(t + 2) * kstep;
;             const char* a3 = a2 + kstep; const char* b3 = b2 + kstep;
;             PG8_LDB(B0, 0, 0); PG8_LDB(B1, 0, 1); PG8_SCHED; PG8_LDA(At, 0, 0); PG8_STAGE(PG8_SA(1, 1), a1 + hstepA, voffA);
;             PG8_WAIT_V(8); PG8_WAIT_L(0); PG8_BAR; PG8_MMA(0, 0, At, B0); PG8_MMA(0, 1, At, B1); PG8_BAR; PG8_SCHED;
;             PG8_LDA(At, 0, 1); PG8_STAGE(PG8_SB(0, 0), b2, voffB); PG8_STAGE(PG8_SB(0, 1), b2 + hstepB, voffB); PG8_STAGE(PG8_SA(0, 0), a2, voffA);
.LBB0_387:
	s_add_u32 s31, s20, s30
	s_addc_u32 s38, s21, 0
	s_add_u32 s36, s31, 0x100
	s_addc_u32 s37, s38, 0
	s_and_b64 s[34:35], s[28:29], exec
	s_cselect_b32 s35, s17, s37
	s_cselect_b32 s34, s63, s36
	s_add_u32 s30, s18, s30
	s_addc_u32 s36, s19, 0
	s_add_u32 s30, s30, 0x100
	s_addc_u32 s36, s36, 0
	s_and_b64 s[28:29], s[28:29], exec
	s_cselect_b32 s37, s15, s36
	s_cselect_b32 s36, s64, s30
	s_add_u32 s40, s31, 0x10080
	ds_read_b128 v[146:149], v143
	ds_read_b128 v[150:153], v143 offset:1024
	ds_read_b128 v[154:157], v143 offset:2048
	ds_read_b128 v[158:161], v143 offset:3072
	ds_read_b128 v[162:165], v144
	ds_read_b128 v[166:169], v144 offset:1024
	ds_read_b128 v[170:173], v144 offset:2048
	ds_read_b128 v[174:177], v144 offset:3072
	s_addc_u32 s41, s38, 0
	s_add_i32 s76, s59, s46
	s_add_i32 m0, s13, 0xc000
	s_add_i32 s52, s13, 0xe000
	s_add_i32 s73, s76, 0x2000
	s_add_u32 s38, s36, 0x10000
	s_addc_u32 s39, s37, 0
	s_add_i32 s75, s60, s46
	s_add_i32 s74, s75, 0x2000
	s_add_i32 s72, 0, 0x18000
	s_add_i32 s71, 0, 0x1c000
	s_add_u32 s30, s34, 0x10000
	s_addc_u32 s31, s35, 0
	s_add_i32 s66, s72, s46
	s_add_i32 s65, s66, 0x2000
	s_add_u32 s28, s36, 0x10080
	s_addc_u32 s29, s37, 0
	s_add_i32 s78, s71, s46
	s_add_i32 s77, s78, 0x2000
	v_lshl_add_u64 v[210:211], s[40:41], 0, v[134:135]
	ds_read_b128 v[178:181], v145
	ds_read_b128 v[182:185], v145 offset:1024
	ds_read_b128 v[186:189], v145 offset:2048
	ds_read_b128 v[190:193], v145 offset:3072
	ds_read_b128 v[194:197], v145 offset:4096
	ds_read_b128 v[198:201], v145 offset:5120
	ds_read_b128 v[202:205], v145 offset:6144
	ds_read_b128 v[206:209], v145 offset:7168
	global_load_lds_dwordx4 v[210:211], off
	v_lshl_add_u64 v[210:211], s[40:41], 0, v[130:131]
	s_mov_b32 m0, s52
	s_nop 0
	global_load_lds_dwordx4 v[210:211], off
	s_waitcnt vmcnt(8)
	s_waitcnt lgkmcnt(0)
	s_barrier
	s_setprio 1
	s_waitcnt lgkmcnt(0)
	v_mfma_f32_16x16x32_bf16 v[124:127], v[146:149], v[178:181], v[124:127]
	v_mfma_f32_16x16x32_bf16 v[120:123], v[154:157], v[178:181], v[120:123]
	v_mfma_f32_16x16x32_bf16 v[116:119], v[146:149], v[186:189], v[116:119]
	v_mfma_f32_16x16x32_bf16 v[112:115], v[154:157], v[186:189], v[112:115]
	v_mfma_f32_16x16x32_bf16 v[100:103], v[146:149], v[194:197], v[100:103]
	v_mfma_f32_16x16x32_bf16 v[96:99], v[154:157], v[194:197], v[96:99]
	v_mfma_f32_16x16x32_bf16 v[84:87], v[146:149], v[202:205], v[84:87]
	v_mfma_f32_16x16x32_bf16 v[80:83], v[154:157], v[202:205], v[80:83]
	s_setprio 0
	s_setprio 1
	v_mfma_f32_16x16x32_bf16 v[124:127], v[150:153], v[182:185], v[124:127]
	v_mfma_f32_16x16x32_bf16 v[120:123], v[158:161], v[182:185], v[120:123]
	v_mfma_f32_16x16x32_bf16 v[116:119], v[150:153], v[190:193], v[116:119]
	v_mfma_f32_16x16x32_bf16 v[112:115], v[158:161], v[190:193], v[112:115]
	v_mfma_f32_16x16x32_bf16 v[100:103], v[150:153], v[198:201], v[100:103]
	v_mfma_f32_16x16x32_bf16 v[96:99], v[158:161], v[198:201], v[96:99]
	v_mfma_f32_16x16x32_bf16 v[84:87], v[150:153], v[206:209], v[84:87]
	v_mfma_f32_16x16x32_bf16 v[80:83], v[158:161], v[206:209], v[80:83]
	s_setprio 0
	s_setprio 1
	v_mfma_f32_16x16x32_bf16 v[108:111], v[162:165], v[178:181], v[108:111]
	v_mfma_f32_16x16x32_bf16 v[104:107], v[170:173], v[178:181], v[104:107]
	v_mfma_f32_16x16x32_bf16 v[92:95], v[162:165], v[186:189], v[92:95]
	v_mfma_f32_16x16x32_bf16 v[88:91], v[170:173], v[186:189], v[88:91]
	v_mfma_f32_16x16x32_bf16 v[76:79], v[162:165], v[194:197], v[76:79]
	v_mfma_f32_16x16x32_bf16 v[72:75], v[170:173], v[194:197], v[72:75]
	v_mfma_f32_16x16x32_bf16 v[68:71], v[162:165], v[202:205], v[68:71]
	v_mfma_f32_16x16x32_bf16 v[64:67], v[170:173], v[202:205], v[64:67]
	s_setprio 0
	s_setprio 1
	v_mfma_f32_16x16x32_bf16 v[108:111], v[166:169], v[182:185], v[108:111]
	v_mfma_f32_16x16x32_bf16 v[104:107], v[174:177], v[182:185], v[104:107]
	v_mfma_f32_16x16x32_bf16 v[92:95], v[166:169], v[190:193], v[92:95]
	v_mfma_f32_16x16x32_bf16 v[88:91], v[174:177], v[190:193], v[88:91]
	v_mfma_f32_16x16x32_bf16 v[76:79], v[166:169], v[198:201], v[76:79]
	v_mfma_f32_16x16x32_bf16 v[72:75], v[174:177], v[198:201], v[72:75]
	v_mfma_f32_16x16x32_bf16 v[68:71], v[166:169], v[206:209], v[68:71]
	v_mfma_f32_16x16x32_bf16 v[64:67], v[174:177], v[206:209], v[64:67]
	s_setprio 0
	s_barrier
	s_mov_b32 m0, s76
	v_lshl_add_u64 v[210:211], s[36:37], 0, v[132:133]
	ds_read_b128 v[178:181], v145 offset:16384
	ds_read_b128 v[182:185], v145 offset:17408
	ds_read_b128 v[186:189], v145 offset:18432
	ds_read_b128 v[190:193], v145 offset:19456
	ds_read_b128 v[194:197], v145 offset:20480
	ds_read_b128 v[198:201], v145 offset:21504
	ds_read_b128 v[202:205], v145 offset:22528
	ds_read_b128 v[206:209], v145 offset:23552
	global_load_lds_dwordx4 v[210:211], off
	v_lshl_add_u64 v[212:213], s[36:37], 0, v[128:129]
	s_mov_b32 m0, s73
	v_lshl_add_u64 v[214:215], s[38:39], 0, v[132:133]
	global_load_lds_dwordx4 v[212:213], off
	s_mov_b32 m0, s75
	v_lshl_add_u64 v[216:217], s[34:35], 0, v[130:131]
	global_load_lds_dwordx4 v[214:215], off
	v_lshl_add_u64 v[214:215], s[38:39], 0, v[128:129]
	s_mov_b32 m0, s74
	s_nop 0
	global_load_lds_dwordx4 v[214:215], off
	v_lshl_add_u64 v[214:215], s[34:35], 0, v[134:135]
	s_mov_b32 m0, s13
	s_nop 0
	global_load_lds_dwordx4 v[214:215], off
	s_mov_b32 m0, s48
	s_nop 0
	global_load_lds_dwordx4 v[216:217], off
	s_waitcnt vmcnt(8)
	s_waitcnt lgkmcnt(0)
	s_barrier
; #define PG8_STAGE(bufoff, gbase, voff) do { _Pragma("unroll") for (int _i = 0; _i < 2; ++_i) \
;         __builtin_amdgcn_global_load_lds((const unsigned*)((const char*)(gbase) + (voff)[_i]), (PG8_LAS unsigned*)(lds + (bufoff) + ldsw + _i * 8192), 16, 0, 0); } while (0)
; #define PG8_LDA(dst, b, h) do { _Pragma("unroll") for (int m = 0; m < 4; ++m) _Pragma("unroll") for (int k = 0; k < 2; ++k) dst[m][k] = *(const PG8_LAS bf16x8*)(lds + PG8_SA(b, h) + aoff + m * 2048 + k * 1024); } while (0)
; #define PG8_LDB(dst, b, h) do { _Pragma("unroll") for (int n = 0; n < 2; ++n) _Pragma("unroll") for (int k = 0; k < 2; ++k) dst[n][k] = *(const PG8_LAS bf16x8*)(lds + PG8_SB(b, h) + boff + n * 2048 + k * 1024); } while (0)
; #define PG8_MMA(ai, bj, At, Bt) do { __builtin_amdgcn_s_setprio(1); _Pragma("unroll") for (int m = 0; m < 4; ++m) _Pragma("unroll") for (int n = 0; n < 2; ++n) _Pragma("unroll") for (int k = 0; k < 2; ++k) \
;         acc[ai][bj][m][n] = __builtin_amdgcn_mfma_f32_16x16x32_bf16(Bt[n][k], At[m][k], acc[ai][bj][m][n], 0, 0, 0); __builtin_amdgcn_s_setprio(0); } while (0)
; #define PG8_WAIT_V(n) asm volatile("s_waitcnt vmcnt(" #n ")" ::: "memory")
; #define PG8_WAIT_L(n) asm volatile("s_waitcnt lgkmcnt(" #n ")" ::: "memory")
; #define PG8_BAR __builtin_amdgcn_s_barrier()
; #define PG8_SCHED __builtin_amdgcn_sched_barrier(0)
; template <class Epi, class Sched, bool ALIGN_EPI = true, bool SP2 = true>
; __device__ __forceinline__ void gemm_phase(PG8_LAS unsigned char* lds, const Gemm g, const Sched& S, const Epi& E) {
;     ...
;             PG8_WAIT_V(8); PG8_WAIT_L(0); PG8_BAR; PG8_MMA(1, 0, At, B0); PG8_MMA(1, 1, At, B1); PG8_BAR; PG8_SCHED;
;             PG8_LDB(B0, 1, 0); PG8_LDB(B1, 1, 1); PG8_SCHED; PG8_LDA(At, 1, 0); PG8_STAGE(PG8_SA(0, 1), a2 + hstepA, voffA);
;             PG8_WAIT_V(8); PG8_WAIT_L(0); PG8_BAR; PG8_MMA(0, 0, At, B0); PG8_MMA(0, 1, At, B1); PG8_BAR; PG8_SCHED;
	s_setprio 1
	s_waitcnt lgkmcnt(0)
	v_mfma_f32_16x16x32_bf16 v[60:63], v[146:149], v[178:181], v[60:63]
	v_mfma_f32_16x16x32_bf16 v[56:59], v[154:157], v[178:181], v[56:59]
	v_mfma_f32_16x16x32_bf16 v[52:55], v[146:149], v[186:189], v[52:55]
	v_mfma_f32_16x16x32_bf16 v[48:51], v[154:157], v[186:189], v[48:51]
	v_mfma_f32_16x16x32_bf16 v[36:39], v[146:149], v[194:197], v[36:39]
	v_mfma_f32_16x16x32_bf16 v[32:35], v[154:157], v[194:197], v[32:35]
	v_mfma_f32_16x16x32_bf16 v[20:23], v[146:149], v[202:205], v[20:23]
	v_mfma_f32_16x16x32_bf16 v[16:19], v[154:157], v[202:205], v[16:19]
	s_setprio 0
	s_setprio 1
	v_mfma_f32_16x16x32_bf16 v[60:63], v[150:153], v[182:185], v[60:63]
	v_mfma_f32_16x16x32_bf16 v[56:59], v[158:161], v[182:185], v[56:59]
	v_mfma_f32_16x16x32_bf16 v[52:55], v[150:153], v[190:193], v[52:55]
	v_mfma_f32_16x16x32_bf16 v[48:51], v[158:161], v[190:193], v[48:51]
	v_mfma_f32_16x16x32_bf16 v[36:39], v[150:153], v[198:201], v[36:39]
	v_mfma_f32_16x16x32_bf16 v[32:35], v[158:161], v[198:201], v[32:35]
	v_mfma_f32_16x16x32_bf16 v[20:23], v[150:153], v[206:209], v[20:23]
	v_mfma_f32_16x16x32_bf16 v[16:19], v[158:161], v[206:209], v[16:19]
	s_setprio 0
	s_setprio 1
	v_mfma_f32_16x16x32_bf16 v[44:47], v[162:165], v[178:181], v[44:47]
	v_mfma_f32_16x16x32_bf16 v[40:43], v[170:173], v[178:181], v[40:43]
	v_mfma_f32_16x16x32_bf16 v[28:31], v[162:165], v[186:189], v[28:31]
	v_mfma_f32_16x16x32_bf16 v[24:27], v[170:173], v[186:189], v[24:27]
	v_mfma_f32_16x16x32_bf16 v[12:15], v[162:165], v[194:197], v[12:15]
	v_mfma_f32_16x16x32_bf16 v[8:11], v[170:173], v[194:197], v[8:11]
	v_mfma_f32_16x16x32_bf16 v[4:7], v[162:165], v[202:205], v[4:7]
	v_mfma_f32_16x16x32_bf16 v[0:3], v[170:173], v[202:205], v[0:3]
	s_setprio 0
	s_setprio 1
	v_mfma_f32_16x16x32_bf16 v[44:47], v[166:169], v[182:185], v[44:47]
	v_mfma_f32_16x16x32_bf16 v[40:43], v[174:177], v[182:185], v[40:43]
	v_mfma_f32_16x16x32_bf16 v[28:31], v[166:169], v[190:193], v[28:31]
	v_mfma_f32_16x16x32_bf16 v[24:27], v[174:177], v[190:193], v[24:27]
	v_mfma_f32_16x16x32_bf16 v[12:15], v[166:169], v[198:201], v[12:15]
	v_mfma_f32_16x16x32_bf16 v[8:11], v[174:177], v[198:201], v[8:11]
	v_mfma_f32_16x16x32_bf16 v[4:7], v[166:169], v[206:209], v[4:7]
	v_mfma_f32_16x16x32_bf16 v[0:3], v[174:177], v[206:209], v[0:3]
	s_setprio 0
	s_barrier
	v_add_u32_e32 v158, s72, v141
	v_add_u32_e32 v174, s71, v141
	ds_read_b128 v[146:149], v158
	ds_read_b128 v[150:153], v158 offset:1024
	ds_read_b128 v[154:157], v158 offset:2048
	ds_read_b128 v[158:161], v158 offset:3072
	ds_read_b128 v[162:165], v174
	ds_read_b128 v[166:169], v174 offset:1024
	ds_read_b128 v[170:173], v174 offset:2048
	ds_read_b128 v[174:177], v174 offset:3072
	s_mov_b32 m0, s49
	v_lshl_add_u64 v[218:219], s[30:31], 0, v[134:135]
	ds_read_b128 v[178:181], v145 offset:32768
	ds_read_b128 v[182:185], v145 offset:33792
	ds_read_b128 v[186:189], v145 offset:34816
	ds_read_b128 v[190:193], v145 offset:35840
	ds_read_b128 v[194:197], v145 offset:36864
	ds_read_b128 v[198:201], v145 offset:37888
	ds_read_b128 v[202:205], v145 offset:38912
	ds_read_b128 v[206:209], v145 offset:39936
	global_load_lds_dwordx4 v[218:219], off
	v_lshl_add_u64 v[218:219], s[30:31], 0, v[130:131]
	s_mov_b32 m0, s50
	s_nop 0
	global_load_lds_dwordx4 v[218:219], off
	s_waitcnt vmcnt(8)
	s_waitcnt lgkmcnt(0)
	s_barrier
	s_setprio 1
	s_waitcnt lgkmcnt(0)
	v_mfma_f32_16x16x32_bf16 v[124:127], v[146:149], v[178:181], v[124:127]
	v_mfma_f32_16x16x32_bf16 v[120:123], v[154:157], v[178:181], v[120:123]
	v_mfma_f32_16x16x32_bf16 v[116:119], v[146:149], v[186:189], v[116:119]
	v_mfma_f32_16x16x32_bf16 v[112:115], v[154:157], v[186:189], v[112:115]
	v_mfma_f32_16x16x32_bf16 v[100:103], v[146:149], v[194:197], v[100:103]
	v_mfma_f32_16x16x32_bf16 v[96:99], v[154:157], v[194:197], v[96:99]
	v_mfma_f32_16x16x32_bf16 v[84:87], v[146:149], v[202:205], v[84:87]
	v_mfma_f32_16x16x32_bf16 v[80:83], v[154:157], v[202:205], v[80:83]
	s_setprio 0
	s_setprio 1
	v_mfma_f32_16x16x32_bf16 v[124:127], v[150:153], v[182:185], v[124:127]
	v_mfma_f32_16x16x32_bf16 v[120:123], v[158:161], v[182:185], v[120:123]
	v_mfma_f32_16x16x32_bf16 v[116:119], v[150:153], v[190:193], v[116:119]
	v_mfma_f32_16x16x32_bf16 v[112:115], v[158:161], v[190:193], v[112:115]
	v_mfma_f32_16x16x32_bf16 v[100:103], v[150:153], v[198:201], v[100:103]
	v_mfma_f32_16x16x32_bf16 v[96:99], v[158:161], v[198:201], v[96:99]
	v_mfma_f32_16x16x32_bf16 v[84:87], v[150:153], v[206:209], v[84:87]
	v_mfma_f32_16x16x32_bf16 v[80:83], v[158:161], v[206:209], v[80:83]
	s_setprio 0
	s_setprio 1
	v_mfma_f32_16x16x32_bf16 v[108:111], v[162:165], v[178:181], v[108:111]
	v_mfma_f32_16x16x32_bf16 v[104:107], v[170:173], v[178:181], v[104:107]
	v_mfma_f32_16x16x32_bf16 v[92:95], v[162:165], v[186:189], v[92:95]
	v_mfma_f32_16x16x32_bf16 v[88:91], v[170:173], v[186:189], v[88:91]
	v_mfma_f32_16x16x32_bf16 v[76:79], v[162:165], v[194:197], v[76:79]
	v_mfma_f32_16x16x32_bf16 v[72:75], v[170:173], v[194:197], v[72:75]
	v_mfma_f32_16x16x32_bf16 v[68:71], v[162:165], v[202:205], v[68:71]
	v_mfma_f32_16x16x32_bf16 v[64:67], v[170:173], v[202:205], v[64:67]
	s_setprio 0
	s_setprio 1
	v_mfma_f32_16x16x32_bf16 v[108:111], v[166:169], v[182:185], v[108:111]
	v_mfma_f32_16x16x32_bf16 v[104:107], v[174:177], v[182:185], v[104:107]
	v_mfma_f32_16x16x32_bf16 v[92:95], v[166:169], v[190:193], v[92:95]
	v_mfma_f32_16x16x32_bf16 v[88:91], v[174:177], v[190:193], v[88:91]
	v_mfma_f32_16x16x32_bf16 v[76:79], v[166:169], v[198:201], v[76:79]
	v_mfma_f32_16x16x32_bf16 v[72:75], v[174:177], v[198:201], v[72:75]
	v_mfma_f32_16x16x32_bf16 v[68:71], v[166:169], v[206:209], v[68:71]
	v_mfma_f32_16x16x32_bf16 v[64:67], v[174:177], v[206:209], v[64:67]
	s_setprio 0
	s_barrier
; #define PG8_STAGE(bufoff, gbase, voff) do { _Pragma("unroll") for (int _i = 0; _i < 2; ++_i) \
;         __builtin_amdgcn_global_load_lds((const unsigned*)((const char*)(gbase) + (voff)[_i]), (PG8_LAS unsigned*)(lds + (bufoff) + ldsw + _i * 8192), 16, 0, 0); } while (0)
; #define PG8_LDA(dst, b, h) do { _Pragma("unroll") for (int m = 0; m < 4; ++m) _Pragma("unroll") for (int k = 0; k < 2; ++k) dst[m][k] = *(const PG8_LAS bf16x8*)(lds + PG8_SA(b, h) + aoff + m * 2048 + k * 1024); } while (0)
; #define PG8_MMA(ai, bj, At, Bt) do { __builtin_amdgcn_s_setprio(1); _Pragma("unroll") for (int m = 0; m < 4; ++m) _Pragma("unroll") for (int n = 0; n < 2; ++n) _Pragma("unroll") for (int k = 0; k < 2; ++k) \
;         acc[ai][bj][m][n] = __builtin_amdgcn_mfma_f32_16x16x32_bf16(Bt[n][k], At[m][k], acc[ai][bj][m][n], 0, 0, 0); __builtin_amdgcn_s_setprio(0); } while (0)
; #define PG8_WAIT_V(n) asm volatile("s_waitcnt vmcnt(" #n ")" ::: "memory")
; #define PG8_WAIT_L(n) asm volatile("s_waitcnt lgkmcnt(" #n ")" ::: "memory")
; #define PG8_BAR __builtin_amdgcn_s_barrier()
; #define PG8_SCHED __builtin_amdgcn_sched_barrier(0)
; template <class Epi, class Sched, bool ALIGN_EPI = true, bool SP2 = true>
; __device__ __forceinline__ void gemm_phase(PG8_LAS unsigned char* lds, const Gemm g, const Sched& S, const Epi& E) {
;     ...
;             PG8_LDA(At, 1, 1); PG8_STAGE(PG8_SB(1, 0), b3, voffB); PG8_STAGE(PG8_SB(1, 1), b3 + hstepB, voffB); PG8_STAGE(PG8_SA(1, 0), a3, voffA);
;             PG8_WAIT_V(8); PG8_WAIT_L(0); PG8_BAR; PG8_MMA(1, 0, At, B0); PG8_MMA(1, 1, At, B1); PG8_BAR; PG8_SCHED;
;         }
;         if constexpr (ALIGN_EPI) { if (wr == 0) PG8_BAR; }
	s_mov_b32 m0, s66
	v_lshl_add_u64 v[210:211], v[210:211], 0, s[8:9]
	ds_read_b128 v[178:181], v145 offset:49152
	ds_read_b128 v[182:185], v145 offset:50176
	ds_read_b128 v[186:189], v145 offset:51200
	ds_read_b128 v[190:193], v145 offset:52224
	ds_read_b128 v[194:197], v145 offset:53248
	ds_read_b128 v[198:201], v145 offset:54272
	ds_read_b128 v[202:205], v145 offset:55296
	ds_read_b128 v[206:209], v145 offset:56320
	global_load_lds_dwordx4 v[210:211], off
	v_lshl_add_u64 v[210:211], v[212:213], 0, s[8:9]
	s_mov_b32 m0, s65
	s_nop 0
	global_load_lds_dwordx4 v[210:211], off
	v_lshl_add_u64 v[210:211], s[28:29], 0, v[132:133]
	s_mov_b32 m0, s78
	s_nop 0
	global_load_lds_dwordx4 v[210:211], off
	v_lshl_add_u64 v[210:211], s[28:29], 0, v[128:129]
	s_mov_b32 m0, s77
	s_nop 0
	global_load_lds_dwordx4 v[210:211], off
	v_lshl_add_u64 v[210:211], v[214:215], 0, s[8:9]
	s_mov_b32 m0, s55
	s_nop 0
	global_load_lds_dwordx4 v[210:211], off
	v_lshl_add_u64 v[210:211], v[216:217], 0, s[8:9]
	s_mov_b32 m0, s56
	s_nop 0
	global_load_lds_dwordx4 v[210:211], off
	s_waitcnt vmcnt(8)
	s_waitcnt lgkmcnt(0)
	s_barrier
	s_setprio 1
	s_waitcnt lgkmcnt(0)
	v_mfma_f32_16x16x32_bf16 v[60:63], v[146:149], v[178:181], v[60:63]
	v_mfma_f32_16x16x32_bf16 v[56:59], v[154:157], v[178:181], v[56:59]
	v_mfma_f32_16x16x32_bf16 v[52:55], v[146:149], v[186:189], v[52:55]
	v_mfma_f32_16x16x32_bf16 v[48:51], v[154:157], v[186:189], v[48:51]
	v_mfma_f32_16x16x32_bf16 v[36:39], v[146:149], v[194:197], v[36:39]
	v_mfma_f32_16x16x32_bf16 v[32:35], v[154:157], v[194:197], v[32:35]
	v_mfma_f32_16x16x32_bf16 v[20:23], v[146:149], v[202:205], v[20:23]
	v_mfma_f32_16x16x32_bf16 v[16:19], v[154:157], v[202:205], v[16:19]
	s_setprio 0
	s_setprio 1
	v_mfma_f32_16x16x32_bf16 v[60:63], v[150:153], v[182:185], v[60:63]
	v_mfma_f32_16x16x32_bf16 v[56:59], v[158:161], v[182:185], v[56:59]
	v_mfma_f32_16x16x32_bf16 v[52:55], v[150:153], v[190:193], v[52:55]
	v_mfma_f32_16x16x32_bf16 v[48:51], v[158:161], v[190:193], v[48:51]
	v_mfma_f32_16x16x32_bf16 v[36:39], v[150:153], v[198:201], v[36:39]
	v_mfma_f32_16x16x32_bf16 v[32:35], v[158:161], v[198:201], v[32:35]
	v_mfma_f32_16x16x32_bf16 v[20:23], v[150:153], v[206:209], v[20:23]
	v_mfma_f32_16x16x32_bf16 v[16:19], v[158:161], v[206:209], v[16:19]
	s_setprio 0
	s_setprio 1
	v_mfma_f32_16x16x32_bf16 v[44:47], v[162:165], v[178:181], v[44:47]
	v_mfma_f32_16x16x32_bf16 v[40:43], v[170:173], v[178:181], v[40:43]
	v_mfma_f32_16x16x32_bf16 v[28:31], v[162:165], v[186:189], v[28:31]
	v_mfma_f32_16x16x32_bf16 v[24:27], v[170:173], v[186:189], v[24:27]
	v_mfma_f32_16x16x32_bf16 v[12:15], v[162:165], v[194:197], v[12:15]
	v_mfma_f32_16x16x32_bf16 v[8:11], v[170:173], v[194:197], v[8:11]
	v_mfma_f32_16x16x32_bf16 v[4:7], v[162:165], v[202:205], v[4:7]
	v_mfma_f32_16x16x32_bf16 v[0:3], v[170:173], v[202:205], v[0:3]
	s_setprio 0
	s_setprio 1
	v_mfma_f32_16x16x32_bf16 v[44:47], v[166:169], v[182:185], v[44:47]
	v_mfma_f32_16x16x32_bf16 v[40:43], v[174:177], v[182:185], v[40:43]
	v_mfma_f32_16x16x32_bf16 v[28:31], v[166:169], v[190:193], v[28:31]
	v_mfma_f32_16x16x32_bf16 v[24:27], v[174:177], v[190:193], v[24:27]
	v_mfma_f32_16x16x32_bf16 v[12:15], v[166:169], v[198:201], v[12:15]
	v_mfma_f32_16x16x32_bf16 v[8:11], v[174:177], v[198:201], v[8:11]
	v_mfma_f32_16x16x32_bf16 v[4:7], v[166:169], v[206:209], v[4:7]
	v_mfma_f32_16x16x32_bf16 v[0:3], v[174:177], v[206:209], v[0:3]
	s_setprio 0
	s_barrier
	s_movk_i32 s30, 0x100
	s_andn2_b64 vcc, exec, s[26:27]
	s_mov_b64 s[28:29], -1
	s_mov_b64 s[26:27], 0
	s_cbranch_vccz .LBB0_387
	s_and_b64 vcc, exec, s[10:11]
	s_cbranch_vccz .LBB0_390
	s_barrier

; #define PG8_STAGE(bufoff, gbase, voff) do { _Pragma("unroll") for (int _i = 0; _i < 2; ++_i) \
;         __builtin_amdgcn_global_load_lds((const unsigned*)((const char*)(gbase) + (voff)[_i]), (PG8_LAS unsigned*)(lds + (bufoff) + ldsw + _i * 8192), 16, 0, 0); } while (0)
; #define PG8_LDA(dst, b, h) do { _Pragma("unroll") for (int m = 0; m < 4; ++m) _Pragma("unroll") for (int k = 0; k < 2; ++k) dst[m][k] = *(const PG8_LAS bf16x8*)(lds + PG8_SA(b, h) + aoff + m * 2048 + k * 1024); } while (0)
; #define PG8_LDB(dst, b, h) do { _Pragma("unroll") for (int n = 0; n < 2; ++n) _Pragma("unroll") for (int k = 0; k < 2; ++k) dst[n][k] = *(const PG8_LAS bf16x8*)(lds + PG8_SB(b, h) + boff + n * 2048 + k * 1024); } while (0)
; #define PG8_MMA(ai, bj, At, Bt) do { __builtin_amdgcn_s_setprio(1); _Pragma("unroll") for (int m = 0; m < 4; ++m) _Pragma("unroll") for (int n = 0; n < 2; ++n) _Pragma("unroll") for (int k = 0; k < 2; ++k) \
;         acc[ai][bj][m][n] = __builtin_amdgcn_mfma_f32_16x16x32_bf16(Bt[n][k], At[m][k], acc[ai][bj][m][n], 0, 0, 0); __builtin_amdgcn_s_setprio(0); } while (0)
; #define PG8_WAIT_V(n) asm volatile("s_waitcnt vmcnt(" #n ")" ::: "memory")
; #define PG8_BAR __builtin_amdgcn_s_barrier()
; template <class Epi, class Sched, bool ALIGN_EPI = true, bool SP2 = true>
; __device__ __forceinline__ void gemm_phase(PG8_LAS unsigned char* lds, const Gemm g, const Sched& S, const Epi& E) {
;     ...
;         const bool has_next = S.next(ui + 1, nxt);
;         const char* nA = has_next ? (const char*)g.A + (size_t)nxt.pm * tstepA : cA; const char* nB = has_next ? (const char*)g.Bt + (size_t)nxt.pn * tstepB : cB;
;         for (int t = 0; t < nt; t += 2) {
;             const bool last = (t == nt - 2);
;             const char* a1 = cA + (size_t)(t + 1) * kstep;
;             const char* a2 = last ? nA : cA + (size_t)(t + 2) * kstep; const char* b2 = last ? nB : cB + (size_t)(t + 2) * kstep;
;             const char* a3 = a2 + kstep; const char* b3 = b2 + kstep;
;             PG8_LDB(B0, 0, 0); PG8_LDB(B1, 0, 1); PG8_SCHED; PG8_LDA(At, 0, 0); PG8_STAGE(PG8_SA(1, 1), a1 + hstepA, voffA);
;             PG8_WAIT_V(8); PG8_WAIT_L(0); PG8_BAR; PG8_MMA(0, 0, At, B0); PG8_MMA(0, 1, At, B1); PG8_BAR; PG8_SCHED;
;             PG8_LDA(At, 0, 1); PG8_STAGE(PG8_SB(0, 0), b2, voffB); PG8_STAGE(PG8_SB(0, 1), b2 + hstepB, voffB); PG8_STAGE(PG8_SA(0, 0), a2, voffA);
.LBB0_410:
	ds_read_b128 v[0:3], v143
	ds_read_b128 v[4:7], v143 offset:1024
	ds_read_b128 v[8:11], v143 offset:2048
	ds_read_b128 v[12:15], v143 offset:3072
	ds_read_b128 v[16:19], v144
	ds_read_b128 v[20:23], v144 offset:1024
	ds_read_b128 v[24:27], v144 offset:2048
	ds_read_b128 v[28:31], v144 offset:3072
	s_ashr_i32 s29, s28, 31
	s_lshl_b64 s[30:31], s[28:29], 16
	s_add_u32 s30, s43, s30
	s_addc_u32 s31, s45, s31
	s_and_b64 s[34:35], s[2:3], exec
	s_cselect_b32 s41, s31, s39
	s_cselect_b32 s40, s30, s38
	s_ashr_i32 s27, s26, 31
	s_lshl_b64 s[34:35], s[26:27], 16
	s_add_u32 s34, s46, s34
	s_addc_u32 s35, s47, s35
	s_and_b64 s[72:73], s[2:3], exec
	s_cselect_b32 s37, s35, s37
	s_cselect_b32 s36, s34, s36
	s_add_u32 s38, s38, 0x8080
	s_addc_u32 s39, s39, 0
	v_lshl_add_u64 v[64:65], s[38:39], 0, v[128:129]
	s_add_i32 m0, s25, 0xc000
	ds_read_b128 v[32:35], v145
	ds_read_b128 v[36:39], v145 offset:1024
	ds_read_b128 v[40:43], v145 offset:2048
	ds_read_b128 v[44:47], v145 offset:3072
	ds_read_b128 v[48:51], v145 offset:4096
	ds_read_b128 v[52:55], v145 offset:5120
	ds_read_b128 v[56:59], v145 offset:6144
	ds_read_b128 v[60:63], v145 offset:7168
	global_load_lds_dwordx4 v[64:65], off
	v_lshl_add_u64 v[64:65], s[38:39], 0, v[132:133]
	s_add_i32 m0, s25, 0xe000
	s_nop 0
	global_load_lds_dwordx4 v[64:65], off
	s_waitcnt vmcnt(8)
	s_waitcnt lgkmcnt(0)
	s_barrier
	s_setprio 1
	s_waitcnt lgkmcnt(0)
	v_mfma_f32_16x16x32_bf16 v[80:83], v[0:3], v[48:51], 0
	v_mfma_f32_16x16x32_bf16 v[88:91], v[4:7], v[52:55], v[80:83]
	v_mfma_f32_16x16x32_bf16 v[80:83], v[8:11], v[48:51], 0
	v_mfma_f32_16x16x32_bf16 v[92:95], v[12:15], v[52:55], v[80:83]
	v_mfma_f32_16x16x32_bf16 v[80:83], v[0:3], v[56:59], 0
	v_mfma_f32_16x16x32_bf16 v[64:67], v[0:3], v[32:35], 0
	v_mfma_f32_16x16x32_bf16 v[68:71], v[8:11], v[32:35], 0
	v_mfma_f32_16x16x32_bf16 v[72:75], v[0:3], v[40:43], 0
	s_setprio 0
	s_setprio 1
	v_mfma_f32_16x16x32_bf16 v[76:79], v[8:11], v[40:43], 0
	v_mfma_f32_16x16x32_bf16 v[96:99], v[4:7], v[60:63], v[80:83]
	v_mfma_f32_16x16x32_bf16 v[80:83], v[8:11], v[56:59], 0
	v_mfma_f32_16x16x32_bf16 v[64:67], v[4:7], v[36:39], v[64:67]
	v_mfma_f32_16x16x32_bf16 v[68:71], v[12:15], v[36:39], v[68:71]
	v_mfma_f32_16x16x32_bf16 v[72:75], v[4:7], v[44:47], v[72:75]
	v_mfma_f32_16x16x32_bf16 v[76:79], v[12:15], v[44:47], v[76:79]
	v_mfma_f32_16x16x32_bf16 v[100:103], v[12:15], v[60:63], v[80:83]
	s_setprio 0
	s_setprio 1
	v_mfma_f32_16x16x32_bf16 v[80:83], v[16:19], v[32:35], 0
	v_mfma_f32_16x16x32_bf16 v[32:35], v[24:27], v[32:35], 0
	v_mfma_f32_16x16x32_bf16 v[104:107], v[20:23], v[36:39], v[80:83]
	v_mfma_f32_16x16x32_bf16 v[32:35], v[28:31], v[36:39], v[32:35]
	v_mfma_f32_16x16x32_bf16 v[36:39], v[16:19], v[40:43], 0
	v_mfma_f32_16x16x32_bf16 v[40:43], v[24:27], v[40:43], 0
	v_mfma_f32_16x16x32_bf16 v[36:39], v[20:23], v[44:47], v[36:39]
	v_mfma_f32_16x16x32_bf16 v[40:43], v[28:31], v[44:47], v[40:43]
	s_setprio 0
	s_setprio 1
	v_mfma_f32_16x16x32_bf16 v[44:47], v[16:19], v[48:51], 0
	v_mfma_f32_16x16x32_bf16 v[48:51], v[24:27], v[48:51], 0
	v_mfma_f32_16x16x32_bf16 v[146:149], v[28:31], v[52:55], v[48:51]
	v_mfma_f32_16x16x32_bf16 v[48:51], v[16:19], v[56:59], 0
	v_mfma_f32_16x16x32_bf16 v[150:153], v[20:23], v[60:63], v[48:51]
	v_mfma_f32_16x16x32_bf16 v[48:51], v[24:27], v[56:59], 0
	v_mfma_f32_16x16x32_bf16 v[44:47], v[20:23], v[52:55], v[44:47]
	v_mfma_f32_16x16x32_bf16 v[56:59], v[28:31], v[60:63], v[48:51]
	s_setprio 0
	s_barrier
	s_add_i32 s27, s59, s48
	v_lshl_add_u64 v[250:251], s[36:37], 0, v[130:131]
	s_mov_b32 m0, s27
	s_nop 0
	ds_read_b128 v[48:51], v145 offset:16384
	ds_read_b128 v[52:55], v145 offset:17408
	ds_read_b128 v[60:63], v145 offset:18432
	ds_read_b128 v[80:83], v145 offset:19456
	ds_read_b128 v[84:87], v145 offset:20480
	ds_read_b128 v[108:111], v145 offset:21504
	ds_read_b128 v[112:115], v145 offset:22528
	ds_read_b128 v[116:119], v145 offset:23552
	global_load_lds_dwordx4 v[250:251], off
	s_add_i32 m0, s27, 0x2000
	s_add_u32 s38, s36, 0x8000
	v_lshl_add_u64 v[252:253], s[36:37], 0, v[134:135]
	s_addc_u32 s39, s37, 0
	s_add_i32 s27, s60, s48
	global_load_lds_dwordx4 v[252:253], off
	v_lshl_add_u64 v[120:121], s[38:39], 0, v[130:131]
	s_mov_b32 m0, s27
	v_lshl_add_u64 v[136:137], s[40:41], 0, v[128:129]
	global_load_lds_dwordx4 v[120:121], off
	v_lshl_add_u64 v[120:121], s[38:39], 0, v[134:135]
	s_add_i32 m0, s27, 0x2000
	v_lshl_add_u64 v[138:139], s[40:41], 0, v[132:133]
	global_load_lds_dwordx4 v[120:121], off
	s_mov_b32 m0, s25
	s_nop 0
	global_load_lds_dwordx4 v[136:137], off
	s_mov_b32 m0, s49
	s_nop 0
	global_load_lds_dwordx4 v[138:139], off
	s_waitcnt vmcnt(8)
	s_waitcnt lgkmcnt(0)
	s_barrier
; #define PG8_STAGE(bufoff, gbase, voff) do { _Pragma("unroll") for (int _i = 0; _i < 2; ++_i) \
;         __builtin_amdgcn_global_load_lds((const unsigned*)((const char*)(gbase) + (voff)[_i]), (PG8_LAS unsigned*)(lds + (bufoff) + ldsw + _i * 8192), 16, 0, 0); } while (0)
; #define PG8_LDA(dst, b, h) do { _Pragma("unroll") for (int m = 0; m < 4; ++m) _Pragma("unroll") for (int k = 0; k < 2; ++k) dst[m][k] = *(const PG8_LAS bf16x8*)(lds + PG8_SA(b, h) + aoff + m * 2048 + k * 1024); } while (0)
; #define PG8_LDB(dst, b, h) do { _Pragma("unroll") for (int n = 0; n < 2; ++n) _Pragma("unroll") for (int k = 0; k < 2; ++k) dst[n][k] = *(const PG8_LAS bf16x8*)(lds + PG8_SB(b, h) + boff + n * 2048 + k * 1024); } while (0)
; #define PG8_MMA(ai, bj, At, Bt) do { __builtin_amdgcn_s_setprio(1); _Pragma("unroll") for (int m = 0; m < 4; ++m) _Pragma("unroll") for (int n = 0; n < 2; ++n) _Pragma("unroll") for (int k = 0; k < 2; ++k) \
;         acc[ai][bj][m][n] = __builtin_amdgcn_mfma_f32_16x16x32_bf16(Bt[n][k], At[m][k], acc[ai][bj][m][n], 0, 0, 0); __builtin_amdgcn_s_setprio(0); } while (0)
; #define PG8_WAIT_V(n) asm volatile("s_waitcnt vmcnt(" #n ")" ::: "memory")
; #define PG8_WAIT_L(n) asm volatile("s_waitcnt lgkmcnt(" #n ")" ::: "memory")
; #define PG8_BAR __builtin_amdgcn_s_barrier()
; #define PG8_SCHED __builtin_amdgcn_sched_barrier(0)
; template <class Epi, class Sched, bool ALIGN_EPI = true, bool SP2 = true>
; __device__ __forceinline__ void gemm_phase(PG8_LAS unsigned char* lds, const Gemm g, const Sched& S, const Epi& E) {
;     ...
;             PG8_WAIT_V(8); PG8_WAIT_L(0); PG8_BAR; PG8_MMA(1, 0, At, B0); PG8_MMA(1, 1, At, B1); PG8_BAR; PG8_SCHED;
;             PG8_LDB(B0, 1, 0); PG8_LDB(B1, 1, 1); PG8_SCHED; PG8_LDA(At, 1, 0); PG8_STAGE(PG8_SA(0, 1), a2 + hstepA, voffA);
;             PG8_WAIT_V(8); PG8_WAIT_L(0); PG8_BAR; PG8_MMA(0, 0, At, B0); PG8_MMA(0, 1, At, B1); PG8_BAR; PG8_SCHED;
	s_setprio 1
	s_waitcnt lgkmcnt(0)
	v_mfma_f32_16x16x32_bf16 v[120:123], v[0:3], v[48:51], 0
	v_mfma_f32_16x16x32_bf16 v[154:157], v[4:7], v[52:55], v[120:123]
	v_mfma_f32_16x16x32_bf16 v[120:123], v[8:11], v[48:51], 0
	v_mfma_f32_16x16x32_bf16 v[158:161], v[12:15], v[52:55], v[120:123]
	v_mfma_f32_16x16x32_bf16 v[120:123], v[0:3], v[60:63], 0
	v_mfma_f32_16x16x32_bf16 v[162:165], v[4:7], v[80:83], v[120:123]
	v_mfma_f32_16x16x32_bf16 v[120:123], v[8:11], v[60:63], 0
	v_mfma_f32_16x16x32_bf16 v[166:169], v[12:15], v[80:83], v[120:123]
	s_setprio 0
	s_setprio 1
	v_mfma_f32_16x16x32_bf16 v[120:123], v[0:3], v[84:87], 0
	v_mfma_f32_16x16x32_bf16 v[0:3], v[0:3], v[112:115], 0
	v_mfma_f32_16x16x32_bf16 v[170:173], v[4:7], v[108:111], v[120:123]
	v_mfma_f32_16x16x32_bf16 v[0:3], v[4:7], v[116:119], v[0:3]
	v_mfma_f32_16x16x32_bf16 v[4:7], v[8:11], v[112:115], 0
	v_mfma_f32_16x16x32_bf16 v[120:123], v[8:11], v[84:87], 0
	v_mfma_f32_16x16x32_bf16 v[4:7], v[12:15], v[116:119], v[4:7]
	v_mfma_f32_16x16x32_bf16 v[174:177], v[12:15], v[108:111], v[120:123]
	s_setprio 0
	s_setprio 1
	v_mfma_f32_16x16x32_bf16 v[8:11], v[16:19], v[48:51], 0
	v_mfma_f32_16x16x32_bf16 v[12:15], v[24:27], v[48:51], 0
	v_mfma_f32_16x16x32_bf16 v[48:51], v[16:19], v[60:63], 0
	v_mfma_f32_16x16x32_bf16 v[178:181], v[20:23], v[80:83], v[48:51]
	v_mfma_f32_16x16x32_bf16 v[48:51], v[24:27], v[60:63], 0
	v_mfma_f32_16x16x32_bf16 v[182:185], v[28:31], v[80:83], v[48:51]
	v_mfma_f32_16x16x32_bf16 v[48:51], v[16:19], v[84:87], 0
	v_mfma_f32_16x16x32_bf16 v[16:19], v[16:19], v[112:115], 0
	s_setprio 0
	s_setprio 1
	v_mfma_f32_16x16x32_bf16 v[8:11], v[20:23], v[52:55], v[8:11]
	v_mfma_f32_16x16x32_bf16 v[12:15], v[28:31], v[52:55], v[12:15]
	v_mfma_f32_16x16x32_bf16 v[186:189], v[20:23], v[108:111], v[48:51]
	v_mfma_f32_16x16x32_bf16 v[48:51], v[24:27], v[84:87], 0
	v_mfma_f32_16x16x32_bf16 v[194:197], v[20:23], v[116:119], v[16:19]
	v_mfma_f32_16x16x32_bf16 v[16:19], v[24:27], v[112:115], 0
	v_mfma_f32_16x16x32_bf16 v[190:193], v[28:31], v[108:111], v[48:51]
	v_mfma_f32_16x16x32_bf16 v[198:201], v[28:31], v[116:119], v[16:19]
	s_setprio 0
	s_barrier
	s_add_i32 s27, 0, 0x18000
	s_nop 2
	v_add_u32_e32 v16, s27, v141
	s_add_i32 s29, 0, 0x1c000
	ds_read_b128 v[202:205], v16
	ds_read_b128 v[206:209], v16 offset:1024
	ds_read_b128 v[210:213], v16 offset:2048
	ds_read_b128 v[214:217], v16 offset:3072
	v_add_u32_e32 v16, s29, v141
	ds_read_b128 v[218:221], v16
	ds_read_b128 v[222:225], v16 offset:1024
	ds_read_b128 v[226:229], v16 offset:2048
	ds_read_b128 v[230:233], v16 offset:3072
	s_add_u32 s38, s40, 0x8000
	s_addc_u32 s39, s41, 0
	s_mov_b32 m0, s50
	v_lshl_add_u64 v[16:17], s[38:39], 0, v[128:129]
	ds_read_b128 v[24:27], v145 offset:32768
	ds_read_b128 v[28:31], v145 offset:33792
	ds_read_b128 v[60:63], v145 offset:34816
	ds_read_b128 v[108:111], v145 offset:35840
	ds_read_b128 v[234:237], v145 offset:36864
	ds_read_b128 v[238:241], v145 offset:37888
	ds_read_b128 v[242:245], v145 offset:38912
	ds_read_b128 v[246:249], v145 offset:39936
	global_load_lds_dwordx4 v[16:17], off
	v_lshl_add_u64 v[16:17], s[38:39], 0, v[132:133]
	s_mov_b32 m0, s51
	s_nop 0
	global_load_lds_dwordx4 v[16:17], off
	s_waitcnt vmcnt(8)
	s_waitcnt lgkmcnt(0)
	s_barrier
	s_setprio 1
	s_waitcnt lgkmcnt(0)
	v_mfma_f32_16x16x32_bf16 v[16:19], v[202:205], v[24:27], v[64:67]
	v_mfma_f32_16x16x32_bf16 v[112:115], v[206:209], v[28:31], v[16:19]
	v_mfma_f32_16x16x32_bf16 v[16:19], v[210:213], v[24:27], v[68:71]
	v_mfma_f32_16x16x32_bf16 v[116:119], v[214:217], v[28:31], v[16:19]
	v_mfma_f32_16x16x32_bf16 v[16:19], v[202:205], v[60:63], v[72:75]
	v_mfma_f32_16x16x32_bf16 v[80:83], v[206:209], v[108:111], v[16:19]
	v_mfma_f32_16x16x32_bf16 v[16:19], v[210:213], v[60:63], v[76:79]
	v_mfma_f32_16x16x32_bf16 v[84:87], v[214:217], v[108:111], v[16:19]
	s_setprio 0
	s_setprio 1
	v_mfma_f32_16x16x32_bf16 v[16:19], v[202:205], v[234:237], v[88:91]
	v_mfma_f32_16x16x32_bf16 v[48:51], v[206:209], v[238:241], v[16:19]
	v_mfma_f32_16x16x32_bf16 v[16:19], v[210:213], v[234:237], v[92:95]
	v_mfma_f32_16x16x32_bf16 v[52:55], v[214:217], v[238:241], v[16:19]
	v_mfma_f32_16x16x32_bf16 v[16:19], v[202:205], v[242:245], v[96:99]
	v_mfma_f32_16x16x32_bf16 v[20:23], v[210:213], v[242:245], v[100:103]
	v_mfma_f32_16x16x32_bf16 v[16:19], v[206:209], v[246:249], v[16:19]
	v_mfma_f32_16x16x32_bf16 v[20:23], v[214:217], v[246:249], v[20:23]
	s_setprio 0
	s_setprio 1
	v_mfma_f32_16x16x32_bf16 v[64:67], v[218:221], v[24:27], v[104:107]
	v_mfma_f32_16x16x32_bf16 v[24:27], v[226:229], v[24:27], v[32:35]
	v_mfma_f32_16x16x32_bf16 v[124:127], v[230:233], v[28:31], v[24:27]
	v_mfma_f32_16x16x32_bf16 v[24:27], v[218:221], v[60:63], v[36:39]
	v_mfma_f32_16x16x32_bf16 v[104:107], v[222:225], v[108:111], v[24:27]
	v_mfma_f32_16x16x32_bf16 v[24:27], v[226:229], v[60:63], v[40:43]
	v_mfma_f32_16x16x32_bf16 v[108:111], v[230:233], v[108:111], v[24:27]
	v_mfma_f32_16x16x32_bf16 v[24:27], v[218:221], v[234:237], v[44:47]
	s_setprio 0
	s_setprio 1
	v_mfma_f32_16x16x32_bf16 v[120:123], v[222:225], v[28:31], v[64:67]
	v_mfma_f32_16x16x32_bf16 v[64:67], v[222:225], v[238:241], v[24:27]
	v_mfma_f32_16x16x32_bf16 v[24:27], v[226:229], v[234:237], v[146:149]
	v_mfma_f32_16x16x32_bf16 v[68:71], v[230:233], v[238:241], v[24:27]
	v_mfma_f32_16x16x32_bf16 v[24:27], v[218:221], v[242:245], v[150:153]
	v_mfma_f32_16x16x32_bf16 v[32:35], v[222:225], v[246:249], v[24:27]
	v_mfma_f32_16x16x32_bf16 v[24:27], v[226:229], v[242:245], v[56:59]
	v_mfma_f32_16x16x32_bf16 v[36:39], v[230:233], v[246:249], v[24:27]
	s_setprio 0
	s_barrier
; #define PG8_STAGE(bufoff, gbase, voff) do { _Pragma("unroll") for (int _i = 0; _i < 2; ++_i) \
;         __builtin_amdgcn_global_load_lds((const unsigned*)((const char*)(gbase) + (voff)[_i]), (PG8_LAS unsigned*)(lds + (bufoff) + ldsw + _i * 8192), 16, 0, 0); } while (0)
; #define PG8_LDA(dst, b, h) do { _Pragma("unroll") for (int m = 0; m < 4; ++m) _Pragma("unroll") for (int k = 0; k < 2; ++k) dst[m][k] = *(const PG8_LAS bf16x8*)(lds + PG8_SA(b, h) + aoff + m * 2048 + k * 1024); } while (0)
; #define PG8_MMA(ai, bj, At, Bt) do { __builtin_amdgcn_s_setprio(1); _Pragma("unroll") for (int m = 0; m < 4; ++m) _Pragma("unroll") for (int n = 0; n < 2; ++n) _Pragma("unroll") for (int k = 0; k < 2; ++k) \
;         acc[ai][bj][m][n] = __builtin_amdgcn_mfma_f32_16x16x32_bf16(Bt[n][k], At[m][k], acc[ai][bj][m][n], 0, 0, 0); __builtin_amdgcn_s_setprio(0); } while (0)
; #define PG8_WAIT_V(n) asm volatile("s_waitcnt vmcnt(" #n ")" ::: "memory")
; #define PG8_WAIT_L(n) asm volatile("s_waitcnt lgkmcnt(" #n ")" ::: "memory")
; #define PG8_BAR __builtin_amdgcn_s_barrier()
; #define PG8_SCHED __builtin_amdgcn_sched_barrier(0)
; template <class Epi, class Sched, bool ALIGN_EPI = true, bool SP2 = true>
; __device__ __forceinline__ void gemm_phase(PG8_LAS unsigned char* lds, const Gemm g, const Sched& S, const Epi& E) {
;     ...
;             PG8_LDA(At, 1, 1); PG8_STAGE(PG8_SB(1, 0), b3, voffB); PG8_STAGE(PG8_SB(1, 1), b3 + hstepB, voffB); PG8_STAGE(PG8_SA(1, 0), a3, voffA);
;             PG8_WAIT_V(8); PG8_WAIT_L(0); PG8_BAR; PG8_MMA(1, 0, At, B0); PG8_MMA(1, 1, At, B1); PG8_BAR; PG8_SCHED;
;         }
;         if constexpr (ALIGN_EPI) { if (wr == 0) PG8_BAR; }
	s_add_i32 s27, s27, s48
	s_nop 3
	v_lshl_add_u64 v[24:25], v[250:251], 0, s[10:11]
	s_mov_b32 m0, s27
	ds_read_b128 v[40:43], v145 offset:49152
	ds_read_b128 v[44:47], v145 offset:50176
	ds_read_b128 v[76:79], v145 offset:51200
	ds_read_b128 v[146:149], v145 offset:52224
	ds_read_b128 v[150:153], v145 offset:53248
	ds_read_b128 v[234:237], v145 offset:54272
	ds_read_b128 v[238:241], v145 offset:55296
	ds_read_b128 v[242:245], v145 offset:56320
	global_load_lds_dwordx4 v[24:25], off
	s_add_i32 m0, s27, 0x2000
	s_add_u32 s36, s36, 0x8080
	v_lshl_add_u64 v[24:25], v[252:253], 0, s[10:11]
	s_addc_u32 s37, s37, 0
	s_add_i32 s27, s29, s48
	global_load_lds_dwordx4 v[24:25], off
	v_lshl_add_u64 v[24:25], s[36:37], 0, v[130:131]
	s_mov_b32 m0, s27
	s_nop 0
	global_load_lds_dwordx4 v[24:25], off
	v_lshl_add_u64 v[24:25], s[36:37], 0, v[134:135]
	s_add_i32 m0, s27, 0x2000
	s_nop 0
	global_load_lds_dwordx4 v[24:25], off
	v_lshl_add_u64 v[24:25], v[136:137], 0, s[10:11]
	s_mov_b32 m0, s55
	s_nop 0
	global_load_lds_dwordx4 v[24:25], off
	v_lshl_add_u64 v[24:25], v[138:139], 0, s[10:11]
	s_mov_b32 m0, s56
	s_nop 0
	global_load_lds_dwordx4 v[24:25], off
	s_waitcnt vmcnt(8)
	s_waitcnt lgkmcnt(0)
	s_barrier
	s_setprio 1
	s_waitcnt lgkmcnt(0)
	v_mfma_f32_16x16x32_bf16 v[24:27], v[202:205], v[40:43], v[154:157]
	v_mfma_f32_16x16x32_bf16 v[88:91], v[206:209], v[44:47], v[24:27]
	v_mfma_f32_16x16x32_bf16 v[24:27], v[210:213], v[40:43], v[158:161]
	v_mfma_f32_16x16x32_bf16 v[92:95], v[214:217], v[44:47], v[24:27]
	v_mfma_f32_16x16x32_bf16 v[24:27], v[202:205], v[76:79], v[162:165]
	v_mfma_f32_16x16x32_bf16 v[56:59], v[206:209], v[146:149], v[24:27]
	v_mfma_f32_16x16x32_bf16 v[24:27], v[210:213], v[76:79], v[166:169]
	v_mfma_f32_16x16x32_bf16 v[60:63], v[214:217], v[146:149], v[24:27]
	s_setprio 0
	s_setprio 1
	v_mfma_f32_16x16x32_bf16 v[24:27], v[202:205], v[150:153], v[170:173]
	v_mfma_f32_16x16x32_bf16 v[28:31], v[210:213], v[150:153], v[174:177]
	v_mfma_f32_16x16x32_bf16 v[0:3], v[202:205], v[238:241], v[0:3]
	v_mfma_f32_16x16x32_bf16 v[4:7], v[210:213], v[238:241], v[4:7]
	v_mfma_f32_16x16x32_bf16 v[24:27], v[206:209], v[234:237], v[24:27]
	v_mfma_f32_16x16x32_bf16 v[28:31], v[214:217], v[234:237], v[28:31]
	v_mfma_f32_16x16x32_bf16 v[0:3], v[206:209], v[242:245], v[0:3]
	v_mfma_f32_16x16x32_bf16 v[4:7], v[214:217], v[242:245], v[4:7]
	s_setprio 0
	s_setprio 1
	v_mfma_f32_16x16x32_bf16 v[8:11], v[218:221], v[40:43], v[8:11]
	v_mfma_f32_16x16x32_bf16 v[96:99], v[222:225], v[44:47], v[8:11]
	v_mfma_f32_16x16x32_bf16 v[8:11], v[226:229], v[40:43], v[12:15]
	v_mfma_f32_16x16x32_bf16 v[100:103], v[230:233], v[44:47], v[8:11]
	v_mfma_f32_16x16x32_bf16 v[8:11], v[218:221], v[76:79], v[178:181]
	v_mfma_f32_16x16x32_bf16 v[72:75], v[222:225], v[146:149], v[8:11]
	v_mfma_f32_16x16x32_bf16 v[8:11], v[226:229], v[76:79], v[182:185]
	v_mfma_f32_16x16x32_bf16 v[76:79], v[230:233], v[146:149], v[8:11]
	s_setprio 0
	s_setprio 1
	v_mfma_f32_16x16x32_bf16 v[8:11], v[218:221], v[150:153], v[186:189]
	v_mfma_f32_16x16x32_bf16 v[40:43], v[222:225], v[234:237], v[8:11]
	v_mfma_f32_16x16x32_bf16 v[8:11], v[226:229], v[150:153], v[190:193]
	v_mfma_f32_16x16x32_bf16 v[44:47], v[230:233], v[234:237], v[8:11]
	v_mfma_f32_16x16x32_bf16 v[8:11], v[218:221], v[238:241], v[194:197]
	v_mfma_f32_16x16x32_bf16 v[12:15], v[226:229], v[238:241], v[198:201]
	v_mfma_f32_16x16x32_bf16 v[8:11], v[222:225], v[242:245], v[8:11]
	v_mfma_f32_16x16x32_bf16 v[12:15], v[230:233], v[242:245], v[12:15]
	s_setprio 0
	s_barrier
	s_andn2_b64 vcc, exec, s[12:13]
	s_cbranch_vccnz .LBB0_412
	s_barrier

; #define PG8_STAGE(bufoff, gbase, voff) do { _Pragma("unroll") for (int _i = 0; _i < 2; ++_i) \
;         __builtin_amdgcn_global_load_lds((const unsigned*)((const char*)(gbase) + (voff)[_i]), (PG8_LAS unsigned*)(lds + (bufoff) + ldsw + _i * 8192), 16, 0, 0); } while (0)
; #define PG8_LDA(dst, b, h) do { _Pragma("unroll") for (int m = 0; m < 4; ++m) _Pragma("unroll") for (int k = 0; k < 2; ++k) dst[m][k] = *(const PG8_LAS bf16x8*)(lds + PG8_SA(b, h) + aoff + m * 2048 + k * 1024); } while (0)
; #define PG8_LDB(dst, b, h) do { _Pragma("unroll") for (int n = 0; n < 2; ++n) _Pragma("unroll") for (int k = 0; k < 2; ++k) dst[n][k] = *(const PG8_LAS bf16x8*)(lds + PG8_SB(b, h) + boff + n * 2048 + k * 1024); } while (0)
; #define PG8_MMA(ai, bj, At, Bt) do { __builtin_amdgcn_s_setprio(1); _Pragma("unroll") for (int m = 0; m < 4; ++m) _Pragma("unroll") for (int n = 0; n < 2; ++n) _Pragma("unroll") for (int k = 0; k < 2; ++k) \
;         acc[ai][bj][m][n] = __builtin_amdgcn_mfma_f32_16x16x32_bf16(Bt[n][k], At[m][k], acc[ai][bj][m][n], 0, 0, 0); __builtin_amdgcn_s_setprio(0); } while (0)
; #define PG8_WAIT_V(n) asm volatile("s_waitcnt vmcnt(" #n ")" ::: "memory")
; #define PG8_BAR __builtin_amdgcn_s_barrier()
; template <class Epi, class Sched, bool ALIGN_EPI = true, bool SP2 = true>
; __device__ __forceinline__ void gemm_phase(PG8_LAS unsigned char* lds, const Gemm g, const Sched& S, const Epi& E) {
;     ...
;         const bool has_next = S.next(ui + 1, nxt);
;         const char* nA = has_next ? (const char*)g.A + (size_t)nxt.pm * tstepA : cA; const char* nB = has_next ? (const char*)g.Bt + (size_t)nxt.pn * tstepB : cB;
;         for (int t = 0; t < nt; t += 2) {
;             const bool last = (t == nt - 2);
;             const char* a1 = cA + (size_t)(t + 1) * kstep;
;             const char* a2 = last ? nA : cA + (size_t)(t + 2) * kstep; const char* b2 = last ? nB : cB + (size_t)(t + 2) * kstep;
;             const char* a3 = a2 + kstep; const char* b3 = b2 + kstep;
;             PG8_LDB(B0, 0, 0); PG8_LDB(B1, 0, 1); PG8_SCHED; PG8_LDA(At, 0, 0); PG8_STAGE(PG8_SA(1, 1), a1 + hstepA, voffA);
;             PG8_WAIT_V(8); PG8_WAIT_L(0); PG8_BAR; PG8_MMA(0, 0, At, B0); PG8_MMA(0, 1, At, B1); PG8_BAR; PG8_SCHED;
;             PG8_LDA(At, 0, 1); PG8_STAGE(PG8_SB(0, 0), b2, voffB); PG8_STAGE(PG8_SB(0, 1), b2 + hstepB, voffB); PG8_STAGE(PG8_SA(0, 0), a2, voffA);
.LBB0_432:
	ds_read_b128 v[0:3], v143
	ds_read_b128 v[4:7], v143 offset:1024
	ds_read_b128 v[8:11], v143 offset:2048
	ds_read_b128 v[12:15], v143 offset:3072
	ds_read_b128 v[16:19], v144
	ds_read_b128 v[20:23], v144 offset:1024
	ds_read_b128 v[24:27], v144 offset:2048
	ds_read_b128 v[28:31], v144 offset:3072
	s_ashr_i32 s27, s26, 31
	s_lshl_b64 s[28:29], s[26:27], 16
	s_add_u32 s28, s1, s28
	s_addc_u32 s29, s40, s29
	s_and_b64 s[30:31], s[2:3], exec
	s_cselect_b32 s39, s29, s37
	s_cselect_b32 s38, s28, s36
	s_ashr_i32 s25, s24, 31
	s_lshl_b64 s[30:31], s[24:25], 16
	s_add_u32 s30, s41, s30
	s_addc_u32 s31, s43, s31
	s_and_b64 s[62:63], s[2:3], exec
	s_cselect_b32 s35, s31, s35
	s_cselect_b32 s34, s30, s34
	s_add_u32 s36, s36, 0x8080
	s_addc_u32 s37, s37, 0
	v_lshl_add_u64 v[64:65], s[36:37], 0, v[128:129]
	s_add_i32 m0, s23, 0xc000
	ds_read_b128 v[32:35], v145
	ds_read_b128 v[36:39], v145 offset:1024
	ds_read_b128 v[40:43], v145 offset:2048
	ds_read_b128 v[44:47], v145 offset:3072
	ds_read_b128 v[48:51], v145 offset:4096
	ds_read_b128 v[52:55], v145 offset:5120
	ds_read_b128 v[56:59], v145 offset:6144
	ds_read_b128 v[60:63], v145 offset:7168
	global_load_lds_dwordx4 v[64:65], off
	v_lshl_add_u64 v[64:65], s[36:37], 0, v[132:133]
	s_add_i32 m0, s23, 0xe000
	s_nop 0
	global_load_lds_dwordx4 v[64:65], off
	s_waitcnt vmcnt(8)
	s_waitcnt lgkmcnt(0)
	s_barrier
	s_setprio 1
	s_waitcnt lgkmcnt(0)
	v_mfma_f32_16x16x32_bf16 v[80:83], v[0:3], v[48:51], 0
	v_mfma_f32_16x16x32_bf16 v[88:91], v[4:7], v[52:55], v[80:83]
	v_mfma_f32_16x16x32_bf16 v[80:83], v[8:11], v[48:51], 0
	v_mfma_f32_16x16x32_bf16 v[92:95], v[12:15], v[52:55], v[80:83]
	v_mfma_f32_16x16x32_bf16 v[80:83], v[0:3], v[56:59], 0
	v_mfma_f32_16x16x32_bf16 v[64:67], v[0:3], v[32:35], 0
	v_mfma_f32_16x16x32_bf16 v[68:71], v[8:11], v[32:35], 0
	v_mfma_f32_16x16x32_bf16 v[72:75], v[0:3], v[40:43], 0
	s_setprio 0
	s_setprio 1
	v_mfma_f32_16x16x32_bf16 v[76:79], v[8:11], v[40:43], 0
	v_mfma_f32_16x16x32_bf16 v[96:99], v[4:7], v[60:63], v[80:83]
	v_mfma_f32_16x16x32_bf16 v[80:83], v[8:11], v[56:59], 0
	v_mfma_f32_16x16x32_bf16 v[64:67], v[4:7], v[36:39], v[64:67]
	v_mfma_f32_16x16x32_bf16 v[68:71], v[12:15], v[36:39], v[68:71]
	v_mfma_f32_16x16x32_bf16 v[72:75], v[4:7], v[44:47], v[72:75]
	v_mfma_f32_16x16x32_bf16 v[76:79], v[12:15], v[44:47], v[76:79]
	v_mfma_f32_16x16x32_bf16 v[100:103], v[12:15], v[60:63], v[80:83]
	s_setprio 0
	s_setprio 1
	v_mfma_f32_16x16x32_bf16 v[80:83], v[16:19], v[32:35], 0
	v_mfma_f32_16x16x32_bf16 v[32:35], v[24:27], v[32:35], 0
	v_mfma_f32_16x16x32_bf16 v[104:107], v[20:23], v[36:39], v[80:83]
	v_mfma_f32_16x16x32_bf16 v[32:35], v[28:31], v[36:39], v[32:35]
	v_mfma_f32_16x16x32_bf16 v[36:39], v[16:19], v[40:43], 0
	v_mfma_f32_16x16x32_bf16 v[40:43], v[24:27], v[40:43], 0
	v_mfma_f32_16x16x32_bf16 v[36:39], v[20:23], v[44:47], v[36:39]
	v_mfma_f32_16x16x32_bf16 v[40:43], v[28:31], v[44:47], v[40:43]
	s_setprio 0
	s_setprio 1
	v_mfma_f32_16x16x32_bf16 v[44:47], v[16:19], v[48:51], 0
	v_mfma_f32_16x16x32_bf16 v[48:51], v[24:27], v[48:51], 0
	v_mfma_f32_16x16x32_bf16 v[146:149], v[28:31], v[52:55], v[48:51]
	v_mfma_f32_16x16x32_bf16 v[48:51], v[16:19], v[56:59], 0
	v_mfma_f32_16x16x32_bf16 v[150:153], v[20:23], v[60:63], v[48:51]
	v_mfma_f32_16x16x32_bf16 v[48:51], v[24:27], v[56:59], 0
	v_mfma_f32_16x16x32_bf16 v[44:47], v[20:23], v[52:55], v[44:47]
	v_mfma_f32_16x16x32_bf16 v[56:59], v[28:31], v[60:63], v[48:51]
	s_setprio 0
	s_barrier
	s_add_i32 s25, s0, s45
	v_lshl_add_u64 v[250:251], s[34:35], 0, v[130:131]
	s_mov_b32 m0, s25
	s_nop 0
	ds_read_b128 v[48:51], v145 offset:16384
	ds_read_b128 v[52:55], v145 offset:17408
	ds_read_b128 v[60:63], v145 offset:18432
	ds_read_b128 v[80:83], v145 offset:19456
	ds_read_b128 v[84:87], v145 offset:20480
	ds_read_b128 v[108:111], v145 offset:21504
	ds_read_b128 v[112:115], v145 offset:22528
	ds_read_b128 v[116:119], v145 offset:23552
	global_load_lds_dwordx4 v[250:251], off
	s_add_i32 m0, s25, 0x2000
	s_add_u32 s36, s34, 0x8000
	v_lshl_add_u64 v[252:253], s[34:35], 0, v[134:135]
	s_addc_u32 s37, s35, 0
	s_add_i32 s25, s56, s45
	global_load_lds_dwordx4 v[252:253], off
	v_lshl_add_u64 v[120:121], s[36:37], 0, v[130:131]
	s_mov_b32 m0, s25
	v_lshl_add_u64 v[136:137], s[38:39], 0, v[128:129]
	global_load_lds_dwordx4 v[120:121], off
	v_lshl_add_u64 v[120:121], s[36:37], 0, v[134:135]
	s_add_i32 m0, s25, 0x2000
	v_lshl_add_u64 v[138:139], s[38:39], 0, v[132:133]
	global_load_lds_dwordx4 v[120:121], off
	s_mov_b32 m0, s23
	s_nop 0
	global_load_lds_dwordx4 v[136:137], off
	s_mov_b32 m0, s46
	s_nop 0
	global_load_lds_dwordx4 v[138:139], off
	s_waitcnt vmcnt(8)
	s_waitcnt lgkmcnt(0)
	s_barrier
; #define PG8_STAGE(bufoff, gbase, voff) do { _Pragma("unroll") for (int _i = 0; _i < 2; ++_i) \
;         __builtin_amdgcn_global_load_lds((const unsigned*)((const char*)(gbase) + (voff)[_i]), (PG8_LAS unsigned*)(lds + (bufoff) + ldsw + _i * 8192), 16, 0, 0); } while (0)
; #define PG8_LDA(dst, b, h) do { _Pragma("unroll") for (int m = 0; m < 4; ++m) _Pragma("unroll") for (int k = 0; k < 2; ++k) dst[m][k] = *(const PG8_LAS bf16x8*)(lds + PG8_SA(b, h) + aoff + m * 2048 + k * 1024); } while (0)
; #define PG8_LDB(dst, b, h) do { _Pragma("unroll") for (int n = 0; n < 2; ++n) _Pragma("unroll") for (int k = 0; k < 2; ++k) dst[n][k] = *(const PG8_LAS bf16x8*)(lds + PG8_SB(b, h) + boff + n * 2048 + k * 1024); } while (0)
; #define PG8_MMA(ai, bj, At, Bt) do { __builtin_amdgcn_s_setprio(1); _Pragma("unroll") for (int m = 0; m < 4; ++m) _Pragma("unroll") for (int n = 0; n < 2; ++n) _Pragma("unroll") for (int k = 0; k < 2; ++k) \
;         acc[ai][bj][m][n] = __builtin_amdgcn_mfma_f32_16x16x32_bf16(Bt[n][k], At[m][k], acc[ai][bj][m][n], 0, 0, 0); __builtin_amdgcn_s_setprio(0); } while (0)
; #define PG8_WAIT_V(n) asm volatile("s_waitcnt vmcnt(" #n ")" ::: "memory")
; #define PG8_WAIT_L(n) asm volatile("s_waitcnt lgkmcnt(" #n ")" ::: "memory")
; #define PG8_BAR __builtin_amdgcn_s_barrier()
; #define PG8_SCHED __builtin_amdgcn_sched_barrier(0)
; template <class Epi, class Sched, bool ALIGN_EPI = true, bool SP2 = true>
; __device__ __forceinline__ void gemm_phase(PG8_LAS unsigned char* lds, const Gemm g, const Sched& S, const Epi& E) {
;     ...
;             PG8_WAIT_V(8); PG8_WAIT_L(0); PG8_BAR; PG8_MMA(1, 0, At, B0); PG8_MMA(1, 1, At, B1); PG8_BAR; PG8_SCHED;
;             PG8_LDB(B0, 1, 0); PG8_LDB(B1, 1, 1); PG8_SCHED; PG8_LDA(At, 1, 0); PG8_STAGE(PG8_SA(0, 1), a2 + hstepA, voffA);
;             PG8_WAIT_V(8); PG8_WAIT_L(0); PG8_BAR; PG8_MMA(0, 0, At, B0); PG8_MMA(0, 1, At, B1); PG8_BAR; PG8_SCHED;
	s_setprio 1
	s_waitcnt lgkmcnt(0)
	v_mfma_f32_16x16x32_bf16 v[120:123], v[0:3], v[48:51], 0
	v_mfma_f32_16x16x32_bf16 v[154:157], v[4:7], v[52:55], v[120:123]
	v_mfma_f32_16x16x32_bf16 v[120:123], v[8:11], v[48:51], 0
	v_mfma_f32_16x16x32_bf16 v[158:161], v[12:15], v[52:55], v[120:123]
	v_mfma_f32_16x16x32_bf16 v[120:123], v[0:3], v[60:63], 0
	v_mfma_f32_16x16x32_bf16 v[162:165], v[4:7], v[80:83], v[120:123]
	v_mfma_f32_16x16x32_bf16 v[120:123], v[8:11], v[60:63], 0
	v_mfma_f32_16x16x32_bf16 v[166:169], v[12:15], v[80:83], v[120:123]
	s_setprio 0
	s_setprio 1
	v_mfma_f32_16x16x32_bf16 v[120:123], v[0:3], v[84:87], 0
	v_mfma_f32_16x16x32_bf16 v[0:3], v[0:3], v[112:115], 0
	v_mfma_f32_16x16x32_bf16 v[170:173], v[4:7], v[108:111], v[120:123]
	v_mfma_f32_16x16x32_bf16 v[0:3], v[4:7], v[116:119], v[0:3]
	v_mfma_f32_16x16x32_bf16 v[4:7], v[8:11], v[112:115], 0
	v_mfma_f32_16x16x32_bf16 v[120:123], v[8:11], v[84:87], 0
	v_mfma_f32_16x16x32_bf16 v[4:7], v[12:15], v[116:119], v[4:7]
	v_mfma_f32_16x16x32_bf16 v[174:177], v[12:15], v[108:111], v[120:123]
	s_setprio 0
	s_setprio 1
	v_mfma_f32_16x16x32_bf16 v[8:11], v[16:19], v[48:51], 0
	v_mfma_f32_16x16x32_bf16 v[12:15], v[24:27], v[48:51], 0
	v_mfma_f32_16x16x32_bf16 v[48:51], v[16:19], v[60:63], 0
	v_mfma_f32_16x16x32_bf16 v[178:181], v[20:23], v[80:83], v[48:51]
	v_mfma_f32_16x16x32_bf16 v[48:51], v[24:27], v[60:63], 0
	v_mfma_f32_16x16x32_bf16 v[182:185], v[28:31], v[80:83], v[48:51]
	v_mfma_f32_16x16x32_bf16 v[48:51], v[16:19], v[84:87], 0
	v_mfma_f32_16x16x32_bf16 v[16:19], v[16:19], v[112:115], 0
	s_setprio 0
	s_setprio 1
	v_mfma_f32_16x16x32_bf16 v[8:11], v[20:23], v[52:55], v[8:11]
	v_mfma_f32_16x16x32_bf16 v[12:15], v[28:31], v[52:55], v[12:15]
	v_mfma_f32_16x16x32_bf16 v[186:189], v[20:23], v[108:111], v[48:51]
	v_mfma_f32_16x16x32_bf16 v[48:51], v[24:27], v[84:87], 0
	v_mfma_f32_16x16x32_bf16 v[194:197], v[20:23], v[116:119], v[16:19]
	v_mfma_f32_16x16x32_bf16 v[16:19], v[24:27], v[112:115], 0
	v_mfma_f32_16x16x32_bf16 v[190:193], v[28:31], v[108:111], v[48:51]
	v_mfma_f32_16x16x32_bf16 v[198:201], v[28:31], v[116:119], v[16:19]
	s_setprio 0
	s_barrier
	s_add_i32 s25, 0, 0x18000
	s_nop 2
	v_add_u32_e32 v16, s25, v141
	s_add_i32 s27, 0, 0x1c000
	ds_read_b128 v[202:205], v16
	ds_read_b128 v[206:209], v16 offset:1024
	ds_read_b128 v[210:213], v16 offset:2048
	ds_read_b128 v[214:217], v16 offset:3072
	v_add_u32_e32 v16, s27, v141
	ds_read_b128 v[218:221], v16
	ds_read_b128 v[222:225], v16 offset:1024
	ds_read_b128 v[226:229], v16 offset:2048
	ds_read_b128 v[230:233], v16 offset:3072
	s_add_u32 s36, s38, 0x8000
	s_addc_u32 s37, s39, 0
	s_mov_b32 m0, s47
	v_lshl_add_u64 v[16:17], s[36:37], 0, v[128:129]
	ds_read_b128 v[24:27], v145 offset:32768
	ds_read_b128 v[28:31], v145 offset:33792
	ds_read_b128 v[60:63], v145 offset:34816
	ds_read_b128 v[108:111], v145 offset:35840
	ds_read_b128 v[234:237], v145 offset:36864
	ds_read_b128 v[238:241], v145 offset:37888
	ds_read_b128 v[242:245], v145 offset:38912
	ds_read_b128 v[246:249], v145 offset:39936
	global_load_lds_dwordx4 v[16:17], off
	v_lshl_add_u64 v[16:17], s[36:37], 0, v[132:133]
	s_mov_b32 m0, s48
	s_nop 0
	global_load_lds_dwordx4 v[16:17], off
	s_waitcnt vmcnt(8)
	s_waitcnt lgkmcnt(0)
	s_barrier
	s_setprio 1
	s_waitcnt lgkmcnt(0)
	v_mfma_f32_16x16x32_bf16 v[16:19], v[202:205], v[24:27], v[64:67]
	v_mfma_f32_16x16x32_bf16 v[112:115], v[206:209], v[28:31], v[16:19]
	v_mfma_f32_16x16x32_bf16 v[16:19], v[210:213], v[24:27], v[68:71]
	v_mfma_f32_16x16x32_bf16 v[116:119], v[214:217], v[28:31], v[16:19]
	v_mfma_f32_16x16x32_bf16 v[16:19], v[202:205], v[60:63], v[72:75]
	v_mfma_f32_16x16x32_bf16 v[80:83], v[206:209], v[108:111], v[16:19]
	v_mfma_f32_16x16x32_bf16 v[16:19], v[210:213], v[60:63], v[76:79]
	v_mfma_f32_16x16x32_bf16 v[84:87], v[214:217], v[108:111], v[16:19]
	s_setprio 0
	s_setprio 1
	v_mfma_f32_16x16x32_bf16 v[16:19], v[202:205], v[234:237], v[88:91]
	v_mfma_f32_16x16x32_bf16 v[48:51], v[206:209], v[238:241], v[16:19]
	v_mfma_f32_16x16x32_bf16 v[16:19], v[210:213], v[234:237], v[92:95]
	v_mfma_f32_16x16x32_bf16 v[52:55], v[214:217], v[238:241], v[16:19]
	v_mfma_f32_16x16x32_bf16 v[16:19], v[202:205], v[242:245], v[96:99]
	v_mfma_f32_16x16x32_bf16 v[20:23], v[210:213], v[242:245], v[100:103]
	v_mfma_f32_16x16x32_bf16 v[16:19], v[206:209], v[246:249], v[16:19]
	v_mfma_f32_16x16x32_bf16 v[20:23], v[214:217], v[246:249], v[20:23]
	s_setprio 0
	s_setprio 1
	v_mfma_f32_16x16x32_bf16 v[64:67], v[218:221], v[24:27], v[104:107]
	v_mfma_f32_16x16x32_bf16 v[24:27], v[226:229], v[24:27], v[32:35]
	v_mfma_f32_16x16x32_bf16 v[124:127], v[230:233], v[28:31], v[24:27]
	v_mfma_f32_16x16x32_bf16 v[24:27], v[218:221], v[60:63], v[36:39]
	v_mfma_f32_16x16x32_bf16 v[104:107], v[222:225], v[108:111], v[24:27]
	v_mfma_f32_16x16x32_bf16 v[24:27], v[226:229], v[60:63], v[40:43]
	v_mfma_f32_16x16x32_bf16 v[108:111], v[230:233], v[108:111], v[24:27]
	v_mfma_f32_16x16x32_bf16 v[24:27], v[218:221], v[234:237], v[44:47]
	s_setprio 0
	s_setprio 1
	v_mfma_f32_16x16x32_bf16 v[120:123], v[222:225], v[28:31], v[64:67]
	v_mfma_f32_16x16x32_bf16 v[64:67], v[222:225], v[238:241], v[24:27]
	v_mfma_f32_16x16x32_bf16 v[24:27], v[226:229], v[234:237], v[146:149]
	v_mfma_f32_16x16x32_bf16 v[68:71], v[230:233], v[238:241], v[24:27]
	v_mfma_f32_16x16x32_bf16 v[24:27], v[218:221], v[242:245], v[150:153]
	v_mfma_f32_16x16x32_bf16 v[32:35], v[222:225], v[246:249], v[24:27]
	v_mfma_f32_16x16x32_bf16 v[24:27], v[226:229], v[242:245], v[56:59]
	v_mfma_f32_16x16x32_bf16 v[36:39], v[230:233], v[246:249], v[24:27]
	s_setprio 0
	s_barrier
; #define PG8_STAGE(bufoff, gbase, voff) do { _Pragma("unroll") for (int _i = 0; _i < 2; ++_i) \
;         __builtin_amdgcn_global_load_lds((const unsigned*)((const char*)(gbase) + (voff)[_i]), (PG8_LAS unsigned*)(lds + (bufoff) + ldsw + _i * 8192), 16, 0, 0); } while (0)
; #define PG8_LDA(dst, b, h) do { _Pragma("unroll") for (int m = 0; m < 4; ++m) _Pragma("unroll") for (int k = 0; k < 2; ++k) dst[m][k] = *(const PG8_LAS bf16x8*)(lds + PG8_SA(b, h) + aoff + m * 2048 + k * 1024); } while (0)
; #define PG8_MMA(ai, bj, At, Bt) do { __builtin_amdgcn_s_setprio(1); _Pragma("unroll") for (int m = 0; m < 4; ++m) _Pragma("unroll") for (int n = 0; n < 2; ++n) _Pragma("unroll") for (int k = 0; k < 2; ++k) \
;         acc[ai][bj][m][n] = __builtin_amdgcn_mfma_f32_16x16x32_bf16(Bt[n][k], At[m][k], acc[ai][bj][m][n], 0, 0, 0); __builtin_amdgcn_s_setprio(0); } while (0)
; #define PG8_WAIT_V(n) asm volatile("s_waitcnt vmcnt(" #n ")" ::: "memory")
; #define PG8_WAIT_L(n) asm volatile("s_waitcnt lgkmcnt(" #n ")" ::: "memory")
; #define PG8_BAR __builtin_amdgcn_s_barrier()
; #define PG8_SCHED __builtin_amdgcn_sched_barrier(0)
; template <class Epi, class Sched, bool ALIGN_EPI = true, bool SP2 = true>
; __device__ __forceinline__ void gemm_phase(PG8_LAS unsigned char* lds, const Gemm g, const Sched& S, const Epi& E) {
;     ...
;             PG8_LDA(At, 1, 1); PG8_STAGE(PG8_SB(1, 0), b3, voffB); PG8_STAGE(PG8_SB(1, 1), b3 + hstepB, voffB); PG8_STAGE(PG8_SA(1, 0), a3, voffA);
;             PG8_WAIT_V(8); PG8_WAIT_L(0); PG8_BAR; PG8_MMA(1, 0, At, B0); PG8_MMA(1, 1, At, B1); PG8_BAR; PG8_SCHED;
;         }
;         if constexpr (ALIGN_EPI) { if (wr == 0) PG8_BAR; }
	s_add_i32 s25, s25, s45
	s_nop 3
	v_lshl_add_u64 v[24:25], v[250:251], 0, s[8:9]
	s_mov_b32 m0, s25
	ds_read_b128 v[40:43], v145 offset:49152
	ds_read_b128 v[44:47], v145 offset:50176
	ds_read_b128 v[76:79], v145 offset:51200
	ds_read_b128 v[146:149], v145 offset:52224
	ds_read_b128 v[150:153], v145 offset:53248
	ds_read_b128 v[234:237], v145 offset:54272
	ds_read_b128 v[238:241], v145 offset:55296
	ds_read_b128 v[242:245], v145 offset:56320
	global_load_lds_dwordx4 v[24:25], off
	s_add_i32 m0, s25, 0x2000
	s_add_u32 s34, s34, 0x8080
	v_lshl_add_u64 v[24:25], v[252:253], 0, s[8:9]
	s_addc_u32 s35, s35, 0
	s_add_i32 s25, s27, s45
	global_load_lds_dwordx4 v[24:25], off
	v_lshl_add_u64 v[24:25], s[34:35], 0, v[130:131]
	s_mov_b32 m0, s25
	s_nop 0
	global_load_lds_dwordx4 v[24:25], off
	v_lshl_add_u64 v[24:25], s[34:35], 0, v[134:135]
	s_add_i32 m0, s25, 0x2000
	s_nop 0
	global_load_lds_dwordx4 v[24:25], off
	v_lshl_add_u64 v[24:25], v[136:137], 0, s[8:9]
	s_mov_b32 m0, s49
	s_nop 0
	global_load_lds_dwordx4 v[24:25], off
	v_lshl_add_u64 v[24:25], v[138:139], 0, s[8:9]
	s_mov_b32 m0, s50
	s_nop 0
	global_load_lds_dwordx4 v[24:25], off
	s_waitcnt vmcnt(8)
	s_waitcnt lgkmcnt(0)
	s_barrier
	s_setprio 1
	s_waitcnt lgkmcnt(0)
	v_mfma_f32_16x16x32_bf16 v[24:27], v[202:205], v[40:43], v[154:157]
	v_mfma_f32_16x16x32_bf16 v[88:91], v[206:209], v[44:47], v[24:27]
	v_mfma_f32_16x16x32_bf16 v[24:27], v[210:213], v[40:43], v[158:161]
	v_mfma_f32_16x16x32_bf16 v[92:95], v[214:217], v[44:47], v[24:27]
	v_mfma_f32_16x16x32_bf16 v[24:27], v[202:205], v[76:79], v[162:165]
	v_mfma_f32_16x16x32_bf16 v[56:59], v[206:209], v[146:149], v[24:27]
	v_mfma_f32_16x16x32_bf16 v[24:27], v[210:213], v[76:79], v[166:169]
	v_mfma_f32_16x16x32_bf16 v[60:63], v[214:217], v[146:149], v[24:27]
	s_setprio 0
	s_setprio 1
	v_mfma_f32_16x16x32_bf16 v[24:27], v[202:205], v[150:153], v[170:173]
	v_mfma_f32_16x16x32_bf16 v[28:31], v[210:213], v[150:153], v[174:177]
	v_mfma_f32_16x16x32_bf16 v[0:3], v[202:205], v[238:241], v[0:3]
	v_mfma_f32_16x16x32_bf16 v[4:7], v[210:213], v[238:241], v[4:7]
	v_mfma_f32_16x16x32_bf16 v[24:27], v[206:209], v[234:237], v[24:27]
	v_mfma_f32_16x16x32_bf16 v[28:31], v[214:217], v[234:237], v[28:31]
	v_mfma_f32_16x16x32_bf16 v[0:3], v[206:209], v[242:245], v[0:3]
	v_mfma_f32_16x16x32_bf16 v[4:7], v[214:217], v[242:245], v[4:7]
	s_setprio 0
	s_setprio 1
	v_mfma_f32_16x16x32_bf16 v[8:11], v[218:221], v[40:43], v[8:11]
	v_mfma_f32_16x16x32_bf16 v[96:99], v[222:225], v[44:47], v[8:11]
	v_mfma_f32_16x16x32_bf16 v[8:11], v[226:229], v[40:43], v[12:15]
	v_mfma_f32_16x16x32_bf16 v[100:103], v[230:233], v[44:47], v[8:11]
	v_mfma_f32_16x16x32_bf16 v[8:11], v[218:221], v[76:79], v[178:181]
	v_mfma_f32_16x16x32_bf16 v[72:75], v[222:225], v[146:149], v[8:11]
	v_mfma_f32_16x16x32_bf16 v[8:11], v[226:229], v[76:79], v[182:185]
	v_mfma_f32_16x16x32_bf16 v[76:79], v[230:233], v[146:149], v[8:11]
	s_setprio 0
	s_setprio 1
	v_mfma_f32_16x16x32_bf16 v[8:11], v[218:221], v[150:153], v[186:189]
	v_mfma_f32_16x16x32_bf16 v[40:43], v[222:225], v[234:237], v[8:11]
	v_mfma_f32_16x16x32_bf16 v[8:11], v[226:229], v[150:153], v[190:193]
	v_mfma_f32_16x16x32_bf16 v[44:47], v[230:233], v[234:237], v[8:11]
	v_mfma_f32_16x16x32_bf16 v[8:11], v[218:221], v[238:241], v[194:197]
	v_mfma_f32_16x16x32_bf16 v[12:15], v[226:229], v[238:241], v[198:201]
	v_mfma_f32_16x16x32_bf16 v[8:11], v[222:225], v[242:245], v[8:11]
	v_mfma_f32_16x16x32_bf16 v[12:15], v[230:233], v[242:245], v[12:15]
	s_setprio 0
	s_barrier
	s_andn2_b64 vcc, exec, s[10:11]
	s_cbranch_vccnz .LBB0_434
	s_barrier

; #define PG8_STAGE(bufoff, gbase, voff) do { _Pragma("unroll") for (int _i = 0; _i < 2; ++_i) \
;         __builtin_amdgcn_global_load_lds((const unsigned*)((const char*)(gbase) + (voff)[_i]), (PG8_LAS unsigned*)(lds + (bufoff) + ldsw + _i * 8192), 16, 0, 0); } while (0)
; #define PG8_LDA(dst, b, h) do { _Pragma("unroll") for (int m = 0; m < 4; ++m) _Pragma("unroll") for (int k = 0; k < 2; ++k) dst[m][k] = *(const PG8_LAS bf16x8*)(lds + PG8_SA(b, h) + aoff + m * 2048 + k * 1024); } while (0)
; #define PG8_LDB(dst, b, h) do { _Pragma("unroll") for (int n = 0; n < 2; ++n) _Pragma("unroll") for (int k = 0; k < 2; ++k) dst[n][k] = *(const PG8_LAS bf16x8*)(lds + PG8_SB(b, h) + boff + n * 2048 + k * 1024); } while (0)
; #define PG8_MMA(ai, bj, At, Bt) do { __builtin_amdgcn_s_setprio(1); _Pragma("unroll") for (int m = 0; m < 4; ++m) _Pragma("unroll") for (int n = 0; n < 2; ++n) _Pragma("unroll") for (int k = 0; k < 2; ++k) \
;         acc[ai][bj][m][n] = __builtin_amdgcn_mfma_f32_16x16x32_bf16(Bt[n][k], At[m][k], acc[ai][bj][m][n], 0, 0, 0); __builtin_amdgcn_s_setprio(0); } while (0)
; #define PG8_WAIT_V(n) asm volatile("s_waitcnt vmcnt(" #n ")" ::: "memory")
; #define PG8_BAR __builtin_amdgcn_s_barrier()
; template <class Epi, class Sched, bool ALIGN_EPI = true, bool SP2 = true>
; __device__ __forceinline__ void gemm_phase(PG8_LAS unsigned char* lds, const Gemm g, const Sched& S, const Epi& E) {
;     ...
;         const bool has_next = S.next(ui + 1, nxt);
;         const char* nA = has_next ? (const char*)g.A + (size_t)nxt.pm * tstepA : cA; const char* nB = has_next ? (const char*)g.Bt + (size_t)nxt.pn * tstepB : cB;
;         for (int t = 0; t < nt; t += 2) {
;             const bool last = (t == nt - 2);
;             const char* a1 = cA + (size_t)(t + 1) * kstep;
;             const char* a2 = last ? nA : cA + (size_t)(t + 2) * kstep; const char* b2 = last ? nB : cB + (size_t)(t + 2) * kstep;
;             const char* a3 = a2 + kstep; const char* b3 = b2 + kstep;
;             PG8_LDB(B0, 0, 0); PG8_LDB(B1, 0, 1); PG8_SCHED; PG8_LDA(At, 0, 0); PG8_STAGE(PG8_SA(1, 1), a1 + hstepA, voffA);
;             PG8_WAIT_V(8); PG8_WAIT_L(0); PG8_BAR; PG8_MMA(0, 0, At, B0); PG8_MMA(0, 1, At, B1); PG8_BAR; PG8_SCHED;
;             PG8_LDA(At, 0, 1); PG8_STAGE(PG8_SB(0, 0), b2, voffB); PG8_STAGE(PG8_SB(0, 1), b2 + hstepB, voffB); PG8_STAGE(PG8_SA(0, 0), a2, voffA);
.LBB0_494:
	s_add_u32 s31, s20, s30
	s_addc_u32 s38, s21, 0
	s_add_u32 s36, s31, 0x100
	s_addc_u32 s37, s38, 0
	s_and_b64 s[34:35], s[28:29], exec
	s_cselect_b32 s35, s15, s37
	s_cselect_b32 s34, s64, s36
	s_add_u32 s30, s18, s30
	s_addc_u32 s36, s19, 0
	s_add_u32 s30, s30, 0x100
	s_addc_u32 s36, s36, 0
	s_and_b64 s[28:29], s[28:29], exec
	s_cselect_b32 s37, s13, s36
	s_cselect_b32 s36, s65, s30
	s_add_u32 s40, s31, 0x10080
	ds_read_b128 v[142:145], v139
	ds_read_b128 v[146:149], v139 offset:1024
	ds_read_b128 v[150:153], v139 offset:2048
	ds_read_b128 v[154:157], v139 offset:3072
	ds_read_b128 v[158:161], v140
	ds_read_b128 v[162:165], v140 offset:1024
	ds_read_b128 v[166:169], v140 offset:2048
	ds_read_b128 v[170:173], v140 offset:3072
	s_addc_u32 s41, s38, 0
	s_add_i32 s77, s61, s47
	s_add_i32 m0, s49, 0xc000
	s_add_i32 s52, s49, 0xe000
	s_add_i32 s74, s77, 0x2000
	s_add_u32 s38, s36, 0x10000
	s_addc_u32 s39, s37, 0
	s_add_i32 s76, s62, s47
	s_add_i32 s75, s76, 0x2000
	s_add_i32 s73, 0, 0x18000
	s_add_i32 s72, 0, 0x1c000
	s_add_u32 s30, s34, 0x10000
	s_addc_u32 s31, s35, 0
	s_add_i32 s71, s73, s47
	s_add_i32 s66, s71, 0x2000
	s_add_u32 s28, s36, 0x10080
	s_addc_u32 s29, s37, 0
	s_add_i32 s79, s72, s47
	s_add_i32 s78, s79, 0x2000
	v_lshl_add_u64 v[206:207], s[40:41], 0, v[134:135]
	ds_read_b128 v[174:177], v141
	ds_read_b128 v[178:181], v141 offset:1024
	ds_read_b128 v[182:185], v141 offset:2048
	ds_read_b128 v[186:189], v141 offset:3072
	ds_read_b128 v[190:193], v141 offset:4096
	ds_read_b128 v[194:197], v141 offset:5120
	ds_read_b128 v[198:201], v141 offset:6144
	ds_read_b128 v[202:205], v141 offset:7168
	global_load_lds_dwordx4 v[206:207], off
	v_lshl_add_u64 v[206:207], s[40:41], 0, v[130:131]
	s_mov_b32 m0, s52
	s_nop 0
	global_load_lds_dwordx4 v[206:207], off
	s_waitcnt vmcnt(8)
	s_waitcnt lgkmcnt(0)
	s_barrier
	s_setprio 1
	s_waitcnt lgkmcnt(0)
	v_mfma_f32_16x16x32_bf16 v[124:127], v[142:145], v[174:177], v[124:127]
	v_mfma_f32_16x16x32_bf16 v[120:123], v[150:153], v[174:177], v[120:123]
	v_mfma_f32_16x16x32_bf16 v[116:119], v[142:145], v[182:185], v[116:119]
	v_mfma_f32_16x16x32_bf16 v[112:115], v[150:153], v[182:185], v[112:115]
	v_mfma_f32_16x16x32_bf16 v[100:103], v[142:145], v[190:193], v[100:103]
	v_mfma_f32_16x16x32_bf16 v[96:99], v[150:153], v[190:193], v[96:99]
	v_mfma_f32_16x16x32_bf16 v[84:87], v[142:145], v[198:201], v[84:87]
	v_mfma_f32_16x16x32_bf16 v[80:83], v[150:153], v[198:201], v[80:83]
	s_setprio 0
	s_setprio 1
	v_mfma_f32_16x16x32_bf16 v[124:127], v[146:149], v[178:181], v[124:127]
	v_mfma_f32_16x16x32_bf16 v[120:123], v[154:157], v[178:181], v[120:123]
	v_mfma_f32_16x16x32_bf16 v[116:119], v[146:149], v[186:189], v[116:119]
	v_mfma_f32_16x16x32_bf16 v[112:115], v[154:157], v[186:189], v[112:115]
	v_mfma_f32_16x16x32_bf16 v[100:103], v[146:149], v[194:197], v[100:103]
	v_mfma_f32_16x16x32_bf16 v[96:99], v[154:157], v[194:197], v[96:99]
	v_mfma_f32_16x16x32_bf16 v[84:87], v[146:149], v[202:205], v[84:87]
	v_mfma_f32_16x16x32_bf16 v[80:83], v[154:157], v[202:205], v[80:83]
	s_setprio 0
	s_setprio 1
	v_mfma_f32_16x16x32_bf16 v[108:111], v[158:161], v[174:177], v[108:111]
	v_mfma_f32_16x16x32_bf16 v[104:107], v[166:169], v[174:177], v[104:107]
	v_mfma_f32_16x16x32_bf16 v[92:95], v[158:161], v[182:185], v[92:95]
	v_mfma_f32_16x16x32_bf16 v[88:91], v[166:169], v[182:185], v[88:91]
	v_mfma_f32_16x16x32_bf16 v[76:79], v[158:161], v[190:193], v[76:79]
	v_mfma_f32_16x16x32_bf16 v[72:75], v[166:169], v[190:193], v[72:75]
	v_mfma_f32_16x16x32_bf16 v[68:71], v[158:161], v[198:201], v[68:71]
	v_mfma_f32_16x16x32_bf16 v[64:67], v[166:169], v[198:201], v[64:67]
	s_setprio 0
	s_setprio 1
	v_mfma_f32_16x16x32_bf16 v[108:111], v[162:165], v[178:181], v[108:111]
	v_mfma_f32_16x16x32_bf16 v[104:107], v[170:173], v[178:181], v[104:107]
	v_mfma_f32_16x16x32_bf16 v[92:95], v[162:165], v[186:189], v[92:95]
	v_mfma_f32_16x16x32_bf16 v[88:91], v[170:173], v[186:189], v[88:91]
	v_mfma_f32_16x16x32_bf16 v[76:79], v[162:165], v[194:197], v[76:79]
	v_mfma_f32_16x16x32_bf16 v[72:75], v[170:173], v[194:197], v[72:75]
	v_mfma_f32_16x16x32_bf16 v[68:71], v[162:165], v[202:205], v[68:71]
	v_mfma_f32_16x16x32_bf16 v[64:67], v[170:173], v[202:205], v[64:67]
	s_setprio 0
	s_barrier
	s_mov_b32 m0, s77
	v_lshl_add_u64 v[206:207], s[36:37], 0, v[132:133]
	ds_read_b128 v[174:177], v141 offset:16384
	ds_read_b128 v[178:181], v141 offset:17408
	ds_read_b128 v[182:185], v141 offset:18432
	ds_read_b128 v[186:189], v141 offset:19456
	ds_read_b128 v[190:193], v141 offset:20480
	ds_read_b128 v[194:197], v141 offset:21504
	ds_read_b128 v[198:201], v141 offset:22528
	ds_read_b128 v[202:205], v141 offset:23552
	global_load_lds_dwordx4 v[206:207], off
	v_lshl_add_u64 v[208:209], s[36:37], 0, v[128:129]
	s_mov_b32 m0, s74
	v_lshl_add_u64 v[210:211], s[38:39], 0, v[132:133]
	global_load_lds_dwordx4 v[208:209], off
	s_mov_b32 m0, s76
	v_lshl_add_u64 v[212:213], s[34:35], 0, v[130:131]
	global_load_lds_dwordx4 v[210:211], off
	v_lshl_add_u64 v[210:211], s[38:39], 0, v[128:129]
	s_mov_b32 m0, s75
	s_nop 0
	global_load_lds_dwordx4 v[210:211], off
	v_lshl_add_u64 v[210:211], s[34:35], 0, v[134:135]
	s_mov_b32 m0, s49
	s_nop 0
	global_load_lds_dwordx4 v[210:211], off
	s_mov_b32 m0, s50
	s_nop 0
	global_load_lds_dwordx4 v[212:213], off
	s_waitcnt vmcnt(8)
	s_waitcnt lgkmcnt(0)
	s_barrier
; #define PG8_STAGE(bufoff, gbase, voff) do { _Pragma("unroll") for (int _i = 0; _i < 2; ++_i) \
;         __builtin_amdgcn_global_load_lds((const unsigned*)((const char*)(gbase) + (voff)[_i]), (PG8_LAS unsigned*)(lds + (bufoff) + ldsw + _i * 8192), 16, 0, 0); } while (0)
; #define PG8_LDA(dst, b, h) do { _Pragma("unroll") for (int m = 0; m < 4; ++m) _Pragma("unroll") for (int k = 0; k < 2; ++k) dst[m][k] = *(const PG8_LAS bf16x8*)(lds + PG8_SA(b, h) + aoff + m * 2048 + k * 1024); } while (0)
; #define PG8_LDB(dst, b, h) do { _Pragma("unroll") for (int n = 0; n < 2; ++n) _Pragma("unroll") for (int k = 0; k < 2; ++k) dst[n][k] = *(const PG8_LAS bf16x8*)(lds + PG8_SB(b, h) + boff + n * 2048 + k * 1024); } while (0)
; #define PG8_MMA(ai, bj, At, Bt) do { __builtin_amdgcn_s_setprio(1); _Pragma("unroll") for (int m = 0; m < 4; ++m) _Pragma("unroll") for (int n = 0; n < 2; ++n) _Pragma("unroll") for (int k = 0; k < 2; ++k) \
;         acc[ai][bj][m][n] = __builtin_amdgcn_mfma_f32_16x16x32_bf16(Bt[n][k], At[m][k], acc[ai][bj][m][n], 0, 0, 0); __builtin_amdgcn_s_setprio(0); } while (0)
; #define PG8_WAIT_V(n) asm volatile("s_waitcnt vmcnt(" #n ")" ::: "memory")
; #define PG8_WAIT_L(n) asm volatile("s_waitcnt lgkmcnt(" #n ")" ::: "memory")
; #define PG8_BAR __builtin_amdgcn_s_barrier()
; #define PG8_SCHED __builtin_amdgcn_sched_barrier(0)
; template <class Epi, class Sched, bool ALIGN_EPI = true, bool SP2 = true>
; __device__ __forceinline__ void gemm_phase(PG8_LAS unsigned char* lds, const Gemm g, const Sched& S, const Epi& E) {
;     ...
;             PG8_WAIT_V(8); PG8_WAIT_L(0); PG8_BAR; PG8_MMA(1, 0, At, B0); PG8_MMA(1, 1, At, B1); PG8_BAR; PG8_SCHED;
;             PG8_LDB(B0, 1, 0); PG8_LDB(B1, 1, 1); PG8_SCHED; PG8_LDA(At, 1, 0); PG8_STAGE(PG8_SA(0, 1), a2 + hstepA, voffA);
;             PG8_WAIT_V(8); PG8_WAIT_L(0); PG8_BAR; PG8_MMA(0, 0, At, B0); PG8_MMA(0, 1, At, B1); PG8_BAR; PG8_SCHED;
	s_setprio 1
	s_waitcnt lgkmcnt(0)
	v_mfma_f32_16x16x32_bf16 v[60:63], v[142:145], v[174:177], v[60:63]
	v_mfma_f32_16x16x32_bf16 v[56:59], v[150:153], v[174:177], v[56:59]
	v_mfma_f32_16x16x32_bf16 v[52:55], v[142:145], v[182:185], v[52:55]
	v_mfma_f32_16x16x32_bf16 v[48:51], v[150:153], v[182:185], v[48:51]
	v_mfma_f32_16x16x32_bf16 v[36:39], v[142:145], v[190:193], v[36:39]
	v_mfma_f32_16x16x32_bf16 v[32:35], v[150:153], v[190:193], v[32:35]
	v_mfma_f32_16x16x32_bf16 v[20:23], v[142:145], v[198:201], v[20:23]
	v_mfma_f32_16x16x32_bf16 v[16:19], v[150:153], v[198:201], v[16:19]
	s_setprio 0
	s_setprio 1
	v_mfma_f32_16x16x32_bf16 v[60:63], v[146:149], v[178:181], v[60:63]
	v_mfma_f32_16x16x32_bf16 v[56:59], v[154:157], v[178:181], v[56:59]
	v_mfma_f32_16x16x32_bf16 v[52:55], v[146:149], v[186:189], v[52:55]
	v_mfma_f32_16x16x32_bf16 v[48:51], v[154:157], v[186:189], v[48:51]
	v_mfma_f32_16x16x32_bf16 v[36:39], v[146:149], v[194:197], v[36:39]
	v_mfma_f32_16x16x32_bf16 v[32:35], v[154:157], v[194:197], v[32:35]
	v_mfma_f32_16x16x32_bf16 v[20:23], v[146:149], v[202:205], v[20:23]
	v_mfma_f32_16x16x32_bf16 v[16:19], v[154:157], v[202:205], v[16:19]
	s_setprio 0
	s_setprio 1
	v_mfma_f32_16x16x32_bf16 v[44:47], v[158:161], v[174:177], v[44:47]
	v_mfma_f32_16x16x32_bf16 v[40:43], v[166:169], v[174:177], v[40:43]
	v_mfma_f32_16x16x32_bf16 v[28:31], v[158:161], v[182:185], v[28:31]
	v_mfma_f32_16x16x32_bf16 v[24:27], v[166:169], v[182:185], v[24:27]
	v_mfma_f32_16x16x32_bf16 v[12:15], v[158:161], v[190:193], v[12:15]
	v_mfma_f32_16x16x32_bf16 v[8:11], v[166:169], v[190:193], v[8:11]
	v_mfma_f32_16x16x32_bf16 v[4:7], v[158:161], v[198:201], v[4:7]
	v_mfma_f32_16x16x32_bf16 v[0:3], v[166:169], v[198:201], v[0:3]
	s_setprio 0
	s_setprio 1
	v_mfma_f32_16x16x32_bf16 v[44:47], v[162:165], v[178:181], v[44:47]
	v_mfma_f32_16x16x32_bf16 v[40:43], v[170:173], v[178:181], v[40:43]
	v_mfma_f32_16x16x32_bf16 v[28:31], v[162:165], v[186:189], v[28:31]
	v_mfma_f32_16x16x32_bf16 v[24:27], v[170:173], v[186:189], v[24:27]
	v_mfma_f32_16x16x32_bf16 v[12:15], v[162:165], v[194:197], v[12:15]
	v_mfma_f32_16x16x32_bf16 v[8:11], v[170:173], v[194:197], v[8:11]
	v_mfma_f32_16x16x32_bf16 v[4:7], v[162:165], v[202:205], v[4:7]
	v_mfma_f32_16x16x32_bf16 v[0:3], v[170:173], v[202:205], v[0:3]
	s_setprio 0
	s_barrier
	v_add_u32_e32 v154, s73, v137
	v_add_u32_e32 v170, s72, v137
	ds_read_b128 v[142:145], v154
	ds_read_b128 v[146:149], v154 offset:1024
	ds_read_b128 v[150:153], v154 offset:2048
	ds_read_b128 v[154:157], v154 offset:3072
	ds_read_b128 v[158:161], v170
	ds_read_b128 v[162:165], v170 offset:1024
	ds_read_b128 v[166:169], v170 offset:2048
	ds_read_b128 v[170:173], v170 offset:3072
	s_mov_b32 m0, s51
	v_lshl_add_u64 v[214:215], s[30:31], 0, v[134:135]
	ds_read_b128 v[174:177], v141 offset:32768
	ds_read_b128 v[178:181], v141 offset:33792
	ds_read_b128 v[182:185], v141 offset:34816
	ds_read_b128 v[186:189], v141 offset:35840
	ds_read_b128 v[190:193], v141 offset:36864
	ds_read_b128 v[194:197], v141 offset:37888
	ds_read_b128 v[198:201], v141 offset:38912
	ds_read_b128 v[202:205], v141 offset:39936
	global_load_lds_dwordx4 v[214:215], off
	v_lshl_add_u64 v[214:215], s[30:31], 0, v[130:131]
	s_mov_b32 m0, s55
	s_nop 0
	global_load_lds_dwordx4 v[214:215], off
	s_waitcnt vmcnt(8)
	s_waitcnt lgkmcnt(0)
	s_barrier
	s_setprio 1
	s_waitcnt lgkmcnt(0)
	v_mfma_f32_16x16x32_bf16 v[124:127], v[142:145], v[174:177], v[124:127]
	v_mfma_f32_16x16x32_bf16 v[120:123], v[150:153], v[174:177], v[120:123]
	v_mfma_f32_16x16x32_bf16 v[116:119], v[142:145], v[182:185], v[116:119]
	v_mfma_f32_16x16x32_bf16 v[112:115], v[150:153], v[182:185], v[112:115]
	v_mfma_f32_16x16x32_bf16 v[100:103], v[142:145], v[190:193], v[100:103]
	v_mfma_f32_16x16x32_bf16 v[96:99], v[150:153], v[190:193], v[96:99]
	v_mfma_f32_16x16x32_bf16 v[84:87], v[142:145], v[198:201], v[84:87]
	v_mfma_f32_16x16x32_bf16 v[80:83], v[150:153], v[198:201], v[80:83]
	s_setprio 0
	s_setprio 1
	v_mfma_f32_16x16x32_bf16 v[124:127], v[146:149], v[178:181], v[124:127]
	v_mfma_f32_16x16x32_bf16 v[120:123], v[154:157], v[178:181], v[120:123]
	v_mfma_f32_16x16x32_bf16 v[116:119], v[146:149], v[186:189], v[116:119]
	v_mfma_f32_16x16x32_bf16 v[112:115], v[154:157], v[186:189], v[112:115]
	v_mfma_f32_16x16x32_bf16 v[100:103], v[146:149], v[194:197], v[100:103]
	v_mfma_f32_16x16x32_bf16 v[96:99], v[154:157], v[194:197], v[96:99]
	v_mfma_f32_16x16x32_bf16 v[84:87], v[146:149], v[202:205], v[84:87]
	v_mfma_f32_16x16x32_bf16 v[80:83], v[154:157], v[202:205], v[80:83]
	s_setprio 0
	s_setprio 1
	v_mfma_f32_16x16x32_bf16 v[108:111], v[158:161], v[174:177], v[108:111]
	v_mfma_f32_16x16x32_bf16 v[104:107], v[166:169], v[174:177], v[104:107]
	v_mfma_f32_16x16x32_bf16 v[92:95], v[158:161], v[182:185], v[92:95]
	v_mfma_f32_16x16x32_bf16 v[88:91], v[166:169], v[182:185], v[88:91]
	v_mfma_f32_16x16x32_bf16 v[76:79], v[158:161], v[190:193], v[76:79]
	v_mfma_f32_16x16x32_bf16 v[72:75], v[166:169], v[190:193], v[72:75]
	v_mfma_f32_16x16x32_bf16 v[68:71], v[158:161], v[198:201], v[68:71]
	v_mfma_f32_16x16x32_bf16 v[64:67], v[166:169], v[198:201], v[64:67]
	s_setprio 0
	s_setprio 1
	v_mfma_f32_16x16x32_bf16 v[108:111], v[162:165], v[178:181], v[108:111]
	v_mfma_f32_16x16x32_bf16 v[104:107], v[170:173], v[178:181], v[104:107]
	v_mfma_f32_16x16x32_bf16 v[92:95], v[162:165], v[186:189], v[92:95]
	v_mfma_f32_16x16x32_bf16 v[88:91], v[170:173], v[186:189], v[88:91]
	v_mfma_f32_16x16x32_bf16 v[76:79], v[162:165], v[194:197], v[76:79]
	v_mfma_f32_16x16x32_bf16 v[72:75], v[170:173], v[194:197], v[72:75]
	v_mfma_f32_16x16x32_bf16 v[68:71], v[162:165], v[202:205], v[68:71]
	v_mfma_f32_16x16x32_bf16 v[64:67], v[170:173], v[202:205], v[64:67]
	s_setprio 0
	s_barrier
; #define PG8_STAGE(bufoff, gbase, voff) do { _Pragma("unroll") for (int _i = 0; _i < 2; ++_i) \
;         __builtin_amdgcn_global_load_lds((const unsigned*)((const char*)(gbase) + (voff)[_i]), (PG8_LAS unsigned*)(lds + (bufoff) + ldsw + _i * 8192), 16, 0, 0); } while (0)
; #define PG8_LDA(dst, b, h) do { _Pragma("unroll") for (int m = 0; m < 4; ++m) _Pragma("unroll") for (int k = 0; k < 2; ++k) dst[m][k] = *(const PG8_LAS bf16x8*)(lds + PG8_SA(b, h) + aoff + m * 2048 + k * 1024); } while (0)
; #define PG8_MMA(ai, bj, At, Bt) do { __builtin_amdgcn_s_setprio(1); _Pragma("unroll") for (int m = 0; m < 4; ++m) _Pragma("unroll") for (int n = 0; n < 2; ++n) _Pragma("unroll") for (int k = 0; k < 2; ++k) \
;         acc[ai][bj][m][n] = __builtin_amdgcn_mfma_f32_16x16x32_bf16(Bt[n][k], At[m][k], acc[ai][bj][m][n], 0, 0, 0); __builtin_amdgcn_s_setprio(0); } while (0)
; #define PG8_WAIT_V(n) asm volatile("s_waitcnt vmcnt(" #n ")" ::: "memory")
; #define PG8_WAIT_L(n) asm volatile("s_waitcnt lgkmcnt(" #n ")" ::: "memory")
; #define PG8_BAR __builtin_amdgcn_s_barrier()
; #define PG8_SCHED __builtin_amdgcn_sched_barrier(0)
; template <class Epi, class Sched, bool ALIGN_EPI = true, bool SP2 = true>
; __device__ __forceinline__ void gemm_phase(PG8_LAS unsigned char* lds, const Gemm g, const Sched& S, const Epi& E) {
;     ...
;             PG8_LDA(At, 1, 1); PG8_STAGE(PG8_SB(1, 0), b3, voffB); PG8_STAGE(PG8_SB(1, 1), b3 + hstepB, voffB); PG8_STAGE(PG8_SA(1, 0), a3, voffA);
;             PG8_WAIT_V(8); PG8_WAIT_L(0); PG8_BAR; PG8_MMA(1, 0, At, B0); PG8_MMA(1, 1, At, B1); PG8_BAR; PG8_SCHED;
;         }
;         if constexpr (ALIGN_EPI) { if (wr == 0) PG8_BAR; }
	s_mov_b32 m0, s71
	v_lshl_add_u64 v[206:207], v[206:207], 0, s[6:7]
	ds_read_b128 v[174:177], v141 offset:49152
	ds_read_b128 v[178:181], v141 offset:50176
	ds_read_b128 v[182:185], v141 offset:51200
	ds_read_b128 v[186:189], v141 offset:52224
	ds_read_b128 v[190:193], v141 offset:53248
	ds_read_b128 v[194:197], v141 offset:54272
	ds_read_b128 v[198:201], v141 offset:55296
	ds_read_b128 v[202:205], v141 offset:56320
	global_load_lds_dwordx4 v[206:207], off
	v_lshl_add_u64 v[206:207], v[208:209], 0, s[6:7]
	s_mov_b32 m0, s66
	s_nop 0
	global_load_lds_dwordx4 v[206:207], off
	v_lshl_add_u64 v[206:207], s[28:29], 0, v[132:133]
	s_mov_b32 m0, s79
	s_nop 0
	global_load_lds_dwordx4 v[206:207], off
	v_lshl_add_u64 v[206:207], s[28:29], 0, v[128:129]
	s_mov_b32 m0, s78
	s_nop 0
	global_load_lds_dwordx4 v[206:207], off
	v_lshl_add_u64 v[206:207], v[210:211], 0, s[6:7]
	s_mov_b32 m0, s56
	s_nop 0
	global_load_lds_dwordx4 v[206:207], off
	v_lshl_add_u64 v[206:207], v[212:213], 0, s[6:7]
	s_mov_b32 m0, s57
	s_nop 0
	global_load_lds_dwordx4 v[206:207], off
	s_waitcnt vmcnt(8)
	s_waitcnt lgkmcnt(0)
	s_barrier
	s_setprio 1
	s_waitcnt lgkmcnt(0)
	v_mfma_f32_16x16x32_bf16 v[60:63], v[142:145], v[174:177], v[60:63]
	v_mfma_f32_16x16x32_bf16 v[56:59], v[150:153], v[174:177], v[56:59]
	v_mfma_f32_16x16x32_bf16 v[52:55], v[142:145], v[182:185], v[52:55]
	v_mfma_f32_16x16x32_bf16 v[48:51], v[150:153], v[182:185], v[48:51]
	v_mfma_f32_16x16x32_bf16 v[36:39], v[142:145], v[190:193], v[36:39]
	v_mfma_f32_16x16x32_bf16 v[32:35], v[150:153], v[190:193], v[32:35]
	v_mfma_f32_16x16x32_bf16 v[20:23], v[142:145], v[198:201], v[20:23]
	v_mfma_f32_16x16x32_bf16 v[16:19], v[150:153], v[198:201], v[16:19]
	s_setprio 0
	s_setprio 1
	v_mfma_f32_16x16x32_bf16 v[60:63], v[146:149], v[178:181], v[60:63]
	v_mfma_f32_16x16x32_bf16 v[56:59], v[154:157], v[178:181], v[56:59]
	v_mfma_f32_16x16x32_bf16 v[52:55], v[146:149], v[186:189], v[52:55]
	v_mfma_f32_16x16x32_bf16 v[48:51], v[154:157], v[186:189], v[48:51]
	v_mfma_f32_16x16x32_bf16 v[36:39], v[146:149], v[194:197], v[36:39]
	v_mfma_f32_16x16x32_bf16 v[32:35], v[154:157], v[194:197], v[32:35]
	v_mfma_f32_16x16x32_bf16 v[20:23], v[146:149], v[202:205], v[20:23]
	v_mfma_f32_16x16x32_bf16 v[16:19], v[154:157], v[202:205], v[16:19]
	s_setprio 0
	s_setprio 1
	v_mfma_f32_16x16x32_bf16 v[44:47], v[158:161], v[174:177], v[44:47]
	v_mfma_f32_16x16x32_bf16 v[40:43], v[166:169], v[174:177], v[40:43]
	v_mfma_f32_16x16x32_bf16 v[28:31], v[158:161], v[182:185], v[28:31]
	v_mfma_f32_16x16x32_bf16 v[24:27], v[166:169], v[182:185], v[24:27]
	v_mfma_f32_16x16x32_bf16 v[12:15], v[158:161], v[190:193], v[12:15]
	v_mfma_f32_16x16x32_bf16 v[8:11], v[166:169], v[190:193], v[8:11]
	v_mfma_f32_16x16x32_bf16 v[4:7], v[158:161], v[198:201], v[4:7]
	v_mfma_f32_16x16x32_bf16 v[0:3], v[166:169], v[198:201], v[0:3]
	s_setprio 0
	s_setprio 1
	v_mfma_f32_16x16x32_bf16 v[44:47], v[162:165], v[178:181], v[44:47]
	v_mfma_f32_16x16x32_bf16 v[40:43], v[170:173], v[178:181], v[40:43]
	v_mfma_f32_16x16x32_bf16 v[28:31], v[162:165], v[186:189], v[28:31]
	v_mfma_f32_16x16x32_bf16 v[24:27], v[170:173], v[186:189], v[24:27]
	v_mfma_f32_16x16x32_bf16 v[12:15], v[162:165], v[194:197], v[12:15]
	v_mfma_f32_16x16x32_bf16 v[8:11], v[170:173], v[194:197], v[8:11]
	v_mfma_f32_16x16x32_bf16 v[4:7], v[162:165], v[202:205], v[4:7]
	v_mfma_f32_16x16x32_bf16 v[0:3], v[170:173], v[202:205], v[0:3]
	s_setprio 0
	s_barrier
	s_movk_i32 s30, 0x100
	s_andn2_b64 vcc, exec, s[26:27]
	s_mov_b64 s[28:29], -1
	s_mov_b64 s[26:27], 0
	s_cbranch_vccz .LBB0_494
	s_and_b64 vcc, exec, s[8:9]
	s_cbranch_vccz .LBB0_497
	s_barrier

; #define PG8_STAGE(bufoff, gbase, voff) do { _Pragma("unroll") for (int _i = 0; _i < 2; ++_i) \
;         __builtin_amdgcn_global_load_lds((const unsigned*)((const char*)(gbase) + (voff)[_i]), (PG8_LAS unsigned*)(lds + (bufoff) + ldsw + _i * 8192), 16, 0, 0); } while (0)
; #define PG8_LDA(dst, b, h) do { _Pragma("unroll") for (int m = 0; m < 4; ++m) _Pragma("unroll") for (int k = 0; k < 2; ++k) dst[m][k] = *(const PG8_LAS bf16x8*)(lds + PG8_SA(b, h) + aoff + m * 2048 + k * 1024); } while (0)
; #define PG8_LDB(dst, b, h) do { _Pragma("unroll") for (int n = 0; n < 2; ++n) _Pragma("unroll") for (int k = 0; k < 2; ++k) dst[n][k] = *(const PG8_LAS bf16x8*)(lds + PG8_SB(b, h) + boff + n * 2048 + k * 1024); } while (0)
; #define PG8_MMA(ai, bj, At, Bt) do { __builtin_amdgcn_s_setprio(1); _Pragma("unroll") for (int m = 0; m < 4; ++m) _Pragma("unroll") for (int n = 0; n < 2; ++n) _Pragma("unroll") for (int k = 0; k < 2; ++k) \
;         acc[ai][bj][m][n] = __builtin_amdgcn_mfma_f32_16x16x32_bf16(Bt[n][k], At[m][k], acc[ai][bj][m][n], 0, 0, 0); __builtin_amdgcn_s_setprio(0); } while (0)
; #define PG8_WAIT_V(n) asm volatile("s_waitcnt vmcnt(" #n ")" ::: "memory")
; #define PG8_BAR __builtin_amdgcn_s_barrier()
; template <class Epi, class Sched, bool ALIGN_EPI = true, bool SP2 = true>
; __device__ __forceinline__ void gemm_phase(PG8_LAS unsigned char* lds, const Gemm g, const Sched& S, const Epi& E) {
;     ...
;         const bool has_next = S.next(ui + 1, nxt);
;         const char* nA = has_next ? (const char*)g.A + (size_t)nxt.pm * tstepA : cA; const char* nB = has_next ? (const char*)g.Bt + (size_t)nxt.pn * tstepB : cB;
;         for (int t = 0; t < nt; t += 2) {
;             const bool last = (t == nt - 2);
;             const char* a1 = cA + (size_t)(t + 1) * kstep;
;             const char* a2 = last ? nA : cA + (size_t)(t + 2) * kstep; const char* b2 = last ? nB : cB + (size_t)(t + 2) * kstep;
;             const char* a3 = a2 + kstep; const char* b3 = b2 + kstep;
;             PG8_LDB(B0, 0, 0); PG8_LDB(B1, 0, 1); PG8_SCHED; PG8_LDA(At, 0, 0); PG8_STAGE(PG8_SA(1, 1), a1 + hstepA, voffA);
;             PG8_WAIT_V(8); PG8_WAIT_L(0); PG8_BAR; PG8_MMA(0, 0, At, B0); PG8_MMA(0, 1, At, B1); PG8_BAR; PG8_SCHED;
;             PG8_LDA(At, 0, 1); PG8_STAGE(PG8_SB(0, 0), b2, voffB); PG8_STAGE(PG8_SB(0, 1), b2 + hstepB, voffB); PG8_STAGE(PG8_SA(0, 0), a2, voffA);
.LBB0_994:
	ds_read_b128 v[144:147], v151
	ds_read_b128 v[154:157], v151 offset:1024
	ds_read_b128 v[158:161], v151 offset:2048
	ds_read_b128 v[162:165], v151 offset:3072
	ds_read_b128 v[166:169], v152
	ds_read_b128 v[170:173], v152 offset:1024
	ds_read_b128 v[174:177], v152 offset:2048
	ds_read_b128 v[178:181], v152 offset:3072
	s_add_u32 s38, s36, 0xfffc0080
	s_addc_u32 s39, s37, -1
	s_cmp_eq_u32 s65, 12
	s_cselect_b32 s41, s25, s39
	s_cselect_b32 s40, s61, s38
	s_cselect_b32 s39, s23, s64
	s_cselect_b32 s38, s62, s63
	v_lshl_add_u64 v[214:215], s[36:37], 0, v[138:139]
	s_add_i32 m0, s31, 0xc000
	ds_read_b128 v[182:185], v153
	ds_read_b128 v[186:189], v153 offset:1024
	ds_read_b128 v[190:193], v153 offset:2048
	ds_read_b128 v[194:197], v153 offset:3072
	ds_read_b128 v[198:201], v153 offset:4096
	ds_read_b128 v[202:205], v153 offset:5120
	ds_read_b128 v[206:209], v153 offset:6144
	ds_read_b128 v[210:213], v153 offset:7168
	global_load_lds_dwordx4 v[214:215], off
	v_lshl_add_u64 v[214:215], s[36:37], 0, v[136:137]
	s_add_i32 m0, s31, 0xe000
	s_nop 0
	global_load_lds_dwordx4 v[214:215], off
	s_waitcnt vmcnt(8)
	s_waitcnt lgkmcnt(0)
	s_barrier
	s_setprio 1
	s_waitcnt lgkmcnt(0)
	v_mfma_f32_16x16x32_bf16 v[124:127], v[144:147], v[182:185], v[124:127]
	v_mfma_f32_16x16x32_bf16 v[120:123], v[158:161], v[182:185], v[120:123]
	v_mfma_f32_16x16x32_bf16 v[116:119], v[144:147], v[190:193], v[116:119]
	v_mfma_f32_16x16x32_bf16 v[104:107], v[158:161], v[190:193], v[104:107]
	v_mfma_f32_16x16x32_bf16 v[100:103], v[144:147], v[198:201], v[100:103]
	v_mfma_f32_16x16x32_bf16 v[88:91], v[158:161], v[198:201], v[88:91]
	v_mfma_f32_16x16x32_bf16 v[84:87], v[144:147], v[206:209], v[84:87]
	v_mfma_f32_16x16x32_bf16 v[72:75], v[158:161], v[206:209], v[72:75]
	s_setprio 0
	s_setprio 1
	v_mfma_f32_16x16x32_bf16 v[124:127], v[154:157], v[186:189], v[124:127]
	v_mfma_f32_16x16x32_bf16 v[120:123], v[162:165], v[186:189], v[120:123]
	v_mfma_f32_16x16x32_bf16 v[116:119], v[154:157], v[194:197], v[116:119]
	v_mfma_f32_16x16x32_bf16 v[104:107], v[162:165], v[194:197], v[104:107]
	v_mfma_f32_16x16x32_bf16 v[100:103], v[154:157], v[202:205], v[100:103]
	v_mfma_f32_16x16x32_bf16 v[88:91], v[162:165], v[202:205], v[88:91]
	v_mfma_f32_16x16x32_bf16 v[84:87], v[154:157], v[210:213], v[84:87]
	v_mfma_f32_16x16x32_bf16 v[72:75], v[162:165], v[210:213], v[72:75]
	s_setprio 0
	s_setprio 1
	v_mfma_f32_16x16x32_bf16 v[112:115], v[166:169], v[182:185], v[112:115]
	v_mfma_f32_16x16x32_bf16 v[108:111], v[174:177], v[182:185], v[108:111]
	v_mfma_f32_16x16x32_bf16 v[96:99], v[166:169], v[190:193], v[96:99]
	v_mfma_f32_16x16x32_bf16 v[92:95], v[174:177], v[190:193], v[92:95]
	v_mfma_f32_16x16x32_bf16 v[80:83], v[166:169], v[198:201], v[80:83]
	v_mfma_f32_16x16x32_bf16 v[76:79], v[174:177], v[198:201], v[76:79]
	v_mfma_f32_16x16x32_bf16 v[68:71], v[166:169], v[206:209], v[68:71]
	v_mfma_f32_16x16x32_bf16 v[64:67], v[174:177], v[206:209], v[64:67]
	s_setprio 0
	s_setprio 1
	v_mfma_f32_16x16x32_bf16 v[112:115], v[170:173], v[186:189], v[112:115]
	v_mfma_f32_16x16x32_bf16 v[108:111], v[178:181], v[186:189], v[108:111]
	v_mfma_f32_16x16x32_bf16 v[96:99], v[170:173], v[194:197], v[96:99]
	v_mfma_f32_16x16x32_bf16 v[92:95], v[178:181], v[194:197], v[92:95]
	v_mfma_f32_16x16x32_bf16 v[80:83], v[170:173], v[202:205], v[80:83]
	v_mfma_f32_16x16x32_bf16 v[76:79], v[178:181], v[202:205], v[76:79]
	v_mfma_f32_16x16x32_bf16 v[68:71], v[170:173], v[210:213], v[68:71]
	v_mfma_f32_16x16x32_bf16 v[64:67], v[178:181], v[210:213], v[64:67]
	s_setprio 0
	s_barrier
	s_add_i32 s52, s58, s47
	v_lshl_add_u64 v[214:215], s[38:39], 0, v[130:131]
	s_mov_b32 m0, s52
	ds_read_b128 v[182:185], v153 offset:16384
	ds_read_b128 v[186:189], v153 offset:17408
	ds_read_b128 v[190:193], v153 offset:18432
	ds_read_b128 v[194:197], v153 offset:19456
	ds_read_b128 v[198:201], v153 offset:20480
	ds_read_b128 v[202:205], v153 offset:21504
	ds_read_b128 v[206:209], v153 offset:22528
	ds_read_b128 v[210:213], v153 offset:23552
	global_load_lds_dwordx4 v[214:215], off
	s_add_i32 m0, s52, 0x2000
	s_add_u32 s52, s38, 0x40000
	v_lshl_add_u64 v[216:217], s[38:39], 0, v[134:135]
	s_addc_u32 s53, s39, 0
	s_add_i32 s66, s59, s47
	global_load_lds_dwordx4 v[216:217], off
	v_lshl_add_u64 v[218:219], s[52:53], 0, v[130:131]
	s_mov_b32 m0, s66
	v_lshl_add_u64 v[220:221], s[40:41], 0, v[132:133]
	global_load_lds_dwordx4 v[218:219], off
	v_lshl_add_u64 v[218:219], s[52:53], 0, v[134:135]
	s_add_i32 m0, s66, 0x2000
	s_nop 0
	global_load_lds_dwordx4 v[218:219], off
	v_lshl_add_u64 v[218:219], s[40:41], 0, v[128:129]
	s_mov_b32 m0, s31
	s_nop 0
	global_load_lds_dwordx4 v[218:219], off
	s_mov_b32 m0, s48
	s_nop 0
	global_load_lds_dwordx4 v[220:221], off
	s_waitcnt vmcnt(8)
	s_waitcnt lgkmcnt(0)
	s_barrier
; #define PG8_STAGE(bufoff, gbase, voff) do { _Pragma("unroll") for (int _i = 0; _i < 2; ++_i) \
;         __builtin_amdgcn_global_load_lds((const unsigned*)((const char*)(gbase) + (voff)[_i]), (PG8_LAS unsigned*)(lds + (bufoff) + ldsw + _i * 8192), 16, 0, 0); } while (0)
; #define PG8_LDA(dst, b, h) do { _Pragma("unroll") for (int m = 0; m < 4; ++m) _Pragma("unroll") for (int k = 0; k < 2; ++k) dst[m][k] = *(const PG8_LAS bf16x8*)(lds + PG8_SA(b, h) + aoff + m * 2048 + k * 1024); } while (0)
; #define PG8_LDB(dst, b, h) do { _Pragma("unroll") for (int n = 0; n < 2; ++n) _Pragma("unroll") for (int k = 0; k < 2; ++k) dst[n][k] = *(const PG8_LAS bf16x8*)(lds + PG8_SB(b, h) + boff + n * 2048 + k * 1024); } while (0)
; #define PG8_MMA(ai, bj, At, Bt) do { __builtin_amdgcn_s_setprio(1); _Pragma("unroll") for (int m = 0; m < 4; ++m) _Pragma("unroll") for (int n = 0; n < 2; ++n) _Pragma("unroll") for (int k = 0; k < 2; ++k) \
;         acc[ai][bj][m][n] = __builtin_amdgcn_mfma_f32_16x16x32_bf16(Bt[n][k], At[m][k], acc[ai][bj][m][n], 0, 0, 0); __builtin_amdgcn_s_setprio(0); } while (0)
; #define PG8_WAIT_V(n) asm volatile("s_waitcnt vmcnt(" #n ")" ::: "memory")
; #define PG8_WAIT_L(n) asm volatile("s_waitcnt lgkmcnt(" #n ")" ::: "memory")
; #define PG8_BAR __builtin_amdgcn_s_barrier()
; #define PG8_SCHED __builtin_amdgcn_sched_barrier(0)
; template <class Epi, class Sched, bool ALIGN_EPI = true, bool SP2 = true>
; __device__ __forceinline__ void gemm_phase(PG8_LAS unsigned char* lds, const Gemm g, const Sched& S, const Epi& E) {
;     ...
;             PG8_WAIT_V(8); PG8_WAIT_L(0); PG8_BAR; PG8_MMA(1, 0, At, B0); PG8_MMA(1, 1, At, B1); PG8_BAR; PG8_SCHED;
;             PG8_LDB(B0, 1, 0); PG8_LDB(B1, 1, 1); PG8_SCHED; PG8_LDA(At, 1, 0); PG8_STAGE(PG8_SA(0, 1), a2 + hstepA, voffA);
;             PG8_WAIT_V(8); PG8_WAIT_L(0); PG8_BAR; PG8_MMA(0, 0, At, B0); PG8_MMA(0, 1, At, B1); PG8_BAR; PG8_SCHED;
	s_setprio 1
	s_waitcnt lgkmcnt(0)
	v_mfma_f32_16x16x32_bf16 v[60:63], v[144:147], v[182:185], v[60:63]
	v_mfma_f32_16x16x32_bf16 v[56:59], v[158:161], v[182:185], v[56:59]
	v_mfma_f32_16x16x32_bf16 v[52:55], v[144:147], v[190:193], v[52:55]
	v_mfma_f32_16x16x32_bf16 v[40:43], v[158:161], v[190:193], v[40:43]
	v_mfma_f32_16x16x32_bf16 v[36:39], v[144:147], v[198:201], v[36:39]
	v_mfma_f32_16x16x32_bf16 v[24:27], v[158:161], v[198:201], v[24:27]
	v_mfma_f32_16x16x32_bf16 v[20:23], v[144:147], v[206:209], v[20:23]
	v_mfma_f32_16x16x32_bf16 v[8:11], v[158:161], v[206:209], v[8:11]
	s_setprio 0
	s_setprio 1
	v_mfma_f32_16x16x32_bf16 v[60:63], v[154:157], v[186:189], v[60:63]
	v_mfma_f32_16x16x32_bf16 v[56:59], v[162:165], v[186:189], v[56:59]
	v_mfma_f32_16x16x32_bf16 v[52:55], v[154:157], v[194:197], v[52:55]
	v_mfma_f32_16x16x32_bf16 v[40:43], v[162:165], v[194:197], v[40:43]
	v_mfma_f32_16x16x32_bf16 v[36:39], v[154:157], v[202:205], v[36:39]
	v_mfma_f32_16x16x32_bf16 v[24:27], v[162:165], v[202:205], v[24:27]
	v_mfma_f32_16x16x32_bf16 v[20:23], v[154:157], v[210:213], v[20:23]
	v_mfma_f32_16x16x32_bf16 v[8:11], v[162:165], v[210:213], v[8:11]
	s_setprio 0
	s_setprio 1
	v_mfma_f32_16x16x32_bf16 v[48:51], v[166:169], v[182:185], v[48:51]
	v_mfma_f32_16x16x32_bf16 v[44:47], v[174:177], v[182:185], v[44:47]
	v_mfma_f32_16x16x32_bf16 v[32:35], v[166:169], v[190:193], v[32:35]
	v_mfma_f32_16x16x32_bf16 v[28:31], v[174:177], v[190:193], v[28:31]
	v_mfma_f32_16x16x32_bf16 v[16:19], v[166:169], v[198:201], v[16:19]
	v_mfma_f32_16x16x32_bf16 v[12:15], v[174:177], v[198:201], v[12:15]
	v_mfma_f32_16x16x32_bf16 v[4:7], v[166:169], v[206:209], v[4:7]
	v_mfma_f32_16x16x32_bf16 v[0:3], v[174:177], v[206:209], v[0:3]
	s_setprio 0
	s_setprio 1
	v_mfma_f32_16x16x32_bf16 v[48:51], v[170:173], v[186:189], v[48:51]
	v_mfma_f32_16x16x32_bf16 v[44:47], v[178:181], v[186:189], v[44:47]
	v_mfma_f32_16x16x32_bf16 v[32:35], v[170:173], v[194:197], v[32:35]
	v_mfma_f32_16x16x32_bf16 v[28:31], v[178:181], v[194:197], v[28:31]
	v_mfma_f32_16x16x32_bf16 v[16:19], v[170:173], v[202:205], v[16:19]
	v_mfma_f32_16x16x32_bf16 v[12:15], v[178:181], v[202:205], v[12:15]
	v_mfma_f32_16x16x32_bf16 v[4:7], v[170:173], v[210:213], v[4:7]
	v_mfma_f32_16x16x32_bf16 v[0:3], v[178:181], v[210:213], v[0:3]
	s_setprio 0
	s_barrier
	s_add_i32 s52, 0, 0x18000
	s_add_i32 s53, 0, 0x1c000
	v_add_u32_e32 v162, s52, v149
	v_add_u32_e32 v178, s53, v149
	ds_read_b128 v[144:147], v162
	ds_read_b128 v[154:157], v162 offset:1024
	ds_read_b128 v[158:161], v162 offset:2048
	ds_read_b128 v[162:165], v162 offset:3072
	ds_read_b128 v[166:169], v178
	ds_read_b128 v[170:173], v178 offset:1024
	ds_read_b128 v[174:177], v178 offset:2048
	ds_read_b128 v[178:181], v178 offset:3072
	s_add_u32 s40, s40, 0x40000
	s_addc_u32 s41, s41, 0
	s_mov_b32 m0, s49
	v_lshl_add_u64 v[222:223], s[40:41], 0, v[128:129]
	ds_read_b128 v[182:185], v153 offset:32768
	ds_read_b128 v[186:189], v153 offset:33792
	ds_read_b128 v[190:193], v153 offset:34816
	ds_read_b128 v[194:197], v153 offset:35840
	ds_read_b128 v[198:201], v153 offset:36864
	ds_read_b128 v[202:205], v153 offset:37888
	ds_read_b128 v[206:209], v153 offset:38912
	ds_read_b128 v[210:213], v153 offset:39936
	global_load_lds_dwordx4 v[222:223], off
	v_lshl_add_u64 v[222:223], s[40:41], 0, v[132:133]
	s_mov_b32 m0, s50
	s_nop 0
	global_load_lds_dwordx4 v[222:223], off
	s_waitcnt vmcnt(8)
	s_waitcnt lgkmcnt(0)
	s_barrier
	s_setprio 1
	s_waitcnt lgkmcnt(0)
	v_mfma_f32_16x16x32_bf16 v[124:127], v[144:147], v[182:185], v[124:127]
	v_mfma_f32_16x16x32_bf16 v[120:123], v[158:161], v[182:185], v[120:123]
	v_mfma_f32_16x16x32_bf16 v[116:119], v[144:147], v[190:193], v[116:119]
	v_mfma_f32_16x16x32_bf16 v[104:107], v[158:161], v[190:193], v[104:107]
	v_mfma_f32_16x16x32_bf16 v[100:103], v[144:147], v[198:201], v[100:103]
	v_mfma_f32_16x16x32_bf16 v[88:91], v[158:161], v[198:201], v[88:91]
	v_mfma_f32_16x16x32_bf16 v[84:87], v[144:147], v[206:209], v[84:87]
	v_mfma_f32_16x16x32_bf16 v[72:75], v[158:161], v[206:209], v[72:75]
	s_setprio 0
	s_setprio 1
	v_mfma_f32_16x16x32_bf16 v[124:127], v[154:157], v[186:189], v[124:127]
	v_mfma_f32_16x16x32_bf16 v[120:123], v[162:165], v[186:189], v[120:123]
	v_mfma_f32_16x16x32_bf16 v[116:119], v[154:157], v[194:197], v[116:119]
	v_mfma_f32_16x16x32_bf16 v[104:107], v[162:165], v[194:197], v[104:107]
	v_mfma_f32_16x16x32_bf16 v[100:103], v[154:157], v[202:205], v[100:103]
	v_mfma_f32_16x16x32_bf16 v[88:91], v[162:165], v[202:205], v[88:91]
	v_mfma_f32_16x16x32_bf16 v[84:87], v[154:157], v[210:213], v[84:87]
	v_mfma_f32_16x16x32_bf16 v[72:75], v[162:165], v[210:213], v[72:75]
	s_setprio 0
	s_setprio 1
	v_mfma_f32_16x16x32_bf16 v[112:115], v[166:169], v[182:185], v[112:115]
	v_mfma_f32_16x16x32_bf16 v[108:111], v[174:177], v[182:185], v[108:111]
	v_mfma_f32_16x16x32_bf16 v[96:99], v[166:169], v[190:193], v[96:99]
	v_mfma_f32_16x16x32_bf16 v[92:95], v[174:177], v[190:193], v[92:95]
	v_mfma_f32_16x16x32_bf16 v[80:83], v[166:169], v[198:201], v[80:83]
	v_mfma_f32_16x16x32_bf16 v[76:79], v[174:177], v[198:201], v[76:79]
	v_mfma_f32_16x16x32_bf16 v[68:71], v[166:169], v[206:209], v[68:71]
	v_mfma_f32_16x16x32_bf16 v[64:67], v[174:177], v[206:209], v[64:67]
	s_setprio 0
	s_setprio 1
	v_mfma_f32_16x16x32_bf16 v[112:115], v[170:173], v[186:189], v[112:115]
	v_mfma_f32_16x16x32_bf16 v[108:111], v[178:181], v[186:189], v[108:111]
	v_mfma_f32_16x16x32_bf16 v[96:99], v[170:173], v[194:197], v[96:99]
	v_mfma_f32_16x16x32_bf16 v[92:95], v[178:181], v[194:197], v[92:95]
	v_mfma_f32_16x16x32_bf16 v[80:83], v[170:173], v[202:205], v[80:83]
	v_mfma_f32_16x16x32_bf16 v[76:79], v[178:181], v[202:205], v[76:79]
	v_mfma_f32_16x16x32_bf16 v[68:71], v[170:173], v[210:213], v[68:71]
	v_mfma_f32_16x16x32_bf16 v[64:67], v[178:181], v[210:213], v[64:67]
	s_setprio 0
	s_barrier
; #define PG8_STAGE(bufoff, gbase, voff) do { _Pragma("unroll") for (int _i = 0; _i < 2; ++_i) \
;         __builtin_amdgcn_global_load_lds((const unsigned*)((const char*)(gbase) + (voff)[_i]), (PG8_LAS unsigned*)(lds + (bufoff) + ldsw + _i * 8192), 16, 0, 0); } while (0)
; #define PG8_LDA(dst, b, h) do { _Pragma("unroll") for (int m = 0; m < 4; ++m) _Pragma("unroll") for (int k = 0; k < 2; ++k) dst[m][k] = *(const PG8_LAS bf16x8*)(lds + PG8_SA(b, h) + aoff + m * 2048 + k * 1024); } while (0)
; #define PG8_MMA(ai, bj, At, Bt) do { __builtin_amdgcn_s_setprio(1); _Pragma("unroll") for (int m = 0; m < 4; ++m) _Pragma("unroll") for (int n = 0; n < 2; ++n) _Pragma("unroll") for (int k = 0; k < 2; ++k) \
;         acc[ai][bj][m][n] = __builtin_amdgcn_mfma_f32_16x16x32_bf16(Bt[n][k], At[m][k], acc[ai][bj][m][n], 0, 0, 0); __builtin_amdgcn_s_setprio(0); } while (0)
; #define PG8_WAIT_V(n) asm volatile("s_waitcnt vmcnt(" #n ")" ::: "memory")
; #define PG8_WAIT_L(n) asm volatile("s_waitcnt lgkmcnt(" #n ")" ::: "memory")
; #define PG8_BAR __builtin_amdgcn_s_barrier()
; #define PG8_SCHED __builtin_amdgcn_sched_barrier(0)
; template <class Epi, class Sched, bool ALIGN_EPI = true, bool SP2 = true>
; __device__ __forceinline__ void gemm_phase(PG8_LAS unsigned char* lds, const Gemm g, const Sched& S, const Epi& E) {
;     ...
;             PG8_LDA(At, 1, 1); PG8_STAGE(PG8_SB(1, 0), b3, voffB); PG8_STAGE(PG8_SB(1, 1), b3 + hstepB, voffB); PG8_STAGE(PG8_SA(1, 0), a3, voffA);
;             PG8_WAIT_V(8); PG8_WAIT_L(0); PG8_BAR; PG8_MMA(1, 0, At, B0); PG8_MMA(1, 1, At, B1); PG8_BAR; PG8_SCHED;
;         }
;         if constexpr (ALIGN_EPI) { if (wr == 0) PG8_BAR; }
	s_add_i32 s40, s52, s47
	v_lshl_add_u64 v[214:215], v[214:215], 0, s[10:11]
	s_mov_b32 m0, s40
	ds_read_b128 v[182:185], v153 offset:49152
	ds_read_b128 v[186:189], v153 offset:50176
	ds_read_b128 v[190:193], v153 offset:51200
	ds_read_b128 v[194:197], v153 offset:52224
	ds_read_b128 v[198:201], v153 offset:53248
	ds_read_b128 v[202:205], v153 offset:54272
	ds_read_b128 v[206:209], v153 offset:55296
	ds_read_b128 v[210:213], v153 offset:56320
	global_load_lds_dwordx4 v[214:215], off
	s_add_i32 m0, s40, 0x2000
	s_add_u32 s38, s38, 0x40080
	v_lshl_add_u64 v[214:215], v[216:217], 0, s[10:11]
	s_addc_u32 s39, s39, 0
	s_add_i32 s40, s53, s47
	global_load_lds_dwordx4 v[214:215], off
	v_lshl_add_u64 v[214:215], s[38:39], 0, v[130:131]
	s_mov_b32 m0, s40
	s_nop 0
	global_load_lds_dwordx4 v[214:215], off
	v_lshl_add_u64 v[214:215], s[38:39], 0, v[134:135]
	s_add_i32 m0, s40, 0x2000
	s_nop 0
	global_load_lds_dwordx4 v[214:215], off
	v_lshl_add_u64 v[214:215], v[218:219], 0, s[10:11]
	s_mov_b32 m0, s54
	s_nop 0
	global_load_lds_dwordx4 v[214:215], off
	v_lshl_add_u64 v[214:215], v[220:221], 0, s[10:11]
	s_mov_b32 m0, s55
	s_nop 0
	global_load_lds_dwordx4 v[214:215], off
	s_waitcnt vmcnt(8)
	s_waitcnt lgkmcnt(0)
	s_barrier
	s_setprio 1
	s_waitcnt lgkmcnt(0)
	v_mfma_f32_16x16x32_bf16 v[60:63], v[144:147], v[182:185], v[60:63]
	v_mfma_f32_16x16x32_bf16 v[56:59], v[158:161], v[182:185], v[56:59]
	v_mfma_f32_16x16x32_bf16 v[52:55], v[144:147], v[190:193], v[52:55]
	v_mfma_f32_16x16x32_bf16 v[40:43], v[158:161], v[190:193], v[40:43]
	v_mfma_f32_16x16x32_bf16 v[36:39], v[144:147], v[198:201], v[36:39]
	v_mfma_f32_16x16x32_bf16 v[24:27], v[158:161], v[198:201], v[24:27]
	v_mfma_f32_16x16x32_bf16 v[20:23], v[144:147], v[206:209], v[20:23]
	v_mfma_f32_16x16x32_bf16 v[8:11], v[158:161], v[206:209], v[8:11]
	s_setprio 0
	s_setprio 1
	v_mfma_f32_16x16x32_bf16 v[60:63], v[154:157], v[186:189], v[60:63]
	v_mfma_f32_16x16x32_bf16 v[56:59], v[162:165], v[186:189], v[56:59]
	v_mfma_f32_16x16x32_bf16 v[52:55], v[154:157], v[194:197], v[52:55]
	v_mfma_f32_16x16x32_bf16 v[40:43], v[162:165], v[194:197], v[40:43]
	v_mfma_f32_16x16x32_bf16 v[36:39], v[154:157], v[202:205], v[36:39]
	v_mfma_f32_16x16x32_bf16 v[24:27], v[162:165], v[202:205], v[24:27]
	v_mfma_f32_16x16x32_bf16 v[20:23], v[154:157], v[210:213], v[20:23]
	v_mfma_f32_16x16x32_bf16 v[8:11], v[162:165], v[210:213], v[8:11]
	s_setprio 0
	s_setprio 1
	v_mfma_f32_16x16x32_bf16 v[48:51], v[166:169], v[182:185], v[48:51]
	v_mfma_f32_16x16x32_bf16 v[44:47], v[174:177], v[182:185], v[44:47]
	v_mfma_f32_16x16x32_bf16 v[32:35], v[166:169], v[190:193], v[32:35]
	v_mfma_f32_16x16x32_bf16 v[28:31], v[174:177], v[190:193], v[28:31]
	v_mfma_f32_16x16x32_bf16 v[16:19], v[166:169], v[198:201], v[16:19]
	v_mfma_f32_16x16x32_bf16 v[12:15], v[174:177], v[198:201], v[12:15]
	v_mfma_f32_16x16x32_bf16 v[4:7], v[166:169], v[206:209], v[4:7]
	v_mfma_f32_16x16x32_bf16 v[0:3], v[174:177], v[206:209], v[0:3]
	s_setprio 0
	s_setprio 1
	v_mfma_f32_16x16x32_bf16 v[48:51], v[170:173], v[186:189], v[48:51]
	v_mfma_f32_16x16x32_bf16 v[44:47], v[178:181], v[186:189], v[44:47]
	v_mfma_f32_16x16x32_bf16 v[32:35], v[170:173], v[194:197], v[32:35]
	v_mfma_f32_16x16x32_bf16 v[28:31], v[178:181], v[194:197], v[28:31]
	v_mfma_f32_16x16x32_bf16 v[16:19], v[170:173], v[202:205], v[16:19]
	v_mfma_f32_16x16x32_bf16 v[12:15], v[178:181], v[202:205], v[12:15]
	v_mfma_f32_16x16x32_bf16 v[4:7], v[170:173], v[210:213], v[4:7]
	v_mfma_f32_16x16x32_bf16 v[0:3], v[178:181], v[210:213], v[0:3]
	s_setprio 0
	s_barrier
	s_add_i32 s65, s65, 2
	s_add_u32 s63, s63, 0x100
	s_addc_u32 s64, s64, 0
	s_add_u32 s36, s36, 0x100
	s_addc_u32 s37, s37, 0
	s_cmp_gt_u32 s65, 13
	s_cbranch_scc0 .LBB0_994
	s_and_b64 vcc, exec, s[12:13]
	s_cbranch_vccz .LBB0_997
	s_barrier

; #define PG8_STAGE(bufoff, gbase, voff) do { _Pragma("unroll") for (int _i = 0; _i < 2; ++_i) \
;         __builtin_amdgcn_global_load_lds((const unsigned*)((const char*)(gbase) + (voff)[_i]), (PG8_LAS unsigned*)(lds + (bufoff) + ldsw + _i * 8192), 16, 0, 0); } while (0)
; #define PG8_LDA(dst, b, h) do { _Pragma("unroll") for (int m = 0; m < 4; ++m) _Pragma("unroll") for (int k = 0; k < 2; ++k) dst[m][k] = *(const PG8_LAS bf16x8*)(lds + PG8_SA(b, h) + aoff + m * 2048 + k * 1024); } while (0)
; #define PG8_LDB(dst, b, h) do { _Pragma("unroll") for (int n = 0; n < 2; ++n) _Pragma("unroll") for (int k = 0; k < 2; ++k) dst[n][k] = *(const PG8_LAS bf16x8*)(lds + PG8_SB(b, h) + boff + n * 2048 + k * 1024); } while (0)
; #define PG8_MMA(ai, bj, At, Bt) do { __builtin_amdgcn_s_setprio(1); _Pragma("unroll") for (int m = 0; m < 4; ++m) _Pragma("unroll") for (int n = 0; n < 2; ++n) _Pragma("unroll") for (int k = 0; k < 2; ++k) \
;         acc[ai][bj][m][n] = __builtin_amdgcn_mfma_f32_16x16x32_bf16(Bt[n][k], At[m][k], acc[ai][bj][m][n], 0, 0, 0); __builtin_amdgcn_s_setprio(0); } while (0)
; #define PG8_WAIT_V(n) asm volatile("s_waitcnt vmcnt(" #n ")" ::: "memory")
; #define PG8_BAR __builtin_amdgcn_s_barrier()
; template <class Epi, class Sched, bool ALIGN_EPI = true, bool SP2 = true>
; __device__ __forceinline__ void gemm_phase(PG8_LAS unsigned char* lds, const Gemm g, const Sched& S, const Epi& E) {
;     ...
;         const bool has_next = S.next(ui + 1, nxt);
;         const char* nA = has_next ? (const char*)g.A + (size_t)nxt.pm * tstepA : cA; const char* nB = has_next ? (const char*)g.Bt + (size_t)nxt.pn * tstepB : cB;
;         for (int t = 0; t < nt; t += 2) {
;             const bool last = (t == nt - 2);
;             const char* a1 = cA + (size_t)(t + 1) * kstep;
;             const char* a2 = last ? nA : cA + (size_t)(t + 2) * kstep; const char* b2 = last ? nB : cB + (size_t)(t + 2) * kstep;
;             const char* a3 = a2 + kstep; const char* b3 = b2 + kstep;
;             PG8_LDB(B0, 0, 0); PG8_LDB(B1, 0, 1); PG8_SCHED; PG8_LDA(At, 0, 0); PG8_STAGE(PG8_SA(1, 1), a1 + hstepA, voffA);
;             PG8_WAIT_V(8); PG8_WAIT_L(0); PG8_BAR; PG8_MMA(0, 0, At, B0); PG8_MMA(0, 1, At, B1); PG8_BAR; PG8_SCHED;
;             PG8_LDA(At, 0, 1); PG8_STAGE(PG8_SB(0, 0), b2, voffB); PG8_STAGE(PG8_SB(0, 1), b2 + hstepB, voffB); PG8_STAGE(PG8_SA(0, 0), a2, voffA);
.LBB0_1054:
	ds_read_b128 v[140:143], v147
	ds_read_b128 v[150:153], v147 offset:1024
	ds_read_b128 v[154:157], v147 offset:2048
	ds_read_b128 v[158:161], v147 offset:3072
	ds_read_b128 v[162:165], v148
	ds_read_b128 v[166:169], v148 offset:1024
	ds_read_b128 v[170:173], v148 offset:2048
	ds_read_b128 v[174:177], v148 offset:3072
	s_add_u32 s40, s36, 0xfffc0080
	s_addc_u32 s41, s37, -1
	s_cmp_eq_u32 s72, 12
	s_cselect_b32 s43, s23, s41
	s_cselect_b32 s42, s64, s40
	s_cselect_b32 s41, s21, s71
	s_cselect_b32 s40, s65, s66
	v_lshl_add_u64 v[210:211], s[36:37], 0, v[138:139]
	s_add_i32 m0, s31, 0xc000
	ds_read_b128 v[178:181], v149
	ds_read_b128 v[182:185], v149 offset:1024
	ds_read_b128 v[186:189], v149 offset:2048
	ds_read_b128 v[190:193], v149 offset:3072
	ds_read_b128 v[194:197], v149 offset:4096
	ds_read_b128 v[198:201], v149 offset:5120
	ds_read_b128 v[202:205], v149 offset:6144
	ds_read_b128 v[206:209], v149 offset:7168
	global_load_lds_dwordx4 v[210:211], off
	v_lshl_add_u64 v[210:211], s[36:37], 0, v[136:137]
	s_add_i32 m0, s31, 0xe000
	s_nop 0
	global_load_lds_dwordx4 v[210:211], off
	s_waitcnt vmcnt(8)
	s_waitcnt lgkmcnt(0)
	s_barrier
	s_setprio 1
	s_waitcnt lgkmcnt(0)
	v_mfma_f32_16x16x32_bf16 v[124:127], v[140:143], v[178:181], v[124:127]
	v_mfma_f32_16x16x32_bf16 v[120:123], v[154:157], v[178:181], v[120:123]
	v_mfma_f32_16x16x32_bf16 v[116:119], v[140:143], v[186:189], v[116:119]
	v_mfma_f32_16x16x32_bf16 v[104:107], v[154:157], v[186:189], v[104:107]
	v_mfma_f32_16x16x32_bf16 v[100:103], v[140:143], v[194:197], v[100:103]
	v_mfma_f32_16x16x32_bf16 v[88:91], v[154:157], v[194:197], v[88:91]
	v_mfma_f32_16x16x32_bf16 v[84:87], v[140:143], v[202:205], v[84:87]
	v_mfma_f32_16x16x32_bf16 v[72:75], v[154:157], v[202:205], v[72:75]
	s_setprio 0
	s_setprio 1
	v_mfma_f32_16x16x32_bf16 v[124:127], v[150:153], v[182:185], v[124:127]
	v_mfma_f32_16x16x32_bf16 v[120:123], v[158:161], v[182:185], v[120:123]
	v_mfma_f32_16x16x32_bf16 v[116:119], v[150:153], v[190:193], v[116:119]
	v_mfma_f32_16x16x32_bf16 v[104:107], v[158:161], v[190:193], v[104:107]
	v_mfma_f32_16x16x32_bf16 v[100:103], v[150:153], v[198:201], v[100:103]
	v_mfma_f32_16x16x32_bf16 v[88:91], v[158:161], v[198:201], v[88:91]
	v_mfma_f32_16x16x32_bf16 v[84:87], v[150:153], v[206:209], v[84:87]
	v_mfma_f32_16x16x32_bf16 v[72:75], v[158:161], v[206:209], v[72:75]
	s_setprio 0
	s_setprio 1
	v_mfma_f32_16x16x32_bf16 v[112:115], v[162:165], v[178:181], v[112:115]
	v_mfma_f32_16x16x32_bf16 v[108:111], v[170:173], v[178:181], v[108:111]
	v_mfma_f32_16x16x32_bf16 v[96:99], v[162:165], v[186:189], v[96:99]
	v_mfma_f32_16x16x32_bf16 v[92:95], v[170:173], v[186:189], v[92:95]
	v_mfma_f32_16x16x32_bf16 v[80:83], v[162:165], v[194:197], v[80:83]
	v_mfma_f32_16x16x32_bf16 v[76:79], v[170:173], v[194:197], v[76:79]
	v_mfma_f32_16x16x32_bf16 v[68:71], v[162:165], v[202:205], v[68:71]
	v_mfma_f32_16x16x32_bf16 v[64:67], v[170:173], v[202:205], v[64:67]
	s_setprio 0
	s_setprio 1
	v_mfma_f32_16x16x32_bf16 v[112:115], v[166:169], v[182:185], v[112:115]
	v_mfma_f32_16x16x32_bf16 v[108:111], v[174:177], v[182:185], v[108:111]
	v_mfma_f32_16x16x32_bf16 v[96:99], v[166:169], v[190:193], v[96:99]
	v_mfma_f32_16x16x32_bf16 v[92:95], v[174:177], v[190:193], v[92:95]
	v_mfma_f32_16x16x32_bf16 v[80:83], v[166:169], v[198:201], v[80:83]
	v_mfma_f32_16x16x32_bf16 v[76:79], v[174:177], v[198:201], v[76:79]
	v_mfma_f32_16x16x32_bf16 v[68:71], v[166:169], v[206:209], v[68:71]
	v_mfma_f32_16x16x32_bf16 v[64:67], v[174:177], v[206:209], v[64:67]
	s_setprio 0
	s_barrier
	s_add_i32 s52, s61, s49
	v_lshl_add_u64 v[210:211], s[40:41], 0, v[132:133]
	s_mov_b32 m0, s52
	ds_read_b128 v[178:181], v149 offset:16384
	ds_read_b128 v[182:185], v149 offset:17408
	ds_read_b128 v[186:189], v149 offset:18432
	ds_read_b128 v[190:193], v149 offset:19456
	ds_read_b128 v[194:197], v149 offset:20480
	ds_read_b128 v[198:201], v149 offset:21504
	ds_read_b128 v[202:205], v149 offset:22528
	ds_read_b128 v[206:209], v149 offset:23552
	global_load_lds_dwordx4 v[210:211], off
	s_add_i32 m0, s52, 0x2000
	s_add_u32 s52, s40, 0x40000
	v_lshl_add_u64 v[212:213], s[40:41], 0, v[128:129]
	s_addc_u32 s53, s41, 0
	s_add_i32 s68, s62, s49
	global_load_lds_dwordx4 v[212:213], off
	v_lshl_add_u64 v[214:215], s[52:53], 0, v[132:133]
	s_mov_b32 m0, s68
	v_lshl_add_u64 v[216:217], s[42:43], 0, v[130:131]
	global_load_lds_dwordx4 v[214:215], off
	v_lshl_add_u64 v[214:215], s[52:53], 0, v[128:129]
	s_add_i32 m0, s68, 0x2000
	s_nop 0
	global_load_lds_dwordx4 v[214:215], off
	v_lshl_add_u64 v[214:215], s[42:43], 0, v[134:135]
	s_mov_b32 m0, s31
	s_nop 0
	global_load_lds_dwordx4 v[214:215], off
	s_mov_b32 m0, s51
	s_nop 0
	global_load_lds_dwordx4 v[216:217], off
	s_waitcnt vmcnt(8)
	s_waitcnt lgkmcnt(0)
	s_barrier
; #define PG8_STAGE(bufoff, gbase, voff) do { _Pragma("unroll") for (int _i = 0; _i < 2; ++_i) \
;         __builtin_amdgcn_global_load_lds((const unsigned*)((const char*)(gbase) + (voff)[_i]), (PG8_LAS unsigned*)(lds + (bufoff) + ldsw + _i * 8192), 16, 0, 0); } while (0)
; #define PG8_LDA(dst, b, h) do { _Pragma("unroll") for (int m = 0; m < 4; ++m) _Pragma("unroll") for (int k = 0; k < 2; ++k) dst[m][k] = *(const PG8_LAS bf16x8*)(lds + PG8_SA(b, h) + aoff + m * 2048 + k * 1024); } while (0)
; #define PG8_LDB(dst, b, h) do { _Pragma("unroll") for (int n = 0; n < 2; ++n) _Pragma("unroll") for (int k = 0; k < 2; ++k) dst[n][k] = *(const PG8_LAS bf16x8*)(lds + PG8_SB(b, h) + boff + n * 2048 + k * 1024); } while (0)
; #define PG8_MMA(ai, bj, At, Bt) do { __builtin_amdgcn_s_setprio(1); _Pragma("unroll") for (int m = 0; m < 4; ++m) _Pragma("unroll") for (int n = 0; n < 2; ++n) _Pragma("unroll") for (int k = 0; k < 2; ++k) \
;         acc[ai][bj][m][n] = __builtin_amdgcn_mfma_f32_16x16x32_bf16(Bt[n][k], At[m][k], acc[ai][bj][m][n], 0, 0, 0); __builtin_amdgcn_s_setprio(0); } while (0)
; #define PG8_WAIT_V(n) asm volatile("s_waitcnt vmcnt(" #n ")" ::: "memory")
; #define PG8_WAIT_L(n) asm volatile("s_waitcnt lgkmcnt(" #n ")" ::: "memory")
; #define PG8_BAR __builtin_amdgcn_s_barrier()
; #define PG8_SCHED __builtin_amdgcn_sched_barrier(0)
; template <class Epi, class Sched, bool ALIGN_EPI = true, bool SP2 = true>
; __device__ __forceinline__ void gemm_phase(PG8_LAS unsigned char* lds, const Gemm g, const Sched& S, const Epi& E) {
;     ...
;             PG8_WAIT_V(8); PG8_WAIT_L(0); PG8_BAR; PG8_MMA(1, 0, At, B0); PG8_MMA(1, 1, At, B1); PG8_BAR; PG8_SCHED;
;             PG8_LDB(B0, 1, 0); PG8_LDB(B1, 1, 1); PG8_SCHED; PG8_LDA(At, 1, 0); PG8_STAGE(PG8_SA(0, 1), a2 + hstepA, voffA);
;             PG8_WAIT_V(8); PG8_WAIT_L(0); PG8_BAR; PG8_MMA(0, 0, At, B0); PG8_MMA(0, 1, At, B1); PG8_BAR; PG8_SCHED;
	s_setprio 1
	s_waitcnt lgkmcnt(0)
	v_mfma_f32_16x16x32_bf16 v[60:63], v[140:143], v[178:181], v[60:63]
	v_mfma_f32_16x16x32_bf16 v[56:59], v[154:157], v[178:181], v[56:59]
	v_mfma_f32_16x16x32_bf16 v[52:55], v[140:143], v[186:189], v[52:55]
	v_mfma_f32_16x16x32_bf16 v[40:43], v[154:157], v[186:189], v[40:43]
	v_mfma_f32_16x16x32_bf16 v[36:39], v[140:143], v[194:197], v[36:39]
	v_mfma_f32_16x16x32_bf16 v[24:27], v[154:157], v[194:197], v[24:27]
	v_mfma_f32_16x16x32_bf16 v[20:23], v[140:143], v[202:205], v[20:23]
	v_mfma_f32_16x16x32_bf16 v[8:11], v[154:157], v[202:205], v[8:11]
	s_setprio 0
	s_setprio 1
	v_mfma_f32_16x16x32_bf16 v[60:63], v[150:153], v[182:185], v[60:63]
	v_mfma_f32_16x16x32_bf16 v[56:59], v[158:161], v[182:185], v[56:59]
	v_mfma_f32_16x16x32_bf16 v[52:55], v[150:153], v[190:193], v[52:55]
	v_mfma_f32_16x16x32_bf16 v[40:43], v[158:161], v[190:193], v[40:43]
	v_mfma_f32_16x16x32_bf16 v[36:39], v[150:153], v[198:201], v[36:39]
	v_mfma_f32_16x16x32_bf16 v[24:27], v[158:161], v[198:201], v[24:27]
	v_mfma_f32_16x16x32_bf16 v[20:23], v[150:153], v[206:209], v[20:23]
	v_mfma_f32_16x16x32_bf16 v[8:11], v[158:161], v[206:209], v[8:11]
	s_setprio 0
	s_setprio 1
	v_mfma_f32_16x16x32_bf16 v[48:51], v[162:165], v[178:181], v[48:51]
	v_mfma_f32_16x16x32_bf16 v[44:47], v[170:173], v[178:181], v[44:47]
	v_mfma_f32_16x16x32_bf16 v[32:35], v[162:165], v[186:189], v[32:35]
	v_mfma_f32_16x16x32_bf16 v[28:31], v[170:173], v[186:189], v[28:31]
	v_mfma_f32_16x16x32_bf16 v[16:19], v[162:165], v[194:197], v[16:19]
	v_mfma_f32_16x16x32_bf16 v[12:15], v[170:173], v[194:197], v[12:15]
	v_mfma_f32_16x16x32_bf16 v[4:7], v[162:165], v[202:205], v[4:7]
	v_mfma_f32_16x16x32_bf16 v[0:3], v[170:173], v[202:205], v[0:3]
	s_setprio 0
	s_setprio 1
	v_mfma_f32_16x16x32_bf16 v[48:51], v[166:169], v[182:185], v[48:51]
	v_mfma_f32_16x16x32_bf16 v[44:47], v[174:177], v[182:185], v[44:47]
	v_mfma_f32_16x16x32_bf16 v[32:35], v[166:169], v[190:193], v[32:35]
	v_mfma_f32_16x16x32_bf16 v[28:31], v[174:177], v[190:193], v[28:31]
	v_mfma_f32_16x16x32_bf16 v[16:19], v[166:169], v[198:201], v[16:19]
	v_mfma_f32_16x16x32_bf16 v[12:15], v[174:177], v[198:201], v[12:15]
	v_mfma_f32_16x16x32_bf16 v[4:7], v[166:169], v[206:209], v[4:7]
	v_mfma_f32_16x16x32_bf16 v[0:3], v[174:177], v[206:209], v[0:3]
	s_setprio 0
	s_barrier
	s_add_i32 s52, 0, 0x18000
	s_add_i32 s53, 0, 0x1c000
	v_add_u32_e32 v158, s52, v145
	v_add_u32_e32 v174, s53, v145
	ds_read_b128 v[140:143], v158
	ds_read_b128 v[150:153], v158 offset:1024
	ds_read_b128 v[154:157], v158 offset:2048
	ds_read_b128 v[158:161], v158 offset:3072
	ds_read_b128 v[162:165], v174
	ds_read_b128 v[166:169], v174 offset:1024
	ds_read_b128 v[170:173], v174 offset:2048
	ds_read_b128 v[174:177], v174 offset:3072
	s_add_u32 s42, s42, 0x40000
	s_addc_u32 s43, s43, 0
	s_mov_b32 m0, s54
	v_lshl_add_u64 v[218:219], s[42:43], 0, v[134:135]
	ds_read_b128 v[178:181], v149 offset:32768
	ds_read_b128 v[182:185], v149 offset:33792
	ds_read_b128 v[186:189], v149 offset:34816
	ds_read_b128 v[190:193], v149 offset:35840
	ds_read_b128 v[194:197], v149 offset:36864
	ds_read_b128 v[198:201], v149 offset:37888
	ds_read_b128 v[202:205], v149 offset:38912
	ds_read_b128 v[206:209], v149 offset:39936
	global_load_lds_dwordx4 v[218:219], off
	v_lshl_add_u64 v[218:219], s[42:43], 0, v[130:131]
	s_mov_b32 m0, s55
	s_nop 0
	global_load_lds_dwordx4 v[218:219], off
	s_waitcnt vmcnt(8)
	s_waitcnt lgkmcnt(0)
	s_barrier
	s_setprio 1
	s_waitcnt lgkmcnt(0)
	v_mfma_f32_16x16x32_bf16 v[124:127], v[140:143], v[178:181], v[124:127]
	v_mfma_f32_16x16x32_bf16 v[120:123], v[154:157], v[178:181], v[120:123]
	v_mfma_f32_16x16x32_bf16 v[116:119], v[140:143], v[186:189], v[116:119]
	v_mfma_f32_16x16x32_bf16 v[104:107], v[154:157], v[186:189], v[104:107]
	v_mfma_f32_16x16x32_bf16 v[100:103], v[140:143], v[194:197], v[100:103]
	v_mfma_f32_16x16x32_bf16 v[88:91], v[154:157], v[194:197], v[88:91]
	v_mfma_f32_16x16x32_bf16 v[84:87], v[140:143], v[202:205], v[84:87]
	v_mfma_f32_16x16x32_bf16 v[72:75], v[154:157], v[202:205], v[72:75]
	s_setprio 0
	s_setprio 1
	v_mfma_f32_16x16x32_bf16 v[124:127], v[150:153], v[182:185], v[124:127]
	v_mfma_f32_16x16x32_bf16 v[120:123], v[158:161], v[182:185], v[120:123]
	v_mfma_f32_16x16x32_bf16 v[116:119], v[150:153], v[190:193], v[116:119]
	v_mfma_f32_16x16x32_bf16 v[104:107], v[158:161], v[190:193], v[104:107]
	v_mfma_f32_16x16x32_bf16 v[100:103], v[150:153], v[198:201], v[100:103]
	v_mfma_f32_16x16x32_bf16 v[88:91], v[158:161], v[198:201], v[88:91]
	v_mfma_f32_16x16x32_bf16 v[84:87], v[150:153], v[206:209], v[84:87]
	v_mfma_f32_16x16x32_bf16 v[72:75], v[158:161], v[206:209], v[72:75]
	s_setprio 0
	s_setprio 1
	v_mfma_f32_16x16x32_bf16 v[112:115], v[162:165], v[178:181], v[112:115]
	v_mfma_f32_16x16x32_bf16 v[108:111], v[170:173], v[178:181], v[108:111]
	v_mfma_f32_16x16x32_bf16 v[96:99], v[162:165], v[186:189], v[96:99]
	v_mfma_f32_16x16x32_bf16 v[92:95], v[170:173], v[186:189], v[92:95]
	v_mfma_f32_16x16x32_bf16 v[80:83], v[162:165], v[194:197], v[80:83]
	v_mfma_f32_16x16x32_bf16 v[76:79], v[170:173], v[194:197], v[76:79]
	v_mfma_f32_16x16x32_bf16 v[68:71], v[162:165], v[202:205], v[68:71]
	v_mfma_f32_16x16x32_bf16 v[64:67], v[170:173], v[202:205], v[64:67]
	s_setprio 0
	s_setprio 1
	v_mfma_f32_16x16x32_bf16 v[112:115], v[166:169], v[182:185], v[112:115]
	v_mfma_f32_16x16x32_bf16 v[108:111], v[174:177], v[182:185], v[108:111]
	v_mfma_f32_16x16x32_bf16 v[96:99], v[166:169], v[190:193], v[96:99]
	v_mfma_f32_16x16x32_bf16 v[92:95], v[174:177], v[190:193], v[92:95]
	v_mfma_f32_16x16x32_bf16 v[80:83], v[166:169], v[198:201], v[80:83]
	v_mfma_f32_16x16x32_bf16 v[76:79], v[174:177], v[198:201], v[76:79]
	v_mfma_f32_16x16x32_bf16 v[68:71], v[166:169], v[206:209], v[68:71]
	v_mfma_f32_16x16x32_bf16 v[64:67], v[174:177], v[206:209], v[64:67]
	s_setprio 0
	s_barrier
; #define PG8_STAGE(bufoff, gbase, voff) do { _Pragma("unroll") for (int _i = 0; _i < 2; ++_i) \
;         __builtin_amdgcn_global_load_lds((const unsigned*)((const char*)(gbase) + (voff)[_i]), (PG8_LAS unsigned*)(lds + (bufoff) + ldsw + _i * 8192), 16, 0, 0); } while (0)
; #define PG8_LDA(dst, b, h) do { _Pragma("unroll") for (int m = 0; m < 4; ++m) _Pragma("unroll") for (int k = 0; k < 2; ++k) dst[m][k] = *(const PG8_LAS bf16x8*)(lds + PG8_SA(b, h) + aoff + m * 2048 + k * 1024); } while (0)
; #define PG8_MMA(ai, bj, At, Bt) do { __builtin_amdgcn_s_setprio(1); _Pragma("unroll") for (int m = 0; m < 4; ++m) _Pragma("unroll") for (int n = 0; n < 2; ++n) _Pragma("unroll") for (int k = 0; k < 2; ++k) \
;         acc[ai][bj][m][n] = __builtin_amdgcn_mfma_f32_16x16x32_bf16(Bt[n][k], At[m][k], acc[ai][bj][m][n], 0, 0, 0); __builtin_amdgcn_s_setprio(0); } while (0)
; #define PG8_WAIT_V(n) asm volatile("s_waitcnt vmcnt(" #n ")" ::: "memory")
; #define PG8_WAIT_L(n) asm volatile("s_waitcnt lgkmcnt(" #n ")" ::: "memory")
; #define PG8_BAR __builtin_amdgcn_s_barrier()
; #define PG8_SCHED __builtin_amdgcn_sched_barrier(0)
; template <class Epi, class Sched, bool ALIGN_EPI = true, bool SP2 = true>
; __device__ __forceinline__ void gemm_phase(PG8_LAS unsigned char* lds, const Gemm g, const Sched& S, const Epi& E) {
;     ...
;             PG8_LDA(At, 1, 1); PG8_STAGE(PG8_SB(1, 0), b3, voffB); PG8_STAGE(PG8_SB(1, 1), b3 + hstepB, voffB); PG8_STAGE(PG8_SA(1, 0), a3, voffA);
;             PG8_WAIT_V(8); PG8_WAIT_L(0); PG8_BAR; PG8_MMA(1, 0, At, B0); PG8_MMA(1, 1, At, B1); PG8_BAR; PG8_SCHED;
;         }
;         if constexpr (ALIGN_EPI) { if (wr == 0) PG8_BAR; }
	s_add_i32 s42, s52, s49
	v_lshl_add_u64 v[210:211], v[210:211], 0, s[8:9]
	s_mov_b32 m0, s42
	ds_read_b128 v[178:181], v149 offset:49152
	ds_read_b128 v[182:185], v149 offset:50176
	ds_read_b128 v[186:189], v149 offset:51200
	ds_read_b128 v[190:193], v149 offset:52224
	ds_read_b128 v[194:197], v149 offset:53248
	ds_read_b128 v[198:201], v149 offset:54272
	ds_read_b128 v[202:205], v149 offset:55296
	ds_read_b128 v[206:209], v149 offset:56320
	global_load_lds_dwordx4 v[210:211], off
	s_add_i32 m0, s42, 0x2000
	s_add_u32 s40, s40, 0x40080
	v_lshl_add_u64 v[210:211], v[212:213], 0, s[8:9]
	s_addc_u32 s41, s41, 0
	s_add_i32 s42, s53, s49
	global_load_lds_dwordx4 v[210:211], off
	v_lshl_add_u64 v[210:211], s[40:41], 0, v[132:133]
	s_mov_b32 m0, s42
	s_nop 0
	global_load_lds_dwordx4 v[210:211], off
	v_lshl_add_u64 v[210:211], s[40:41], 0, v[128:129]
	s_add_i32 m0, s42, 0x2000
	s_nop 0
	global_load_lds_dwordx4 v[210:211], off
	v_lshl_add_u64 v[210:211], v[214:215], 0, s[8:9]
	s_mov_b32 m0, s56
	s_nop 0
	global_load_lds_dwordx4 v[210:211], off
	v_lshl_add_u64 v[210:211], v[216:217], 0, s[8:9]
	s_mov_b32 m0, s57
	s_nop 0
	global_load_lds_dwordx4 v[210:211], off
	s_waitcnt vmcnt(8)
	s_waitcnt lgkmcnt(0)
	s_barrier
	s_setprio 1
	s_waitcnt lgkmcnt(0)
	v_mfma_f32_16x16x32_bf16 v[60:63], v[140:143], v[178:181], v[60:63]
	v_mfma_f32_16x16x32_bf16 v[56:59], v[154:157], v[178:181], v[56:59]
	v_mfma_f32_16x16x32_bf16 v[52:55], v[140:143], v[186:189], v[52:55]
	v_mfma_f32_16x16x32_bf16 v[40:43], v[154:157], v[186:189], v[40:43]
	v_mfma_f32_16x16x32_bf16 v[36:39], v[140:143], v[194:197], v[36:39]
	v_mfma_f32_16x16x32_bf16 v[24:27], v[154:157], v[194:197], v[24:27]
	v_mfma_f32_16x16x32_bf16 v[20:23], v[140:143], v[202:205], v[20:23]
	v_mfma_f32_16x16x32_bf16 v[8:11], v[154:157], v[202:205], v[8:11]
	s_setprio 0
	s_setprio 1
	v_mfma_f32_16x16x32_bf16 v[60:63], v[150:153], v[182:185], v[60:63]
	v_mfma_f32_16x16x32_bf16 v[56:59], v[158:161], v[182:185], v[56:59]
	v_mfma_f32_16x16x32_bf16 v[52:55], v[150:153], v[190:193], v[52:55]
	v_mfma_f32_16x16x32_bf16 v[40:43], v[158:161], v[190:193], v[40:43]
	v_mfma_f32_16x16x32_bf16 v[36:39], v[150:153], v[198:201], v[36:39]
	v_mfma_f32_16x16x32_bf16 v[24:27], v[158:161], v[198:201], v[24:27]
	v_mfma_f32_16x16x32_bf16 v[20:23], v[150:153], v[206:209], v[20:23]
	v_mfma_f32_16x16x32_bf16 v[8:11], v[158:161], v[206:209], v[8:11]
	s_setprio 0
	s_setprio 1
	v_mfma_f32_16x16x32_bf16 v[48:51], v[162:165], v[178:181], v[48:51]
	v_mfma_f32_16x16x32_bf16 v[44:47], v[170:173], v[178:181], v[44:47]
	v_mfma_f32_16x16x32_bf16 v[32:35], v[162:165], v[186:189], v[32:35]
	v_mfma_f32_16x16x32_bf16 v[28:31], v[170:173], v[186:189], v[28:31]
	v_mfma_f32_16x16x32_bf16 v[16:19], v[162:165], v[194:197], v[16:19]
	v_mfma_f32_16x16x32_bf16 v[12:15], v[170:173], v[194:197], v[12:15]
	v_mfma_f32_16x16x32_bf16 v[4:7], v[162:165], v[202:205], v[4:7]
	v_mfma_f32_16x16x32_bf16 v[0:3], v[170:173], v[202:205], v[0:3]
	s_setprio 0
	s_setprio 1
	v_mfma_f32_16x16x32_bf16 v[48:51], v[166:169], v[182:185], v[48:51]
	v_mfma_f32_16x16x32_bf16 v[44:47], v[174:177], v[182:185], v[44:47]
	v_mfma_f32_16x16x32_bf16 v[32:35], v[166:169], v[190:193], v[32:35]
	v_mfma_f32_16x16x32_bf16 v[28:31], v[174:177], v[190:193], v[28:31]
	v_mfma_f32_16x16x32_bf16 v[16:19], v[166:169], v[198:201], v[16:19]
	v_mfma_f32_16x16x32_bf16 v[12:15], v[174:177], v[198:201], v[12:15]
	v_mfma_f32_16x16x32_bf16 v[4:7], v[166:169], v[206:209], v[4:7]
	v_mfma_f32_16x16x32_bf16 v[0:3], v[174:177], v[206:209], v[0:3]
	s_setprio 0
	s_barrier
	s_add_i32 s72, s72, 2
	s_add_u32 s66, s66, 0x100
	s_addc_u32 s71, s71, 0
	s_add_u32 s36, s36, 0x100
	s_addc_u32 s37, s37, 0
	s_cmp_gt_u32 s72, 13
	s_cbranch_scc0 .LBB0_1054
	s_and_b64 vcc, exec, s[10:11]
	s_cbranch_vccz .LBB0_1057
	s_barrier

; #define PG8_STAGE(bufoff, gbase, voff) do { _Pragma("unroll") for (int _i = 0; _i < 2; ++_i) \
;         __builtin_amdgcn_global_load_lds((const unsigned*)((const char*)(gbase) + (voff)[_i]), (PG8_LAS unsigned*)(lds + (bufoff) + ldsw + _i * 8192), 16, 0, 0); } while (0)
; #define PG8_LDA(dst, b, h) do { _Pragma("unroll") for (int m = 0; m < 4; ++m) _Pragma("unroll") for (int k = 0; k < 2; ++k) dst[m][k] = *(const PG8_LAS bf16x8*)(lds + PG8_SA(b, h) + aoff + m * 2048 + k * 1024); } while (0)
; #define PG8_LDB(dst, b, h) do { _Pragma("unroll") for (int n = 0; n < 2; ++n) _Pragma("unroll") for (int k = 0; k < 2; ++k) dst[n][k] = *(const PG8_LAS bf16x8*)(lds + PG8_SB(b, h) + boff + n * 2048 + k * 1024); } while (0)
; #define PG8_MMA(ai, bj, At, Bt) do { __builtin_amdgcn_s_setprio(1); _Pragma("unroll") for (int m = 0; m < 4; ++m) _Pragma("unroll") for (int n = 0; n < 2; ++n) _Pragma("unroll") for (int k = 0; k < 2; ++k) \
;         acc[ai][bj][m][n] = __builtin_amdgcn_mfma_f32_16x16x32_bf16(Bt[n][k], At[m][k], acc[ai][bj][m][n], 0, 0, 0); __builtin_amdgcn_s_setprio(0); } while (0)
; #define PG8_WAIT_V(n) asm volatile("s_waitcnt vmcnt(" #n ")" ::: "memory")
; #define PG8_BAR __builtin_amdgcn_s_barrier()
; template <class Epi, class Sched, bool ALIGN_EPI = true, bool SP2 = true>
; __device__ __forceinline__ void gemm_phase(PG8_LAS unsigned char* lds, const Gemm g, const Sched& S, const Epi& E) {
;     ...
;         const bool has_next = S.next(ui + 1, nxt);
;         const char* nA = has_next ? (const char*)g.A + (size_t)nxt.pm * tstepA : cA; const char* nB = has_next ? (const char*)g.Bt + (size_t)nxt.pn * tstepB : cB;
;         for (int t = 0; t < nt; t += 2) {
;             const bool last = (t == nt - 2);
;             const char* a1 = cA + (size_t)(t + 1) * kstep;
;             const char* a2 = last ? nA : cA + (size_t)(t + 2) * kstep; const char* b2 = last ? nB : cB + (size_t)(t + 2) * kstep;
;             const char* a3 = a2 + kstep; const char* b3 = b2 + kstep;
;             PG8_LDB(B0, 0, 0); PG8_LDB(B1, 0, 1); PG8_SCHED; PG8_LDA(At, 0, 0); PG8_STAGE(PG8_SA(1, 1), a1 + hstepA, voffA);
;             PG8_WAIT_V(8); PG8_WAIT_L(0); PG8_BAR; PG8_MMA(0, 0, At, B0); PG8_MMA(0, 1, At, B1); PG8_BAR; PG8_SCHED;
;             PG8_LDA(At, 0, 1); PG8_STAGE(PG8_SB(0, 0), b2, voffB); PG8_STAGE(PG8_SB(0, 1), b2 + hstepB, voffB); PG8_STAGE(PG8_SA(0, 0), a2, voffA);
.LBB0_1130:
	ds_read_b128 v[150:153], v147
	ds_read_b128 v[154:157], v147 offset:1024
	ds_read_b128 v[158:161], v147 offset:2048
	ds_read_b128 v[162:165], v147 offset:3072
	ds_read_b128 v[166:169], v148
	ds_read_b128 v[170:173], v148 offset:1024
	ds_read_b128 v[174:177], v148 offset:2048
	ds_read_b128 v[178:181], v148 offset:3072
	s_add_u32 s36, s34, 0xfffc0080
	s_addc_u32 s37, s35, -1
	s_cmp_eq_u32 s73, 12
	s_cselect_b32 s41, s27, s37
	s_cselect_b32 s40, s65, s36
	s_cselect_b32 s37, s25, s72
	s_cselect_b32 s36, s66, s71
	v_lshl_add_u64 v[214:215], s[34:35], 0, v[138:139]
	s_add_i32 m0, s23, 0xc000
	ds_read_b128 v[182:185], v149
	ds_read_b128 v[186:189], v149 offset:1024
	ds_read_b128 v[190:193], v149 offset:2048
	ds_read_b128 v[194:197], v149 offset:3072
	ds_read_b128 v[198:201], v149 offset:4096
	ds_read_b128 v[202:205], v149 offset:5120
	ds_read_b128 v[206:209], v149 offset:6144
	ds_read_b128 v[210:213], v149 offset:7168
	global_load_lds_dwordx4 v[214:215], off
	v_lshl_add_u64 v[214:215], s[34:35], 0, v[136:137]
	s_add_i32 m0, s23, 0xe000
	s_nop 0
	global_load_lds_dwordx4 v[214:215], off
	s_waitcnt vmcnt(8)
	s_waitcnt lgkmcnt(0)
	s_barrier
	s_setprio 1
	s_waitcnt lgkmcnt(0)
	v_mfma_f32_16x16x32_bf16 v[124:127], v[150:153], v[182:185], v[124:127]
	v_mfma_f32_16x16x32_bf16 v[120:123], v[158:161], v[182:185], v[120:123]
	v_mfma_f32_16x16x32_bf16 v[116:119], v[150:153], v[190:193], v[116:119]
	v_mfma_f32_16x16x32_bf16 v[112:115], v[158:161], v[190:193], v[112:115]
	v_mfma_f32_16x16x32_bf16 v[100:103], v[150:153], v[198:201], v[100:103]
	v_mfma_f32_16x16x32_bf16 v[96:99], v[158:161], v[198:201], v[96:99]
	v_mfma_f32_16x16x32_bf16 v[84:87], v[150:153], v[206:209], v[84:87]
	v_mfma_f32_16x16x32_bf16 v[80:83], v[158:161], v[206:209], v[80:83]
	s_setprio 0
	s_setprio 1
	v_mfma_f32_16x16x32_bf16 v[124:127], v[154:157], v[186:189], v[124:127]
	v_mfma_f32_16x16x32_bf16 v[120:123], v[162:165], v[186:189], v[120:123]
	v_mfma_f32_16x16x32_bf16 v[116:119], v[154:157], v[194:197], v[116:119]
	v_mfma_f32_16x16x32_bf16 v[112:115], v[162:165], v[194:197], v[112:115]
	v_mfma_f32_16x16x32_bf16 v[100:103], v[154:157], v[202:205], v[100:103]
	v_mfma_f32_16x16x32_bf16 v[96:99], v[162:165], v[202:205], v[96:99]
	v_mfma_f32_16x16x32_bf16 v[84:87], v[154:157], v[210:213], v[84:87]
	v_mfma_f32_16x16x32_bf16 v[80:83], v[162:165], v[210:213], v[80:83]
	s_setprio 0
	s_setprio 1
	v_mfma_f32_16x16x32_bf16 v[108:111], v[166:169], v[182:185], v[108:111]
	v_mfma_f32_16x16x32_bf16 v[104:107], v[174:177], v[182:185], v[104:107]
	v_mfma_f32_16x16x32_bf16 v[92:95], v[166:169], v[190:193], v[92:95]
	v_mfma_f32_16x16x32_bf16 v[88:91], v[174:177], v[190:193], v[88:91]
	v_mfma_f32_16x16x32_bf16 v[76:79], v[166:169], v[198:201], v[76:79]
	v_mfma_f32_16x16x32_bf16 v[72:75], v[174:177], v[198:201], v[72:75]
	v_mfma_f32_16x16x32_bf16 v[68:71], v[166:169], v[206:209], v[68:71]
	v_mfma_f32_16x16x32_bf16 v[64:67], v[174:177], v[206:209], v[64:67]
	s_setprio 0
	s_setprio 1
	v_mfma_f32_16x16x32_bf16 v[108:111], v[170:173], v[186:189], v[108:111]
	v_mfma_f32_16x16x32_bf16 v[104:107], v[178:181], v[186:189], v[104:107]
	v_mfma_f32_16x16x32_bf16 v[92:95], v[170:173], v[194:197], v[92:95]
	v_mfma_f32_16x16x32_bf16 v[88:91], v[178:181], v[194:197], v[88:91]
	v_mfma_f32_16x16x32_bf16 v[76:79], v[170:173], v[202:205], v[76:79]
	v_mfma_f32_16x16x32_bf16 v[72:75], v[178:181], v[202:205], v[72:75]
	v_mfma_f32_16x16x32_bf16 v[68:71], v[170:173], v[210:213], v[68:71]
	v_mfma_f32_16x16x32_bf16 v[64:67], v[178:181], v[210:213], v[64:67]
	s_setprio 0
	s_barrier
	s_add_i32 s52, s58, s47
	v_lshl_add_u64 v[214:215], s[36:37], 0, v[130:131]
	s_mov_b32 m0, s52
	ds_read_b128 v[182:185], v149 offset:16384
	ds_read_b128 v[186:189], v149 offset:17408
	ds_read_b128 v[190:193], v149 offset:18432
	ds_read_b128 v[194:197], v149 offset:19456
	ds_read_b128 v[198:201], v149 offset:20480
	ds_read_b128 v[202:205], v149 offset:21504
	ds_read_b128 v[206:209], v149 offset:22528
	ds_read_b128 v[210:213], v149 offset:23552
	global_load_lds_dwordx4 v[214:215], off
	s_add_i32 m0, s52, 0x2000
	s_add_u32 s52, s36, 0x40000
	v_lshl_add_u64 v[216:217], s[36:37], 0, v[134:135]
	s_addc_u32 s53, s37, 0
	s_add_i32 s68, s59, s47
	global_load_lds_dwordx4 v[216:217], off
	v_lshl_add_u64 v[218:219], s[52:53], 0, v[130:131]
	s_mov_b32 m0, s68
	v_lshl_add_u64 v[220:221], s[40:41], 0, v[132:133]
	global_load_lds_dwordx4 v[218:219], off
	v_lshl_add_u64 v[218:219], s[52:53], 0, v[134:135]
	s_add_i32 m0, s68, 0x2000
	s_nop 0
	global_load_lds_dwordx4 v[218:219], off
	v_lshl_add_u64 v[218:219], s[40:41], 0, v[128:129]
	s_mov_b32 m0, s23
	s_nop 0
	global_load_lds_dwordx4 v[218:219], off
	s_mov_b32 m0, s48
	s_nop 0
	global_load_lds_dwordx4 v[220:221], off
	s_waitcnt vmcnt(8)
	s_waitcnt lgkmcnt(0)
	s_barrier
; #define PG8_STAGE(bufoff, gbase, voff) do { _Pragma("unroll") for (int _i = 0; _i < 2; ++_i) \
;         __builtin_amdgcn_global_load_lds((const unsigned*)((const char*)(gbase) + (voff)[_i]), (PG8_LAS unsigned*)(lds + (bufoff) + ldsw + _i * 8192), 16, 0, 0); } while (0)
; #define PG8_LDA(dst, b, h) do { _Pragma("unroll") for (int m = 0; m < 4; ++m) _Pragma("unroll") for (int k = 0; k < 2; ++k) dst[m][k] = *(const PG8_LAS bf16x8*)(lds + PG8_SA(b, h) + aoff + m * 2048 + k * 1024); } while (0)
; #define PG8_LDB(dst, b, h) do { _Pragma("unroll") for (int n = 0; n < 2; ++n) _Pragma("unroll") for (int k = 0; k < 2; ++k) dst[n][k] = *(const PG8_LAS bf16x8*)(lds + PG8_SB(b, h) + boff + n * 2048 + k * 1024); } while (0)
; #define PG8_MMA(ai, bj, At, Bt) do { __builtin_amdgcn_s_setprio(1); _Pragma("unroll") for (int m = 0; m < 4; ++m) _Pragma("unroll") for (int n = 0; n < 2; ++n) _Pragma("unroll") for (int k = 0; k < 2; ++k) \
;         acc[ai][bj][m][n] = __builtin_amdgcn_mfma_f32_16x16x32_bf16(Bt[n][k], At[m][k], acc[ai][bj][m][n], 0, 0, 0); __builtin_amdgcn_s_setprio(0); } while (0)
; #define PG8_WAIT_V(n) asm volatile("s_waitcnt vmcnt(" #n ")" ::: "memory")
; #define PG8_WAIT_L(n) asm volatile("s_waitcnt lgkmcnt(" #n ")" ::: "memory")
; #define PG8_BAR __builtin_amdgcn_s_barrier()
; #define PG8_SCHED __builtin_amdgcn_sched_barrier(0)
; template <class Epi, class Sched, bool ALIGN_EPI = true, bool SP2 = true>
; __device__ __forceinline__ void gemm_phase(PG8_LAS unsigned char* lds, const Gemm g, const Sched& S, const Epi& E) {
;     ...
;             PG8_WAIT_V(8); PG8_WAIT_L(0); PG8_BAR; PG8_MMA(1, 0, At, B0); PG8_MMA(1, 1, At, B1); PG8_BAR; PG8_SCHED;
;             PG8_LDB(B0, 1, 0); PG8_LDB(B1, 1, 1); PG8_SCHED; PG8_LDA(At, 1, 0); PG8_STAGE(PG8_SA(0, 1), a2 + hstepA, voffA);
;             PG8_WAIT_V(8); PG8_WAIT_L(0); PG8_BAR; PG8_MMA(0, 0, At, B0); PG8_MMA(0, 1, At, B1); PG8_BAR; PG8_SCHED;
	s_setprio 1
	s_waitcnt lgkmcnt(0)
	v_mfma_f32_16x16x32_bf16 v[60:63], v[150:153], v[182:185], v[60:63]
	v_mfma_f32_16x16x32_bf16 v[56:59], v[158:161], v[182:185], v[56:59]
	v_mfma_f32_16x16x32_bf16 v[52:55], v[150:153], v[190:193], v[52:55]
	v_mfma_f32_16x16x32_bf16 v[48:51], v[158:161], v[190:193], v[48:51]
	v_mfma_f32_16x16x32_bf16 v[36:39], v[150:153], v[198:201], v[36:39]
	v_mfma_f32_16x16x32_bf16 v[32:35], v[158:161], v[198:201], v[32:35]
	v_mfma_f32_16x16x32_bf16 v[20:23], v[150:153], v[206:209], v[20:23]
	v_mfma_f32_16x16x32_bf16 v[16:19], v[158:161], v[206:209], v[16:19]
	s_setprio 0
	s_setprio 1
	v_mfma_f32_16x16x32_bf16 v[60:63], v[154:157], v[186:189], v[60:63]
	v_mfma_f32_16x16x32_bf16 v[56:59], v[162:165], v[186:189], v[56:59]
	v_mfma_f32_16x16x32_bf16 v[52:55], v[154:157], v[194:197], v[52:55]
	v_mfma_f32_16x16x32_bf16 v[48:51], v[162:165], v[194:197], v[48:51]
	v_mfma_f32_16x16x32_bf16 v[36:39], v[154:157], v[202:205], v[36:39]
	v_mfma_f32_16x16x32_bf16 v[32:35], v[162:165], v[202:205], v[32:35]
	v_mfma_f32_16x16x32_bf16 v[20:23], v[154:157], v[210:213], v[20:23]
	v_mfma_f32_16x16x32_bf16 v[16:19], v[162:165], v[210:213], v[16:19]
	s_setprio 0
	s_setprio 1
	v_mfma_f32_16x16x32_bf16 v[44:47], v[166:169], v[182:185], v[44:47]
	v_mfma_f32_16x16x32_bf16 v[40:43], v[174:177], v[182:185], v[40:43]
	v_mfma_f32_16x16x32_bf16 v[28:31], v[166:169], v[190:193], v[28:31]
	v_mfma_f32_16x16x32_bf16 v[24:27], v[174:177], v[190:193], v[24:27]
	v_mfma_f32_16x16x32_bf16 v[12:15], v[166:169], v[198:201], v[12:15]
	v_mfma_f32_16x16x32_bf16 v[8:11], v[174:177], v[198:201], v[8:11]
	v_mfma_f32_16x16x32_bf16 v[4:7], v[166:169], v[206:209], v[4:7]
	v_mfma_f32_16x16x32_bf16 v[0:3], v[174:177], v[206:209], v[0:3]
	s_setprio 0
	s_setprio 1
	v_mfma_f32_16x16x32_bf16 v[44:47], v[170:173], v[186:189], v[44:47]
	v_mfma_f32_16x16x32_bf16 v[40:43], v[178:181], v[186:189], v[40:43]
	v_mfma_f32_16x16x32_bf16 v[28:31], v[170:173], v[194:197], v[28:31]
	v_mfma_f32_16x16x32_bf16 v[24:27], v[178:181], v[194:197], v[24:27]
	v_mfma_f32_16x16x32_bf16 v[12:15], v[170:173], v[202:205], v[12:15]
	v_mfma_f32_16x16x32_bf16 v[8:11], v[178:181], v[202:205], v[8:11]
	v_mfma_f32_16x16x32_bf16 v[4:7], v[170:173], v[210:213], v[4:7]
	v_mfma_f32_16x16x32_bf16 v[0:3], v[178:181], v[210:213], v[0:3]
	s_setprio 0
	s_barrier
	s_add_i32 s52, 0, 0x18000
	s_add_i32 s53, 0, 0x1c000
	v_add_u32_e32 v162, s52, v145
	v_add_u32_e32 v178, s53, v145
	ds_read_b128 v[150:153], v162
	ds_read_b128 v[154:157], v162 offset:1024
	ds_read_b128 v[158:161], v162 offset:2048
	ds_read_b128 v[162:165], v162 offset:3072
	ds_read_b128 v[166:169], v178
	ds_read_b128 v[170:173], v178 offset:1024
	ds_read_b128 v[174:177], v178 offset:2048
	ds_read_b128 v[178:181], v178 offset:3072
	s_add_u32 s40, s40, 0x40000
	s_addc_u32 s41, s41, 0
	s_mov_b32 m0, s49
	v_lshl_add_u64 v[222:223], s[40:41], 0, v[128:129]
	ds_read_b128 v[182:185], v149 offset:32768
	ds_read_b128 v[186:189], v149 offset:33792
	ds_read_b128 v[190:193], v149 offset:34816
	ds_read_b128 v[194:197], v149 offset:35840
	ds_read_b128 v[198:201], v149 offset:36864
	ds_read_b128 v[202:205], v149 offset:37888
	ds_read_b128 v[206:209], v149 offset:38912
	ds_read_b128 v[210:213], v149 offset:39936
	global_load_lds_dwordx4 v[222:223], off
	v_lshl_add_u64 v[222:223], s[40:41], 0, v[132:133]
	s_mov_b32 m0, s50
	s_nop 0
	global_load_lds_dwordx4 v[222:223], off
	s_waitcnt vmcnt(8)
	s_waitcnt lgkmcnt(0)
	s_barrier
	s_setprio 1
	s_waitcnt lgkmcnt(0)
	v_mfma_f32_16x16x32_bf16 v[124:127], v[150:153], v[182:185], v[124:127]
	v_mfma_f32_16x16x32_bf16 v[120:123], v[158:161], v[182:185], v[120:123]
	v_mfma_f32_16x16x32_bf16 v[116:119], v[150:153], v[190:193], v[116:119]
	v_mfma_f32_16x16x32_bf16 v[112:115], v[158:161], v[190:193], v[112:115]
	v_mfma_f32_16x16x32_bf16 v[100:103], v[150:153], v[198:201], v[100:103]
	v_mfma_f32_16x16x32_bf16 v[96:99], v[158:161], v[198:201], v[96:99]
	v_mfma_f32_16x16x32_bf16 v[84:87], v[150:153], v[206:209], v[84:87]
	v_mfma_f32_16x16x32_bf16 v[80:83], v[158:161], v[206:209], v[80:83]
	s_setprio 0
	s_setprio 1
	v_mfma_f32_16x16x32_bf16 v[124:127], v[154:157], v[186:189], v[124:127]
	v_mfma_f32_16x16x32_bf16 v[120:123], v[162:165], v[186:189], v[120:123]
	v_mfma_f32_16x16x32_bf16 v[116:119], v[154:157], v[194:197], v[116:119]
	v_mfma_f32_16x16x32_bf16 v[112:115], v[162:165], v[194:197], v[112:115]
	v_mfma_f32_16x16x32_bf16 v[100:103], v[154:157], v[202:205], v[100:103]
	v_mfma_f32_16x16x32_bf16 v[96:99], v[162:165], v[202:205], v[96:99]
	v_mfma_f32_16x16x32_bf16 v[84:87], v[154:157], v[210:213], v[84:87]
	v_mfma_f32_16x16x32_bf16 v[80:83], v[162:165], v[210:213], v[80:83]
	s_setprio 0
	s_setprio 1
	v_mfma_f32_16x16x32_bf16 v[108:111], v[166:169], v[182:185], v[108:111]
	v_mfma_f32_16x16x32_bf16 v[104:107], v[174:177], v[182:185], v[104:107]
	v_mfma_f32_16x16x32_bf16 v[92:95], v[166:169], v[190:193], v[92:95]
	v_mfma_f32_16x16x32_bf16 v[88:91], v[174:177], v[190:193], v[88:91]
	v_mfma_f32_16x16x32_bf16 v[76:79], v[166:169], v[198:201], v[76:79]
	v_mfma_f32_16x16x32_bf16 v[72:75], v[174:177], v[198:201], v[72:75]
	v_mfma_f32_16x16x32_bf16 v[68:71], v[166:169], v[206:209], v[68:71]
	v_mfma_f32_16x16x32_bf16 v[64:67], v[174:177], v[206:209], v[64:67]
	s_setprio 0
	s_setprio 1
	v_mfma_f32_16x16x32_bf16 v[108:111], v[170:173], v[186:189], v[108:111]
	v_mfma_f32_16x16x32_bf16 v[104:107], v[178:181], v[186:189], v[104:107]
	v_mfma_f32_16x16x32_bf16 v[92:95], v[170:173], v[194:197], v[92:95]
	v_mfma_f32_16x16x32_bf16 v[88:91], v[178:181], v[194:197], v[88:91]
	v_mfma_f32_16x16x32_bf16 v[76:79], v[170:173], v[202:205], v[76:79]
	v_mfma_f32_16x16x32_bf16 v[72:75], v[178:181], v[202:205], v[72:75]
	v_mfma_f32_16x16x32_bf16 v[68:71], v[170:173], v[210:213], v[68:71]
	v_mfma_f32_16x16x32_bf16 v[64:67], v[178:181], v[210:213], v[64:67]
	s_setprio 0
	s_barrier
; #define PG8_STAGE(bufoff, gbase, voff) do { _Pragma("unroll") for (int _i = 0; _i < 2; ++_i) \
;         __builtin_amdgcn_global_load_lds((const unsigned*)((const char*)(gbase) + (voff)[_i]), (PG8_LAS unsigned*)(lds + (bufoff) + ldsw + _i * 8192), 16, 0, 0); } while (0)
; #define PG8_LDA(dst, b, h) do { _Pragma("unroll") for (int m = 0; m < 4; ++m) _Pragma("unroll") for (int k = 0; k < 2; ++k) dst[m][k] = *(const PG8_LAS bf16x8*)(lds + PG8_SA(b, h) + aoff + m * 2048 + k * 1024); } while (0)
; #define PG8_MMA(ai, bj, At, Bt) do { __builtin_amdgcn_s_setprio(1); _Pragma("unroll") for (int m = 0; m < 4; ++m) _Pragma("unroll") for (int n = 0; n < 2; ++n) _Pragma("unroll") for (int k = 0; k < 2; ++k) \
;         acc[ai][bj][m][n] = __builtin_amdgcn_mfma_f32_16x16x32_bf16(Bt[n][k], At[m][k], acc[ai][bj][m][n], 0, 0, 0); __builtin_amdgcn_s_setprio(0); } while (0)
; #define PG8_WAIT_V(n) asm volatile("s_waitcnt vmcnt(" #n ")" ::: "memory")
; #define PG8_WAIT_L(n) asm volatile("s_waitcnt lgkmcnt(" #n ")" ::: "memory")
; #define PG8_BAR __builtin_amdgcn_s_barrier()
; #define PG8_SCHED __builtin_amdgcn_sched_barrier(0)
; template <class Epi, class Sched, bool ALIGN_EPI = true, bool SP2 = true>
; __device__ __forceinline__ void gemm_phase(PG8_LAS unsigned char* lds, const Gemm g, const Sched& S, const Epi& E) {
;     ...
;             PG8_LDA(At, 1, 1); PG8_STAGE(PG8_SB(1, 0), b3, voffB); PG8_STAGE(PG8_SB(1, 1), b3 + hstepB, voffB); PG8_STAGE(PG8_SA(1, 0), a3, voffA);
;             PG8_WAIT_V(8); PG8_WAIT_L(0); PG8_BAR; PG8_MMA(1, 0, At, B0); PG8_MMA(1, 1, At, B1); PG8_BAR; PG8_SCHED;
;         }
;         if constexpr (ALIGN_EPI) { if (wr == 0) PG8_BAR; }
	s_add_i32 s40, s52, s47
	v_lshl_add_u64 v[214:215], v[214:215], 0, s[12:13]
	s_mov_b32 m0, s40
	ds_read_b128 v[182:185], v149 offset:49152
	ds_read_b128 v[186:189], v149 offset:50176
	ds_read_b128 v[190:193], v149 offset:51200
	ds_read_b128 v[194:197], v149 offset:52224
	ds_read_b128 v[198:201], v149 offset:53248
	ds_read_b128 v[202:205], v149 offset:54272
	ds_read_b128 v[206:209], v149 offset:55296
	ds_read_b128 v[210:213], v149 offset:56320
	global_load_lds_dwordx4 v[214:215], off
	s_add_i32 m0, s40, 0x2000
	s_add_u32 s36, s36, 0x40080
	v_lshl_add_u64 v[214:215], v[216:217], 0, s[12:13]
	s_addc_u32 s37, s37, 0
	s_add_i32 s40, s53, s47
	global_load_lds_dwordx4 v[214:215], off
	v_lshl_add_u64 v[214:215], s[36:37], 0, v[130:131]
	s_mov_b32 m0, s40
	s_nop 0
	global_load_lds_dwordx4 v[214:215], off
	v_lshl_add_u64 v[214:215], s[36:37], 0, v[134:135]
	s_add_i32 m0, s40, 0x2000
	s_nop 0
	global_load_lds_dwordx4 v[214:215], off
	v_lshl_add_u64 v[214:215], v[218:219], 0, s[12:13]
	s_mov_b32 m0, s54
	s_nop 0
	global_load_lds_dwordx4 v[214:215], off
	v_lshl_add_u64 v[214:215], v[220:221], 0, s[12:13]
	s_mov_b32 m0, s55
	s_nop 0
	global_load_lds_dwordx4 v[214:215], off
	s_waitcnt vmcnt(8)
	s_waitcnt lgkmcnt(0)
	s_barrier
	s_setprio 1
	s_waitcnt lgkmcnt(0)
	v_mfma_f32_16x16x32_bf16 v[60:63], v[150:153], v[182:185], v[60:63]
	v_mfma_f32_16x16x32_bf16 v[56:59], v[158:161], v[182:185], v[56:59]
	v_mfma_f32_16x16x32_bf16 v[52:55], v[150:153], v[190:193], v[52:55]
	v_mfma_f32_16x16x32_bf16 v[48:51], v[158:161], v[190:193], v[48:51]
	v_mfma_f32_16x16x32_bf16 v[36:39], v[150:153], v[198:201], v[36:39]
	v_mfma_f32_16x16x32_bf16 v[32:35], v[158:161], v[198:201], v[32:35]
	v_mfma_f32_16x16x32_bf16 v[20:23], v[150:153], v[206:209], v[20:23]
	v_mfma_f32_16x16x32_bf16 v[16:19], v[158:161], v[206:209], v[16:19]
	s_setprio 0
	s_setprio 1
	v_mfma_f32_16x16x32_bf16 v[60:63], v[154:157], v[186:189], v[60:63]
	v_mfma_f32_16x16x32_bf16 v[56:59], v[162:165], v[186:189], v[56:59]
	v_mfma_f32_16x16x32_bf16 v[52:55], v[154:157], v[194:197], v[52:55]
	v_mfma_f32_16x16x32_bf16 v[48:51], v[162:165], v[194:197], v[48:51]
	v_mfma_f32_16x16x32_bf16 v[36:39], v[154:157], v[202:205], v[36:39]
	v_mfma_f32_16x16x32_bf16 v[32:35], v[162:165], v[202:205], v[32:35]
	v_mfma_f32_16x16x32_bf16 v[20:23], v[154:157], v[210:213], v[20:23]
	v_mfma_f32_16x16x32_bf16 v[16:19], v[162:165], v[210:213], v[16:19]
	s_setprio 0
	s_setprio 1
	v_mfma_f32_16x16x32_bf16 v[44:47], v[166:169], v[182:185], v[44:47]
	v_mfma_f32_16x16x32_bf16 v[40:43], v[174:177], v[182:185], v[40:43]
	v_mfma_f32_16x16x32_bf16 v[28:31], v[166:169], v[190:193], v[28:31]
	v_mfma_f32_16x16x32_bf16 v[24:27], v[174:177], v[190:193], v[24:27]
	v_mfma_f32_16x16x32_bf16 v[12:15], v[166:169], v[198:201], v[12:15]
	v_mfma_f32_16x16x32_bf16 v[8:11], v[174:177], v[198:201], v[8:11]
	v_mfma_f32_16x16x32_bf16 v[4:7], v[166:169], v[206:209], v[4:7]
	v_mfma_f32_16x16x32_bf16 v[0:3], v[174:177], v[206:209], v[0:3]
	s_setprio 0
	s_setprio 1
	v_mfma_f32_16x16x32_bf16 v[44:47], v[170:173], v[186:189], v[44:47]
	v_mfma_f32_16x16x32_bf16 v[40:43], v[178:181], v[186:189], v[40:43]
	v_mfma_f32_16x16x32_bf16 v[28:31], v[170:173], v[194:197], v[28:31]
	v_mfma_f32_16x16x32_bf16 v[24:27], v[178:181], v[194:197], v[24:27]
	v_mfma_f32_16x16x32_bf16 v[12:15], v[170:173], v[202:205], v[12:15]
	v_mfma_f32_16x16x32_bf16 v[8:11], v[178:181], v[202:205], v[8:11]
	v_mfma_f32_16x16x32_bf16 v[4:7], v[170:173], v[210:213], v[4:7]
	v_mfma_f32_16x16x32_bf16 v[0:3], v[178:181], v[210:213], v[0:3]
	s_setprio 0
	s_barrier
	s_add_i32 s73, s73, 2
	s_add_u32 s71, s71, 0x100
	s_addc_u32 s72, s72, 0
	s_add_u32 s34, s34, 0x100
	s_addc_u32 s35, s35, 0
	s_cmp_gt_u32 s73, 13
	s_cbranch_scc0 .LBB0_1130
	s_and_b64 vcc, exec, s[14:15]
	s_cbranch_vccz .LBB0_1133
	s_barrier

; #define PG8_STAGE(bufoff, gbase, voff) do { _Pragma("unroll") for (int _i = 0; _i < 2; ++_i) \
;         __builtin_amdgcn_global_load_lds((const unsigned*)((const char*)(gbase) + (voff)[_i]), (PG8_LAS unsigned*)(lds + (bufoff) + ldsw + _i * 8192), 16, 0, 0); } while (0)
; #define PG8_LDA(dst, b, h) do { _Pragma("unroll") for (int m = 0; m < 4; ++m) _Pragma("unroll") for (int k = 0; k < 2; ++k) dst[m][k] = *(const PG8_LAS bf16x8*)(lds + PG8_SA(b, h) + aoff + m * 2048 + k * 1024); } while (0)
; #define PG8_LDB(dst, b, h) do { _Pragma("unroll") for (int n = 0; n < 2; ++n) _Pragma("unroll") for (int k = 0; k < 2; ++k) dst[n][k] = *(const PG8_LAS bf16x8*)(lds + PG8_SB(b, h) + boff + n * 2048 + k * 1024); } while (0)
; #define PG8_MMA(ai, bj, At, Bt) do { __builtin_amdgcn_s_setprio(1); _Pragma("unroll") for (int m = 0; m < 4; ++m) _Pragma("unroll") for (int n = 0; n < 2; ++n) _Pragma("unroll") for (int k = 0; k < 2; ++k) \
;         acc[ai][bj][m][n] = __builtin_amdgcn_mfma_f32_16x16x32_bf16(Bt[n][k], At[m][k], acc[ai][bj][m][n], 0, 0, 0); __builtin_amdgcn_s_setprio(0); } while (0)
; #define PG8_WAIT_V(n) asm volatile("s_waitcnt vmcnt(" #n ")" ::: "memory")
; #define PG8_BAR __builtin_amdgcn_s_barrier()
; template <class Epi, class Sched, bool ALIGN_EPI = true, bool SP2 = true>
; __device__ __forceinline__ void gemm_phase(PG8_LAS unsigned char* lds, const Gemm g, const Sched& S, const Epi& E) {
;     ...
;         const bool has_next = S.next(ui + 1, nxt);
;         const char* nA = has_next ? (const char*)g.A + (size_t)nxt.pm * tstepA : cA; const char* nB = has_next ? (const char*)g.Bt + (size_t)nxt.pn * tstepB : cB;
;         for (int t = 0; t < nt; t += 2) {
;             const bool last = (t == nt - 2);
;             const char* a1 = cA + (size_t)(t + 1) * kstep;
;             const char* a2 = last ? nA : cA + (size_t)(t + 2) * kstep; const char* b2 = last ? nB : cB + (size_t)(t + 2) * kstep;
;             const char* a3 = a2 + kstep; const char* b3 = b2 + kstep;
;             PG8_LDB(B0, 0, 0); PG8_LDB(B1, 0, 1); PG8_SCHED; PG8_LDA(At, 0, 0); PG8_STAGE(PG8_SA(1, 1), a1 + hstepA, voffA);
;             PG8_WAIT_V(8); PG8_WAIT_L(0); PG8_BAR; PG8_MMA(0, 0, At, B0); PG8_MMA(0, 1, At, B1); PG8_BAR; PG8_SCHED;
;             PG8_LDA(At, 0, 1); PG8_STAGE(PG8_SB(0, 0), b2, voffB); PG8_STAGE(PG8_SB(0, 1), b2 + hstepB, voffB); PG8_STAGE(PG8_SA(0, 0), a2, voffA);
.LBB0_1193:
	ds_read_b128 v[146:149], v143
	ds_read_b128 v[150:153], v143 offset:1024
	ds_read_b128 v[154:157], v143 offset:2048
	ds_read_b128 v[158:161], v143 offset:3072
	ds_read_b128 v[162:165], v144
	ds_read_b128 v[166:169], v144 offset:1024
	ds_read_b128 v[170:173], v144 offset:2048
	ds_read_b128 v[174:177], v144 offset:3072
	s_add_u32 s40, s38, 0xfffc0080
	s_addc_u32 s41, s39, -1
	s_cmp_eq_u32 s73, 12
	s_cselect_b32 s43, s27, s41
	s_cselect_b32 s42, s65, s40
	s_cselect_b32 s41, s25, s72
	s_cselect_b32 s40, s66, s71
	v_lshl_add_u64 v[210:211], s[38:39], 0, v[138:139]
	s_add_i32 m0, s49, 0xc000
	ds_read_b128 v[178:181], v145
	ds_read_b128 v[182:185], v145 offset:1024
	ds_read_b128 v[186:189], v145 offset:2048
	ds_read_b128 v[190:193], v145 offset:3072
	ds_read_b128 v[194:197], v145 offset:4096
	ds_read_b128 v[198:201], v145 offset:5120
	ds_read_b128 v[202:205], v145 offset:6144
	ds_read_b128 v[206:209], v145 offset:7168
	global_load_lds_dwordx4 v[210:211], off
	v_lshl_add_u64 v[210:211], s[38:39], 0, v[136:137]
	s_add_i32 m0, s49, 0xe000
	s_nop 0
	global_load_lds_dwordx4 v[210:211], off
	s_waitcnt vmcnt(8)
	s_waitcnt lgkmcnt(0)
	s_barrier
	s_setprio 1
	s_waitcnt lgkmcnt(0)
	v_mfma_f32_16x16x32_bf16 v[124:127], v[146:149], v[178:181], v[124:127]
	v_mfma_f32_16x16x32_bf16 v[120:123], v[154:157], v[178:181], v[120:123]
	v_mfma_f32_16x16x32_bf16 v[116:119], v[146:149], v[186:189], v[116:119]
	v_mfma_f32_16x16x32_bf16 v[112:115], v[154:157], v[186:189], v[112:115]
	v_mfma_f32_16x16x32_bf16 v[100:103], v[146:149], v[194:197], v[100:103]
	v_mfma_f32_16x16x32_bf16 v[96:99], v[154:157], v[194:197], v[96:99]
	v_mfma_f32_16x16x32_bf16 v[84:87], v[146:149], v[202:205], v[84:87]
	v_mfma_f32_16x16x32_bf16 v[80:83], v[154:157], v[202:205], v[80:83]
	s_setprio 0
	s_setprio 1
	v_mfma_f32_16x16x32_bf16 v[124:127], v[150:153], v[182:185], v[124:127]
	v_mfma_f32_16x16x32_bf16 v[120:123], v[158:161], v[182:185], v[120:123]
	v_mfma_f32_16x16x32_bf16 v[116:119], v[150:153], v[190:193], v[116:119]
	v_mfma_f32_16x16x32_bf16 v[112:115], v[158:161], v[190:193], v[112:115]
	v_mfma_f32_16x16x32_bf16 v[100:103], v[150:153], v[198:201], v[100:103]
	v_mfma_f32_16x16x32_bf16 v[96:99], v[158:161], v[198:201], v[96:99]
	v_mfma_f32_16x16x32_bf16 v[84:87], v[150:153], v[206:209], v[84:87]
	v_mfma_f32_16x16x32_bf16 v[80:83], v[158:161], v[206:209], v[80:83]
	s_setprio 0
	s_setprio 1
	v_mfma_f32_16x16x32_bf16 v[108:111], v[162:165], v[178:181], v[108:111]
	v_mfma_f32_16x16x32_bf16 v[104:107], v[170:173], v[178:181], v[104:107]
	v_mfma_f32_16x16x32_bf16 v[92:95], v[162:165], v[186:189], v[92:95]
	v_mfma_f32_16x16x32_bf16 v[88:91], v[170:173], v[186:189], v[88:91]
	v_mfma_f32_16x16x32_bf16 v[76:79], v[162:165], v[194:197], v[76:79]
	v_mfma_f32_16x16x32_bf16 v[72:75], v[170:173], v[194:197], v[72:75]
	v_mfma_f32_16x16x32_bf16 v[68:71], v[162:165], v[202:205], v[68:71]
	v_mfma_f32_16x16x32_bf16 v[64:67], v[170:173], v[202:205], v[64:67]
	s_setprio 0
	s_setprio 1
	v_mfma_f32_16x16x32_bf16 v[108:111], v[166:169], v[182:185], v[108:111]
	v_mfma_f32_16x16x32_bf16 v[104:107], v[174:177], v[182:185], v[104:107]
	v_mfma_f32_16x16x32_bf16 v[92:95], v[166:169], v[190:193], v[92:95]
	v_mfma_f32_16x16x32_bf16 v[88:91], v[174:177], v[190:193], v[88:91]
	v_mfma_f32_16x16x32_bf16 v[76:79], v[166:169], v[198:201], v[76:79]
	v_mfma_f32_16x16x32_bf16 v[72:75], v[174:177], v[198:201], v[72:75]
	v_mfma_f32_16x16x32_bf16 v[68:71], v[166:169], v[206:209], v[68:71]
	v_mfma_f32_16x16x32_bf16 v[64:67], v[174:177], v[206:209], v[64:67]
	s_setprio 0
	s_barrier
	s_add_i32 s52, s59, s47
	v_lshl_add_u64 v[210:211], s[40:41], 0, v[132:133]
	s_mov_b32 m0, s52
	ds_read_b128 v[178:181], v145 offset:16384
	ds_read_b128 v[182:185], v145 offset:17408
	ds_read_b128 v[186:189], v145 offset:18432
	ds_read_b128 v[190:193], v145 offset:19456
	ds_read_b128 v[194:197], v145 offset:20480
	ds_read_b128 v[198:201], v145 offset:21504
	ds_read_b128 v[202:205], v145 offset:22528
	ds_read_b128 v[206:209], v145 offset:23552
	global_load_lds_dwordx4 v[210:211], off
	s_add_i32 m0, s52, 0x2000
	s_add_u32 s52, s40, 0x40000
	v_lshl_add_u64 v[212:213], s[40:41], 0, v[128:129]
	s_addc_u32 s53, s41, 0
	s_add_i32 s68, s60, s47
	global_load_lds_dwordx4 v[212:213], off
	v_lshl_add_u64 v[214:215], s[52:53], 0, v[132:133]
	s_mov_b32 m0, s68
	v_lshl_add_u64 v[216:217], s[42:43], 0, v[130:131]
	global_load_lds_dwordx4 v[214:215], off
	v_lshl_add_u64 v[214:215], s[52:53], 0, v[128:129]
	s_add_i32 m0, s68, 0x2000
	s_nop 0
	global_load_lds_dwordx4 v[214:215], off
	v_lshl_add_u64 v[214:215], s[42:43], 0, v[134:135]
	s_mov_b32 m0, s49
	s_nop 0
	global_load_lds_dwordx4 v[214:215], off
	s_mov_b32 m0, s50
	s_nop 0
	global_load_lds_dwordx4 v[216:217], off
	s_waitcnt vmcnt(8)
	s_waitcnt lgkmcnt(0)
	s_barrier
; #define PG8_STAGE(bufoff, gbase, voff) do { _Pragma("unroll") for (int _i = 0; _i < 2; ++_i) \
;         __builtin_amdgcn_global_load_lds((const unsigned*)((const char*)(gbase) + (voff)[_i]), (PG8_LAS unsigned*)(lds + (bufoff) + ldsw + _i * 8192), 16, 0, 0); } while (0)
; #define PG8_LDA(dst, b, h) do { _Pragma("unroll") for (int m = 0; m < 4; ++m) _Pragma("unroll") for (int k = 0; k < 2; ++k) dst[m][k] = *(const PG8_LAS bf16x8*)(lds + PG8_SA(b, h) + aoff + m * 2048 + k * 1024); } while (0)
; #define PG8_LDB(dst, b, h) do { _Pragma("unroll") for (int n = 0; n < 2; ++n) _Pragma("unroll") for (int k = 0; k < 2; ++k) dst[n][k] = *(const PG8_LAS bf16x8*)(lds + PG8_SB(b, h) + boff + n * 2048 + k * 1024); } while (0)
; #define PG8_MMA(ai, bj, At, Bt) do { __builtin_amdgcn_s_setprio(1); _Pragma("unroll") for (int m = 0; m < 4; ++m) _Pragma("unroll") for (int n = 0; n < 2; ++n) _Pragma("unroll") for (int k = 0; k < 2; ++k) \
;         acc[ai][bj][m][n] = __builtin_amdgcn_mfma_f32_16x16x32_bf16(Bt[n][k], At[m][k], acc[ai][bj][m][n], 0, 0, 0); __builtin_amdgcn_s_setprio(0); } while (0)
; #define PG8_WAIT_V(n) asm volatile("s_waitcnt vmcnt(" #n ")" ::: "memory")
; #define PG8_WAIT_L(n) asm volatile("s_waitcnt lgkmcnt(" #n ")" ::: "memory")
; #define PG8_BAR __builtin_amdgcn_s_barrier()
; #define PG8_SCHED __builtin_amdgcn_sched_barrier(0)
; template <class Epi, class Sched, bool ALIGN_EPI = true, bool SP2 = true>
; __device__ __forceinline__ void gemm_phase(PG8_LAS unsigned char* lds, const Gemm g, const Sched& S, const Epi& E) {
;     ...
;             PG8_WAIT_V(8); PG8_WAIT_L(0); PG8_BAR; PG8_MMA(1, 0, At, B0); PG8_MMA(1, 1, At, B1); PG8_BAR; PG8_SCHED;
;             PG8_LDB(B0, 1, 0); PG8_LDB(B1, 1, 1); PG8_SCHED; PG8_LDA(At, 1, 0); PG8_STAGE(PG8_SA(0, 1), a2 + hstepA, voffA);
;             PG8_WAIT_V(8); PG8_WAIT_L(0); PG8_BAR; PG8_MMA(0, 0, At, B0); PG8_MMA(0, 1, At, B1); PG8_BAR; PG8_SCHED;
	s_setprio 1
	s_waitcnt lgkmcnt(0)
	v_mfma_f32_16x16x32_bf16 v[60:63], v[146:149], v[178:181], v[60:63]
	v_mfma_f32_16x16x32_bf16 v[56:59], v[154:157], v[178:181], v[56:59]
	v_mfma_f32_16x16x32_bf16 v[52:55], v[146:149], v[186:189], v[52:55]
	v_mfma_f32_16x16x32_bf16 v[48:51], v[154:157], v[186:189], v[48:51]
	v_mfma_f32_16x16x32_bf16 v[36:39], v[146:149], v[194:197], v[36:39]
	v_mfma_f32_16x16x32_bf16 v[32:35], v[154:157], v[194:197], v[32:35]
	v_mfma_f32_16x16x32_bf16 v[20:23], v[146:149], v[202:205], v[20:23]
	v_mfma_f32_16x16x32_bf16 v[16:19], v[154:157], v[202:205], v[16:19]
	s_setprio 0
	s_setprio 1
	v_mfma_f32_16x16x32_bf16 v[60:63], v[150:153], v[182:185], v[60:63]
	v_mfma_f32_16x16x32_bf16 v[56:59], v[158:161], v[182:185], v[56:59]
	v_mfma_f32_16x16x32_bf16 v[52:55], v[150:153], v[190:193], v[52:55]
	v_mfma_f32_16x16x32_bf16 v[48:51], v[158:161], v[190:193], v[48:51]
	v_mfma_f32_16x16x32_bf16 v[36:39], v[150:153], v[198:201], v[36:39]
	v_mfma_f32_16x16x32_bf16 v[32:35], v[158:161], v[198:201], v[32:35]
	v_mfma_f32_16x16x32_bf16 v[20:23], v[150:153], v[206:209], v[20:23]
	v_mfma_f32_16x16x32_bf16 v[16:19], v[158:161], v[206:209], v[16:19]
	s_setprio 0
	s_setprio 1
	v_mfma_f32_16x16x32_bf16 v[44:47], v[162:165], v[178:181], v[44:47]
	v_mfma_f32_16x16x32_bf16 v[40:43], v[170:173], v[178:181], v[40:43]
	v_mfma_f32_16x16x32_bf16 v[28:31], v[162:165], v[186:189], v[28:31]
	v_mfma_f32_16x16x32_bf16 v[24:27], v[170:173], v[186:189], v[24:27]
	v_mfma_f32_16x16x32_bf16 v[12:15], v[162:165], v[194:197], v[12:15]
	v_mfma_f32_16x16x32_bf16 v[8:11], v[170:173], v[194:197], v[8:11]
	v_mfma_f32_16x16x32_bf16 v[4:7], v[162:165], v[202:205], v[4:7]
	v_mfma_f32_16x16x32_bf16 v[0:3], v[170:173], v[202:205], v[0:3]
	s_setprio 0
	s_setprio 1
	v_mfma_f32_16x16x32_bf16 v[44:47], v[166:169], v[182:185], v[44:47]
	v_mfma_f32_16x16x32_bf16 v[40:43], v[174:177], v[182:185], v[40:43]
	v_mfma_f32_16x16x32_bf16 v[28:31], v[166:169], v[190:193], v[28:31]
	v_mfma_f32_16x16x32_bf16 v[24:27], v[174:177], v[190:193], v[24:27]
	v_mfma_f32_16x16x32_bf16 v[12:15], v[166:169], v[198:201], v[12:15]
	v_mfma_f32_16x16x32_bf16 v[8:11], v[174:177], v[198:201], v[8:11]
	v_mfma_f32_16x16x32_bf16 v[4:7], v[166:169], v[206:209], v[4:7]
	v_mfma_f32_16x16x32_bf16 v[0:3], v[174:177], v[206:209], v[0:3]
	s_setprio 0
	s_barrier
	s_add_i32 s52, 0, 0x18000
	s_add_i32 s53, 0, 0x1c000
	v_add_u32_e32 v158, s52, v141
	v_add_u32_e32 v174, s53, v141
	ds_read_b128 v[146:149], v158
	ds_read_b128 v[150:153], v158 offset:1024
	ds_read_b128 v[154:157], v158 offset:2048
	ds_read_b128 v[158:161], v158 offset:3072
	ds_read_b128 v[162:165], v174
	ds_read_b128 v[166:169], v174 offset:1024
	ds_read_b128 v[170:173], v174 offset:2048
	ds_read_b128 v[174:177], v174 offset:3072
	s_add_u32 s42, s42, 0x40000
	s_addc_u32 s43, s43, 0
	s_mov_b32 m0, s51
	v_lshl_add_u64 v[218:219], s[42:43], 0, v[134:135]
	ds_read_b128 v[178:181], v145 offset:32768
	ds_read_b128 v[182:185], v145 offset:33792
	ds_read_b128 v[186:189], v145 offset:34816
	ds_read_b128 v[190:193], v145 offset:35840
	ds_read_b128 v[194:197], v145 offset:36864
	ds_read_b128 v[198:201], v145 offset:37888
	ds_read_b128 v[202:205], v145 offset:38912
	ds_read_b128 v[206:209], v145 offset:39936
	global_load_lds_dwordx4 v[218:219], off
	v_lshl_add_u64 v[218:219], s[42:43], 0, v[130:131]
	s_mov_b32 m0, s54
	s_nop 0
	global_load_lds_dwordx4 v[218:219], off
	s_waitcnt vmcnt(8)
	s_waitcnt lgkmcnt(0)
	s_barrier
	s_setprio 1
	s_waitcnt lgkmcnt(0)
	v_mfma_f32_16x16x32_bf16 v[124:127], v[146:149], v[178:181], v[124:127]
	v_mfma_f32_16x16x32_bf16 v[120:123], v[154:157], v[178:181], v[120:123]
	v_mfma_f32_16x16x32_bf16 v[116:119], v[146:149], v[186:189], v[116:119]
	v_mfma_f32_16x16x32_bf16 v[112:115], v[154:157], v[186:189], v[112:115]
	v_mfma_f32_16x16x32_bf16 v[100:103], v[146:149], v[194:197], v[100:103]
	v_mfma_f32_16x16x32_bf16 v[96:99], v[154:157], v[194:197], v[96:99]
	v_mfma_f32_16x16x32_bf16 v[84:87], v[146:149], v[202:205], v[84:87]
	v_mfma_f32_16x16x32_bf16 v[80:83], v[154:157], v[202:205], v[80:83]
	s_setprio 0
	s_setprio 1
	v_mfma_f32_16x16x32_bf16 v[124:127], v[150:153], v[182:185], v[124:127]
	v_mfma_f32_16x16x32_bf16 v[120:123], v[158:161], v[182:185], v[120:123]
	v_mfma_f32_16x16x32_bf16 v[116:119], v[150:153], v[190:193], v[116:119]
	v_mfma_f32_16x16x32_bf16 v[112:115], v[158:161], v[190:193], v[112:115]
	v_mfma_f32_16x16x32_bf16 v[100:103], v[150:153], v[198:201], v[100:103]
	v_mfma_f32_16x16x32_bf16 v[96:99], v[158:161], v[198:201], v[96:99]
	v_mfma_f32_16x16x32_bf16 v[84:87], v[150:153], v[206:209], v[84:87]
	v_mfma_f32_16x16x32_bf16 v[80:83], v[158:161], v[206:209], v[80:83]
	s_setprio 0
	s_setprio 1
	v_mfma_f32_16x16x32_bf16 v[108:111], v[162:165], v[178:181], v[108:111]
	v_mfma_f32_16x16x32_bf16 v[104:107], v[170:173], v[178:181], v[104:107]
	v_mfma_f32_16x16x32_bf16 v[92:95], v[162:165], v[186:189], v[92:95]
	v_mfma_f32_16x16x32_bf16 v[88:91], v[170:173], v[186:189], v[88:91]
	v_mfma_f32_16x16x32_bf16 v[76:79], v[162:165], v[194:197], v[76:79]
	v_mfma_f32_16x16x32_bf16 v[72:75], v[170:173], v[194:197], v[72:75]
	v_mfma_f32_16x16x32_bf16 v[68:71], v[162:165], v[202:205], v[68:71]
	v_mfma_f32_16x16x32_bf16 v[64:67], v[170:173], v[202:205], v[64:67]
	s_setprio 0
	s_setprio 1
	v_mfma_f32_16x16x32_bf16 v[108:111], v[166:169], v[182:185], v[108:111]
	v_mfma_f32_16x16x32_bf16 v[104:107], v[174:177], v[182:185], v[104:107]
	v_mfma_f32_16x16x32_bf16 v[92:95], v[166:169], v[190:193], v[92:95]
	v_mfma_f32_16x16x32_bf16 v[88:91], v[174:177], v[190:193], v[88:91]
	v_mfma_f32_16x16x32_bf16 v[76:79], v[166:169], v[198:201], v[76:79]
	v_mfma_f32_16x16x32_bf16 v[72:75], v[174:177], v[198:201], v[72:75]
	v_mfma_f32_16x16x32_bf16 v[68:71], v[166:169], v[206:209], v[68:71]
	v_mfma_f32_16x16x32_bf16 v[64:67], v[174:177], v[206:209], v[64:67]
	s_setprio 0
	s_barrier
; #define PG8_STAGE(bufoff, gbase, voff) do { _Pragma("unroll") for (int _i = 0; _i < 2; ++_i) \
;         __builtin_amdgcn_global_load_lds((const unsigned*)((const char*)(gbase) + (voff)[_i]), (PG8_LAS unsigned*)(lds + (bufoff) + ldsw + _i * 8192), 16, 0, 0); } while (0)
; #define PG8_LDA(dst, b, h) do { _Pragma("unroll") for (int m = 0; m < 4; ++m) _Pragma("unroll") for (int k = 0; k < 2; ++k) dst[m][k] = *(const PG8_LAS bf16x8*)(lds + PG8_SA(b, h) + aoff + m * 2048 + k * 1024); } while (0)
; #define PG8_MMA(ai, bj, At, Bt) do { __builtin_amdgcn_s_setprio(1); _Pragma("unroll") for (int m = 0; m < 4; ++m) _Pragma("unroll") for (int n = 0; n < 2; ++n) _Pragma("unroll") for (int k = 0; k < 2; ++k) \
;         acc[ai][bj][m][n] = __builtin_amdgcn_mfma_f32_16x16x32_bf16(Bt[n][k], At[m][k], acc[ai][bj][m][n], 0, 0, 0); __builtin_amdgcn_s_setprio(0); } while (0)
; #define PG8_WAIT_V(n) asm volatile("s_waitcnt vmcnt(" #n ")" ::: "memory")
; #define PG8_WAIT_L(n) asm volatile("s_waitcnt lgkmcnt(" #n ")" ::: "memory")
; #define PG8_BAR __builtin_amdgcn_s_barrier()
; #define PG8_SCHED __builtin_amdgcn_sched_barrier(0)
; template <class Epi, class Sched, bool ALIGN_EPI = true, bool SP2 = true>
; __device__ __forceinline__ void gemm_phase(PG8_LAS unsigned char* lds, const Gemm g, const Sched& S, const Epi& E) {
;     ...
;             PG8_LDA(At, 1, 1); PG8_STAGE(PG8_SB(1, 0), b3, voffB); PG8_STAGE(PG8_SB(1, 1), b3 + hstepB, voffB); PG8_STAGE(PG8_SA(1, 0), a3, voffA);
;             PG8_WAIT_V(8); PG8_WAIT_L(0); PG8_BAR; PG8_MMA(1, 0, At, B0); PG8_MMA(1, 1, At, B1); PG8_BAR; PG8_SCHED;
;         }
;         if constexpr (ALIGN_EPI) { if (wr == 0) PG8_BAR; }
	s_add_i32 s42, s52, s47
	v_lshl_add_u64 v[210:211], v[210:211], 0, s[10:11]
	s_mov_b32 m0, s42
	ds_read_b128 v[178:181], v145 offset:49152
	ds_read_b128 v[182:185], v145 offset:50176
	ds_read_b128 v[186:189], v145 offset:51200
	ds_read_b128 v[190:193], v145 offset:52224
	ds_read_b128 v[194:197], v145 offset:53248
	ds_read_b128 v[198:201], v145 offset:54272
	ds_read_b128 v[202:205], v145 offset:55296
	ds_read_b128 v[206:209], v145 offset:56320
	global_load_lds_dwordx4 v[210:211], off
	s_add_i32 m0, s42, 0x2000
	s_add_u32 s40, s40, 0x40080
	v_lshl_add_u64 v[210:211], v[212:213], 0, s[10:11]
	s_addc_u32 s41, s41, 0
	s_add_i32 s42, s53, s47
	global_load_lds_dwordx4 v[210:211], off
	v_lshl_add_u64 v[210:211], s[40:41], 0, v[132:133]
	s_mov_b32 m0, s42
	s_nop 0
	global_load_lds_dwordx4 v[210:211], off
	v_lshl_add_u64 v[210:211], s[40:41], 0, v[128:129]
	s_add_i32 m0, s42, 0x2000
	s_nop 0
	global_load_lds_dwordx4 v[210:211], off
	v_lshl_add_u64 v[210:211], v[214:215], 0, s[10:11]
	s_mov_b32 m0, s55
	s_nop 0
	global_load_lds_dwordx4 v[210:211], off
	v_lshl_add_u64 v[210:211], v[216:217], 0, s[10:11]
	s_mov_b32 m0, s56
	s_nop 0
	global_load_lds_dwordx4 v[210:211], off
	s_waitcnt vmcnt(8)
	s_waitcnt lgkmcnt(0)
	s_barrier
	s_setprio 1
	s_waitcnt lgkmcnt(0)
	v_mfma_f32_16x16x32_bf16 v[60:63], v[146:149], v[178:181], v[60:63]
	v_mfma_f32_16x16x32_bf16 v[56:59], v[154:157], v[178:181], v[56:59]
	v_mfma_f32_16x16x32_bf16 v[52:55], v[146:149], v[186:189], v[52:55]
	v_mfma_f32_16x16x32_bf16 v[48:51], v[154:157], v[186:189], v[48:51]
	v_mfma_f32_16x16x32_bf16 v[36:39], v[146:149], v[194:197], v[36:39]
	v_mfma_f32_16x16x32_bf16 v[32:35], v[154:157], v[194:197], v[32:35]
	v_mfma_f32_16x16x32_bf16 v[20:23], v[146:149], v[202:205], v[20:23]
	v_mfma_f32_16x16x32_bf16 v[16:19], v[154:157], v[202:205], v[16:19]
	s_setprio 0
	s_setprio 1
	v_mfma_f32_16x16x32_bf16 v[60:63], v[150:153], v[182:185], v[60:63]
	v_mfma_f32_16x16x32_bf16 v[56:59], v[158:161], v[182:185], v[56:59]
	v_mfma_f32_16x16x32_bf16 v[52:55], v[150:153], v[190:193], v[52:55]
	v_mfma_f32_16x16x32_bf16 v[48:51], v[158:161], v[190:193], v[48:51]
	v_mfma_f32_16x16x32_bf16 v[36:39], v[150:153], v[198:201], v[36:39]
	v_mfma_f32_16x16x32_bf16 v[32:35], v[158:161], v[198:201], v[32:35]
	v_mfma_f32_16x16x32_bf16 v[20:23], v[150:153], v[206:209], v[20:23]
	v_mfma_f32_16x16x32_bf16 v[16:19], v[158:161], v[206:209], v[16:19]
	s_setprio 0
	s_setprio 1
	v_mfma_f32_16x16x32_bf16 v[44:47], v[162:165], v[178:181], v[44:47]
	v_mfma_f32_16x16x32_bf16 v[40:43], v[170:173], v[178:181], v[40:43]
	v_mfma_f32_16x16x32_bf16 v[28:31], v[162:165], v[186:189], v[28:31]
	v_mfma_f32_16x16x32_bf16 v[24:27], v[170:173], v[186:189], v[24:27]
	v_mfma_f32_16x16x32_bf16 v[12:15], v[162:165], v[194:197], v[12:15]
	v_mfma_f32_16x16x32_bf16 v[8:11], v[170:173], v[194:197], v[8:11]
	v_mfma_f32_16x16x32_bf16 v[4:7], v[162:165], v[202:205], v[4:7]
	v_mfma_f32_16x16x32_bf16 v[0:3], v[170:173], v[202:205], v[0:3]
	s_setprio 0
	s_setprio 1
	v_mfma_f32_16x16x32_bf16 v[44:47], v[166:169], v[182:185], v[44:47]
	v_mfma_f32_16x16x32_bf16 v[40:43], v[174:177], v[182:185], v[40:43]
	v_mfma_f32_16x16x32_bf16 v[28:31], v[166:169], v[190:193], v[28:31]
	v_mfma_f32_16x16x32_bf16 v[24:27], v[174:177], v[190:193], v[24:27]
	v_mfma_f32_16x16x32_bf16 v[12:15], v[166:169], v[198:201], v[12:15]
	v_mfma_f32_16x16x32_bf16 v[8:11], v[174:177], v[198:201], v[8:11]
	v_mfma_f32_16x16x32_bf16 v[4:7], v[166:169], v[206:209], v[4:7]
	v_mfma_f32_16x16x32_bf16 v[0:3], v[174:177], v[206:209], v[0:3]
	s_setprio 0
	s_barrier
	s_add_i32 s73, s73, 2
	s_add_u32 s71, s71, 0x100
	s_addc_u32 s72, s72, 0
	s_add_u32 s38, s38, 0x100
	s_addc_u32 s39, s39, 0
	s_cmp_gt_u32 s73, 13
	s_cbranch_scc0 .LBB0_1193
	s_and_b64 vcc, exec, s[14:15]
	s_cbranch_vccz .LBB0_1196
	s_barrier

; #define PG8_STAGE(bufoff, gbase, voff) do { _Pragma("unroll") for (int _i = 0; _i < 2; ++_i) \
;         __builtin_amdgcn_global_load_lds((const unsigned*)((const char*)(gbase) + (voff)[_i]), (PG8_LAS unsigned*)(lds + (bufoff) + ldsw + _i * 8192), 16, 0, 0); } while (0)
; #define PG8_LDA(dst, b, h) do { _Pragma("unroll") for (int m = 0; m < 4; ++m) _Pragma("unroll") for (int k = 0; k < 2; ++k) dst[m][k] = *(const PG8_LAS bf16x8*)(lds + PG8_SA(b, h) + aoff + m * 2048 + k * 1024); } while (0)
; #define PG8_LDB(dst, b, h) do { _Pragma("unroll") for (int n = 0; n < 2; ++n) _Pragma("unroll") for (int k = 0; k < 2; ++k) dst[n][k] = *(const PG8_LAS bf16x8*)(lds + PG8_SB(b, h) + boff + n * 2048 + k * 1024); } while (0)
; #define PG8_MMA(ai, bj, At, Bt) do { __builtin_amdgcn_s_setprio(1); _Pragma("unroll") for (int m = 0; m < 4; ++m) _Pragma("unroll") for (int n = 0; n < 2; ++n) _Pragma("unroll") for (int k = 0; k < 2; ++k) \
;         acc[ai][bj][m][n] = __builtin_amdgcn_mfma_f32_16x16x32_bf16(Bt[n][k], At[m][k], acc[ai][bj][m][n], 0, 0, 0); __builtin_amdgcn_s_setprio(0); } while (0)
; #define PG8_WAIT_V(n) asm volatile("s_waitcnt vmcnt(" #n ")" ::: "memory")
; #define PG8_WAIT_L(n) asm volatile("s_waitcnt lgkmcnt(" #n ")" ::: "memory")
; #define PG8_BAR __builtin_amdgcn_s_barrier()
; #define PG8_SCHED __builtin_amdgcn_sched_barrier(0)
; template <class Epi, class Sched, bool ALIGN_EPI = true, bool SP2 = true>
; __device__ __forceinline__ void gemm_phase(PG8_LAS unsigned char* lds, const Gemm g, const Sched& S, const Epi& E) {
;     ...
;             PG8_LDB(B0, 0, 0); PG8_LDB(B1, 0, 1); PG8_SCHED; PG8_LDA(At, 0, 0); PG8_STAGE(PG8_SA(1, 1), a1 + hstepA, voffA);
;             PG8_WAIT_V(8); PG8_WAIT_L(0); PG8_BAR; PG8_MMA(0, 0, At, B0); PG8_MMA(0, 1, At, B1); PG8_BAR; PG8_SCHED;
;             PG8_LDA(At, 0, 1); PG8_STAGE(PG8_SB(0, 0), b2, voffB); PG8_STAGE(PG8_SB(0, 1), b2 + hstepB, voffB); PG8_STAGE(PG8_SA(0, 0), a2, voffA);
;             PG8_WAIT_V(8); PG8_WAIT_L(0); PG8_BAR; PG8_MMA(1, 0, At, B0); PG8_MMA(1, 1, At, B1); PG8_BAR; PG8_SCHED;
.LBB0_1311:
	ds_read_b128 v[144:147], v153
	ds_read_b128 v[156:159], v153 offset:1024
	ds_read_b128 v[160:163], v153 offset:2048
	ds_read_b128 v[164:167], v153 offset:3072
	ds_read_b128 v[168:171], v154
	ds_read_b128 v[172:175], v154 offset:1024
	ds_read_b128 v[176:179], v154 offset:2048
	ds_read_b128 v[180:183], v154 offset:3072
	s_add_u32 s38, s34, 0xfffc0080
	s_addc_u32 s39, s35, -1
	s_cmp_eq_u32 s72, 12
	s_cselect_b32 s41, s25, s39
	s_cselect_b32 s40, s64, s38
	s_cselect_b32 s39, s23, s71
	s_cselect_b32 s38, s65, s66
	v_lshl_add_u64 v[148:149], s[34:35], 0, v[138:139]
	s_add_i32 m0, s47, 0xc000
	ds_read_b128 v[184:187], v155
	ds_read_b128 v[188:191], v155 offset:1024
	ds_read_b128 v[192:195], v155 offset:2048
	ds_read_b128 v[196:199], v155 offset:3072
	ds_read_b128 v[200:203], v155 offset:4096
	ds_read_b128 v[204:207], v155 offset:5120
	ds_read_b128 v[208:211], v155 offset:6144
	ds_read_b128 v[212:215], v155 offset:7168
	global_load_lds_dwordx4 v[148:149], off
	v_lshl_add_u64 v[148:149], s[34:35], 0, v[136:137]
	s_add_i32 m0, s47, 0xe000
	s_nop 0
	global_load_lds_dwordx4 v[148:149], off
	s_waitcnt vmcnt(8)
	s_waitcnt lgkmcnt(0)
	s_barrier
	s_setprio 1
	s_waitcnt lgkmcnt(0)
	v_mfma_f32_16x16x32_bf16 v[124:127], v[144:147], v[184:187], v[124:127]
	v_mfma_f32_16x16x32_bf16 v[120:123], v[160:163], v[184:187], v[120:123]
	v_mfma_f32_16x16x32_bf16 v[108:111], v[144:147], v[192:195], v[108:111]
	v_mfma_f32_16x16x32_bf16 v[104:107], v[160:163], v[192:195], v[104:107]
	v_mfma_f32_16x16x32_bf16 v[92:95], v[144:147], v[200:203], v[92:95]
	v_mfma_f32_16x16x32_bf16 v[88:91], v[160:163], v[200:203], v[88:91]
	v_mfma_f32_16x16x32_bf16 v[76:79], v[144:147], v[208:211], v[76:79]
	v_mfma_f32_16x16x32_bf16 v[72:75], v[160:163], v[208:211], v[72:75]
	s_setprio 0
	s_setprio 1
	v_mfma_f32_16x16x32_bf16 v[124:127], v[156:159], v[188:191], v[124:127]
	v_mfma_f32_16x16x32_bf16 v[120:123], v[164:167], v[188:191], v[120:123]
	v_mfma_f32_16x16x32_bf16 v[108:111], v[156:159], v[196:199], v[108:111]
	v_mfma_f32_16x16x32_bf16 v[104:107], v[164:167], v[196:199], v[104:107]
	v_mfma_f32_16x16x32_bf16 v[92:95], v[156:159], v[204:207], v[92:95]
	v_mfma_f32_16x16x32_bf16 v[88:91], v[164:167], v[204:207], v[88:91]
	v_mfma_f32_16x16x32_bf16 v[76:79], v[156:159], v[212:215], v[76:79]
	v_mfma_f32_16x16x32_bf16 v[72:75], v[164:167], v[212:215], v[72:75]
	s_setprio 0
	s_setprio 1
	v_mfma_f32_16x16x32_bf16 v[116:119], v[168:171], v[184:187], v[116:119]
	v_mfma_f32_16x16x32_bf16 v[112:115], v[176:179], v[184:187], v[112:115]
	v_mfma_f32_16x16x32_bf16 v[100:103], v[168:171], v[192:195], v[100:103]
	v_mfma_f32_16x16x32_bf16 v[96:99], v[176:179], v[192:195], v[96:99]
	v_mfma_f32_16x16x32_bf16 v[84:87], v[168:171], v[200:203], v[84:87]
	v_mfma_f32_16x16x32_bf16 v[80:83], v[176:179], v[200:203], v[80:83]
	v_mfma_f32_16x16x32_bf16 v[68:71], v[168:171], v[208:211], v[68:71]
	v_mfma_f32_16x16x32_bf16 v[64:67], v[176:179], v[208:211], v[64:67]
	s_setprio 0
	s_setprio 1
	v_mfma_f32_16x16x32_bf16 v[116:119], v[172:175], v[188:191], v[116:119]
	v_mfma_f32_16x16x32_bf16 v[112:115], v[180:183], v[188:191], v[112:115]
	v_mfma_f32_16x16x32_bf16 v[100:103], v[172:175], v[196:199], v[100:103]
	v_mfma_f32_16x16x32_bf16 v[96:99], v[180:183], v[196:199], v[96:99]
	v_mfma_f32_16x16x32_bf16 v[84:87], v[172:175], v[204:207], v[84:87]
	v_mfma_f32_16x16x32_bf16 v[80:83], v[180:183], v[204:207], v[80:83]
	v_mfma_f32_16x16x32_bf16 v[68:71], v[172:175], v[212:215], v[68:71]
	v_mfma_f32_16x16x32_bf16 v[64:67], v[180:183], v[212:215], v[64:67]
	s_setprio 0
	s_barrier
	s_add_i32 s52, s58, s46
	v_lshl_add_u64 v[148:149], s[38:39], 0, v[130:131]
	s_mov_b32 m0, s52
	ds_read_b128 v[184:187], v155 offset:16384
	ds_read_b128 v[188:191], v155 offset:17408
	ds_read_b128 v[192:195], v155 offset:18432
	ds_read_b128 v[196:199], v155 offset:19456
	ds_read_b128 v[200:203], v155 offset:20480
	ds_read_b128 v[204:207], v155 offset:21504
	ds_read_b128 v[208:211], v155 offset:22528
	ds_read_b128 v[212:215], v155 offset:23552
	global_load_lds_dwordx4 v[148:149], off
	s_add_i32 m0, s52, 0x2000
	s_add_u32 s52, s38, 0x40000
	v_lshl_add_u64 v[216:217], s[38:39], 0, v[134:135]
	s_addc_u32 s53, s39, 0
	s_add_i32 s68, s59, s46
	global_load_lds_dwordx4 v[216:217], off
	v_lshl_add_u64 v[218:219], s[52:53], 0, v[130:131]
	s_mov_b32 m0, s68
	v_lshl_add_u64 v[220:221], s[40:41], 0, v[132:133]
	global_load_lds_dwordx4 v[218:219], off
	v_lshl_add_u64 v[218:219], s[52:53], 0, v[134:135]
	s_add_i32 m0, s68, 0x2000
	s_nop 0
	global_load_lds_dwordx4 v[218:219], off
	v_lshl_add_u64 v[218:219], s[40:41], 0, v[128:129]
	s_mov_b32 m0, s47
	s_nop 0
	global_load_lds_dwordx4 v[218:219], off
	s_mov_b32 m0, s48
	s_nop 0
	global_load_lds_dwordx4 v[220:221], off
	s_waitcnt vmcnt(8)
	s_waitcnt lgkmcnt(0)
	s_barrier
; #define PG8_STAGE(bufoff, gbase, voff) do { _Pragma("unroll") for (int _i = 0; _i < 2; ++_i) \
;         __builtin_amdgcn_global_load_lds((const unsigned*)((const char*)(gbase) + (voff)[_i]), (PG8_LAS unsigned*)(lds + (bufoff) + ldsw + _i * 8192), 16, 0, 0); } while (0)
; #define PG8_LDA(dst, b, h) do { _Pragma("unroll") for (int m = 0; m < 4; ++m) _Pragma("unroll") for (int k = 0; k < 2; ++k) dst[m][k] = *(const PG8_LAS bf16x8*)(lds + PG8_SA(b, h) + aoff + m * 2048 + k * 1024); } while (0)
; #define PG8_LDB(dst, b, h) do { _Pragma("unroll") for (int n = 0; n < 2; ++n) _Pragma("unroll") for (int k = 0; k < 2; ++k) dst[n][k] = *(const PG8_LAS bf16x8*)(lds + PG8_SB(b, h) + boff + n * 2048 + k * 1024); } while (0)
; #define PG8_MMA(ai, bj, At, Bt) do { __builtin_amdgcn_s_setprio(1); _Pragma("unroll") for (int m = 0; m < 4; ++m) _Pragma("unroll") for (int n = 0; n < 2; ++n) _Pragma("unroll") for (int k = 0; k < 2; ++k) \
;         acc[ai][bj][m][n] = __builtin_amdgcn_mfma_f32_16x16x32_bf16(Bt[n][k], At[m][k], acc[ai][bj][m][n], 0, 0, 0); __builtin_amdgcn_s_setprio(0); } while (0)
; #define PG8_WAIT_V(n) asm volatile("s_waitcnt vmcnt(" #n ")" ::: "memory")
; #define PG8_WAIT_L(n) asm volatile("s_waitcnt lgkmcnt(" #n ")" ::: "memory")
; #define PG8_BAR __builtin_amdgcn_s_barrier()
; #define PG8_SCHED __builtin_amdgcn_sched_barrier(0)
; template <class Epi, class Sched, bool ALIGN_EPI = true, bool SP2 = true>
; __device__ __forceinline__ void gemm_phase(PG8_LAS unsigned char* lds, const Gemm g, const Sched& S, const Epi& E) {
;     ...
;             PG8_WAIT_V(8); PG8_WAIT_L(0); PG8_BAR; PG8_MMA(1, 0, At, B0); PG8_MMA(1, 1, At, B1); PG8_BAR; PG8_SCHED;
;             PG8_LDB(B0, 1, 0); PG8_LDB(B1, 1, 1); PG8_SCHED; PG8_LDA(At, 1, 0); PG8_STAGE(PG8_SA(0, 1), a2 + hstepA, voffA);
;             PG8_WAIT_V(8); PG8_WAIT_L(0); PG8_BAR; PG8_MMA(0, 0, At, B0); PG8_MMA(0, 1, At, B1); PG8_BAR; PG8_SCHED;
	s_setprio 1
	s_waitcnt lgkmcnt(0)
	v_mfma_f32_16x16x32_bf16 v[60:63], v[144:147], v[184:187], v[60:63]
	v_mfma_f32_16x16x32_bf16 v[56:59], v[160:163], v[184:187], v[56:59]
	v_mfma_f32_16x16x32_bf16 v[44:47], v[144:147], v[192:195], v[44:47]
	v_mfma_f32_16x16x32_bf16 v[40:43], v[160:163], v[192:195], v[40:43]
	v_mfma_f32_16x16x32_bf16 v[28:31], v[144:147], v[200:203], v[28:31]
	v_mfma_f32_16x16x32_bf16 v[24:27], v[160:163], v[200:203], v[24:27]
	v_mfma_f32_16x16x32_bf16 v[12:15], v[144:147], v[208:211], v[12:15]
	v_mfma_f32_16x16x32_bf16 v[8:11], v[160:163], v[208:211], v[8:11]
	s_setprio 0
	s_setprio 1
	v_mfma_f32_16x16x32_bf16 v[60:63], v[156:159], v[188:191], v[60:63]
	v_mfma_f32_16x16x32_bf16 v[56:59], v[164:167], v[188:191], v[56:59]
	v_mfma_f32_16x16x32_bf16 v[44:47], v[156:159], v[196:199], v[44:47]
	v_mfma_f32_16x16x32_bf16 v[40:43], v[164:167], v[196:199], v[40:43]
	v_mfma_f32_16x16x32_bf16 v[28:31], v[156:159], v[204:207], v[28:31]
	v_mfma_f32_16x16x32_bf16 v[24:27], v[164:167], v[204:207], v[24:27]
	v_mfma_f32_16x16x32_bf16 v[12:15], v[156:159], v[212:215], v[12:15]
	v_mfma_f32_16x16x32_bf16 v[8:11], v[164:167], v[212:215], v[8:11]
	s_setprio 0
	s_setprio 1
	v_mfma_f32_16x16x32_bf16 v[52:55], v[168:171], v[184:187], v[52:55]
	v_mfma_f32_16x16x32_bf16 v[48:51], v[176:179], v[184:187], v[48:51]
	v_mfma_f32_16x16x32_bf16 v[36:39], v[168:171], v[192:195], v[36:39]
	v_mfma_f32_16x16x32_bf16 v[32:35], v[176:179], v[192:195], v[32:35]
	v_mfma_f32_16x16x32_bf16 v[20:23], v[168:171], v[200:203], v[20:23]
	v_mfma_f32_16x16x32_bf16 v[16:19], v[176:179], v[200:203], v[16:19]
	v_mfma_f32_16x16x32_bf16 v[4:7], v[168:171], v[208:211], v[4:7]
	v_mfma_f32_16x16x32_bf16 v[0:3], v[176:179], v[208:211], v[0:3]
	s_setprio 0
	s_setprio 1
	v_mfma_f32_16x16x32_bf16 v[52:55], v[172:175], v[188:191], v[52:55]
	v_mfma_f32_16x16x32_bf16 v[48:51], v[180:183], v[188:191], v[48:51]
	v_mfma_f32_16x16x32_bf16 v[36:39], v[172:175], v[196:199], v[36:39]
	v_mfma_f32_16x16x32_bf16 v[32:35], v[180:183], v[196:199], v[32:35]
	v_mfma_f32_16x16x32_bf16 v[20:23], v[172:175], v[204:207], v[20:23]
	v_mfma_f32_16x16x32_bf16 v[16:19], v[180:183], v[204:207], v[16:19]
	v_mfma_f32_16x16x32_bf16 v[4:7], v[172:175], v[212:215], v[4:7]
	v_mfma_f32_16x16x32_bf16 v[0:3], v[180:183], v[212:215], v[0:3]
	s_setprio 0
	s_barrier
	s_add_i32 s52, 0, 0x18000
	s_add_i32 s53, 0, 0x1c000
	v_add_u32_e32 v164, s52, v151
	v_add_u32_e32 v180, s53, v151
	ds_read_b128 v[144:147], v164
	ds_read_b128 v[156:159], v164 offset:1024
	ds_read_b128 v[160:163], v164 offset:2048
	ds_read_b128 v[164:167], v164 offset:3072
	ds_read_b128 v[168:171], v180
	ds_read_b128 v[172:175], v180 offset:1024
	ds_read_b128 v[176:179], v180 offset:2048
	ds_read_b128 v[180:183], v180 offset:3072
	s_add_u32 s40, s40, 0x40000
	s_addc_u32 s41, s41, 0
	s_mov_b32 m0, s49
	v_lshl_add_u64 v[222:223], s[40:41], 0, v[128:129]
	ds_read_b128 v[184:187], v155 offset:32768
	ds_read_b128 v[188:191], v155 offset:33792
	ds_read_b128 v[192:195], v155 offset:34816
	ds_read_b128 v[196:199], v155 offset:35840
	ds_read_b128 v[200:203], v155 offset:36864
	ds_read_b128 v[204:207], v155 offset:37888
	ds_read_b128 v[208:211], v155 offset:38912
	ds_read_b128 v[212:215], v155 offset:39936
	global_load_lds_dwordx4 v[222:223], off
	v_lshl_add_u64 v[222:223], s[40:41], 0, v[132:133]
	s_mov_b32 m0, s50
	s_nop 0
	global_load_lds_dwordx4 v[222:223], off
	s_waitcnt vmcnt(8)
	s_waitcnt lgkmcnt(0)
	s_barrier
	s_setprio 1
	s_waitcnt lgkmcnt(0)
	v_mfma_f32_16x16x32_bf16 v[124:127], v[144:147], v[184:187], v[124:127]
	v_mfma_f32_16x16x32_bf16 v[120:123], v[160:163], v[184:187], v[120:123]
	v_mfma_f32_16x16x32_bf16 v[108:111], v[144:147], v[192:195], v[108:111]
	v_mfma_f32_16x16x32_bf16 v[104:107], v[160:163], v[192:195], v[104:107]
	v_mfma_f32_16x16x32_bf16 v[92:95], v[144:147], v[200:203], v[92:95]
	v_mfma_f32_16x16x32_bf16 v[88:91], v[160:163], v[200:203], v[88:91]
	v_mfma_f32_16x16x32_bf16 v[76:79], v[144:147], v[208:211], v[76:79]
	v_mfma_f32_16x16x32_bf16 v[72:75], v[160:163], v[208:211], v[72:75]
	s_setprio 0
	s_setprio 1
	v_mfma_f32_16x16x32_bf16 v[124:127], v[156:159], v[188:191], v[124:127]
	v_mfma_f32_16x16x32_bf16 v[120:123], v[164:167], v[188:191], v[120:123]
	v_mfma_f32_16x16x32_bf16 v[108:111], v[156:159], v[196:199], v[108:111]
	v_mfma_f32_16x16x32_bf16 v[104:107], v[164:167], v[196:199], v[104:107]
	v_mfma_f32_16x16x32_bf16 v[92:95], v[156:159], v[204:207], v[92:95]
	v_mfma_f32_16x16x32_bf16 v[88:91], v[164:167], v[204:207], v[88:91]
	v_mfma_f32_16x16x32_bf16 v[76:79], v[156:159], v[212:215], v[76:79]
	v_mfma_f32_16x16x32_bf16 v[72:75], v[164:167], v[212:215], v[72:75]
	s_setprio 0
	s_setprio 1
	v_mfma_f32_16x16x32_bf16 v[116:119], v[168:171], v[184:187], v[116:119]
	v_mfma_f32_16x16x32_bf16 v[112:115], v[176:179], v[184:187], v[112:115]
	v_mfma_f32_16x16x32_bf16 v[100:103], v[168:171], v[192:195], v[100:103]
	v_mfma_f32_16x16x32_bf16 v[96:99], v[176:179], v[192:195], v[96:99]
	v_mfma_f32_16x16x32_bf16 v[84:87], v[168:171], v[200:203], v[84:87]
	v_mfma_f32_16x16x32_bf16 v[80:83], v[176:179], v[200:203], v[80:83]
	v_mfma_f32_16x16x32_bf16 v[68:71], v[168:171], v[208:211], v[68:71]
	v_mfma_f32_16x16x32_bf16 v[64:67], v[176:179], v[208:211], v[64:67]
	s_setprio 0
	s_setprio 1
	v_mfma_f32_16x16x32_bf16 v[116:119], v[172:175], v[188:191], v[116:119]
	v_mfma_f32_16x16x32_bf16 v[112:115], v[180:183], v[188:191], v[112:115]
	v_mfma_f32_16x16x32_bf16 v[100:103], v[172:175], v[196:199], v[100:103]
	v_mfma_f32_16x16x32_bf16 v[96:99], v[180:183], v[196:199], v[96:99]
	v_mfma_f32_16x16x32_bf16 v[84:87], v[172:175], v[204:207], v[84:87]
	v_mfma_f32_16x16x32_bf16 v[80:83], v[180:183], v[204:207], v[80:83]
	v_mfma_f32_16x16x32_bf16 v[68:71], v[172:175], v[212:215], v[68:71]
	v_mfma_f32_16x16x32_bf16 v[64:67], v[180:183], v[212:215], v[64:67]
	s_setprio 0
	s_barrier
; #define PG8_STAGE(bufoff, gbase, voff) do { _Pragma("unroll") for (int _i = 0; _i < 2; ++_i) \
;         __builtin_amdgcn_global_load_lds((const unsigned*)((const char*)(gbase) + (voff)[_i]), (PG8_LAS unsigned*)(lds + (bufoff) + ldsw + _i * 8192), 16, 0, 0); } while (0)
; #define PG8_LDA(dst, b, h) do { _Pragma("unroll") for (int m = 0; m < 4; ++m) _Pragma("unroll") for (int k = 0; k < 2; ++k) dst[m][k] = *(const PG8_LAS bf16x8*)(lds + PG8_SA(b, h) + aoff + m * 2048 + k * 1024); } while (0)
; #define PG8_MMA(ai, bj, At, Bt) do { __builtin_amdgcn_s_setprio(1); _Pragma("unroll") for (int m = 0; m < 4; ++m) _Pragma("unroll") for (int n = 0; n < 2; ++n) _Pragma("unroll") for (int k = 0; k < 2; ++k) \
;         acc[ai][bj][m][n] = __builtin_amdgcn_mfma_f32_16x16x32_bf16(Bt[n][k], At[m][k], acc[ai][bj][m][n], 0, 0, 0); __builtin_amdgcn_s_setprio(0); } while (0)
; #define PG8_WAIT_V(n) asm volatile("s_waitcnt vmcnt(" #n ")" ::: "memory")
; #define PG8_WAIT_L(n) asm volatile("s_waitcnt lgkmcnt(" #n ")" ::: "memory")
; #define PG8_BAR __builtin_amdgcn_s_barrier()
; #define PG8_SCHED __builtin_amdgcn_sched_barrier(0)
; template <class Epi, class Sched, bool ALIGN_EPI = true, bool SP2 = true>
; __device__ __forceinline__ void gemm_phase(PG8_LAS unsigned char* lds, const Gemm g, const Sched& S, const Epi& E) {
;     ...
;             PG8_LDA(At, 1, 1); PG8_STAGE(PG8_SB(1, 0), b3, voffB); PG8_STAGE(PG8_SB(1, 1), b3 + hstepB, voffB); PG8_STAGE(PG8_SA(1, 0), a3, voffA);
;             PG8_WAIT_V(8); PG8_WAIT_L(0); PG8_BAR; PG8_MMA(1, 0, At, B0); PG8_MMA(1, 1, At, B1); PG8_BAR; PG8_SCHED;
;         }
	s_add_i32 s40, s52, s46
	v_lshl_add_u64 v[148:149], v[148:149], 0, s[10:11]
	s_mov_b32 m0, s40
	ds_read_b128 v[184:187], v155 offset:49152
	ds_read_b128 v[188:191], v155 offset:50176
	ds_read_b128 v[192:195], v155 offset:51200
	ds_read_b128 v[196:199], v155 offset:52224
	ds_read_b128 v[200:203], v155 offset:53248
	ds_read_b128 v[204:207], v155 offset:54272
	ds_read_b128 v[208:211], v155 offset:55296
	ds_read_b128 v[212:215], v155 offset:56320
	global_load_lds_dwordx4 v[148:149], off
	s_add_i32 m0, s40, 0x2000
	s_add_u32 s38, s38, 0x40080
	v_lshl_add_u64 v[148:149], v[216:217], 0, s[10:11]
	s_addc_u32 s39, s39, 0
	s_add_i32 s40, s53, s46
	global_load_lds_dwordx4 v[148:149], off
	v_lshl_add_u64 v[148:149], s[38:39], 0, v[130:131]
	s_mov_b32 m0, s40
	s_nop 0
	global_load_lds_dwordx4 v[148:149], off
	v_lshl_add_u64 v[148:149], s[38:39], 0, v[134:135]
	s_add_i32 m0, s40, 0x2000
	s_nop 0
	global_load_lds_dwordx4 v[148:149], off
	v_lshl_add_u64 v[148:149], v[218:219], 0, s[10:11]
	s_mov_b32 m0, s54
	s_nop 0
	global_load_lds_dwordx4 v[148:149], off
	v_lshl_add_u64 v[148:149], v[220:221], 0, s[10:11]
	s_mov_b32 m0, s55
	s_nop 0
	global_load_lds_dwordx4 v[148:149], off
	s_waitcnt vmcnt(8)
	s_waitcnt lgkmcnt(0)
	s_barrier
	s_setprio 1
	s_waitcnt lgkmcnt(0)
	v_mfma_f32_16x16x32_bf16 v[60:63], v[144:147], v[184:187], v[60:63]
	v_mfma_f32_16x16x32_bf16 v[56:59], v[160:163], v[184:187], v[56:59]
	v_mfma_f32_16x16x32_bf16 v[44:47], v[144:147], v[192:195], v[44:47]
	v_mfma_f32_16x16x32_bf16 v[40:43], v[160:163], v[192:195], v[40:43]
	v_mfma_f32_16x16x32_bf16 v[28:31], v[144:147], v[200:203], v[28:31]
	v_mfma_f32_16x16x32_bf16 v[24:27], v[160:163], v[200:203], v[24:27]
	v_mfma_f32_16x16x32_bf16 v[12:15], v[144:147], v[208:211], v[12:15]
	v_mfma_f32_16x16x32_bf16 v[8:11], v[160:163], v[208:211], v[8:11]
	s_setprio 0
	s_setprio 1
	v_mfma_f32_16x16x32_bf16 v[60:63], v[156:159], v[188:191], v[60:63]
	v_mfma_f32_16x16x32_bf16 v[56:59], v[164:167], v[188:191], v[56:59]
	v_mfma_f32_16x16x32_bf16 v[44:47], v[156:159], v[196:199], v[44:47]
	v_mfma_f32_16x16x32_bf16 v[40:43], v[164:167], v[196:199], v[40:43]
	v_mfma_f32_16x16x32_bf16 v[28:31], v[156:159], v[204:207], v[28:31]
	v_mfma_f32_16x16x32_bf16 v[24:27], v[164:167], v[204:207], v[24:27]
	v_mfma_f32_16x16x32_bf16 v[12:15], v[156:159], v[212:215], v[12:15]
	v_mfma_f32_16x16x32_bf16 v[8:11], v[164:167], v[212:215], v[8:11]
	s_setprio 0
	s_setprio 1
	v_mfma_f32_16x16x32_bf16 v[52:55], v[168:171], v[184:187], v[52:55]
	v_mfma_f32_16x16x32_bf16 v[48:51], v[176:179], v[184:187], v[48:51]
	v_mfma_f32_16x16x32_bf16 v[36:39], v[168:171], v[192:195], v[36:39]
	v_mfma_f32_16x16x32_bf16 v[32:35], v[176:179], v[192:195], v[32:35]
	v_mfma_f32_16x16x32_bf16 v[20:23], v[168:171], v[200:203], v[20:23]
	v_mfma_f32_16x16x32_bf16 v[16:19], v[176:179], v[200:203], v[16:19]
	v_mfma_f32_16x16x32_bf16 v[4:7], v[168:171], v[208:211], v[4:7]
	v_mfma_f32_16x16x32_bf16 v[0:3], v[176:179], v[208:211], v[0:3]
	s_setprio 0
	s_setprio 1
	v_mfma_f32_16x16x32_bf16 v[52:55], v[172:175], v[188:191], v[52:55]
	v_mfma_f32_16x16x32_bf16 v[48:51], v[180:183], v[188:191], v[48:51]
	v_mfma_f32_16x16x32_bf16 v[36:39], v[172:175], v[196:199], v[36:39]
	v_mfma_f32_16x16x32_bf16 v[32:35], v[180:183], v[196:199], v[32:35]
	v_mfma_f32_16x16x32_bf16 v[20:23], v[172:175], v[204:207], v[20:23]
	v_mfma_f32_16x16x32_bf16 v[16:19], v[180:183], v[204:207], v[16:19]
	v_mfma_f32_16x16x32_bf16 v[4:7], v[172:175], v[212:215], v[4:7]
	v_mfma_f32_16x16x32_bf16 v[0:3], v[180:183], v[212:215], v[0:3]
	s_setprio 0
	s_barrier
	s_add_i32 s72, s72, 2
	s_add_u32 s66, s66, 0x100
	s_addc_u32 s71, s71, 0
	s_add_u32 s34, s34, 0x100
	s_addc_u32 s35, s35, 0
	s_cmp_gt_u32 s72, 13
	s_cbranch_scc0 .LBB0_1311
	s_and_b64 vcc, exec, s[12:13]
	s_cbranch_vccz .LBB0_1314
	s_barrier

; #define PG8_STAGE(bufoff, gbase, voff) do { _Pragma("unroll") for (int _i = 0; _i < 2; ++_i) \
;         __builtin_amdgcn_global_load_lds((const unsigned*)((const char*)(gbase) + (voff)[_i]), (PG8_LAS unsigned*)(lds + (bufoff) + ldsw + _i * 8192), 16, 0, 0); } while (0)
; #define PG8_LDA(dst, b, h) do { _Pragma("unroll") for (int m = 0; m < 4; ++m) _Pragma("unroll") for (int k = 0; k < 2; ++k) dst[m][k] = *(const PG8_LAS bf16x8*)(lds + PG8_SA(b, h) + aoff + m * 2048 + k * 1024); } while (0)
; #define PG8_LDB(dst, b, h) do { _Pragma("unroll") for (int n = 0; n < 2; ++n) _Pragma("unroll") for (int k = 0; k < 2; ++k) dst[n][k] = *(const PG8_LAS bf16x8*)(lds + PG8_SB(b, h) + boff + n * 2048 + k * 1024); } while (0)
; #define PG8_MMA(ai, bj, At, Bt) do { __builtin_amdgcn_s_setprio(1); _Pragma("unroll") for (int m = 0; m < 4; ++m) _Pragma("unroll") for (int n = 0; n < 2; ++n) _Pragma("unroll") for (int k = 0; k < 2; ++k) \
;         acc[ai][bj][m][n] = __builtin_amdgcn_mfma_f32_16x16x32_bf16(Bt[n][k], At[m][k], acc[ai][bj][m][n], 0, 0, 0); __builtin_amdgcn_s_setprio(0); } while (0)
; #define PG8_WAIT_V(n) asm volatile("s_waitcnt vmcnt(" #n ")" ::: "memory")
; #define PG8_WAIT_L(n) asm volatile("s_waitcnt lgkmcnt(" #n ")" ::: "memory")
; #define PG8_BAR __builtin_amdgcn_s_barrier()
; #define PG8_SCHED __builtin_amdgcn_sched_barrier(0)
; template <class Epi, class Sched, bool ALIGN_EPI = true, bool SP2 = true>
; __device__ __forceinline__ void gemm_phase(PG8_LAS unsigned char* lds, const Gemm g, const Sched& S, const Epi& E) {
;     ...
;             PG8_LDB(B0, 0, 0); PG8_LDB(B1, 0, 1); PG8_SCHED; PG8_LDA(At, 0, 0); PG8_STAGE(PG8_SA(1, 1), a1 + hstepA, voffA);
;             PG8_WAIT_V(8); PG8_WAIT_L(0); PG8_BAR; PG8_MMA(0, 0, At, B0); PG8_MMA(0, 1, At, B1); PG8_BAR; PG8_SCHED;
;             PG8_LDA(At, 0, 1); PG8_STAGE(PG8_SB(0, 0), b2, voffB); PG8_STAGE(PG8_SB(0, 1), b2 + hstepB, voffB); PG8_STAGE(PG8_SA(0, 0), a2, voffA);
;             PG8_WAIT_V(8); PG8_WAIT_L(0); PG8_BAR; PG8_MMA(1, 0, At, B0); PG8_MMA(1, 1, At, B1); PG8_BAR; PG8_SCHED;
.LBB0_1445:
	ds_read_b128 v[84:87], v243
	ds_read_b128 v[88:91], v243 offset:1024
	ds_read_b128 v[92:95], v243 offset:2048
	ds_read_b128 v[96:99], v243 offset:3072
	ds_read_b128 v[100:103], v244
	ds_read_b128 v[104:107], v244 offset:1024
	ds_read_b128 v[108:111], v244 offset:2048
	ds_read_b128 v[112:115], v244 offset:3072
	s_add_u32 s12, s8, 0xfffc0080
	s_addc_u32 s13, s9, -1
	s_cmp_eq_u32 s84, 12
	s_cselect_b32 s59, s7, s13
	s_cselect_b32 s58, s11, s12
	s_cselect_b32 s13, s49, s61
	s_cselect_b32 s12, s51, s60
	v_lshl_add_u64 v[208:209], s[8:9], 0, v[202:203]
	s_add_i32 m0, s63, 0xc000
	ds_read_b128 v[128:131], v245
	ds_read_b128 v[132:135], v245 offset:1024
	ds_read_b128 v[136:139], v245 offset:2048
	ds_read_b128 v[140:143], v245 offset:3072
	ds_read_b128 v[144:147], v245 offset:4096
	ds_read_b128 v[148:151], v245 offset:5120
	ds_read_b128 v[152:155], v245 offset:6144
	ds_read_b128 v[156:159], v245 offset:7168
	global_load_lds_dwordx4 v[208:209], off
	v_lshl_add_u64 v[208:209], s[8:9], 0, v[200:201]
	s_add_i32 m0, s63, 0xe000
	s_nop 0
	global_load_lds_dwordx4 v[208:209], off
	s_waitcnt vmcnt(8)
	s_waitcnt lgkmcnt(0)
	s_barrier
	s_setprio 1
	s_waitcnt lgkmcnt(0)
	v_mfma_f32_16x16x32_bf16 v[188:191], v[84:87], v[128:131], v[188:191]
	v_mfma_f32_16x16x32_bf16 v[180:183], v[92:95], v[128:131], v[180:183]
	v_mfma_f32_16x16x32_bf16 v[172:175], v[84:87], v[136:139], v[172:175]
	v_mfma_f32_16x16x32_bf16 v[164:167], v[92:95], v[136:139], v[164:167]
	v_mfma_f32_16x16x32_bf16 v[124:127], v[84:87], v[144:147], v[124:127]
	v_mfma_f32_16x16x32_bf16 v[76:79], v[92:95], v[144:147], v[76:79]
	v_mfma_f32_16x16x32_bf16 v[120:123], v[84:87], v[152:155], v[120:123]
	v_mfma_f32_16x16x32_bf16 v[72:75], v[92:95], v[152:155], v[72:75]
	s_setprio 0
	s_setprio 1
	v_mfma_f32_16x16x32_bf16 v[188:191], v[88:91], v[132:135], v[188:191]
	v_mfma_f32_16x16x32_bf16 v[180:183], v[96:99], v[132:135], v[180:183]
	v_mfma_f32_16x16x32_bf16 v[172:175], v[88:91], v[140:143], v[172:175]
	v_mfma_f32_16x16x32_bf16 v[164:167], v[96:99], v[140:143], v[164:167]
	v_mfma_f32_16x16x32_bf16 v[124:127], v[88:91], v[148:151], v[124:127]
	v_mfma_f32_16x16x32_bf16 v[76:79], v[96:99], v[148:151], v[76:79]
	v_mfma_f32_16x16x32_bf16 v[120:123], v[88:91], v[156:159], v[120:123]
	v_mfma_f32_16x16x32_bf16 v[72:75], v[96:99], v[156:159], v[72:75]
	s_setprio 0
	s_setprio 1
	v_mfma_f32_16x16x32_bf16 v[184:187], v[100:103], v[128:131], v[184:187]
	v_mfma_f32_16x16x32_bf16 v[128:131], v[108:111], v[128:131], v[176:179]
	v_mfma_f32_16x16x32_bf16 v[116:119], v[100:103], v[144:147], v[116:119]
	v_mfma_f32_16x16x32_bf16 v[68:71], v[108:111], v[144:147], v[68:71]
	v_mfma_f32_16x16x32_bf16 v[80:83], v[100:103], v[152:155], v[80:83]
	v_mfma_f32_16x16x32_bf16 v[64:67], v[108:111], v[152:155], v[64:67]
	v_mfma_f32_16x16x32_bf16 v[184:187], v[104:107], v[132:135], v[184:187]
	v_mfma_f32_16x16x32_bf16 v[128:131], v[112:115], v[132:135], v[128:131]
	s_setprio 0
	s_setprio 1
	v_mfma_f32_16x16x32_bf16 v[132:135], v[100:103], v[136:139], v[168:171]
	v_mfma_f32_16x16x32_bf16 v[136:139], v[108:111], v[136:139], v[160:163]
	v_mfma_f32_16x16x32_bf16 v[116:119], v[104:107], v[148:151], v[116:119]
	v_mfma_f32_16x16x32_bf16 v[68:71], v[112:115], v[148:151], v[68:71]
	v_mfma_f32_16x16x32_bf16 v[80:83], v[104:107], v[156:159], v[80:83]
	v_mfma_f32_16x16x32_bf16 v[64:67], v[112:115], v[156:159], v[64:67]
	v_mfma_f32_16x16x32_bf16 v[132:135], v[104:107], v[140:143], v[132:135]
	v_mfma_f32_16x16x32_bf16 v[136:139], v[112:115], v[140:143], v[136:139]
	s_setprio 0
	s_barrier
	s_add_i32 s52, s78, s62
	v_lshl_add_u64 v[220:221], s[12:13], 0, v[194:195]
	s_mov_b32 m0, s52
	ds_read_b128 v[140:143], v245 offset:16384
	ds_read_b128 v[144:147], v245 offset:17408
	ds_read_b128 v[148:151], v245 offset:18432
	ds_read_b128 v[152:155], v245 offset:19456
	ds_read_b128 v[156:159], v245 offset:20480
	ds_read_b128 v[160:163], v245 offset:21504
	ds_read_b128 v[168:171], v245 offset:22528
	ds_read_b128 v[176:179], v245 offset:23552
	global_load_lds_dwordx4 v[220:221], off
	s_add_i32 m0, s52, 0x2000
	s_add_u32 s52, s12, 0x40000
	v_lshl_add_u64 v[222:223], s[12:13], 0, v[198:199]
	s_addc_u32 s53, s13, 0
	s_add_i32 s68, s79, s62
	global_load_lds_dwordx4 v[222:223], off
	v_lshl_add_u64 v[208:209], s[52:53], 0, v[194:195]
	s_mov_b32 m0, s68
	v_lshl_add_u64 v[224:225], s[58:59], 0, v[192:193]
	global_load_lds_dwordx4 v[208:209], off
	v_lshl_add_u64 v[208:209], s[52:53], 0, v[198:199]
	s_add_i32 m0, s68, 0x2000
	v_lshl_add_u64 v[226:227], s[58:59], 0, v[196:197]
	global_load_lds_dwordx4 v[208:209], off
	s_mov_b32 m0, s63
	s_nop 0
	global_load_lds_dwordx4 v[224:225], off
	s_mov_b32 m0, s64
	s_nop 0
	global_load_lds_dwordx4 v[226:227], off
	s_waitcnt vmcnt(8)
	s_waitcnt lgkmcnt(0)
	s_barrier
; #define PG8_STAGE(bufoff, gbase, voff) do { _Pragma("unroll") for (int _i = 0; _i < 2; ++_i) \
;         __builtin_amdgcn_global_load_lds((const unsigned*)((const char*)(gbase) + (voff)[_i]), (PG8_LAS unsigned*)(lds + (bufoff) + ldsw + _i * 8192), 16, 0, 0); } while (0)
; #define PG8_LDA(dst, b, h) do { _Pragma("unroll") for (int m = 0; m < 4; ++m) _Pragma("unroll") for (int k = 0; k < 2; ++k) dst[m][k] = *(const PG8_LAS bf16x8*)(lds + PG8_SA(b, h) + aoff + m * 2048 + k * 1024); } while (0)
; #define PG8_LDB(dst, b, h) do { _Pragma("unroll") for (int n = 0; n < 2; ++n) _Pragma("unroll") for (int k = 0; k < 2; ++k) dst[n][k] = *(const PG8_LAS bf16x8*)(lds + PG8_SB(b, h) + boff + n * 2048 + k * 1024); } while (0)
; #define PG8_MMA(ai, bj, At, Bt) do { __builtin_amdgcn_s_setprio(1); _Pragma("unroll") for (int m = 0; m < 4; ++m) _Pragma("unroll") for (int n = 0; n < 2; ++n) _Pragma("unroll") for (int k = 0; k < 2; ++k) \
;         acc[ai][bj][m][n] = __builtin_amdgcn_mfma_f32_16x16x32_bf16(Bt[n][k], At[m][k], acc[ai][bj][m][n], 0, 0, 0); __builtin_amdgcn_s_setprio(0); } while (0)
; #define PG8_WAIT_V(n) asm volatile("s_waitcnt vmcnt(" #n ")" ::: "memory")
; #define PG8_WAIT_L(n) asm volatile("s_waitcnt lgkmcnt(" #n ")" ::: "memory")
; #define PG8_BAR __builtin_amdgcn_s_barrier()
; #define PG8_SCHED __builtin_amdgcn_sched_barrier(0)
; template <class Epi, class Sched, bool ALIGN_EPI = true, bool SP2 = true>
; __device__ __forceinline__ void gemm_phase(PG8_LAS unsigned char* lds, const Gemm g, const Sched& S, const Epi& E) {
;     ...
;             PG8_WAIT_V(8); PG8_WAIT_L(0); PG8_BAR; PG8_MMA(1, 0, At, B0); PG8_MMA(1, 1, At, B1); PG8_BAR; PG8_SCHED;
;             PG8_LDB(B0, 1, 0); PG8_LDB(B1, 1, 1); PG8_SCHED; PG8_LDA(At, 1, 0); PG8_STAGE(PG8_SA(0, 1), a2 + hstepA, voffA);
;             PG8_WAIT_V(8); PG8_WAIT_L(0); PG8_BAR; PG8_MMA(0, 0, At, B0); PG8_MMA(0, 1, At, B1); PG8_BAR; PG8_SCHED;
	s_setprio 1
	s_waitcnt lgkmcnt(0)
	v_mfma_f32_16x16x32_bf16 v[60:63], v[84:87], v[140:143], v[60:63]
	v_mfma_f32_16x16x32_bf16 v[52:55], v[92:95], v[140:143], v[52:55]
	v_mfma_f32_16x16x32_bf16 v[44:47], v[84:87], v[148:151], v[44:47]
	v_mfma_f32_16x16x32_bf16 v[36:39], v[92:95], v[148:151], v[36:39]
	v_mfma_f32_16x16x32_bf16 v[28:31], v[84:87], v[156:159], v[28:31]
	v_mfma_f32_16x16x32_bf16 v[12:15], v[92:95], v[156:159], v[12:15]
	v_mfma_f32_16x16x32_bf16 v[24:27], v[84:87], v[168:171], v[24:27]
	v_mfma_f32_16x16x32_bf16 v[8:11], v[92:95], v[168:171], v[8:11]
	s_setprio 0
	s_setprio 1
	v_mfma_f32_16x16x32_bf16 v[60:63], v[88:91], v[144:147], v[60:63]
	v_mfma_f32_16x16x32_bf16 v[52:55], v[96:99], v[144:147], v[52:55]
	v_mfma_f32_16x16x32_bf16 v[44:47], v[88:91], v[152:155], v[44:47]
	v_mfma_f32_16x16x32_bf16 v[36:39], v[96:99], v[152:155], v[36:39]
	v_mfma_f32_16x16x32_bf16 v[28:31], v[88:91], v[160:163], v[28:31]
	v_mfma_f32_16x16x32_bf16 v[12:15], v[96:99], v[160:163], v[12:15]
	v_mfma_f32_16x16x32_bf16 v[24:27], v[88:91], v[176:179], v[24:27]
	v_mfma_f32_16x16x32_bf16 v[8:11], v[96:99], v[176:179], v[8:11]
	s_setprio 0
	s_setprio 1
	v_mfma_f32_16x16x32_bf16 v[56:59], v[100:103], v[140:143], v[56:59]
	v_mfma_f32_16x16x32_bf16 v[48:51], v[108:111], v[140:143], v[48:51]
	v_mfma_f32_16x16x32_bf16 v[40:43], v[100:103], v[148:151], v[40:43]
	v_mfma_f32_16x16x32_bf16 v[32:35], v[108:111], v[148:151], v[32:35]
	v_mfma_f32_16x16x32_bf16 v[20:23], v[100:103], v[156:159], v[20:23]
	v_mfma_f32_16x16x32_bf16 v[4:7], v[108:111], v[156:159], v[4:7]
	v_mfma_f32_16x16x32_bf16 v[16:19], v[100:103], v[168:171], v[16:19]
	v_mfma_f32_16x16x32_bf16 v[0:3], v[108:111], v[168:171], v[0:3]
	s_setprio 0
	s_setprio 1
	v_mfma_f32_16x16x32_bf16 v[56:59], v[104:107], v[144:147], v[56:59]
	v_mfma_f32_16x16x32_bf16 v[48:51], v[112:115], v[144:147], v[48:51]
	v_mfma_f32_16x16x32_bf16 v[40:43], v[104:107], v[152:155], v[40:43]
	v_mfma_f32_16x16x32_bf16 v[32:35], v[112:115], v[152:155], v[32:35]
	v_mfma_f32_16x16x32_bf16 v[20:23], v[104:107], v[160:163], v[20:23]
	v_mfma_f32_16x16x32_bf16 v[4:7], v[112:115], v[160:163], v[4:7]
	v_mfma_f32_16x16x32_bf16 v[16:19], v[104:107], v[176:179], v[16:19]
	v_mfma_f32_16x16x32_bf16 v[0:3], v[112:115], v[176:179], v[0:3]
	s_setprio 0
	s_barrier
	s_add_i32 s68, 0, 0x18000
	s_add_i32 s69, 0, 0x1c000
	v_add_u32_e32 v96, s68, v242
	v_add_u32_e32 v112, s69, v242
	ds_read_b128 v[84:87], v96
	ds_read_b128 v[88:91], v96 offset:1024
	ds_read_b128 v[92:95], v96 offset:2048
	ds_read_b128 v[96:99], v96 offset:3072
	ds_read_b128 v[100:103], v112
	ds_read_b128 v[104:107], v112 offset:1024
	ds_read_b128 v[108:111], v112 offset:2048
	ds_read_b128 v[112:115], v112 offset:3072
	s_add_u32 s52, s58, 0x40000
	s_addc_u32 s53, s59, 0
	s_mov_b32 m0, s65
	v_lshl_add_u64 v[160:161], s[52:53], 0, v[192:193]
	ds_read_b128 v[140:143], v245 offset:32768
	ds_read_b128 v[144:147], v245 offset:33792
	ds_read_b128 v[148:151], v245 offset:34816
	ds_read_b128 v[152:155], v245 offset:35840
	ds_read_b128 v[156:159], v245 offset:36864
	ds_read_b128 v[208:211], v245 offset:37888
	ds_read_b128 v[212:215], v245 offset:38912
	ds_read_b128 v[216:219], v245 offset:39936
	global_load_lds_dwordx4 v[160:161], off
	v_lshl_add_u64 v[160:161], s[52:53], 0, v[196:197]
	s_mov_b32 m0, s66
	s_nop 0
	global_load_lds_dwordx4 v[160:161], off
	s_waitcnt vmcnt(8)
	s_waitcnt lgkmcnt(0)
	s_barrier
	s_setprio 1
	s_waitcnt lgkmcnt(0)
	v_mfma_f32_16x16x32_bf16 v[160:163], v[84:87], v[140:143], v[188:191]
	v_mfma_f32_16x16x32_bf16 v[188:191], v[88:91], v[144:147], v[160:163]
	v_mfma_f32_16x16x32_bf16 v[160:163], v[92:95], v[140:143], v[180:183]
	v_mfma_f32_16x16x32_bf16 v[180:183], v[96:99], v[144:147], v[160:163]
	v_mfma_f32_16x16x32_bf16 v[160:163], v[84:87], v[148:151], v[172:175]
	v_mfma_f32_16x16x32_bf16 v[172:175], v[88:91], v[152:155], v[160:163]
	v_mfma_f32_16x16x32_bf16 v[160:163], v[92:95], v[148:151], v[164:167]
	v_mfma_f32_16x16x32_bf16 v[124:127], v[84:87], v[156:159], v[124:127]
	s_setprio 0
	s_setprio 1
	v_mfma_f32_16x16x32_bf16 v[76:79], v[92:95], v[156:159], v[76:79]
	v_mfma_f32_16x16x32_bf16 v[120:123], v[84:87], v[212:215], v[120:123]
	v_mfma_f32_16x16x32_bf16 v[72:75], v[92:95], v[212:215], v[72:75]
	v_mfma_f32_16x16x32_bf16 v[164:167], v[96:99], v[152:155], v[160:163]
	v_mfma_f32_16x16x32_bf16 v[124:127], v[88:91], v[208:211], v[124:127]
	v_mfma_f32_16x16x32_bf16 v[76:79], v[96:99], v[208:211], v[76:79]
	v_mfma_f32_16x16x32_bf16 v[120:123], v[88:91], v[216:219], v[120:123]
	v_mfma_f32_16x16x32_bf16 v[72:75], v[96:99], v[216:219], v[72:75]
	s_setprio 0
	s_setprio 1
	v_mfma_f32_16x16x32_bf16 v[128:131], v[108:111], v[140:143], v[128:131]
	v_mfma_f32_16x16x32_bf16 v[176:179], v[112:115], v[144:147], v[128:131]
	v_mfma_f32_16x16x32_bf16 v[128:131], v[100:103], v[148:151], v[132:135]
	v_mfma_f32_16x16x32_bf16 v[160:163], v[100:103], v[140:143], v[184:187]
	v_mfma_f32_16x16x32_bf16 v[168:171], v[104:107], v[152:155], v[128:131]
	v_mfma_f32_16x16x32_bf16 v[128:131], v[108:111], v[148:151], v[136:139]
	v_mfma_f32_16x16x32_bf16 v[116:119], v[100:103], v[156:159], v[116:119]
	v_mfma_f32_16x16x32_bf16 v[68:71], v[108:111], v[156:159], v[68:71]
	s_setprio 0
	s_setprio 1
	v_mfma_f32_16x16x32_bf16 v[80:83], v[100:103], v[212:215], v[80:83]
	v_mfma_f32_16x16x32_bf16 v[64:67], v[108:111], v[212:215], v[64:67]
	v_mfma_f32_16x16x32_bf16 v[184:187], v[104:107], v[144:147], v[160:163]
	v_mfma_f32_16x16x32_bf16 v[160:163], v[112:115], v[152:155], v[128:131]
	v_mfma_f32_16x16x32_bf16 v[116:119], v[104:107], v[208:211], v[116:119]
	v_mfma_f32_16x16x32_bf16 v[68:71], v[112:115], v[208:211], v[68:71]
	v_mfma_f32_16x16x32_bf16 v[80:83], v[104:107], v[216:219], v[80:83]
	v_mfma_f32_16x16x32_bf16 v[64:67], v[112:115], v[216:219], v[64:67]
	s_setprio 0
	s_barrier
; #define PG8_STAGE(bufoff, gbase, voff) do { _Pragma("unroll") for (int _i = 0; _i < 2; ++_i) \
;         __builtin_amdgcn_global_load_lds((const unsigned*)((const char*)(gbase) + (voff)[_i]), (PG8_LAS unsigned*)(lds + (bufoff) + ldsw + _i * 8192), 16, 0, 0); } while (0)
; #define PG8_LDA(dst, b, h) do { _Pragma("unroll") for (int m = 0; m < 4; ++m) _Pragma("unroll") for (int k = 0; k < 2; ++k) dst[m][k] = *(const PG8_LAS bf16x8*)(lds + PG8_SA(b, h) + aoff + m * 2048 + k * 1024); } while (0)
; #define PG8_MMA(ai, bj, At, Bt) do { __builtin_amdgcn_s_setprio(1); _Pragma("unroll") for (int m = 0; m < 4; ++m) _Pragma("unroll") for (int n = 0; n < 2; ++n) _Pragma("unroll") for (int k = 0; k < 2; ++k) \
;         acc[ai][bj][m][n] = __builtin_amdgcn_mfma_f32_16x16x32_bf16(Bt[n][k], At[m][k], acc[ai][bj][m][n], 0, 0, 0); __builtin_amdgcn_s_setprio(0); } while (0)
; #define PG8_WAIT_V(n) asm volatile("s_waitcnt vmcnt(" #n ")" ::: "memory")
; #define PG8_WAIT_L(n) asm volatile("s_waitcnt lgkmcnt(" #n ")" ::: "memory")
; #define PG8_BAR __builtin_amdgcn_s_barrier()
; #define PG8_SCHED __builtin_amdgcn_sched_barrier(0)
; template <class Epi, class Sched, bool ALIGN_EPI = true, bool SP2 = true>
; __device__ __forceinline__ void gemm_phase(PG8_LAS unsigned char* lds, const Gemm g, const Sched& S, const Epi& E) {
;     ...
;             PG8_LDA(At, 1, 1); PG8_STAGE(PG8_SB(1, 0), b3, voffB); PG8_STAGE(PG8_SB(1, 1), b3 + hstepB, voffB); PG8_STAGE(PG8_SA(1, 0), a3, voffA);
;             PG8_WAIT_V(8); PG8_WAIT_L(0); PG8_BAR; PG8_MMA(1, 0, At, B0); PG8_MMA(1, 1, At, B1); PG8_BAR; PG8_SCHED;
;         }
;         if constexpr (ALIGN_EPI) { if (wr == 0) PG8_BAR; }
	s_add_i32 s52, s68, s62
	v_lshl_add_u64 v[208:209], v[220:221], 0, s[24:25]
	s_mov_b32 m0, s52
	ds_read_b128 v[128:131], v245 offset:49152
	ds_read_b128 v[132:135], v245 offset:50176
	ds_read_b128 v[136:139], v245 offset:51200
	ds_read_b128 v[140:143], v245 offset:52224
	ds_read_b128 v[144:147], v245 offset:53248
	ds_read_b128 v[148:151], v245 offset:54272
	ds_read_b128 v[152:155], v245 offset:55296
	ds_read_b128 v[156:159], v245 offset:56320
	global_load_lds_dwordx4 v[208:209], off
	s_add_i32 m0, s52, 0x2000
	s_add_u32 s12, s12, 0x40080
	v_lshl_add_u64 v[208:209], v[222:223], 0, s[24:25]
	s_addc_u32 s13, s13, 0
	s_add_i32 s52, s69, s62
	global_load_lds_dwordx4 v[208:209], off
	v_lshl_add_u64 v[208:209], s[12:13], 0, v[194:195]
	s_mov_b32 m0, s52
	s_nop 0
	global_load_lds_dwordx4 v[208:209], off
	v_lshl_add_u64 v[208:209], s[12:13], 0, v[198:199]
	s_add_i32 m0, s52, 0x2000
	s_nop 0
	global_load_lds_dwordx4 v[208:209], off
	v_lshl_add_u64 v[208:209], v[224:225], 0, s[24:25]
	s_mov_b32 m0, s72
	s_nop 0
	global_load_lds_dwordx4 v[208:209], off
	v_lshl_add_u64 v[208:209], v[226:227], 0, s[24:25]
	s_mov_b32 m0, s73
	s_nop 0
	global_load_lds_dwordx4 v[208:209], off
	s_waitcnt vmcnt(8)
	s_waitcnt lgkmcnt(0)
	s_barrier
	s_setprio 1
	s_waitcnt lgkmcnt(0)
	v_mfma_f32_16x16x32_bf16 v[60:63], v[84:87], v[128:131], v[60:63]
	v_mfma_f32_16x16x32_bf16 v[52:55], v[92:95], v[128:131], v[52:55]
	v_mfma_f32_16x16x32_bf16 v[44:47], v[84:87], v[136:139], v[44:47]
	v_mfma_f32_16x16x32_bf16 v[36:39], v[92:95], v[136:139], v[36:39]
	v_mfma_f32_16x16x32_bf16 v[28:31], v[84:87], v[144:147], v[28:31]
	v_mfma_f32_16x16x32_bf16 v[12:15], v[92:95], v[144:147], v[12:15]
	v_mfma_f32_16x16x32_bf16 v[24:27], v[84:87], v[152:155], v[24:27]
	v_mfma_f32_16x16x32_bf16 v[8:11], v[92:95], v[152:155], v[8:11]
	s_setprio 0
	s_setprio 1
	v_mfma_f32_16x16x32_bf16 v[60:63], v[88:91], v[132:135], v[60:63]
	v_mfma_f32_16x16x32_bf16 v[52:55], v[96:99], v[132:135], v[52:55]
	v_mfma_f32_16x16x32_bf16 v[44:47], v[88:91], v[140:143], v[44:47]
	v_mfma_f32_16x16x32_bf16 v[36:39], v[96:99], v[140:143], v[36:39]
	v_mfma_f32_16x16x32_bf16 v[28:31], v[88:91], v[148:151], v[28:31]
	v_mfma_f32_16x16x32_bf16 v[12:15], v[96:99], v[148:151], v[12:15]
	v_mfma_f32_16x16x32_bf16 v[24:27], v[88:91], v[156:159], v[24:27]
	v_mfma_f32_16x16x32_bf16 v[8:11], v[96:99], v[156:159], v[8:11]
	s_setprio 0
	s_setprio 1
	v_mfma_f32_16x16x32_bf16 v[56:59], v[100:103], v[128:131], v[56:59]
	v_mfma_f32_16x16x32_bf16 v[48:51], v[108:111], v[128:131], v[48:51]
	v_mfma_f32_16x16x32_bf16 v[40:43], v[100:103], v[136:139], v[40:43]
	v_mfma_f32_16x16x32_bf16 v[32:35], v[108:111], v[136:139], v[32:35]
	v_mfma_f32_16x16x32_bf16 v[20:23], v[100:103], v[144:147], v[20:23]
	v_mfma_f32_16x16x32_bf16 v[4:7], v[108:111], v[144:147], v[4:7]
	v_mfma_f32_16x16x32_bf16 v[16:19], v[100:103], v[152:155], v[16:19]
	v_mfma_f32_16x16x32_bf16 v[0:3], v[108:111], v[152:155], v[0:3]
	s_setprio 0
	s_setprio 1
	v_mfma_f32_16x16x32_bf16 v[56:59], v[104:107], v[132:135], v[56:59]
	v_mfma_f32_16x16x32_bf16 v[48:51], v[112:115], v[132:135], v[48:51]
	v_mfma_f32_16x16x32_bf16 v[40:43], v[104:107], v[140:143], v[40:43]
	v_mfma_f32_16x16x32_bf16 v[32:35], v[112:115], v[140:143], v[32:35]
	v_mfma_f32_16x16x32_bf16 v[20:23], v[104:107], v[148:151], v[20:23]
	v_mfma_f32_16x16x32_bf16 v[4:7], v[112:115], v[148:151], v[4:7]
	v_mfma_f32_16x16x32_bf16 v[16:19], v[104:107], v[156:159], v[16:19]
	v_mfma_f32_16x16x32_bf16 v[0:3], v[112:115], v[156:159], v[0:3]
	s_setprio 0
	s_barrier
	s_add_i32 s84, s84, 2
	s_add_u32 s60, s60, 0x100
	s_addc_u32 s61, s61, 0
	s_add_u32 s8, s8, 0x100
	s_addc_u32 s9, s9, 0
	s_cmp_gt_u32 s84, 13
	s_cbranch_scc0 .LBB0_1445
	s_and_b64 vcc, exec, s[26:27]
	s_cbranch_vccz .LBB0_1448
	s_barrier

; #define PG8_STAGE(bufoff, gbase, voff) do { _Pragma("unroll") for (int _i = 0; _i < 2; ++_i) \
;         __builtin_amdgcn_global_load_lds((const unsigned*)((const char*)(gbase) + (voff)[_i]), (PG8_LAS unsigned*)(lds + (bufoff) + ldsw + _i * 8192), 16, 0, 0); } while (0)
; #define PG8_LDA(dst, b, h) do { _Pragma("unroll") for (int m = 0; m < 4; ++m) _Pragma("unroll") for (int k = 0; k < 2; ++k) dst[m][k] = *(const PG8_LAS bf16x8*)(lds + PG8_SA(b, h) + aoff + m * 2048 + k * 1024); } while (0)
; #define PG8_LDB(dst, b, h) do { _Pragma("unroll") for (int n = 0; n < 2; ++n) _Pragma("unroll") for (int k = 0; k < 2; ++k) dst[n][k] = *(const PG8_LAS bf16x8*)(lds + PG8_SB(b, h) + boff + n * 2048 + k * 1024); } while (0)
; #define PG8_MMA(ai, bj, At, Bt) do { __builtin_amdgcn_s_setprio(1); _Pragma("unroll") for (int m = 0; m < 4; ++m) _Pragma("unroll") for (int n = 0; n < 2; ++n) _Pragma("unroll") for (int k = 0; k < 2; ++k) \
;         acc[ai][bj][m][n] = __builtin_amdgcn_mfma_f32_16x16x32_bf16(Bt[n][k], At[m][k], acc[ai][bj][m][n], 0, 0, 0); __builtin_amdgcn_s_setprio(0); } while (0)
; #define PG8_BAR __builtin_amdgcn_s_barrier()
; template <class Epi, class Sched, bool ALIGN_EPI = true, bool SP2 = true>
; __device__ __forceinline__ void gemm_phase(PG8_LAS unsigned char* lds, const Gemm g, const Sched& S, const Epi& E) {
;     ...
;         const char* nA = has_next ? (const char*)g.A + (size_t)nxt.pm * tstepA : cA; const char* nB = has_next ? (const char*)g.Bt + (size_t)nxt.pn * tstepB : cB;
;         for (int t = 0; t < nt; t += 2) {
;             const bool last = (t == nt - 2);
;             const char* a1 = cA + (size_t)(t + 1) * kstep;
;             const char* a2 = last ? nA : cA + (size_t)(t + 2) * kstep; const char* b2 = last ? nB : cB + (size_t)(t + 2) * kstep;
;             const char* a3 = a2 + kstep; const char* b3 = b2 + kstep;
;             PG8_LDB(B0, 0, 0); PG8_LDB(B1, 0, 1); PG8_SCHED; PG8_LDA(At, 0, 0); PG8_STAGE(PG8_SA(1, 1), a1 + hstepA, voffA);
;             PG8_WAIT_V(8); PG8_WAIT_L(0); PG8_BAR; PG8_MMA(0, 0, At, B0); PG8_MMA(0, 1, At, B1); PG8_BAR; PG8_SCHED;
;             PG8_LDA(At, 0, 1); PG8_STAGE(PG8_SB(0, 0), b2, voffB); PG8_STAGE(PG8_SB(0, 1), b2 + hstepB, voffB); PG8_STAGE(PG8_SA(0, 0), a2, voffA);
;             PG8_WAIT_V(8); PG8_WAIT_L(0); PG8_BAR; PG8_MMA(1, 0, At, B0); PG8_MMA(1, 1, At, B1); PG8_BAR; PG8_SCHED;
.LBB0_1530:
	s_add_u32 s47, s34, s46
	s_addc_u32 s52, s35, 0
	s_add_u32 s50, s47, 0x100
	s_addc_u32 s51, s52, 0
	s_and_b64 s[48:49], s[42:43], exec
	s_cselect_b32 s49, s23, s51
	s_cselect_b32 s48, s80, s50
	s_add_u32 s46, s28, s46
	s_addc_u32 s50, s29, 0
	s_add_u32 s46, s46, 0x100
	s_addc_u32 s50, s50, 0
	s_add_i32 s53, 0, 0x10000
	s_and_b64 s[42:43], s[42:43], exec
	s_cselect_b32 s51, s21, s50
	s_cselect_b32 s50, s81, s46
	s_add_i32 s43, 0, 0x14000
	s_add_u32 s56, s47, 0x40080
	s_addc_u32 s57, s52, 0
	s_add_i32 s89, s53, s71
	s_add_i32 m0, s27, 0xc000
	s_add_i32 s52, s27, 0xe000
	s_add_i32 s86, s89, 0x2000
	v_add_u32_e32 v143, s53, v140
	s_add_u32 s54, s50, 0x40000
	ds_read_b128 v[144:147], v143
	ds_read_b128 v[148:151], v143 offset:1024
	ds_read_b128 v[152:155], v143 offset:2048
	ds_read_b128 v[156:159], v143 offset:3072
	v_add_u32_e32 v143, s43, v140
	s_addc_u32 s55, s51, 0
	s_add_i32 s88, s43, s71
	ds_read_b128 v[160:163], v143
	ds_read_b128 v[164:167], v143 offset:1024
	ds_read_b128 v[168:171], v143 offset:2048
	ds_read_b128 v[172:175], v143 offset:3072
	s_add_i32 s87, s88, 0x2000
	s_add_i32 s85, 0, 0x18000
	s_add_i32 s84, 0, 0x1c000
	s_add_u32 s46, s48, 0x40000
	s_addc_u32 s47, s49, 0
	s_add_i32 s83, s85, s71
	s_add_i32 s82, s83, 0x2000
	s_add_u32 s42, s50, 0x40080
	s_addc_u32 s43, s51, 0
	s_add_i32 s91, s84, s71
	s_add_i32 s90, s91, 0x2000
	v_lshl_add_u64 v[208:209], s[56:57], 0, v[134:135]
	ds_read_b128 v[176:179], v142
	ds_read_b128 v[180:183], v142 offset:1024
	ds_read_b128 v[184:187], v142 offset:2048
	ds_read_b128 v[188:191], v142 offset:3072
	ds_read_b128 v[192:195], v142 offset:4096
	ds_read_b128 v[196:199], v142 offset:5120
	ds_read_b128 v[200:203], v142 offset:6144
	ds_read_b128 v[204:207], v142 offset:7168
	global_load_lds_dwordx4 v[208:209], off
	v_lshl_add_u64 v[208:209], s[56:57], 0, v[132:133]
	s_mov_b32 m0, s52
	s_nop 0
	global_load_lds_dwordx4 v[208:209], off
	s_waitcnt vmcnt(8)
	s_waitcnt lgkmcnt(0)
	s_barrier
	s_setprio 1
	s_waitcnt lgkmcnt(0)
	v_mfma_f32_16x16x32_bf16 v[124:127], v[144:147], v[176:179], v[124:127]
	v_mfma_f32_16x16x32_bf16 v[120:123], v[152:155], v[176:179], v[120:123]
	v_mfma_f32_16x16x32_bf16 v[116:119], v[144:147], v[184:187], v[116:119]
	v_mfma_f32_16x16x32_bf16 v[112:115], v[152:155], v[184:187], v[112:115]
	v_mfma_f32_16x16x32_bf16 v[100:103], v[144:147], v[192:195], v[100:103]
	v_mfma_f32_16x16x32_bf16 v[96:99], v[152:155], v[192:195], v[96:99]
	v_mfma_f32_16x16x32_bf16 v[84:87], v[144:147], v[200:203], v[84:87]
	v_mfma_f32_16x16x32_bf16 v[80:83], v[152:155], v[200:203], v[80:83]
	s_setprio 0
	s_setprio 1
	v_mfma_f32_16x16x32_bf16 v[124:127], v[148:151], v[180:183], v[124:127]
	v_mfma_f32_16x16x32_bf16 v[120:123], v[156:159], v[180:183], v[120:123]
	v_mfma_f32_16x16x32_bf16 v[116:119], v[148:151], v[188:191], v[116:119]
	v_mfma_f32_16x16x32_bf16 v[112:115], v[156:159], v[188:191], v[112:115]
	v_mfma_f32_16x16x32_bf16 v[100:103], v[148:151], v[196:199], v[100:103]
	v_mfma_f32_16x16x32_bf16 v[96:99], v[156:159], v[196:199], v[96:99]
	v_mfma_f32_16x16x32_bf16 v[84:87], v[148:151], v[204:207], v[84:87]
	v_mfma_f32_16x16x32_bf16 v[80:83], v[156:159], v[204:207], v[80:83]
	s_setprio 0
	s_setprio 1
	v_mfma_f32_16x16x32_bf16 v[108:111], v[160:163], v[176:179], v[108:111]
	v_mfma_f32_16x16x32_bf16 v[104:107], v[168:171], v[176:179], v[104:107]
	v_mfma_f32_16x16x32_bf16 v[92:95], v[160:163], v[184:187], v[92:95]
	v_mfma_f32_16x16x32_bf16 v[88:91], v[168:171], v[184:187], v[88:91]
	v_mfma_f32_16x16x32_bf16 v[76:79], v[160:163], v[192:195], v[76:79]
	v_mfma_f32_16x16x32_bf16 v[72:75], v[168:171], v[192:195], v[72:75]
	v_mfma_f32_16x16x32_bf16 v[68:71], v[160:163], v[200:203], v[68:71]
	v_mfma_f32_16x16x32_bf16 v[64:67], v[168:171], v[200:203], v[64:67]
	s_setprio 0
	s_setprio 1
	v_mfma_f32_16x16x32_bf16 v[108:111], v[164:167], v[180:183], v[108:111]
	v_mfma_f32_16x16x32_bf16 v[104:107], v[172:175], v[180:183], v[104:107]
	v_mfma_f32_16x16x32_bf16 v[92:95], v[164:167], v[188:191], v[92:95]
	v_mfma_f32_16x16x32_bf16 v[88:91], v[172:175], v[188:191], v[88:91]
	v_mfma_f32_16x16x32_bf16 v[76:79], v[164:167], v[196:199], v[76:79]
	v_mfma_f32_16x16x32_bf16 v[72:75], v[172:175], v[196:199], v[72:75]
	v_mfma_f32_16x16x32_bf16 v[68:71], v[164:167], v[204:207], v[68:71]
	v_mfma_f32_16x16x32_bf16 v[64:67], v[172:175], v[204:207], v[64:67]
	s_setprio 0
	s_barrier
	s_mov_b32 m0, s89
	v_lshl_add_u64 v[208:209], s[50:51], 0, v[128:129]
	ds_read_b128 v[176:179], v142 offset:16384
	ds_read_b128 v[180:183], v142 offset:17408
	ds_read_b128 v[184:187], v142 offset:18432
	ds_read_b128 v[188:191], v142 offset:19456
	ds_read_b128 v[192:195], v142 offset:20480
	ds_read_b128 v[196:199], v142 offset:21504
	ds_read_b128 v[200:203], v142 offset:22528
	ds_read_b128 v[204:207], v142 offset:23552
	global_load_lds_dwordx4 v[208:209], off
	v_lshl_add_u64 v[210:211], s[50:51], 0, v[130:131]
	s_mov_b32 m0, s86
	v_lshl_add_u64 v[212:213], s[54:55], 0, v[128:129]
	global_load_lds_dwordx4 v[210:211], off
	s_mov_b32 m0, s88
	v_lshl_add_u64 v[214:215], s[48:49], 0, v[132:133]
	global_load_lds_dwordx4 v[212:213], off
	v_lshl_add_u64 v[212:213], s[54:55], 0, v[130:131]
	s_mov_b32 m0, s87
	s_nop 0
	global_load_lds_dwordx4 v[212:213], off
	v_lshl_add_u64 v[212:213], s[48:49], 0, v[134:135]
	s_mov_b32 m0, s27
	s_nop 0
	global_load_lds_dwordx4 v[212:213], off
	s_mov_b32 m0, s73
	s_nop 0
	global_load_lds_dwordx4 v[214:215], off
	s_waitcnt vmcnt(8)
	s_waitcnt lgkmcnt(0)
	s_barrier
; #define PG8_STAGE(bufoff, gbase, voff) do { _Pragma("unroll") for (int _i = 0; _i < 2; ++_i) \
;         __builtin_amdgcn_global_load_lds((const unsigned*)((const char*)(gbase) + (voff)[_i]), (PG8_LAS unsigned*)(lds + (bufoff) + ldsw + _i * 8192), 16, 0, 0); } while (0)
; #define PG8_LDA(dst, b, h) do { _Pragma("unroll") for (int m = 0; m < 4; ++m) _Pragma("unroll") for (int k = 0; k < 2; ++k) dst[m][k] = *(const PG8_LAS bf16x8*)(lds + PG8_SA(b, h) + aoff + m * 2048 + k * 1024); } while (0)
; #define PG8_LDB(dst, b, h) do { _Pragma("unroll") for (int n = 0; n < 2; ++n) _Pragma("unroll") for (int k = 0; k < 2; ++k) dst[n][k] = *(const PG8_LAS bf16x8*)(lds + PG8_SB(b, h) + boff + n * 2048 + k * 1024); } while (0)
; #define PG8_MMA(ai, bj, At, Bt) do { __builtin_amdgcn_s_setprio(1); _Pragma("unroll") for (int m = 0; m < 4; ++m) _Pragma("unroll") for (int n = 0; n < 2; ++n) _Pragma("unroll") for (int k = 0; k < 2; ++k) \
;         acc[ai][bj][m][n] = __builtin_amdgcn_mfma_f32_16x16x32_bf16(Bt[n][k], At[m][k], acc[ai][bj][m][n], 0, 0, 0); __builtin_amdgcn_s_setprio(0); } while (0)
; #define PG8_WAIT_V(n) asm volatile("s_waitcnt vmcnt(" #n ")" ::: "memory")
; #define PG8_WAIT_L(n) asm volatile("s_waitcnt lgkmcnt(" #n ")" ::: "memory")
; #define PG8_BAR __builtin_amdgcn_s_barrier()
; #define PG8_SCHED __builtin_amdgcn_sched_barrier(0)
; template <class Epi, class Sched, bool ALIGN_EPI = true, bool SP2 = true>
; __device__ __forceinline__ void gemm_phase(PG8_LAS unsigned char* lds, const Gemm g, const Sched& S, const Epi& E) {
;     ...
;             PG8_WAIT_V(8); PG8_WAIT_L(0); PG8_BAR; PG8_MMA(1, 0, At, B0); PG8_MMA(1, 1, At, B1); PG8_BAR; PG8_SCHED;
;             PG8_LDB(B0, 1, 0); PG8_LDB(B1, 1, 1); PG8_SCHED; PG8_LDA(At, 1, 0); PG8_STAGE(PG8_SA(0, 1), a2 + hstepA, voffA);
;             PG8_WAIT_V(8); PG8_WAIT_L(0); PG8_BAR; PG8_MMA(0, 0, At, B0); PG8_MMA(0, 1, At, B1); PG8_BAR; PG8_SCHED;
	s_setprio 1
	s_waitcnt lgkmcnt(0)
	v_mfma_f32_16x16x32_bf16 v[60:63], v[144:147], v[176:179], v[60:63]
	v_mfma_f32_16x16x32_bf16 v[56:59], v[152:155], v[176:179], v[56:59]
	v_mfma_f32_16x16x32_bf16 v[52:55], v[144:147], v[184:187], v[52:55]
	v_mfma_f32_16x16x32_bf16 v[48:51], v[152:155], v[184:187], v[48:51]
	v_mfma_f32_16x16x32_bf16 v[36:39], v[144:147], v[192:195], v[36:39]
	v_mfma_f32_16x16x32_bf16 v[32:35], v[152:155], v[192:195], v[32:35]
	v_mfma_f32_16x16x32_bf16 v[20:23], v[144:147], v[200:203], v[20:23]
	v_mfma_f32_16x16x32_bf16 v[16:19], v[152:155], v[200:203], v[16:19]
	s_setprio 0
	s_setprio 1
	v_mfma_f32_16x16x32_bf16 v[60:63], v[148:151], v[180:183], v[60:63]
	v_mfma_f32_16x16x32_bf16 v[56:59], v[156:159], v[180:183], v[56:59]
	v_mfma_f32_16x16x32_bf16 v[52:55], v[148:151], v[188:191], v[52:55]
	v_mfma_f32_16x16x32_bf16 v[48:51], v[156:159], v[188:191], v[48:51]
	v_mfma_f32_16x16x32_bf16 v[36:39], v[148:151], v[196:199], v[36:39]
	v_mfma_f32_16x16x32_bf16 v[32:35], v[156:159], v[196:199], v[32:35]
	v_mfma_f32_16x16x32_bf16 v[20:23], v[148:151], v[204:207], v[20:23]
	v_mfma_f32_16x16x32_bf16 v[16:19], v[156:159], v[204:207], v[16:19]
	s_setprio 0
	s_setprio 1
	v_mfma_f32_16x16x32_bf16 v[44:47], v[160:163], v[176:179], v[44:47]
	v_mfma_f32_16x16x32_bf16 v[40:43], v[168:171], v[176:179], v[40:43]
	v_mfma_f32_16x16x32_bf16 v[28:31], v[160:163], v[184:187], v[28:31]
	v_mfma_f32_16x16x32_bf16 v[24:27], v[168:171], v[184:187], v[24:27]
	v_mfma_f32_16x16x32_bf16 v[12:15], v[160:163], v[192:195], v[12:15]
	v_mfma_f32_16x16x32_bf16 v[8:11], v[168:171], v[192:195], v[8:11]
	v_mfma_f32_16x16x32_bf16 v[4:7], v[160:163], v[200:203], v[4:7]
	v_mfma_f32_16x16x32_bf16 v[0:3], v[168:171], v[200:203], v[0:3]
	s_setprio 0
	s_setprio 1
	v_mfma_f32_16x16x32_bf16 v[44:47], v[164:167], v[180:183], v[44:47]
	v_mfma_f32_16x16x32_bf16 v[40:43], v[172:175], v[180:183], v[40:43]
	v_mfma_f32_16x16x32_bf16 v[28:31], v[164:167], v[188:191], v[28:31]
	v_mfma_f32_16x16x32_bf16 v[24:27], v[172:175], v[188:191], v[24:27]
	v_mfma_f32_16x16x32_bf16 v[12:15], v[164:167], v[196:199], v[12:15]
	v_mfma_f32_16x16x32_bf16 v[8:11], v[172:175], v[196:199], v[8:11]
	v_mfma_f32_16x16x32_bf16 v[4:7], v[164:167], v[204:207], v[4:7]
	v_mfma_f32_16x16x32_bf16 v[0:3], v[172:175], v[204:207], v[0:3]
	s_setprio 0
	s_barrier
	v_add_u32_e32 v143, s85, v140
	ds_read_b128 v[144:147], v143
	ds_read_b128 v[148:151], v143 offset:1024
	ds_read_b128 v[152:155], v143 offset:2048
	ds_read_b128 v[156:159], v143 offset:3072
	v_add_u32_e32 v143, s84, v140
	ds_read_b128 v[160:163], v143
	ds_read_b128 v[164:167], v143 offset:1024
	ds_read_b128 v[168:171], v143 offset:2048
	ds_read_b128 v[172:175], v143 offset:3072
	s_mov_b32 m0, s74
	v_lshl_add_u64 v[216:217], s[46:47], 0, v[134:135]
	ds_read_b128 v[176:179], v142 offset:32768
	ds_read_b128 v[180:183], v142 offset:33792
	ds_read_b128 v[184:187], v142 offset:34816
	ds_read_b128 v[188:191], v142 offset:35840
	ds_read_b128 v[192:195], v142 offset:36864
	ds_read_b128 v[196:199], v142 offset:37888
	ds_read_b128 v[200:203], v142 offset:38912
	ds_read_b128 v[204:207], v142 offset:39936
	global_load_lds_dwordx4 v[216:217], off
	v_lshl_add_u64 v[216:217], s[46:47], 0, v[132:133]
	s_mov_b32 m0, s75
	s_nop 0
	global_load_lds_dwordx4 v[216:217], off
	s_waitcnt vmcnt(8)
	s_waitcnt lgkmcnt(0)
	s_barrier
	s_setprio 1
	s_waitcnt lgkmcnt(0)
	v_mfma_f32_16x16x32_bf16 v[124:127], v[144:147], v[176:179], v[124:127]
	v_mfma_f32_16x16x32_bf16 v[120:123], v[152:155], v[176:179], v[120:123]
	v_mfma_f32_16x16x32_bf16 v[116:119], v[144:147], v[184:187], v[116:119]
	v_mfma_f32_16x16x32_bf16 v[112:115], v[152:155], v[184:187], v[112:115]
	v_mfma_f32_16x16x32_bf16 v[100:103], v[144:147], v[192:195], v[100:103]
	v_mfma_f32_16x16x32_bf16 v[96:99], v[152:155], v[192:195], v[96:99]
	v_mfma_f32_16x16x32_bf16 v[84:87], v[144:147], v[200:203], v[84:87]
	v_mfma_f32_16x16x32_bf16 v[80:83], v[152:155], v[200:203], v[80:83]
	s_setprio 0
	s_setprio 1
	v_mfma_f32_16x16x32_bf16 v[124:127], v[148:151], v[180:183], v[124:127]
	v_mfma_f32_16x16x32_bf16 v[120:123], v[156:159], v[180:183], v[120:123]
	v_mfma_f32_16x16x32_bf16 v[116:119], v[148:151], v[188:191], v[116:119]
	v_mfma_f32_16x16x32_bf16 v[112:115], v[156:159], v[188:191], v[112:115]
	v_mfma_f32_16x16x32_bf16 v[100:103], v[148:151], v[196:199], v[100:103]
	v_mfma_f32_16x16x32_bf16 v[96:99], v[156:159], v[196:199], v[96:99]
	v_mfma_f32_16x16x32_bf16 v[84:87], v[148:151], v[204:207], v[84:87]
	v_mfma_f32_16x16x32_bf16 v[80:83], v[156:159], v[204:207], v[80:83]
	s_setprio 0
	s_setprio 1
	v_mfma_f32_16x16x32_bf16 v[108:111], v[160:163], v[176:179], v[108:111]
	v_mfma_f32_16x16x32_bf16 v[104:107], v[168:171], v[176:179], v[104:107]
	v_mfma_f32_16x16x32_bf16 v[92:95], v[160:163], v[184:187], v[92:95]
	v_mfma_f32_16x16x32_bf16 v[88:91], v[168:171], v[184:187], v[88:91]
	v_mfma_f32_16x16x32_bf16 v[76:79], v[160:163], v[192:195], v[76:79]
	v_mfma_f32_16x16x32_bf16 v[72:75], v[168:171], v[192:195], v[72:75]
	v_mfma_f32_16x16x32_bf16 v[68:71], v[160:163], v[200:203], v[68:71]
	v_mfma_f32_16x16x32_bf16 v[64:67], v[168:171], v[200:203], v[64:67]
	s_setprio 0
	s_setprio 1
	v_mfma_f32_16x16x32_bf16 v[108:111], v[164:167], v[180:183], v[108:111]
	v_mfma_f32_16x16x32_bf16 v[104:107], v[172:175], v[180:183], v[104:107]
	v_mfma_f32_16x16x32_bf16 v[92:95], v[164:167], v[188:191], v[92:95]
	v_mfma_f32_16x16x32_bf16 v[88:91], v[172:175], v[188:191], v[88:91]
	v_mfma_f32_16x16x32_bf16 v[76:79], v[164:167], v[196:199], v[76:79]
	v_mfma_f32_16x16x32_bf16 v[72:75], v[172:175], v[196:199], v[72:75]
	v_mfma_f32_16x16x32_bf16 v[68:71], v[164:167], v[204:207], v[68:71]
	v_mfma_f32_16x16x32_bf16 v[64:67], v[172:175], v[204:207], v[64:67]
	s_setprio 0
	s_barrier
; #define PG8_STAGE(bufoff, gbase, voff) do { _Pragma("unroll") for (int _i = 0; _i < 2; ++_i) \
;         __builtin_amdgcn_global_load_lds((const unsigned*)((const char*)(gbase) + (voff)[_i]), (PG8_LAS unsigned*)(lds + (bufoff) + ldsw + _i * 8192), 16, 0, 0); } while (0)
; #define PG8_LDA(dst, b, h) do { _Pragma("unroll") for (int m = 0; m < 4; ++m) _Pragma("unroll") for (int k = 0; k < 2; ++k) dst[m][k] = *(const PG8_LAS bf16x8*)(lds + PG8_SA(b, h) + aoff + m * 2048 + k * 1024); } while (0)
; #define PG8_MMA(ai, bj, At, Bt) do { __builtin_amdgcn_s_setprio(1); _Pragma("unroll") for (int m = 0; m < 4; ++m) _Pragma("unroll") for (int n = 0; n < 2; ++n) _Pragma("unroll") for (int k = 0; k < 2; ++k) \
;         acc[ai][bj][m][n] = __builtin_amdgcn_mfma_f32_16x16x32_bf16(Bt[n][k], At[m][k], acc[ai][bj][m][n], 0, 0, 0); __builtin_amdgcn_s_setprio(0); } while (0)
; #define PG8_WAIT_V(n) asm volatile("s_waitcnt vmcnt(" #n ")" ::: "memory")
; #define PG8_WAIT_L(n) asm volatile("s_waitcnt lgkmcnt(" #n ")" ::: "memory")
; #define PG8_BAR __builtin_amdgcn_s_barrier()
; #define PG8_SCHED __builtin_amdgcn_sched_barrier(0)
; template <class Epi, class Sched, bool ALIGN_EPI = true, bool SP2 = true>
; __device__ __forceinline__ void gemm_phase(PG8_LAS unsigned char* lds, const Gemm g, const Sched& S, const Epi& E) {
;     ...
;             PG8_LDA(At, 1, 1); PG8_STAGE(PG8_SB(1, 0), b3, voffB); PG8_STAGE(PG8_SB(1, 1), b3 + hstepB, voffB); PG8_STAGE(PG8_SA(1, 0), a3, voffA);
;             PG8_WAIT_V(8); PG8_WAIT_L(0); PG8_BAR; PG8_MMA(1, 0, At, B0); PG8_MMA(1, 1, At, B1); PG8_BAR; PG8_SCHED;
;         }
;         if constexpr (ALIGN_EPI) { if (wr == 0) PG8_BAR; }
	s_mov_b32 m0, s83
	v_lshl_add_u64 v[208:209], v[208:209], 0, s[4:5]
	ds_read_b128 v[176:179], v142 offset:49152
	ds_read_b128 v[180:183], v142 offset:50176
	ds_read_b128 v[184:187], v142 offset:51200
	ds_read_b128 v[188:191], v142 offset:52224
	ds_read_b128 v[192:195], v142 offset:53248
	ds_read_b128 v[196:199], v142 offset:54272
	ds_read_b128 v[200:203], v142 offset:55296
	ds_read_b128 v[204:207], v142 offset:56320
	global_load_lds_dwordx4 v[208:209], off
	v_lshl_add_u64 v[208:209], v[210:211], 0, s[4:5]
	s_mov_b32 m0, s82
	s_nop 0
	global_load_lds_dwordx4 v[208:209], off
	v_lshl_add_u64 v[208:209], s[42:43], 0, v[128:129]
	s_mov_b32 m0, s91
	s_nop 0
	global_load_lds_dwordx4 v[208:209], off
	v_lshl_add_u64 v[208:209], s[42:43], 0, v[130:131]
	s_mov_b32 m0, s90
	s_nop 0
	global_load_lds_dwordx4 v[208:209], off
	v_lshl_add_u64 v[208:209], v[212:213], 0, s[4:5]
	s_mov_b32 m0, s76
	s_nop 0
	global_load_lds_dwordx4 v[208:209], off
	v_lshl_add_u64 v[208:209], v[214:215], 0, s[4:5]
	s_mov_b32 m0, s77
	s_nop 0
	global_load_lds_dwordx4 v[208:209], off
	s_waitcnt vmcnt(8)
	s_waitcnt lgkmcnt(0)
	s_barrier
	s_setprio 1
	s_waitcnt lgkmcnt(0)
	v_mfma_f32_16x16x32_bf16 v[60:63], v[144:147], v[176:179], v[60:63]
	v_mfma_f32_16x16x32_bf16 v[56:59], v[152:155], v[176:179], v[56:59]
	v_mfma_f32_16x16x32_bf16 v[52:55], v[144:147], v[184:187], v[52:55]
	v_mfma_f32_16x16x32_bf16 v[48:51], v[152:155], v[184:187], v[48:51]
	v_mfma_f32_16x16x32_bf16 v[36:39], v[144:147], v[192:195], v[36:39]
	v_mfma_f32_16x16x32_bf16 v[32:35], v[152:155], v[192:195], v[32:35]
	v_mfma_f32_16x16x32_bf16 v[20:23], v[144:147], v[200:203], v[20:23]
	v_mfma_f32_16x16x32_bf16 v[16:19], v[152:155], v[200:203], v[16:19]
	s_setprio 0
	s_setprio 1
	v_mfma_f32_16x16x32_bf16 v[60:63], v[148:151], v[180:183], v[60:63]
	v_mfma_f32_16x16x32_bf16 v[56:59], v[156:159], v[180:183], v[56:59]
	v_mfma_f32_16x16x32_bf16 v[52:55], v[148:151], v[188:191], v[52:55]
	v_mfma_f32_16x16x32_bf16 v[48:51], v[156:159], v[188:191], v[48:51]
	v_mfma_f32_16x16x32_bf16 v[36:39], v[148:151], v[196:199], v[36:39]
	v_mfma_f32_16x16x32_bf16 v[32:35], v[156:159], v[196:199], v[32:35]
	v_mfma_f32_16x16x32_bf16 v[20:23], v[148:151], v[204:207], v[20:23]
	v_mfma_f32_16x16x32_bf16 v[16:19], v[156:159], v[204:207], v[16:19]
	s_setprio 0
	s_setprio 1
	v_mfma_f32_16x16x32_bf16 v[44:47], v[160:163], v[176:179], v[44:47]
	v_mfma_f32_16x16x32_bf16 v[40:43], v[168:171], v[176:179], v[40:43]
	v_mfma_f32_16x16x32_bf16 v[28:31], v[160:163], v[184:187], v[28:31]
	v_mfma_f32_16x16x32_bf16 v[24:27], v[168:171], v[184:187], v[24:27]
	v_mfma_f32_16x16x32_bf16 v[12:15], v[160:163], v[192:195], v[12:15]
	v_mfma_f32_16x16x32_bf16 v[8:11], v[168:171], v[192:195], v[8:11]
	v_mfma_f32_16x16x32_bf16 v[4:7], v[160:163], v[200:203], v[4:7]
	v_mfma_f32_16x16x32_bf16 v[0:3], v[168:171], v[200:203], v[0:3]
	s_setprio 0
	s_setprio 1
	v_mfma_f32_16x16x32_bf16 v[44:47], v[164:167], v[180:183], v[44:47]
	v_mfma_f32_16x16x32_bf16 v[40:43], v[172:175], v[180:183], v[40:43]
	v_mfma_f32_16x16x32_bf16 v[28:31], v[164:167], v[188:191], v[28:31]
	v_mfma_f32_16x16x32_bf16 v[24:27], v[172:175], v[188:191], v[24:27]
	v_mfma_f32_16x16x32_bf16 v[12:15], v[164:167], v[196:199], v[12:15]
	v_mfma_f32_16x16x32_bf16 v[8:11], v[172:175], v[196:199], v[8:11]
	v_mfma_f32_16x16x32_bf16 v[4:7], v[164:167], v[204:207], v[4:7]
	v_mfma_f32_16x16x32_bf16 v[0:3], v[172:175], v[204:207], v[0:3]
	s_setprio 0
	s_barrier
	s_movk_i32 s46, 0x100
	s_andn2_b64 vcc, exec, s[40:41]
	s_mov_b64 s[42:43], -1
	s_mov_b64 s[40:41], 0
	s_cbranch_vccz .LBB0_1530
	s_and_b64 vcc, exec, s[18:19]
	s_cbranch_vccz .LBB0_1533
	s_barrier

; #define PG8_STAGE(bufoff, gbase, voff) do { _Pragma("unroll") for (int _i = 0; _i < 2; ++_i) \
;         __builtin_amdgcn_global_load_lds((const unsigned*)((const char*)(gbase) + (voff)[_i]), (PG8_LAS unsigned*)(lds + (bufoff) + ldsw + _i * 8192), 16, 0, 0); } while (0)
; #define PG8_LDA(dst, b, h) do { _Pragma("unroll") for (int m = 0; m < 4; ++m) _Pragma("unroll") for (int k = 0; k < 2; ++k) dst[m][k] = *(const PG8_LAS bf16x8*)(lds + PG8_SA(b, h) + aoff + m * 2048 + k * 1024); } while (0)
; #define PG8_LDB(dst, b, h) do { _Pragma("unroll") for (int n = 0; n < 2; ++n) _Pragma("unroll") for (int k = 0; k < 2; ++k) dst[n][k] = *(const PG8_LAS bf16x8*)(lds + PG8_SB(b, h) + boff + n * 2048 + k * 1024); } while (0)
; #define PG8_MMA(ai, bj, At, Bt) do { __builtin_amdgcn_s_setprio(1); _Pragma("unroll") for (int m = 0; m < 4; ++m) _Pragma("unroll") for (int n = 0; n < 2; ++n) _Pragma("unroll") for (int k = 0; k < 2; ++k) \
;         acc[ai][bj][m][n] = __builtin_amdgcn_mfma_f32_16x16x32_bf16(Bt[n][k], At[m][k], acc[ai][bj][m][n], 0, 0, 0); __builtin_amdgcn_s_setprio(0); } while (0)
; #define PG8_WAIT_V(n) asm volatile("s_waitcnt vmcnt(" #n ")" ::: "memory")
; #define PG8_WAIT_L(n) asm volatile("s_waitcnt lgkmcnt(" #n ")" ::: "memory")
; #define PG8_BAR __builtin_amdgcn_s_barrier()
; #define PG8_SCHED __builtin_amdgcn_sched_barrier(0)
; template <class Epi, class Sched, bool ALIGN_EPI = true, bool SP2 = true>
; __device__ __forceinline__ void gemm_phase(PG8_LAS unsigned char* lds, const Gemm g, const Sched& S, const Epi& E) {
;     ...
;             PG8_LDB(B0, 0, 0); PG8_LDB(B1, 0, 1); PG8_SCHED; PG8_LDA(At, 0, 0); PG8_STAGE(PG8_SA(1, 1), a1 + hstepA, voffA);
;             PG8_WAIT_V(8); PG8_WAIT_L(0); PG8_BAR; PG8_MMA(0, 0, At, B0); PG8_MMA(0, 1, At, B1); PG8_BAR; PG8_SCHED;
;             PG8_LDA(At, 0, 1); PG8_STAGE(PG8_SB(0, 0), b2, voffB); PG8_STAGE(PG8_SB(0, 1), b2 + hstepB, voffB); PG8_STAGE(PG8_SA(0, 0), a2, voffA);
;             PG8_WAIT_V(8); PG8_WAIT_L(0); PG8_BAR; PG8_MMA(1, 0, At, B0); PG8_MMA(1, 1, At, B1); PG8_BAR; PG8_SCHED;
.LBB0_1620:
	ds_read_b128 v[144:147], v153
	ds_read_b128 v[156:159], v153 offset:1024
	ds_read_b128 v[160:163], v153 offset:2048
	ds_read_b128 v[164:167], v153 offset:3072
	ds_read_b128 v[168:171], v154
	ds_read_b128 v[172:175], v154 offset:1024
	ds_read_b128 v[176:179], v154 offset:2048
	ds_read_b128 v[180:183], v154 offset:3072
	s_add_u32 s26, s24, 0x100
	s_addc_u32 s27, s25, 0
	s_cmp_eq_u32 s63, 40
	s_cselect_b32 s31, s5, s27
	s_cselect_b32 s30, s4, s26
	s_cselect_b32 s29, s23, s62
	s_cselect_b32 s28, s22, s61
	v_lshl_add_u64 v[148:149], s[24:25], 0, v[138:139]
	s_add_i32 m0, s41, 0xc000
	ds_read_b128 v[184:187], v155
	ds_read_b128 v[188:191], v155 offset:1024
	ds_read_b128 v[192:195], v155 offset:2048
	ds_read_b128 v[196:199], v155 offset:3072
	ds_read_b128 v[200:203], v155 offset:4096
	ds_read_b128 v[204:207], v155 offset:5120
	ds_read_b128 v[208:211], v155 offset:6144
	ds_read_b128 v[212:215], v155 offset:7168
	global_load_lds_dwordx4 v[148:149], off
	v_lshl_add_u64 v[148:149], s[24:25], 0, v[136:137]
	s_add_i32 m0, s41, 0xe000
	s_nop 0
	global_load_lds_dwordx4 v[148:149], off
	s_waitcnt vmcnt(8)
	s_waitcnt lgkmcnt(0)
	s_barrier
	s_setprio 1
	s_waitcnt lgkmcnt(0)
	v_mfma_f32_16x16x32_bf16 v[124:127], v[144:147], v[184:187], v[124:127]
	v_mfma_f32_16x16x32_bf16 v[120:123], v[160:163], v[184:187], v[120:123]
	v_mfma_f32_16x16x32_bf16 v[108:111], v[144:147], v[192:195], v[108:111]
	v_mfma_f32_16x16x32_bf16 v[104:107], v[160:163], v[192:195], v[104:107]
	v_mfma_f32_16x16x32_bf16 v[92:95], v[144:147], v[200:203], v[92:95]
	v_mfma_f32_16x16x32_bf16 v[88:91], v[160:163], v[200:203], v[88:91]
	v_mfma_f32_16x16x32_bf16 v[76:79], v[144:147], v[208:211], v[76:79]
	v_mfma_f32_16x16x32_bf16 v[72:75], v[160:163], v[208:211], v[72:75]
	s_setprio 0
	s_setprio 1
	v_mfma_f32_16x16x32_bf16 v[124:127], v[156:159], v[188:191], v[124:127]
	v_mfma_f32_16x16x32_bf16 v[120:123], v[164:167], v[188:191], v[120:123]
	v_mfma_f32_16x16x32_bf16 v[108:111], v[156:159], v[196:199], v[108:111]
	v_mfma_f32_16x16x32_bf16 v[104:107], v[164:167], v[196:199], v[104:107]
	v_mfma_f32_16x16x32_bf16 v[92:95], v[156:159], v[204:207], v[92:95]
	v_mfma_f32_16x16x32_bf16 v[88:91], v[164:167], v[204:207], v[88:91]
	v_mfma_f32_16x16x32_bf16 v[76:79], v[156:159], v[212:215], v[76:79]
	v_mfma_f32_16x16x32_bf16 v[72:75], v[164:167], v[212:215], v[72:75]
	s_setprio 0
	s_setprio 1
	v_mfma_f32_16x16x32_bf16 v[116:119], v[168:171], v[184:187], v[116:119]
	v_mfma_f32_16x16x32_bf16 v[112:115], v[176:179], v[184:187], v[112:115]
	v_mfma_f32_16x16x32_bf16 v[100:103], v[168:171], v[192:195], v[100:103]
	v_mfma_f32_16x16x32_bf16 v[96:99], v[176:179], v[192:195], v[96:99]
	v_mfma_f32_16x16x32_bf16 v[84:87], v[168:171], v[200:203], v[84:87]
	v_mfma_f32_16x16x32_bf16 v[80:83], v[176:179], v[200:203], v[80:83]
	v_mfma_f32_16x16x32_bf16 v[68:71], v[168:171], v[208:211], v[68:71]
	v_mfma_f32_16x16x32_bf16 v[64:67], v[176:179], v[208:211], v[64:67]
	s_setprio 0
	s_setprio 1
	v_mfma_f32_16x16x32_bf16 v[116:119], v[172:175], v[188:191], v[116:119]
	v_mfma_f32_16x16x32_bf16 v[112:115], v[180:183], v[188:191], v[112:115]
	v_mfma_f32_16x16x32_bf16 v[100:103], v[172:175], v[196:199], v[100:103]
	v_mfma_f32_16x16x32_bf16 v[96:99], v[180:183], v[196:199], v[96:99]
	v_mfma_f32_16x16x32_bf16 v[84:87], v[172:175], v[204:207], v[84:87]
	v_mfma_f32_16x16x32_bf16 v[80:83], v[180:183], v[204:207], v[80:83]
	v_mfma_f32_16x16x32_bf16 v[68:71], v[172:175], v[212:215], v[68:71]
	v_mfma_f32_16x16x32_bf16 v[64:67], v[180:183], v[212:215], v[64:67]
	s_setprio 0
	s_barrier
	s_add_i32 s24, s49, s40
	v_lshl_add_u64 v[148:149], s[28:29], 0, v[130:131]
	s_mov_b32 m0, s24
	ds_read_b128 v[184:187], v155 offset:16384
	ds_read_b128 v[188:191], v155 offset:17408
	ds_read_b128 v[192:195], v155 offset:18432
	ds_read_b128 v[196:199], v155 offset:19456
	ds_read_b128 v[200:203], v155 offset:20480
	ds_read_b128 v[204:207], v155 offset:21504
	ds_read_b128 v[208:211], v155 offset:22528
	ds_read_b128 v[212:215], v155 offset:23552
	global_load_lds_dwordx4 v[148:149], off
	s_add_i32 m0, s24, 0x2000
	s_add_u32 s24, s28, 0xb0000
	v_lshl_add_u64 v[216:217], s[28:29], 0, v[134:135]
	s_addc_u32 s25, s29, 0
	s_add_i32 s52, s50, s40
	global_load_lds_dwordx4 v[216:217], off
	v_lshl_add_u64 v[218:219], s[24:25], 0, v[130:131]
	s_mov_b32 m0, s52
	v_lshl_add_u64 v[220:221], s[30:31], 0, v[132:133]
	global_load_lds_dwordx4 v[218:219], off
	v_lshl_add_u64 v[218:219], s[24:25], 0, v[134:135]
	s_add_i32 m0, s52, 0x2000
	s_nop 0
	global_load_lds_dwordx4 v[218:219], off
	v_lshl_add_u64 v[218:219], s[30:31], 0, v[128:129]
	s_mov_b32 m0, s41
	s_nop 0
	global_load_lds_dwordx4 v[218:219], off
	s_mov_b32 m0, s42
	s_nop 0
	global_load_lds_dwordx4 v[220:221], off
	s_waitcnt vmcnt(8)
	s_waitcnt lgkmcnt(0)
	s_barrier
; #define PG8_STAGE(bufoff, gbase, voff) do { _Pragma("unroll") for (int _i = 0; _i < 2; ++_i) \
;         __builtin_amdgcn_global_load_lds((const unsigned*)((const char*)(gbase) + (voff)[_i]), (PG8_LAS unsigned*)(lds + (bufoff) + ldsw + _i * 8192), 16, 0, 0); } while (0)
; #define PG8_LDA(dst, b, h) do { _Pragma("unroll") for (int m = 0; m < 4; ++m) _Pragma("unroll") for (int k = 0; k < 2; ++k) dst[m][k] = *(const PG8_LAS bf16x8*)(lds + PG8_SA(b, h) + aoff + m * 2048 + k * 1024); } while (0)
; #define PG8_LDB(dst, b, h) do { _Pragma("unroll") for (int n = 0; n < 2; ++n) _Pragma("unroll") for (int k = 0; k < 2; ++k) dst[n][k] = *(const PG8_LAS bf16x8*)(lds + PG8_SB(b, h) + boff + n * 2048 + k * 1024); } while (0)
; #define PG8_MMA(ai, bj, At, Bt) do { __builtin_amdgcn_s_setprio(1); _Pragma("unroll") for (int m = 0; m < 4; ++m) _Pragma("unroll") for (int n = 0; n < 2; ++n) _Pragma("unroll") for (int k = 0; k < 2; ++k) \
;         acc[ai][bj][m][n] = __builtin_amdgcn_mfma_f32_16x16x32_bf16(Bt[n][k], At[m][k], acc[ai][bj][m][n], 0, 0, 0); __builtin_amdgcn_s_setprio(0); } while (0)
; #define PG8_WAIT_V(n) asm volatile("s_waitcnt vmcnt(" #n ")" ::: "memory")
; #define PG8_WAIT_L(n) asm volatile("s_waitcnt lgkmcnt(" #n ")" ::: "memory")
; #define PG8_BAR __builtin_amdgcn_s_barrier()
; #define PG8_SCHED __builtin_amdgcn_sched_barrier(0)
; template <class Epi, class Sched, bool ALIGN_EPI = true, bool SP2 = true>
; __device__ __forceinline__ void gemm_phase(PG8_LAS unsigned char* lds, const Gemm g, const Sched& S, const Epi& E) {
;     ...
;             PG8_WAIT_V(8); PG8_WAIT_L(0); PG8_BAR; PG8_MMA(1, 0, At, B0); PG8_MMA(1, 1, At, B1); PG8_BAR; PG8_SCHED;
;             PG8_LDB(B0, 1, 0); PG8_LDB(B1, 1, 1); PG8_SCHED; PG8_LDA(At, 1, 0); PG8_STAGE(PG8_SA(0, 1), a2 + hstepA, voffA);
;             PG8_WAIT_V(8); PG8_WAIT_L(0); PG8_BAR; PG8_MMA(0, 0, At, B0); PG8_MMA(0, 1, At, B1); PG8_BAR; PG8_SCHED;
	s_setprio 1
	s_waitcnt lgkmcnt(0)
	v_mfma_f32_16x16x32_bf16 v[60:63], v[144:147], v[184:187], v[60:63]
	v_mfma_f32_16x16x32_bf16 v[56:59], v[160:163], v[184:187], v[56:59]
	v_mfma_f32_16x16x32_bf16 v[44:47], v[144:147], v[192:195], v[44:47]
	v_mfma_f32_16x16x32_bf16 v[40:43], v[160:163], v[192:195], v[40:43]
	v_mfma_f32_16x16x32_bf16 v[28:31], v[144:147], v[200:203], v[28:31]
	v_mfma_f32_16x16x32_bf16 v[24:27], v[160:163], v[200:203], v[24:27]
	v_mfma_f32_16x16x32_bf16 v[12:15], v[144:147], v[208:211], v[12:15]
	v_mfma_f32_16x16x32_bf16 v[8:11], v[160:163], v[208:211], v[8:11]
	s_setprio 0
	s_setprio 1
	v_mfma_f32_16x16x32_bf16 v[60:63], v[156:159], v[188:191], v[60:63]
	v_mfma_f32_16x16x32_bf16 v[56:59], v[164:167], v[188:191], v[56:59]
	v_mfma_f32_16x16x32_bf16 v[44:47], v[156:159], v[196:199], v[44:47]
	v_mfma_f32_16x16x32_bf16 v[40:43], v[164:167], v[196:199], v[40:43]
	v_mfma_f32_16x16x32_bf16 v[28:31], v[156:159], v[204:207], v[28:31]
	v_mfma_f32_16x16x32_bf16 v[24:27], v[164:167], v[204:207], v[24:27]
	v_mfma_f32_16x16x32_bf16 v[12:15], v[156:159], v[212:215], v[12:15]
	v_mfma_f32_16x16x32_bf16 v[8:11], v[164:167], v[212:215], v[8:11]
	s_setprio 0
	s_setprio 1
	v_mfma_f32_16x16x32_bf16 v[52:55], v[168:171], v[184:187], v[52:55]
	v_mfma_f32_16x16x32_bf16 v[48:51], v[176:179], v[184:187], v[48:51]
	v_mfma_f32_16x16x32_bf16 v[36:39], v[168:171], v[192:195], v[36:39]
	v_mfma_f32_16x16x32_bf16 v[32:35], v[176:179], v[192:195], v[32:35]
	v_mfma_f32_16x16x32_bf16 v[20:23], v[168:171], v[200:203], v[20:23]
	v_mfma_f32_16x16x32_bf16 v[16:19], v[176:179], v[200:203], v[16:19]
	v_mfma_f32_16x16x32_bf16 v[4:7], v[168:171], v[208:211], v[4:7]
	v_mfma_f32_16x16x32_bf16 v[0:3], v[176:179], v[208:211], v[0:3]
	s_setprio 0
	s_setprio 1
	v_mfma_f32_16x16x32_bf16 v[52:55], v[172:175], v[188:191], v[52:55]
	v_mfma_f32_16x16x32_bf16 v[48:51], v[180:183], v[188:191], v[48:51]
	v_mfma_f32_16x16x32_bf16 v[36:39], v[172:175], v[196:199], v[36:39]
	v_mfma_f32_16x16x32_bf16 v[32:35], v[180:183], v[196:199], v[32:35]
	v_mfma_f32_16x16x32_bf16 v[20:23], v[172:175], v[204:207], v[20:23]
	v_mfma_f32_16x16x32_bf16 v[16:19], v[180:183], v[204:207], v[16:19]
	v_mfma_f32_16x16x32_bf16 v[4:7], v[172:175], v[212:215], v[4:7]
	v_mfma_f32_16x16x32_bf16 v[0:3], v[180:183], v[212:215], v[0:3]
	s_setprio 0
	s_barrier
	s_add_i32 s52, 0, 0x18000
	s_add_i32 s53, 0, 0x1c000
	v_add_u32_e32 v164, s52, v151
	v_add_u32_e32 v180, s53, v151
	ds_read_b128 v[144:147], v164
	ds_read_b128 v[156:159], v164 offset:1024
	ds_read_b128 v[160:163], v164 offset:2048
	ds_read_b128 v[164:167], v164 offset:3072
	ds_read_b128 v[168:171], v180
	ds_read_b128 v[172:175], v180 offset:1024
	ds_read_b128 v[176:179], v180 offset:2048
	ds_read_b128 v[180:183], v180 offset:3072
	s_add_u32 s24, s30, 0xb0000
	s_addc_u32 s25, s31, 0
	s_mov_b32 m0, s43
	v_lshl_add_u64 v[222:223], s[24:25], 0, v[128:129]
	ds_read_b128 v[184:187], v155 offset:32768
	ds_read_b128 v[188:191], v155 offset:33792
	ds_read_b128 v[192:195], v155 offset:34816
	ds_read_b128 v[196:199], v155 offset:35840
	ds_read_b128 v[200:203], v155 offset:36864
	ds_read_b128 v[204:207], v155 offset:37888
	ds_read_b128 v[208:211], v155 offset:38912
	ds_read_b128 v[212:215], v155 offset:39936
	global_load_lds_dwordx4 v[222:223], off
	v_lshl_add_u64 v[222:223], s[24:25], 0, v[132:133]
	s_mov_b32 m0, s45
	s_nop 0
	global_load_lds_dwordx4 v[222:223], off
	s_waitcnt vmcnt(8)
	s_waitcnt lgkmcnt(0)
	s_barrier
	s_setprio 1
	s_waitcnt lgkmcnt(0)
	v_mfma_f32_16x16x32_bf16 v[124:127], v[144:147], v[184:187], v[124:127]
	v_mfma_f32_16x16x32_bf16 v[120:123], v[160:163], v[184:187], v[120:123]
	v_mfma_f32_16x16x32_bf16 v[108:111], v[144:147], v[192:195], v[108:111]
	v_mfma_f32_16x16x32_bf16 v[104:107], v[160:163], v[192:195], v[104:107]
	v_mfma_f32_16x16x32_bf16 v[92:95], v[144:147], v[200:203], v[92:95]
	v_mfma_f32_16x16x32_bf16 v[88:91], v[160:163], v[200:203], v[88:91]
	v_mfma_f32_16x16x32_bf16 v[76:79], v[144:147], v[208:211], v[76:79]
	v_mfma_f32_16x16x32_bf16 v[72:75], v[160:163], v[208:211], v[72:75]
	s_setprio 0
	s_setprio 1
	v_mfma_f32_16x16x32_bf16 v[124:127], v[156:159], v[188:191], v[124:127]
	v_mfma_f32_16x16x32_bf16 v[120:123], v[164:167], v[188:191], v[120:123]
	v_mfma_f32_16x16x32_bf16 v[108:111], v[156:159], v[196:199], v[108:111]
	v_mfma_f32_16x16x32_bf16 v[104:107], v[164:167], v[196:199], v[104:107]
	v_mfma_f32_16x16x32_bf16 v[92:95], v[156:159], v[204:207], v[92:95]
	v_mfma_f32_16x16x32_bf16 v[88:91], v[164:167], v[204:207], v[88:91]
	v_mfma_f32_16x16x32_bf16 v[76:79], v[156:159], v[212:215], v[76:79]
	v_mfma_f32_16x16x32_bf16 v[72:75], v[164:167], v[212:215], v[72:75]
	s_setprio 0
	s_setprio 1
	v_mfma_f32_16x16x32_bf16 v[116:119], v[168:171], v[184:187], v[116:119]
	v_mfma_f32_16x16x32_bf16 v[112:115], v[176:179], v[184:187], v[112:115]
	v_mfma_f32_16x16x32_bf16 v[100:103], v[168:171], v[192:195], v[100:103]
	v_mfma_f32_16x16x32_bf16 v[96:99], v[176:179], v[192:195], v[96:99]
	v_mfma_f32_16x16x32_bf16 v[84:87], v[168:171], v[200:203], v[84:87]
	v_mfma_f32_16x16x32_bf16 v[80:83], v[176:179], v[200:203], v[80:83]
	v_mfma_f32_16x16x32_bf16 v[68:71], v[168:171], v[208:211], v[68:71]
	v_mfma_f32_16x16x32_bf16 v[64:67], v[176:179], v[208:211], v[64:67]
	s_setprio 0
	s_setprio 1
	v_mfma_f32_16x16x32_bf16 v[116:119], v[172:175], v[188:191], v[116:119]
	v_mfma_f32_16x16x32_bf16 v[112:115], v[180:183], v[188:191], v[112:115]
	v_mfma_f32_16x16x32_bf16 v[100:103], v[172:175], v[196:199], v[100:103]
	v_mfma_f32_16x16x32_bf16 v[96:99], v[180:183], v[196:199], v[96:99]
	v_mfma_f32_16x16x32_bf16 v[84:87], v[172:175], v[204:207], v[84:87]
	v_mfma_f32_16x16x32_bf16 v[80:83], v[180:183], v[204:207], v[80:83]
	v_mfma_f32_16x16x32_bf16 v[68:71], v[172:175], v[212:215], v[68:71]
	v_mfma_f32_16x16x32_bf16 v[64:67], v[180:183], v[212:215], v[64:67]
	s_setprio 0
	s_barrier
; #define PG8_STAGE(bufoff, gbase, voff) do { _Pragma("unroll") for (int _i = 0; _i < 2; ++_i) \
;         __builtin_amdgcn_global_load_lds((const unsigned*)((const char*)(gbase) + (voff)[_i]), (PG8_LAS unsigned*)(lds + (bufoff) + ldsw + _i * 8192), 16, 0, 0); } while (0)
; #define PG8_LDA(dst, b, h) do { _Pragma("unroll") for (int m = 0; m < 4; ++m) _Pragma("unroll") for (int k = 0; k < 2; ++k) dst[m][k] = *(const PG8_LAS bf16x8*)(lds + PG8_SA(b, h) + aoff + m * 2048 + k * 1024); } while (0)
; #define PG8_MMA(ai, bj, At, Bt) do { __builtin_amdgcn_s_setprio(1); _Pragma("unroll") for (int m = 0; m < 4; ++m) _Pragma("unroll") for (int n = 0; n < 2; ++n) _Pragma("unroll") for (int k = 0; k < 2; ++k) \
;         acc[ai][bj][m][n] = __builtin_amdgcn_mfma_f32_16x16x32_bf16(Bt[n][k], At[m][k], acc[ai][bj][m][n], 0, 0, 0); __builtin_amdgcn_s_setprio(0); } while (0)
; #define PG8_WAIT_V(n) asm volatile("s_waitcnt vmcnt(" #n ")" ::: "memory")
; #define PG8_WAIT_L(n) asm volatile("s_waitcnt lgkmcnt(" #n ")" ::: "memory")
; #define PG8_BAR __builtin_amdgcn_s_barrier()
; #define PG8_SCHED __builtin_amdgcn_sched_barrier(0)
; template <class Epi, class Sched, bool ALIGN_EPI = true, bool SP2 = true>
; __device__ __forceinline__ void gemm_phase(PG8_LAS unsigned char* lds, const Gemm g, const Sched& S, const Epi& E) {
;     ...
;             PG8_LDA(At, 1, 1); PG8_STAGE(PG8_SB(1, 0), b3, voffB); PG8_STAGE(PG8_SB(1, 1), b3 + hstepB, voffB); PG8_STAGE(PG8_SA(1, 0), a3, voffA);
;             PG8_WAIT_V(8); PG8_WAIT_L(0); PG8_BAR; PG8_MMA(1, 0, At, B0); PG8_MMA(1, 1, At, B1); PG8_BAR; PG8_SCHED;
;         }
;         if constexpr (ALIGN_EPI) { if (wr == 0) PG8_BAR; }
	s_add_i32 s24, s52, s40
	v_lshl_add_u64 v[148:149], v[148:149], 0, s[12:13]
	s_mov_b32 m0, s24
	ds_read_b128 v[184:187], v155 offset:49152
	ds_read_b128 v[188:191], v155 offset:50176
	ds_read_b128 v[192:195], v155 offset:51200
	ds_read_b128 v[196:199], v155 offset:52224
	ds_read_b128 v[200:203], v155 offset:53248
	ds_read_b128 v[204:207], v155 offset:54272
	ds_read_b128 v[208:211], v155 offset:55296
	ds_read_b128 v[212:215], v155 offset:56320
	global_load_lds_dwordx4 v[148:149], off
	s_add_i32 m0, s24, 0x2000
	s_add_u32 s24, s28, 0xb0080
	v_lshl_add_u64 v[148:149], v[216:217], 0, s[12:13]
	s_addc_u32 s25, s29, 0
	s_add_i32 s28, s53, s40
	global_load_lds_dwordx4 v[148:149], off
	v_lshl_add_u64 v[148:149], s[24:25], 0, v[130:131]
	s_mov_b32 m0, s28
	s_nop 0
	global_load_lds_dwordx4 v[148:149], off
	v_lshl_add_u64 v[148:149], s[24:25], 0, v[134:135]
	s_add_i32 m0, s28, 0x2000
	s_nop 0
	global_load_lds_dwordx4 v[148:149], off
	v_lshl_add_u64 v[148:149], v[218:219], 0, s[12:13]
	s_mov_b32 m0, s47
	s_nop 0
	global_load_lds_dwordx4 v[148:149], off
	v_lshl_add_u64 v[148:149], v[220:221], 0, s[12:13]
	s_mov_b32 m0, s48
	s_nop 0
	global_load_lds_dwordx4 v[148:149], off
	s_waitcnt vmcnt(8)
	s_waitcnt lgkmcnt(0)
	s_barrier
	s_setprio 1
	s_waitcnt lgkmcnt(0)
	v_mfma_f32_16x16x32_bf16 v[60:63], v[144:147], v[184:187], v[60:63]
	v_mfma_f32_16x16x32_bf16 v[56:59], v[160:163], v[184:187], v[56:59]
	v_mfma_f32_16x16x32_bf16 v[44:47], v[144:147], v[192:195], v[44:47]
	v_mfma_f32_16x16x32_bf16 v[40:43], v[160:163], v[192:195], v[40:43]
	v_mfma_f32_16x16x32_bf16 v[28:31], v[144:147], v[200:203], v[28:31]
	v_mfma_f32_16x16x32_bf16 v[24:27], v[160:163], v[200:203], v[24:27]
	v_mfma_f32_16x16x32_bf16 v[12:15], v[144:147], v[208:211], v[12:15]
	v_mfma_f32_16x16x32_bf16 v[8:11], v[160:163], v[208:211], v[8:11]
	s_setprio 0
	s_setprio 1
	v_mfma_f32_16x16x32_bf16 v[60:63], v[156:159], v[188:191], v[60:63]
	v_mfma_f32_16x16x32_bf16 v[56:59], v[164:167], v[188:191], v[56:59]
	v_mfma_f32_16x16x32_bf16 v[44:47], v[156:159], v[196:199], v[44:47]
	v_mfma_f32_16x16x32_bf16 v[40:43], v[164:167], v[196:199], v[40:43]
	v_mfma_f32_16x16x32_bf16 v[28:31], v[156:159], v[204:207], v[28:31]
	v_mfma_f32_16x16x32_bf16 v[24:27], v[164:167], v[204:207], v[24:27]
	v_mfma_f32_16x16x32_bf16 v[12:15], v[156:159], v[212:215], v[12:15]
	v_mfma_f32_16x16x32_bf16 v[8:11], v[164:167], v[212:215], v[8:11]
	s_setprio 0
	s_setprio 1
	v_mfma_f32_16x16x32_bf16 v[52:55], v[168:171], v[184:187], v[52:55]
	v_mfma_f32_16x16x32_bf16 v[48:51], v[176:179], v[184:187], v[48:51]
	v_mfma_f32_16x16x32_bf16 v[36:39], v[168:171], v[192:195], v[36:39]
	v_mfma_f32_16x16x32_bf16 v[32:35], v[176:179], v[192:195], v[32:35]
	v_mfma_f32_16x16x32_bf16 v[20:23], v[168:171], v[200:203], v[20:23]
	v_mfma_f32_16x16x32_bf16 v[16:19], v[176:179], v[200:203], v[16:19]
	v_mfma_f32_16x16x32_bf16 v[4:7], v[168:171], v[208:211], v[4:7]
	v_mfma_f32_16x16x32_bf16 v[0:3], v[176:179], v[208:211], v[0:3]
	s_setprio 0
	s_setprio 1
	v_mfma_f32_16x16x32_bf16 v[52:55], v[172:175], v[188:191], v[52:55]
	v_mfma_f32_16x16x32_bf16 v[48:51], v[180:183], v[188:191], v[48:51]
	v_mfma_f32_16x16x32_bf16 v[36:39], v[172:175], v[196:199], v[36:39]
	v_mfma_f32_16x16x32_bf16 v[32:35], v[180:183], v[196:199], v[32:35]
	v_mfma_f32_16x16x32_bf16 v[20:23], v[172:175], v[204:207], v[20:23]
	v_mfma_f32_16x16x32_bf16 v[16:19], v[180:183], v[204:207], v[16:19]
	v_mfma_f32_16x16x32_bf16 v[4:7], v[172:175], v[212:215], v[4:7]
	v_mfma_f32_16x16x32_bf16 v[0:3], v[180:183], v[212:215], v[0:3]
	s_setprio 0
	s_barrier
	s_add_i32 s63, s63, 2
	s_add_u32 s61, s61, 0x100
	s_addc_u32 s62, s62, 0
	s_cmp_gt_u32 s63, 41
	s_mov_b64 s[24:25], s[26:27]
	s_cbranch_scc0 .LBB0_1620
	s_and_b64 vcc, exec, s[14:15]
	s_cbranch_vccz .LBB0_1623
	s_barrier

; #define PG8_STAGE(bufoff, gbase, voff) do { _Pragma("unroll") for (int _i = 0; _i < 2; ++_i) \
;         __builtin_amdgcn_global_load_lds((const unsigned*)((const char*)(gbase) + (voff)[_i]), (PG8_LAS unsigned*)(lds + (bufoff) + ldsw + _i * 8192), 16, 0, 0); } while (0)
; #define PG8_LDA(dst, b, h) do { _Pragma("unroll") for (int m = 0; m < 4; ++m) _Pragma("unroll") for (int k = 0; k < 2; ++k) dst[m][k] = *(const PG8_LAS bf16x8*)(lds + PG8_SA(b, h) + aoff + m * 2048 + k * 1024); } while (0)
; #define PG8_LDB(dst, b, h) do { _Pragma("unroll") for (int n = 0; n < 2; ++n) _Pragma("unroll") for (int k = 0; k < 2; ++k) dst[n][k] = *(const PG8_LAS bf16x8*)(lds + PG8_SB(b, h) + boff + n * 2048 + k * 1024); } while (0)
; #define PG8_MMA(ai, bj, At, Bt) do { __builtin_amdgcn_s_setprio(1); _Pragma("unroll") for (int m = 0; m < 4; ++m) _Pragma("unroll") for (int n = 0; n < 2; ++n) _Pragma("unroll") for (int k = 0; k < 2; ++k) \
;         acc[ai][bj][m][n] = __builtin_amdgcn_mfma_f32_16x16x32_bf16(Bt[n][k], At[m][k], acc[ai][bj][m][n], 0, 0, 0); __builtin_amdgcn_s_setprio(0); } while (0)
; #define PG8_WAIT_V(n) asm volatile("s_waitcnt vmcnt(" #n ")" ::: "memory")
; #define PG8_WAIT_L(n) asm volatile("s_waitcnt lgkmcnt(" #n ")" ::: "memory")
; #define PG8_BAR __builtin_amdgcn_s_barrier()
; #define PG8_SCHED __builtin_amdgcn_sched_barrier(0)
; template <class Epi, class Sched, bool ALIGN_EPI = true, bool SP2 = true>
; __device__ __forceinline__ void gemm_phase(PG8_LAS unsigned char* lds, const Gemm g, const Sched& S, const Epi& E) {
;     ...
;             PG8_LDB(B0, 0, 0); PG8_LDB(B1, 0, 1); PG8_SCHED; PG8_LDA(At, 0, 0); PG8_STAGE(PG8_SA(1, 1), a1 + hstepA, voffA);
;             PG8_WAIT_V(8); PG8_WAIT_L(0); PG8_BAR; PG8_MMA(0, 0, At, B0); PG8_MMA(0, 1, At, B1); PG8_BAR; PG8_SCHED;
;             PG8_LDA(At, 0, 1); PG8_STAGE(PG8_SB(0, 0), b2, voffB); PG8_STAGE(PG8_SB(0, 1), b2 + hstepB, voffB); PG8_STAGE(PG8_SA(0, 0), a2, voffA);
;             PG8_WAIT_V(8); PG8_WAIT_L(0); PG8_BAR; PG8_MMA(1, 0, At, B0); PG8_MMA(1, 1, At, B1); PG8_BAR; PG8_SCHED;
.LBB0_1690:
	ds_read_b128 v[44:47], v227
	ds_read_b128 v[48:51], v227 offset:1024
	ds_read_b128 v[52:55], v227 offset:2048
	ds_read_b128 v[60:63], v227 offset:3072
	ds_read_b128 v[64:67], v228
	ds_read_b128 v[68:71], v228 offset:1024
	ds_read_b128 v[72:75], v228 offset:2048
	ds_read_b128 v[76:79], v228 offset:3072
	s_add_u32 s52, s50, 0xfffc0080
	s_addc_u32 s53, s51, -1
	s_cmp_eq_u32 s79, 12
	s_cselect_b32 s57, s3, s53
	s_cselect_b32 s56, s41, s52
	s_cselect_b32 s55, s39, s78
	s_cselect_b32 s54, s49, s77
	v_lshl_add_u64 v[192:193], s[50:51], 0, v[220:221]
	s_add_i32 m0, s61, 0xc000
	ds_read_b128 v[80:83], v229
	ds_read_b128 v[84:87], v229 offset:1024
	ds_read_b128 v[88:91], v229 offset:2048
	ds_read_b128 v[92:95], v229 offset:3072
	ds_read_b128 v[96:99], v229 offset:4096
	ds_read_b128 v[100:103], v229 offset:5120
	ds_read_b128 v[104:107], v229 offset:6144
	ds_read_b128 v[108:111], v229 offset:7168
	global_load_lds_dwordx4 v[192:193], off
	v_lshl_add_u64 v[192:193], s[50:51], 0, v[218:219]
	s_add_i32 m0, s61, 0xe000
	s_nop 0
	global_load_lds_dwordx4 v[192:193], off
	s_waitcnt vmcnt(8)
	s_waitcnt lgkmcnt(0)
	s_barrier
	s_setprio 1
	s_waitcnt lgkmcnt(0)
	v_mfma_f32_16x16x32_bf16 v[188:191], v[44:47], v[80:83], v[188:191]
	v_mfma_f32_16x16x32_bf16 v[180:183], v[52:55], v[80:83], v[180:183]
	v_mfma_f32_16x16x32_bf16 v[172:175], v[44:47], v[88:91], v[172:175]
	v_mfma_f32_16x16x32_bf16 v[164:167], v[52:55], v[88:91], v[164:167]
	v_mfma_f32_16x16x32_bf16 v[156:159], v[44:47], v[96:99], v[156:159]
	v_mfma_f32_16x16x32_bf16 v[148:151], v[52:55], v[96:99], v[148:151]
	v_mfma_f32_16x16x32_bf16 v[140:143], v[44:47], v[104:107], v[140:143]
	v_mfma_f32_16x16x32_bf16 v[132:135], v[52:55], v[104:107], v[132:135]
	s_setprio 0
	s_setprio 1
	v_mfma_f32_16x16x32_bf16 v[188:191], v[48:51], v[84:87], v[188:191]
	v_mfma_f32_16x16x32_bf16 v[180:183], v[60:63], v[84:87], v[180:183]
	v_mfma_f32_16x16x32_bf16 v[172:175], v[48:51], v[92:95], v[172:175]
	v_mfma_f32_16x16x32_bf16 v[164:167], v[60:63], v[92:95], v[164:167]
	v_mfma_f32_16x16x32_bf16 v[156:159], v[48:51], v[100:103], v[156:159]
	v_mfma_f32_16x16x32_bf16 v[148:151], v[60:63], v[100:103], v[148:151]
	v_mfma_f32_16x16x32_bf16 v[140:143], v[48:51], v[108:111], v[140:143]
	v_mfma_f32_16x16x32_bf16 v[132:135], v[60:63], v[108:111], v[132:135]
	s_setprio 0
	s_setprio 1
	v_mfma_f32_16x16x32_bf16 v[184:187], v[64:67], v[80:83], v[184:187]
	v_mfma_f32_16x16x32_bf16 v[80:83], v[72:75], v[80:83], v[176:179]
	v_mfma_f32_16x16x32_bf16 v[184:187], v[68:71], v[84:87], v[184:187]
	v_mfma_f32_16x16x32_bf16 v[80:83], v[76:79], v[84:87], v[80:83]
	v_mfma_f32_16x16x32_bf16 v[84:87], v[64:67], v[88:91], v[168:171]
	v_mfma_f32_16x16x32_bf16 v[88:91], v[72:75], v[88:91], v[160:163]
	v_mfma_f32_16x16x32_bf16 v[84:87], v[68:71], v[92:95], v[84:87]
	v_mfma_f32_16x16x32_bf16 v[88:91], v[76:79], v[92:95], v[88:91]
	s_setprio 0
	s_setprio 1
	v_mfma_f32_16x16x32_bf16 v[92:95], v[64:67], v[96:99], v[152:155]
	v_mfma_f32_16x16x32_bf16 v[96:99], v[72:75], v[96:99], v[144:147]
	v_mfma_f32_16x16x32_bf16 v[92:95], v[68:71], v[100:103], v[92:95]
	v_mfma_f32_16x16x32_bf16 v[96:99], v[76:79], v[100:103], v[96:99]
	v_mfma_f32_16x16x32_bf16 v[100:103], v[64:67], v[104:107], v[136:139]
	v_mfma_f32_16x16x32_bf16 v[104:107], v[72:75], v[104:107], v[128:131]
	v_mfma_f32_16x16x32_bf16 v[100:103], v[68:71], v[108:111], v[100:103]
	v_mfma_f32_16x16x32_bf16 v[104:107], v[76:79], v[108:111], v[104:107]
	s_setprio 0
	s_barrier
	s_add_i32 s52, s73, s60
	v_lshl_add_u64 v[208:209], s[54:55], 0, v[212:213]
	s_mov_b32 m0, s52
	ds_read_b128 v[108:111], v229 offset:16384
	ds_read_b128 v[128:131], v229 offset:17408
	ds_read_b128 v[136:139], v229 offset:18432
	ds_read_b128 v[144:147], v229 offset:19456
	ds_read_b128 v[152:155], v229 offset:20480
	ds_read_b128 v[160:163], v229 offset:21504
	ds_read_b128 v[168:171], v229 offset:22528
	ds_read_b128 v[176:179], v229 offset:23552
	global_load_lds_dwordx4 v[208:209], off
	s_add_i32 m0, s52, 0x2000
	s_add_u32 s52, s54, 0x40000
	v_lshl_add_u64 v[222:223], s[54:55], 0, v[216:217]
	s_addc_u32 s53, s55, 0
	s_add_i32 s68, s74, s60
	global_load_lds_dwordx4 v[222:223], off
	v_lshl_add_u64 v[192:193], s[52:53], 0, v[212:213]
	s_mov_b32 m0, s68
	v_lshl_add_u64 v[224:225], s[56:57], 0, v[210:211]
	global_load_lds_dwordx4 v[192:193], off
	v_lshl_add_u64 v[192:193], s[52:53], 0, v[216:217]
	s_add_i32 m0, s68, 0x2000
	v_lshl_add_u64 v[230:231], s[56:57], 0, v[214:215]
	global_load_lds_dwordx4 v[192:193], off
	s_mov_b32 m0, s61
	s_nop 0
	global_load_lds_dwordx4 v[224:225], off
	s_mov_b32 m0, s62
	s_nop 0
	global_load_lds_dwordx4 v[230:231], off
	s_waitcnt vmcnt(8)
	s_waitcnt lgkmcnt(0)
	s_barrier
; #define PG8_STAGE(bufoff, gbase, voff) do { _Pragma("unroll") for (int _i = 0; _i < 2; ++_i) \
;         __builtin_amdgcn_global_load_lds((const unsigned*)((const char*)(gbase) + (voff)[_i]), (PG8_LAS unsigned*)(lds + (bufoff) + ldsw + _i * 8192), 16, 0, 0); } while (0)
; #define PG8_LDA(dst, b, h) do { _Pragma("unroll") for (int m = 0; m < 4; ++m) _Pragma("unroll") for (int k = 0; k < 2; ++k) dst[m][k] = *(const PG8_LAS bf16x8*)(lds + PG8_SA(b, h) + aoff + m * 2048 + k * 1024); } while (0)
; #define PG8_LDB(dst, b, h) do { _Pragma("unroll") for (int n = 0; n < 2; ++n) _Pragma("unroll") for (int k = 0; k < 2; ++k) dst[n][k] = *(const PG8_LAS bf16x8*)(lds + PG8_SB(b, h) + boff + n * 2048 + k * 1024); } while (0)
; #define PG8_MMA(ai, bj, At, Bt) do { __builtin_amdgcn_s_setprio(1); _Pragma("unroll") for (int m = 0; m < 4; ++m) _Pragma("unroll") for (int n = 0; n < 2; ++n) _Pragma("unroll") for (int k = 0; k < 2; ++k) \
;         acc[ai][bj][m][n] = __builtin_amdgcn_mfma_f32_16x16x32_bf16(Bt[n][k], At[m][k], acc[ai][bj][m][n], 0, 0, 0); __builtin_amdgcn_s_setprio(0); } while (0)
; #define PG8_WAIT_V(n) asm volatile("s_waitcnt vmcnt(" #n ")" ::: "memory")
; #define PG8_WAIT_L(n) asm volatile("s_waitcnt lgkmcnt(" #n ")" ::: "memory")
; #define PG8_BAR __builtin_amdgcn_s_barrier()
; #define PG8_SCHED __builtin_amdgcn_sched_barrier(0)
; template <class Epi, class Sched, bool ALIGN_EPI = true, bool SP2 = true>
; __device__ __forceinline__ void gemm_phase(PG8_LAS unsigned char* lds, const Gemm g, const Sched& S, const Epi& E) {
;     ...
;             PG8_WAIT_V(8); PG8_WAIT_L(0); PG8_BAR; PG8_MMA(1, 0, At, B0); PG8_MMA(1, 1, At, B1); PG8_BAR; PG8_SCHED;
;             PG8_LDB(B0, 1, 0); PG8_LDB(B1, 1, 1); PG8_SCHED; PG8_LDA(At, 1, 0); PG8_STAGE(PG8_SA(0, 1), a2 + hstepA, voffA);
;             PG8_WAIT_V(8); PG8_WAIT_L(0); PG8_BAR; PG8_MMA(0, 0, At, B0); PG8_MMA(0, 1, At, B1); PG8_BAR; PG8_SCHED;
	s_setprio 1
	s_waitcnt lgkmcnt(0)
	v_mfma_f32_16x16x32_bf16 v[124:127], v[44:47], v[108:111], v[124:127]
	v_mfma_f32_16x16x32_bf16 v[116:119], v[52:55], v[108:111], v[116:119]
	v_mfma_f32_16x16x32_bf16 v[56:59], v[44:47], v[136:139], v[56:59]
	v_mfma_f32_16x16x32_bf16 v[36:39], v[52:55], v[136:139], v[36:39]
	v_mfma_f32_16x16x32_bf16 v[28:31], v[44:47], v[152:155], v[28:31]
	v_mfma_f32_16x16x32_bf16 v[20:23], v[52:55], v[152:155], v[20:23]
	v_mfma_f32_16x16x32_bf16 v[12:15], v[44:47], v[168:171], v[12:15]
	v_mfma_f32_16x16x32_bf16 v[4:7], v[52:55], v[168:171], v[4:7]
	s_setprio 0
	s_setprio 1
	v_mfma_f32_16x16x32_bf16 v[124:127], v[48:51], v[128:131], v[124:127]
	v_mfma_f32_16x16x32_bf16 v[116:119], v[60:63], v[128:131], v[116:119]
	v_mfma_f32_16x16x32_bf16 v[56:59], v[48:51], v[144:147], v[56:59]
	v_mfma_f32_16x16x32_bf16 v[36:39], v[60:63], v[144:147], v[36:39]
	v_mfma_f32_16x16x32_bf16 v[28:31], v[48:51], v[160:163], v[28:31]
	v_mfma_f32_16x16x32_bf16 v[20:23], v[60:63], v[160:163], v[20:23]
	v_mfma_f32_16x16x32_bf16 v[12:15], v[48:51], v[176:179], v[12:15]
	v_mfma_f32_16x16x32_bf16 v[4:7], v[60:63], v[176:179], v[4:7]
	s_setprio 0
	s_setprio 1
	v_mfma_f32_16x16x32_bf16 v[40:43], v[64:67], v[136:139], v[40:43]
	v_mfma_f32_16x16x32_bf16 v[32:35], v[72:75], v[136:139], v[32:35]
	v_mfma_f32_16x16x32_bf16 v[24:27], v[64:67], v[152:155], v[24:27]
	v_mfma_f32_16x16x32_bf16 v[16:19], v[72:75], v[152:155], v[16:19]
	v_mfma_f32_16x16x32_bf16 v[8:11], v[64:67], v[168:171], v[8:11]
	v_mfma_f32_16x16x32_bf16 v[0:3], v[72:75], v[168:171], v[0:3]
	v_mfma_f32_16x16x32_bf16 v[44:47], v[64:67], v[108:111], v[120:123]
	v_mfma_f32_16x16x32_bf16 v[48:51], v[72:75], v[108:111], v[112:115]
	s_setprio 0
	s_setprio 1
	v_mfma_f32_16x16x32_bf16 v[40:43], v[68:71], v[144:147], v[40:43]
	v_mfma_f32_16x16x32_bf16 v[32:35], v[76:79], v[144:147], v[32:35]
	v_mfma_f32_16x16x32_bf16 v[24:27], v[68:71], v[160:163], v[24:27]
	v_mfma_f32_16x16x32_bf16 v[16:19], v[76:79], v[160:163], v[16:19]
	v_mfma_f32_16x16x32_bf16 v[8:11], v[68:71], v[176:179], v[8:11]
	v_mfma_f32_16x16x32_bf16 v[0:3], v[76:79], v[176:179], v[0:3]
	v_mfma_f32_16x16x32_bf16 v[44:47], v[68:71], v[128:131], v[44:47]
	v_mfma_f32_16x16x32_bf16 v[48:51], v[76:79], v[128:131], v[48:51]
	s_setprio 0
	s_barrier
	s_add_i32 s68, 0, 0x18000
	s_add_i32 s69, 0, 0x1c000
	v_add_u32_e32 v68, s68, v226
	v_add_u32_e32 v112, s69, v226
	ds_read_b128 v[52:55], v68
	ds_read_b128 v[60:63], v68 offset:1024
	ds_read_b128 v[64:67], v68 offset:2048
	ds_read_b128 v[68:71], v68 offset:3072
	ds_read_b128 v[72:75], v112
	ds_read_b128 v[76:79], v112 offset:1024
	ds_read_b128 v[108:111], v112 offset:2048
	ds_read_b128 v[192:195], v112 offset:3072
	s_add_u32 s52, s56, 0x40000
	s_addc_u32 s53, s57, 0
	s_mov_b32 m0, s63
	v_lshl_add_u64 v[152:153], s[52:53], 0, v[210:211]
	ds_read_b128 v[112:115], v229 offset:32768
	ds_read_b128 v[120:123], v229 offset:33792
	ds_read_b128 v[128:131], v229 offset:34816
	ds_read_b128 v[136:139], v229 offset:35840
	ds_read_b128 v[144:147], v229 offset:36864
	ds_read_b128 v[196:199], v229 offset:37888
	ds_read_b128 v[200:203], v229 offset:38912
	ds_read_b128 v[204:207], v229 offset:39936
	global_load_lds_dwordx4 v[152:153], off
	v_lshl_add_u64 v[152:153], s[52:53], 0, v[214:215]
	s_mov_b32 m0, s64
	s_nop 0
	global_load_lds_dwordx4 v[152:153], off
	s_waitcnt vmcnt(8)
	s_waitcnt lgkmcnt(0)
	s_barrier
	s_setprio 1
	s_waitcnt lgkmcnt(0)
	v_mfma_f32_16x16x32_bf16 v[152:155], v[52:55], v[112:115], v[188:191]
	v_mfma_f32_16x16x32_bf16 v[188:191], v[60:63], v[120:123], v[152:155]
	v_mfma_f32_16x16x32_bf16 v[152:155], v[64:67], v[112:115], v[180:183]
	v_mfma_f32_16x16x32_bf16 v[180:183], v[68:71], v[120:123], v[152:155]
	v_mfma_f32_16x16x32_bf16 v[152:155], v[52:55], v[128:131], v[172:175]
	v_mfma_f32_16x16x32_bf16 v[172:175], v[60:63], v[136:139], v[152:155]
	v_mfma_f32_16x16x32_bf16 v[152:155], v[64:67], v[128:131], v[164:167]
	v_mfma_f32_16x16x32_bf16 v[164:167], v[68:71], v[136:139], v[152:155]
	s_setprio 0
	s_setprio 1
	v_mfma_f32_16x16x32_bf16 v[152:155], v[52:55], v[144:147], v[156:159]
	v_mfma_f32_16x16x32_bf16 v[148:151], v[64:67], v[144:147], v[148:151]
	v_mfma_f32_16x16x32_bf16 v[140:143], v[52:55], v[200:203], v[140:143]
	v_mfma_f32_16x16x32_bf16 v[132:135], v[64:67], v[200:203], v[132:135]
	v_mfma_f32_16x16x32_bf16 v[156:159], v[60:63], v[196:199], v[152:155]
	v_mfma_f32_16x16x32_bf16 v[148:151], v[68:71], v[196:199], v[148:151]
	v_mfma_f32_16x16x32_bf16 v[140:143], v[60:63], v[204:207], v[140:143]
	v_mfma_f32_16x16x32_bf16 v[132:135], v[68:71], v[204:207], v[132:135]
	s_setprio 0
	s_setprio 1
	v_mfma_f32_16x16x32_bf16 v[80:83], v[108:111], v[112:115], v[80:83]
	v_mfma_f32_16x16x32_bf16 v[176:179], v[192:195], v[120:123], v[80:83]
	v_mfma_f32_16x16x32_bf16 v[80:83], v[72:75], v[128:131], v[84:87]
	v_mfma_f32_16x16x32_bf16 v[168:171], v[76:79], v[136:139], v[80:83]
	v_mfma_f32_16x16x32_bf16 v[80:83], v[108:111], v[128:131], v[88:91]
	v_mfma_f32_16x16x32_bf16 v[152:155], v[72:75], v[112:115], v[184:187]
	v_mfma_f32_16x16x32_bf16 v[160:163], v[192:195], v[136:139], v[80:83]
	v_mfma_f32_16x16x32_bf16 v[80:83], v[72:75], v[144:147], v[92:95]
	s_setprio 0
	s_setprio 1
	v_mfma_f32_16x16x32_bf16 v[184:187], v[76:79], v[120:123], v[152:155]
	v_mfma_f32_16x16x32_bf16 v[152:155], v[76:79], v[196:199], v[80:83]
	v_mfma_f32_16x16x32_bf16 v[80:83], v[108:111], v[144:147], v[96:99]
	v_mfma_f32_16x16x32_bf16 v[144:147], v[192:195], v[196:199], v[80:83]
	v_mfma_f32_16x16x32_bf16 v[80:83], v[72:75], v[200:203], v[100:103]
	v_mfma_f32_16x16x32_bf16 v[136:139], v[76:79], v[204:207], v[80:83]
	v_mfma_f32_16x16x32_bf16 v[80:83], v[108:111], v[200:203], v[104:107]
	v_mfma_f32_16x16x32_bf16 v[128:131], v[192:195], v[204:207], v[80:83]
	s_setprio 0
	s_barrier
; #define PG8_STAGE(bufoff, gbase, voff) do { _Pragma("unroll") for (int _i = 0; _i < 2; ++_i) \
;         __builtin_amdgcn_global_load_lds((const unsigned*)((const char*)(gbase) + (voff)[_i]), (PG8_LAS unsigned*)(lds + (bufoff) + ldsw + _i * 8192), 16, 0, 0); } while (0)
; #define PG8_LDA(dst, b, h) do { _Pragma("unroll") for (int m = 0; m < 4; ++m) _Pragma("unroll") for (int k = 0; k < 2; ++k) dst[m][k] = *(const PG8_LAS bf16x8*)(lds + PG8_SA(b, h) + aoff + m * 2048 + k * 1024); } while (0)
; #define PG8_MMA(ai, bj, At, Bt) do { __builtin_amdgcn_s_setprio(1); _Pragma("unroll") for (int m = 0; m < 4; ++m) _Pragma("unroll") for (int n = 0; n < 2; ++n) _Pragma("unroll") for (int k = 0; k < 2; ++k) \
;         acc[ai][bj][m][n] = __builtin_amdgcn_mfma_f32_16x16x32_bf16(Bt[n][k], At[m][k], acc[ai][bj][m][n], 0, 0, 0); __builtin_amdgcn_s_setprio(0); } while (0)
; #define PG8_WAIT_V(n) asm volatile("s_waitcnt vmcnt(" #n ")" ::: "memory")
; #define PG8_WAIT_L(n) asm volatile("s_waitcnt lgkmcnt(" #n ")" ::: "memory")
; #define PG8_BAR __builtin_amdgcn_s_barrier()
; #define PG8_SCHED __builtin_amdgcn_sched_barrier(0)
; template <class Epi, class Sched, bool ALIGN_EPI = true, bool SP2 = true>
; __device__ __forceinline__ void gemm_phase(PG8_LAS unsigned char* lds, const Gemm g, const Sched& S, const Epi& E) {
;     ...
;             PG8_LDA(At, 1, 1); PG8_STAGE(PG8_SB(1, 0), b3, voffB); PG8_STAGE(PG8_SB(1, 1), b3 + hstepB, voffB); PG8_STAGE(PG8_SA(1, 0), a3, voffA);
;             PG8_WAIT_V(8); PG8_WAIT_L(0); PG8_BAR; PG8_MMA(1, 0, At, B0); PG8_MMA(1, 1, At, B1); PG8_BAR; PG8_SCHED;
;         }
;         if constexpr (ALIGN_EPI) { if (wr == 0) PG8_BAR; }
	s_add_i32 s52, s68, s60
	v_lshl_add_u64 v[112:113], v[208:209], 0, s[14:15]
	s_mov_b32 m0, s52
	s_nop 1
	ds_read_b128 v[80:83], v229 offset:49152
	ds_read_b128 v[84:87], v229 offset:50176
	ds_read_b128 v[88:91], v229 offset:51200
	ds_read_b128 v[92:95], v229 offset:52224
	ds_read_b128 v[96:99], v229 offset:53248
	ds_read_b128 v[100:103], v229 offset:54272
	ds_read_b128 v[104:107], v229 offset:55296
	ds_read_b128 v[196:199], v229 offset:56320
	global_load_lds_dwordx4 v[112:113], off
	s_add_i32 m0, s52, 0x2000
	s_add_u32 s52, s54, 0x40080
	v_lshl_add_u64 v[112:113], v[222:223], 0, s[14:15]
	s_addc_u32 s53, s55, 0
	s_add_i32 s54, s69, s60
	global_load_lds_dwordx4 v[112:113], off
	v_lshl_add_u64 v[112:113], s[52:53], 0, v[212:213]
	s_mov_b32 m0, s54
	s_nop 0
	global_load_lds_dwordx4 v[112:113], off
	v_lshl_add_u64 v[112:113], s[52:53], 0, v[216:217]
	s_add_i32 m0, s54, 0x2000
	s_nop 0
	global_load_lds_dwordx4 v[112:113], off
	v_lshl_add_u64 v[112:113], v[224:225], 0, s[14:15]
	s_mov_b32 m0, s66
	s_nop 0
	global_load_lds_dwordx4 v[112:113], off
	v_lshl_add_u64 v[112:113], v[230:231], 0, s[14:15]
	s_mov_b32 m0, s71
	s_nop 0
	global_load_lds_dwordx4 v[112:113], off
	s_waitcnt vmcnt(8)
	s_waitcnt lgkmcnt(0)
	s_barrier
	s_setprio 1
	s_waitcnt lgkmcnt(0)
	v_mfma_f32_16x16x32_bf16 v[112:115], v[52:55], v[80:83], v[124:127]
	v_mfma_f32_16x16x32_bf16 v[124:127], v[60:63], v[84:87], v[112:115]
	v_mfma_f32_16x16x32_bf16 v[112:115], v[64:67], v[80:83], v[116:119]
	v_mfma_f32_16x16x32_bf16 v[56:59], v[52:55], v[88:91], v[56:59]
	v_mfma_f32_16x16x32_bf16 v[36:39], v[64:67], v[88:91], v[36:39]
	v_mfma_f32_16x16x32_bf16 v[28:31], v[52:55], v[96:99], v[28:31]
	v_mfma_f32_16x16x32_bf16 v[20:23], v[64:67], v[96:99], v[20:23]
	v_mfma_f32_16x16x32_bf16 v[12:15], v[52:55], v[104:107], v[12:15]
	s_setprio 0
	s_setprio 1
	v_mfma_f32_16x16x32_bf16 v[4:7], v[64:67], v[104:107], v[4:7]
	v_mfma_f32_16x16x32_bf16 v[116:119], v[68:71], v[84:87], v[112:115]
	v_mfma_f32_16x16x32_bf16 v[56:59], v[60:63], v[92:95], v[56:59]
	v_mfma_f32_16x16x32_bf16 v[36:39], v[68:71], v[92:95], v[36:39]
	v_mfma_f32_16x16x32_bf16 v[28:31], v[60:63], v[100:103], v[28:31]
	v_mfma_f32_16x16x32_bf16 v[20:23], v[68:71], v[100:103], v[20:23]
	v_mfma_f32_16x16x32_bf16 v[12:15], v[60:63], v[196:199], v[12:15]
	v_mfma_f32_16x16x32_bf16 v[4:7], v[68:71], v[196:199], v[4:7]
	s_setprio 0
	s_setprio 1
	v_mfma_f32_16x16x32_bf16 v[44:47], v[72:75], v[80:83], v[44:47]
	v_mfma_f32_16x16x32_bf16 v[120:123], v[76:79], v[84:87], v[44:47]
	v_mfma_f32_16x16x32_bf16 v[44:47], v[108:111], v[80:83], v[48:51]
	v_mfma_f32_16x16x32_bf16 v[40:43], v[72:75], v[88:91], v[40:43]
	v_mfma_f32_16x16x32_bf16 v[32:35], v[108:111], v[88:91], v[32:35]
	v_mfma_f32_16x16x32_bf16 v[24:27], v[72:75], v[96:99], v[24:27]
	v_mfma_f32_16x16x32_bf16 v[16:19], v[108:111], v[96:99], v[16:19]
	v_mfma_f32_16x16x32_bf16 v[8:11], v[72:75], v[104:107], v[8:11]
	s_setprio 0
	s_setprio 1
	v_mfma_f32_16x16x32_bf16 v[0:3], v[108:111], v[104:107], v[0:3]
	v_mfma_f32_16x16x32_bf16 v[112:115], v[192:195], v[84:87], v[44:47]
	v_mfma_f32_16x16x32_bf16 v[40:43], v[76:79], v[92:95], v[40:43]
	v_mfma_f32_16x16x32_bf16 v[32:35], v[192:195], v[92:95], v[32:35]
	v_mfma_f32_16x16x32_bf16 v[24:27], v[76:79], v[100:103], v[24:27]
	v_mfma_f32_16x16x32_bf16 v[16:19], v[192:195], v[100:103], v[16:19]
	v_mfma_f32_16x16x32_bf16 v[8:11], v[76:79], v[196:199], v[8:11]
	v_mfma_f32_16x16x32_bf16 v[0:3], v[192:195], v[196:199], v[0:3]
	s_setprio 0
	s_barrier
	s_add_i32 s79, s79, 2
	s_add_u32 s77, s77, 0x100
	s_addc_u32 s78, s78, 0
	s_add_u32 s50, s50, 0x100
	s_addc_u32 s51, s51, 0
	s_cmp_gt_u32 s79, 13
	s_cbranch_scc0 .LBB0_1690
	s_and_b64 vcc, exec, s[16:17]
	s_cbranch_vccz .LBB0_1693
	s_barrier

; #define PG8_STAGE(bufoff, gbase, voff) do { _Pragma("unroll") for (int _i = 0; _i < 2; ++_i) \
;         __builtin_amdgcn_global_load_lds((const unsigned*)((const char*)(gbase) + (voff)[_i]), (PG8_LAS unsigned*)(lds + (bufoff) + ldsw + _i * 8192), 16, 0, 0); } while (0)
; #define PG8_LDA(dst, b, h) do { _Pragma("unroll") for (int m = 0; m < 4; ++m) _Pragma("unroll") for (int k = 0; k < 2; ++k) dst[m][k] = *(const PG8_LAS bf16x8*)(lds + PG8_SA(b, h) + aoff + m * 2048 + k * 1024); } while (0)
; #define PG8_LDB(dst, b, h) do { _Pragma("unroll") for (int n = 0; n < 2; ++n) _Pragma("unroll") for (int k = 0; k < 2; ++k) dst[n][k] = *(const PG8_LAS bf16x8*)(lds + PG8_SB(b, h) + boff + n * 2048 + k * 1024); } while (0)
; #define PG8_MMA(ai, bj, At, Bt) do { __builtin_amdgcn_s_setprio(1); _Pragma("unroll") for (int m = 0; m < 4; ++m) _Pragma("unroll") for (int n = 0; n < 2; ++n) _Pragma("unroll") for (int k = 0; k < 2; ++k) \
;         acc[ai][bj][m][n] = __builtin_amdgcn_mfma_f32_16x16x32_bf16(Bt[n][k], At[m][k], acc[ai][bj][m][n], 0, 0, 0); __builtin_amdgcn_s_setprio(0); } while (0)
; #define PG8_WAIT_V(n) asm volatile("s_waitcnt vmcnt(" #n ")" ::: "memory")
; #define PG8_WAIT_L(n) asm volatile("s_waitcnt lgkmcnt(" #n ")" ::: "memory")
; #define PG8_BAR __builtin_amdgcn_s_barrier()
; template <class Epi, class Sched, bool ALIGN_EPI = true, bool SP2 = true>
; __device__ __forceinline__ void gemm_phase(PG8_LAS unsigned char* lds, const Gemm g, const Sched& S, const Epi& E) {
;     ...
;         for (int t = 0; t < nt; t += 2) {
;             const bool last = (t == nt - 2);
;             const char* a1 = cA + (size_t)(t + 1) * kstep;
;             const char* a2 = last ? nA : cA + (size_t)(t + 2) * kstep; const char* b2 = last ? nB : cB + (size_t)(t + 2) * kstep;
;             const char* a3 = a2 + kstep; const char* b3 = b2 + kstep;
;             PG8_LDB(B0, 0, 0); PG8_LDB(B1, 0, 1); PG8_SCHED; PG8_LDA(At, 0, 0); PG8_STAGE(PG8_SA(1, 1), a1 + hstepA, voffA);
;             PG8_WAIT_V(8); PG8_WAIT_L(0); PG8_BAR; PG8_MMA(0, 0, At, B0); PG8_MMA(0, 1, At, B1); PG8_BAR; PG8_SCHED;
;             PG8_LDA(At, 0, 1); PG8_STAGE(PG8_SB(0, 0), b2, voffB); PG8_STAGE(PG8_SB(0, 1), b2 + hstepB, voffB); PG8_STAGE(PG8_SA(0, 0), a2, voffA);
;             PG8_WAIT_V(8); PG8_WAIT_L(0); PG8_BAR; PG8_MMA(1, 0, At, B0); PG8_MMA(1, 1, At, B1); PG8_BAR; PG8_SCHED;
.LBB0_1785:
	s_add_i32 s73, s34, 2
	s_add_u32 s30, s28, 0x100
	s_addc_u32 s31, s29, 0
	s_add_i32 s52, 0, 0x10000
	s_cmp_eq_u32 s62, s34
	s_cselect_b32 s39, s25, s31
	s_cselect_b32 s38, s24, s30
	v_add_u32_e32 v147, s52, v144
	s_cselect_b32 s35, s27, s72
	s_cselect_b32 s34, s26, s71
	s_add_i32 s53, 0, 0x14000
	ds_read_b128 v[148:151], v147
	ds_read_b128 v[152:155], v147 offset:1024
	ds_read_b128 v[156:159], v147 offset:2048
	ds_read_b128 v[160:163], v147 offset:3072
	v_add_u32_e32 v147, s53, v144
	ds_read_b128 v[164:167], v147
	ds_read_b128 v[168:171], v147 offset:1024
	ds_read_b128 v[172:175], v147 offset:2048
	ds_read_b128 v[176:179], v147 offset:3072
	v_lshl_add_u64 v[212:213], s[28:29], 0, v[138:139]
	s_add_i32 m0, s56, 0xc000
	ds_read_b128 v[180:183], v146
	ds_read_b128 v[184:187], v146 offset:1024
	ds_read_b128 v[188:191], v146 offset:2048
	ds_read_b128 v[192:195], v146 offset:3072
	ds_read_b128 v[196:199], v146 offset:4096
	ds_read_b128 v[200:203], v146 offset:5120
	ds_read_b128 v[204:207], v146 offset:6144
	ds_read_b128 v[208:211], v146 offset:7168
	global_load_lds_dwordx4 v[212:213], off
	v_lshl_add_u64 v[212:213], s[28:29], 0, v[136:137]
	s_add_i32 m0, s56, 0xe000
	s_nop 0
	global_load_lds_dwordx4 v[212:213], off
	s_waitcnt vmcnt(8)
	s_waitcnt lgkmcnt(0)
	s_barrier
	s_setprio 1
	s_waitcnt lgkmcnt(0)
	v_mfma_f32_16x16x32_bf16 v[124:127], v[148:151], v[180:183], v[124:127]
	v_mfma_f32_16x16x32_bf16 v[120:123], v[156:159], v[180:183], v[120:123]
	v_mfma_f32_16x16x32_bf16 v[116:119], v[148:151], v[188:191], v[116:119]
	v_mfma_f32_16x16x32_bf16 v[112:115], v[156:159], v[188:191], v[112:115]
	v_mfma_f32_16x16x32_bf16 v[100:103], v[148:151], v[196:199], v[100:103]
	v_mfma_f32_16x16x32_bf16 v[96:99], v[156:159], v[196:199], v[96:99]
	v_mfma_f32_16x16x32_bf16 v[84:87], v[148:151], v[204:207], v[84:87]
	v_mfma_f32_16x16x32_bf16 v[80:83], v[156:159], v[204:207], v[80:83]
	s_setprio 0
	s_setprio 1
	v_mfma_f32_16x16x32_bf16 v[124:127], v[152:155], v[184:187], v[124:127]
	v_mfma_f32_16x16x32_bf16 v[120:123], v[160:163], v[184:187], v[120:123]
	v_mfma_f32_16x16x32_bf16 v[116:119], v[152:155], v[192:195], v[116:119]
	v_mfma_f32_16x16x32_bf16 v[112:115], v[160:163], v[192:195], v[112:115]
	v_mfma_f32_16x16x32_bf16 v[100:103], v[152:155], v[200:203], v[100:103]
	v_mfma_f32_16x16x32_bf16 v[96:99], v[160:163], v[200:203], v[96:99]
	v_mfma_f32_16x16x32_bf16 v[84:87], v[152:155], v[208:211], v[84:87]
	v_mfma_f32_16x16x32_bf16 v[80:83], v[160:163], v[208:211], v[80:83]
	s_setprio 0
	s_setprio 1
	v_mfma_f32_16x16x32_bf16 v[108:111], v[164:167], v[180:183], v[108:111]
	v_mfma_f32_16x16x32_bf16 v[104:107], v[172:175], v[180:183], v[104:107]
	v_mfma_f32_16x16x32_bf16 v[92:95], v[164:167], v[188:191], v[92:95]
	v_mfma_f32_16x16x32_bf16 v[88:91], v[172:175], v[188:191], v[88:91]
	v_mfma_f32_16x16x32_bf16 v[76:79], v[164:167], v[196:199], v[76:79]
	v_mfma_f32_16x16x32_bf16 v[72:75], v[172:175], v[196:199], v[72:75]
	v_mfma_f32_16x16x32_bf16 v[68:71], v[164:167], v[204:207], v[68:71]
	v_mfma_f32_16x16x32_bf16 v[64:67], v[172:175], v[204:207], v[64:67]
	s_setprio 0
	s_setprio 1
	v_mfma_f32_16x16x32_bf16 v[108:111], v[168:171], v[184:187], v[108:111]
	v_mfma_f32_16x16x32_bf16 v[104:107], v[176:179], v[184:187], v[104:107]
	v_mfma_f32_16x16x32_bf16 v[92:95], v[168:171], v[192:195], v[92:95]
	v_mfma_f32_16x16x32_bf16 v[88:91], v[176:179], v[192:195], v[88:91]
	v_mfma_f32_16x16x32_bf16 v[76:79], v[168:171], v[200:203], v[76:79]
	v_mfma_f32_16x16x32_bf16 v[72:75], v[176:179], v[200:203], v[72:75]
	v_mfma_f32_16x16x32_bf16 v[68:71], v[168:171], v[208:211], v[68:71]
	v_mfma_f32_16x16x32_bf16 v[64:67], v[176:179], v[208:211], v[64:67]
	s_setprio 0
	s_barrier
	s_add_i32 s28, s52, s54
	v_lshl_add_u64 v[212:213], s[34:35], 0, v[128:129]
	s_mov_b32 m0, s28
	ds_read_b128 v[180:183], v146 offset:16384
	ds_read_b128 v[184:187], v146 offset:17408
	ds_read_b128 v[188:191], v146 offset:18432
	ds_read_b128 v[192:195], v146 offset:19456
	ds_read_b128 v[196:199], v146 offset:20480
	ds_read_b128 v[200:203], v146 offset:21504
	ds_read_b128 v[204:207], v146 offset:22528
	ds_read_b128 v[208:211], v146 offset:23552
	global_load_lds_dwordx4 v[212:213], off
	s_add_i32 m0, s28, 0x2000
	s_add_u32 s28, s34, 0xb0000
	v_lshl_add_u64 v[214:215], s[34:35], 0, v[130:131]
	s_addc_u32 s29, s35, 0
	s_add_i32 s52, s53, s54
	global_load_lds_dwordx4 v[214:215], off
	v_lshl_add_u64 v[216:217], s[28:29], 0, v[128:129]
	s_mov_b32 m0, s52
	v_lshl_add_u64 v[218:219], s[38:39], 0, v[132:133]
	global_load_lds_dwordx4 v[216:217], off
	v_lshl_add_u64 v[216:217], s[28:29], 0, v[130:131]
	s_add_i32 m0, s52, 0x2000
	s_nop 0
	global_load_lds_dwordx4 v[216:217], off
	v_lshl_add_u64 v[216:217], s[38:39], 0, v[134:135]
	s_mov_b32 m0, s56
	s_nop 0
	global_load_lds_dwordx4 v[216:217], off
	s_mov_b32 m0, s57
	s_nop 0
	global_load_lds_dwordx4 v[218:219], off
	s_waitcnt vmcnt(8)
	s_waitcnt lgkmcnt(0)
	s_barrier
; #define PG8_STAGE(bufoff, gbase, voff) do { _Pragma("unroll") for (int _i = 0; _i < 2; ++_i) \
;         __builtin_amdgcn_global_load_lds((const unsigned*)((const char*)(gbase) + (voff)[_i]), (PG8_LAS unsigned*)(lds + (bufoff) + ldsw + _i * 8192), 16, 0, 0); } while (0)
; #define PG8_LDA(dst, b, h) do { _Pragma("unroll") for (int m = 0; m < 4; ++m) _Pragma("unroll") for (int k = 0; k < 2; ++k) dst[m][k] = *(const PG8_LAS bf16x8*)(lds + PG8_SA(b, h) + aoff + m * 2048 + k * 1024); } while (0)
; #define PG8_LDB(dst, b, h) do { _Pragma("unroll") for (int n = 0; n < 2; ++n) _Pragma("unroll") for (int k = 0; k < 2; ++k) dst[n][k] = *(const PG8_LAS bf16x8*)(lds + PG8_SB(b, h) + boff + n * 2048 + k * 1024); } while (0)
; #define PG8_MMA(ai, bj, At, Bt) do { __builtin_amdgcn_s_setprio(1); _Pragma("unroll") for (int m = 0; m < 4; ++m) _Pragma("unroll") for (int n = 0; n < 2; ++n) _Pragma("unroll") for (int k = 0; k < 2; ++k) \
;         acc[ai][bj][m][n] = __builtin_amdgcn_mfma_f32_16x16x32_bf16(Bt[n][k], At[m][k], acc[ai][bj][m][n], 0, 0, 0); __builtin_amdgcn_s_setprio(0); } while (0)
; #define PG8_WAIT_V(n) asm volatile("s_waitcnt vmcnt(" #n ")" ::: "memory")
; #define PG8_WAIT_L(n) asm volatile("s_waitcnt lgkmcnt(" #n ")" ::: "memory")
; #define PG8_BAR __builtin_amdgcn_s_barrier()
; #define PG8_SCHED __builtin_amdgcn_sched_barrier(0)
; template <class Epi, class Sched, bool ALIGN_EPI = true, bool SP2 = true>
; __device__ __forceinline__ void gemm_phase(PG8_LAS unsigned char* lds, const Gemm g, const Sched& S, const Epi& E) {
;     ...
;             PG8_WAIT_V(8); PG8_WAIT_L(0); PG8_BAR; PG8_MMA(1, 0, At, B0); PG8_MMA(1, 1, At, B1); PG8_BAR; PG8_SCHED;
;             PG8_LDB(B0, 1, 0); PG8_LDB(B1, 1, 1); PG8_SCHED; PG8_LDA(At, 1, 0); PG8_STAGE(PG8_SA(0, 1), a2 + hstepA, voffA);
;             PG8_WAIT_V(8); PG8_WAIT_L(0); PG8_BAR; PG8_MMA(0, 0, At, B0); PG8_MMA(0, 1, At, B1); PG8_BAR; PG8_SCHED;
	s_setprio 1
	s_waitcnt lgkmcnt(0)
	v_mfma_f32_16x16x32_bf16 v[60:63], v[148:151], v[180:183], v[60:63]
	v_mfma_f32_16x16x32_bf16 v[56:59], v[156:159], v[180:183], v[56:59]
	v_mfma_f32_16x16x32_bf16 v[52:55], v[148:151], v[188:191], v[52:55]
	v_mfma_f32_16x16x32_bf16 v[48:51], v[156:159], v[188:191], v[48:51]
	v_mfma_f32_16x16x32_bf16 v[36:39], v[148:151], v[196:199], v[36:39]
	v_mfma_f32_16x16x32_bf16 v[32:35], v[156:159], v[196:199], v[32:35]
	v_mfma_f32_16x16x32_bf16 v[20:23], v[148:151], v[204:207], v[20:23]
	v_mfma_f32_16x16x32_bf16 v[16:19], v[156:159], v[204:207], v[16:19]
	s_setprio 0
	s_setprio 1
	v_mfma_f32_16x16x32_bf16 v[60:63], v[152:155], v[184:187], v[60:63]
	v_mfma_f32_16x16x32_bf16 v[56:59], v[160:163], v[184:187], v[56:59]
	v_mfma_f32_16x16x32_bf16 v[52:55], v[152:155], v[192:195], v[52:55]
	v_mfma_f32_16x16x32_bf16 v[48:51], v[160:163], v[192:195], v[48:51]
	v_mfma_f32_16x16x32_bf16 v[36:39], v[152:155], v[200:203], v[36:39]
	v_mfma_f32_16x16x32_bf16 v[32:35], v[160:163], v[200:203], v[32:35]
	v_mfma_f32_16x16x32_bf16 v[20:23], v[152:155], v[208:211], v[20:23]
	v_mfma_f32_16x16x32_bf16 v[16:19], v[160:163], v[208:211], v[16:19]
	s_setprio 0
	s_setprio 1
	v_mfma_f32_16x16x32_bf16 v[44:47], v[164:167], v[180:183], v[44:47]
	v_mfma_f32_16x16x32_bf16 v[40:43], v[172:175], v[180:183], v[40:43]
	v_mfma_f32_16x16x32_bf16 v[28:31], v[164:167], v[188:191], v[28:31]
	v_mfma_f32_16x16x32_bf16 v[24:27], v[172:175], v[188:191], v[24:27]
	v_mfma_f32_16x16x32_bf16 v[12:15], v[164:167], v[196:199], v[12:15]
	v_mfma_f32_16x16x32_bf16 v[8:11], v[172:175], v[196:199], v[8:11]
	v_mfma_f32_16x16x32_bf16 v[4:7], v[164:167], v[204:207], v[4:7]
	v_mfma_f32_16x16x32_bf16 v[0:3], v[172:175], v[204:207], v[0:3]
	s_setprio 0
	s_setprio 1
	v_mfma_f32_16x16x32_bf16 v[44:47], v[168:171], v[184:187], v[44:47]
	v_mfma_f32_16x16x32_bf16 v[40:43], v[176:179], v[184:187], v[40:43]
	v_mfma_f32_16x16x32_bf16 v[28:31], v[168:171], v[192:195], v[28:31]
	v_mfma_f32_16x16x32_bf16 v[24:27], v[176:179], v[192:195], v[24:27]
	v_mfma_f32_16x16x32_bf16 v[12:15], v[168:171], v[200:203], v[12:15]
	v_mfma_f32_16x16x32_bf16 v[8:11], v[176:179], v[200:203], v[8:11]
	v_mfma_f32_16x16x32_bf16 v[4:7], v[168:171], v[208:211], v[4:7]
	v_mfma_f32_16x16x32_bf16 v[0:3], v[176:179], v[208:211], v[0:3]
	s_setprio 0
	s_barrier
	s_add_i32 s52, 0, 0x18000
	v_add_u32_e32 v147, s52, v144
	s_add_i32 s53, 0, 0x1c000
	ds_read_b128 v[148:151], v147
	ds_read_b128 v[152:155], v147 offset:1024
	ds_read_b128 v[156:159], v147 offset:2048
	ds_read_b128 v[160:163], v147 offset:3072
	v_add_u32_e32 v147, s53, v144
	ds_read_b128 v[164:167], v147
	ds_read_b128 v[168:171], v147 offset:1024
	ds_read_b128 v[172:175], v147 offset:2048
	ds_read_b128 v[176:179], v147 offset:3072
	s_add_u32 s28, s38, 0xb0000
	s_addc_u32 s29, s39, 0
	s_mov_b32 m0, s58
	v_lshl_add_u64 v[220:221], s[28:29], 0, v[134:135]
	ds_read_b128 v[180:183], v146 offset:32768
	ds_read_b128 v[184:187], v146 offset:33792
	ds_read_b128 v[188:191], v146 offset:34816
	ds_read_b128 v[192:195], v146 offset:35840
	ds_read_b128 v[196:199], v146 offset:36864
	ds_read_b128 v[200:203], v146 offset:37888
	ds_read_b128 v[204:207], v146 offset:38912
	ds_read_b128 v[208:211], v146 offset:39936
	global_load_lds_dwordx4 v[220:221], off
	v_lshl_add_u64 v[220:221], s[28:29], 0, v[132:133]
	s_mov_b32 m0, s59
	s_nop 0
	global_load_lds_dwordx4 v[220:221], off
	s_waitcnt vmcnt(8)
	s_waitcnt lgkmcnt(0)
	s_barrier
	s_setprio 1
	s_waitcnt lgkmcnt(0)
	v_mfma_f32_16x16x32_bf16 v[124:127], v[148:151], v[180:183], v[124:127]
	v_mfma_f32_16x16x32_bf16 v[120:123], v[156:159], v[180:183], v[120:123]
	v_mfma_f32_16x16x32_bf16 v[116:119], v[148:151], v[188:191], v[116:119]
	v_mfma_f32_16x16x32_bf16 v[112:115], v[156:159], v[188:191], v[112:115]
	v_mfma_f32_16x16x32_bf16 v[100:103], v[148:151], v[196:199], v[100:103]
	v_mfma_f32_16x16x32_bf16 v[96:99], v[156:159], v[196:199], v[96:99]
	v_mfma_f32_16x16x32_bf16 v[84:87], v[148:151], v[204:207], v[84:87]
	v_mfma_f32_16x16x32_bf16 v[80:83], v[156:159], v[204:207], v[80:83]
	s_setprio 0
	s_setprio 1
	v_mfma_f32_16x16x32_bf16 v[124:127], v[152:155], v[184:187], v[124:127]
	v_mfma_f32_16x16x32_bf16 v[120:123], v[160:163], v[184:187], v[120:123]
	v_mfma_f32_16x16x32_bf16 v[116:119], v[152:155], v[192:195], v[116:119]
	v_mfma_f32_16x16x32_bf16 v[112:115], v[160:163], v[192:195], v[112:115]
	v_mfma_f32_16x16x32_bf16 v[100:103], v[152:155], v[200:203], v[100:103]
	v_mfma_f32_16x16x32_bf16 v[96:99], v[160:163], v[200:203], v[96:99]
	v_mfma_f32_16x16x32_bf16 v[84:87], v[152:155], v[208:211], v[84:87]
	v_mfma_f32_16x16x32_bf16 v[80:83], v[160:163], v[208:211], v[80:83]
	s_setprio 0
	s_setprio 1
	v_mfma_f32_16x16x32_bf16 v[108:111], v[164:167], v[180:183], v[108:111]
	v_mfma_f32_16x16x32_bf16 v[104:107], v[172:175], v[180:183], v[104:107]
	v_mfma_f32_16x16x32_bf16 v[92:95], v[164:167], v[188:191], v[92:95]
	v_mfma_f32_16x16x32_bf16 v[88:91], v[172:175], v[188:191], v[88:91]
	v_mfma_f32_16x16x32_bf16 v[76:79], v[164:167], v[196:199], v[76:79]
	v_mfma_f32_16x16x32_bf16 v[72:75], v[172:175], v[196:199], v[72:75]
	v_mfma_f32_16x16x32_bf16 v[68:71], v[164:167], v[204:207], v[68:71]
	v_mfma_f32_16x16x32_bf16 v[64:67], v[172:175], v[204:207], v[64:67]
	s_setprio 0
	s_setprio 1
	v_mfma_f32_16x16x32_bf16 v[108:111], v[168:171], v[184:187], v[108:111]
	v_mfma_f32_16x16x32_bf16 v[104:107], v[176:179], v[184:187], v[104:107]
	v_mfma_f32_16x16x32_bf16 v[92:95], v[168:171], v[192:195], v[92:95]
	v_mfma_f32_16x16x32_bf16 v[88:91], v[176:179], v[192:195], v[88:91]
	v_mfma_f32_16x16x32_bf16 v[76:79], v[168:171], v[200:203], v[76:79]
	v_mfma_f32_16x16x32_bf16 v[72:75], v[176:179], v[200:203], v[72:75]
	v_mfma_f32_16x16x32_bf16 v[68:71], v[168:171], v[208:211], v[68:71]
	v_mfma_f32_16x16x32_bf16 v[64:67], v[176:179], v[208:211], v[64:67]
	s_setprio 0
	s_barrier
; #define PG8_STAGE(bufoff, gbase, voff) do { _Pragma("unroll") for (int _i = 0; _i < 2; ++_i) \
;         __builtin_amdgcn_global_load_lds((const unsigned*)((const char*)(gbase) + (voff)[_i]), (PG8_LAS unsigned*)(lds + (bufoff) + ldsw + _i * 8192), 16, 0, 0); } while (0)
; #define PG8_LDA(dst, b, h) do { _Pragma("unroll") for (int m = 0; m < 4; ++m) _Pragma("unroll") for (int k = 0; k < 2; ++k) dst[m][k] = *(const PG8_LAS bf16x8*)(lds + PG8_SA(b, h) + aoff + m * 2048 + k * 1024); } while (0)
; #define PG8_MMA(ai, bj, At, Bt) do { __builtin_amdgcn_s_setprio(1); _Pragma("unroll") for (int m = 0; m < 4; ++m) _Pragma("unroll") for (int n = 0; n < 2; ++n) _Pragma("unroll") for (int k = 0; k < 2; ++k) \
;         acc[ai][bj][m][n] = __builtin_amdgcn_mfma_f32_16x16x32_bf16(Bt[n][k], At[m][k], acc[ai][bj][m][n], 0, 0, 0); __builtin_amdgcn_s_setprio(0); } while (0)
; #define PG8_WAIT_V(n) asm volatile("s_waitcnt vmcnt(" #n ")" ::: "memory")
; #define PG8_WAIT_L(n) asm volatile("s_waitcnt lgkmcnt(" #n ")" ::: "memory")
; #define PG8_BAR __builtin_amdgcn_s_barrier()
; #define PG8_SCHED __builtin_amdgcn_sched_barrier(0)
; template <class Epi, class Sched, bool ALIGN_EPI = true, bool SP2 = true>
; __device__ __forceinline__ void gemm_phase(PG8_LAS unsigned char* lds, const Gemm g, const Sched& S, const Epi& E) {
;     ...
;             PG8_LDA(At, 1, 1); PG8_STAGE(PG8_SB(1, 0), b3, voffB); PG8_STAGE(PG8_SB(1, 1), b3 + hstepB, voffB); PG8_STAGE(PG8_SA(1, 0), a3, voffA);
;             PG8_WAIT_V(8); PG8_WAIT_L(0); PG8_BAR; PG8_MMA(1, 0, At, B0); PG8_MMA(1, 1, At, B1); PG8_BAR; PG8_SCHED;
;         }
;         if constexpr (ALIGN_EPI) { if (wr == 0) PG8_BAR; }
	s_add_i32 s28, s52, s54
	v_lshl_add_u64 v[212:213], v[212:213], 0, s[8:9]
	s_mov_b32 m0, s28
	ds_read_b128 v[180:183], v146 offset:49152
	ds_read_b128 v[184:187], v146 offset:50176
	ds_read_b128 v[188:191], v146 offset:51200
	ds_read_b128 v[192:195], v146 offset:52224
	ds_read_b128 v[196:199], v146 offset:53248
	ds_read_b128 v[200:203], v146 offset:54272
	ds_read_b128 v[204:207], v146 offset:55296
	ds_read_b128 v[208:211], v146 offset:56320
	global_load_lds_dwordx4 v[212:213], off
	s_add_i32 m0, s28, 0x2000
	s_add_u32 s28, s34, 0xb0080
	v_lshl_add_u64 v[212:213], v[214:215], 0, s[8:9]
	s_addc_u32 s29, s35, 0
	s_add_i32 s34, s53, s54
	global_load_lds_dwordx4 v[212:213], off
	v_lshl_add_u64 v[212:213], s[28:29], 0, v[128:129]
	s_mov_b32 m0, s34
	s_nop 0
	global_load_lds_dwordx4 v[212:213], off
	v_lshl_add_u64 v[212:213], s[28:29], 0, v[130:131]
	s_add_i32 m0, s34, 0x2000
	s_nop 0
	global_load_lds_dwordx4 v[212:213], off
	v_lshl_add_u64 v[212:213], v[216:217], 0, s[8:9]
	s_mov_b32 m0, s60
	s_nop 0
	global_load_lds_dwordx4 v[212:213], off
	v_lshl_add_u64 v[212:213], v[218:219], 0, s[8:9]
	s_mov_b32 m0, s61
	s_nop 0
	global_load_lds_dwordx4 v[212:213], off
	s_waitcnt vmcnt(8)
	s_waitcnt lgkmcnt(0)
	s_barrier
	s_setprio 1
	s_waitcnt lgkmcnt(0)
	v_mfma_f32_16x16x32_bf16 v[60:63], v[148:151], v[180:183], v[60:63]
	v_mfma_f32_16x16x32_bf16 v[56:59], v[156:159], v[180:183], v[56:59]
	v_mfma_f32_16x16x32_bf16 v[52:55], v[148:151], v[188:191], v[52:55]
	v_mfma_f32_16x16x32_bf16 v[48:51], v[156:159], v[188:191], v[48:51]
	v_mfma_f32_16x16x32_bf16 v[36:39], v[148:151], v[196:199], v[36:39]
	v_mfma_f32_16x16x32_bf16 v[32:35], v[156:159], v[196:199], v[32:35]
	v_mfma_f32_16x16x32_bf16 v[20:23], v[148:151], v[204:207], v[20:23]
	v_mfma_f32_16x16x32_bf16 v[16:19], v[156:159], v[204:207], v[16:19]
	s_setprio 0
	s_setprio 1
	v_mfma_f32_16x16x32_bf16 v[60:63], v[152:155], v[184:187], v[60:63]
	v_mfma_f32_16x16x32_bf16 v[56:59], v[160:163], v[184:187], v[56:59]
	v_mfma_f32_16x16x32_bf16 v[52:55], v[152:155], v[192:195], v[52:55]
	v_mfma_f32_16x16x32_bf16 v[48:51], v[160:163], v[192:195], v[48:51]
	v_mfma_f32_16x16x32_bf16 v[36:39], v[152:155], v[200:203], v[36:39]
	v_mfma_f32_16x16x32_bf16 v[32:35], v[160:163], v[200:203], v[32:35]
	v_mfma_f32_16x16x32_bf16 v[20:23], v[152:155], v[208:211], v[20:23]
	v_mfma_f32_16x16x32_bf16 v[16:19], v[160:163], v[208:211], v[16:19]
	s_setprio 0
	s_setprio 1
	v_mfma_f32_16x16x32_bf16 v[44:47], v[164:167], v[180:183], v[44:47]
	v_mfma_f32_16x16x32_bf16 v[40:43], v[172:175], v[180:183], v[40:43]
	v_mfma_f32_16x16x32_bf16 v[28:31], v[164:167], v[188:191], v[28:31]
	v_mfma_f32_16x16x32_bf16 v[24:27], v[172:175], v[188:191], v[24:27]
	v_mfma_f32_16x16x32_bf16 v[12:15], v[164:167], v[196:199], v[12:15]
	v_mfma_f32_16x16x32_bf16 v[8:11], v[172:175], v[196:199], v[8:11]
	v_mfma_f32_16x16x32_bf16 v[4:7], v[164:167], v[204:207], v[4:7]
	v_mfma_f32_16x16x32_bf16 v[0:3], v[172:175], v[204:207], v[0:3]
	s_setprio 0
	s_setprio 1
	v_mfma_f32_16x16x32_bf16 v[44:47], v[168:171], v[184:187], v[44:47]
	v_mfma_f32_16x16x32_bf16 v[40:43], v[176:179], v[184:187], v[40:43]
	v_mfma_f32_16x16x32_bf16 v[28:31], v[168:171], v[192:195], v[28:31]
	v_mfma_f32_16x16x32_bf16 v[24:27], v[176:179], v[192:195], v[24:27]
	v_mfma_f32_16x16x32_bf16 v[12:15], v[168:171], v[200:203], v[12:15]
	v_mfma_f32_16x16x32_bf16 v[8:11], v[176:179], v[200:203], v[8:11]
	v_mfma_f32_16x16x32_bf16 v[4:7], v[168:171], v[208:211], v[4:7]
	v_mfma_f32_16x16x32_bf16 v[0:3], v[176:179], v[208:211], v[0:3]
	s_setprio 0
	s_barrier
	s_add_u32 s71, s71, 0x100
	s_addc_u32 s72, s72, 0
	s_cmp_ge_u32 s73, s47
	s_mov_b64 s[28:29], s[30:31]
	s_mov_b32 s34, s73
	s_cbranch_scc0 .LBB0_1785
	s_and_b64 vcc, exec, s[22:23]
	s_cbranch_vccz .LBB0_1788
	s_barrier
